# norm epilogues: never-taken denormal scaling around v_rsq removed (argument >= 1e-6), dead address arithmetic of replaced loads removed
# baseline (speedup 1.0000x reference)
; #define PG8_STAGE(bufoff, gbase, voff) do { _Pragma("unroll") for (int _i = 0; _i < 2; ++_i) \
;         __builtin_amdgcn_global_load_lds((const unsigned*)((const char*)(gbase) + (voff)[_i]), (LAS unsigned*)(lds + (bufoff) + ldsw + _i * 8192), 16, 0, 0); } while (0)
; #define PG8_LDA(dst, b, h) do { _Pragma("unroll") for (int m = 0; m < 4; ++m) _Pragma("unroll") for (int k = 0; k < 2; ++k) dst[m][k] = *(const LAS bf16x8*)(lds + PG8_SA(b, h) + aoff + m * 2048 + k * 1024); } while (0)
; #define PG8_LDB(dst, b, h) do { _Pragma("unroll") for (int n = 0; n < 2; ++n) _Pragma("unroll") for (int k = 0; k < 2; ++k) dst[n][k] = *(const LAS bf16x8*)(lds + PG8_SB(b, h) + boff + n * 2048 + k * 1024); } while (0)
; #define PG8_MMA(ai, bj, At, Bt) do { __builtin_amdgcn_s_setprio(1); _Pragma("unroll") for (int m = 0; m < 4; ++m) _Pragma("unroll") for (int n = 0; n < 2; ++n) _Pragma("unroll") for (int k = 0; k < 2; ++k) \
;         acc[ai][bj][m][n] = __builtin_amdgcn_mfma_f32_16x16x32_bf16(Bt[n][k], At[m][k], acc[ai][bj][m][n], 0, 0, 0); __builtin_amdgcn_s_setprio(0); } while (0)
; #define PG8_WAIT_L(n) asm volatile("s_waitcnt lgkmcnt(" #n ")" ::: "memory")
; #define PG8_BAR __builtin_amdgcn_s_barrier()
; #define PG8_SCHED __builtin_amdgcn_sched_barrier(0)
;     ...
;             PG8_LDB(B0, 0, 0); PG8_SCHED; PG8_LDA(At, 0, 0); PG8_STAGE(PG8_SA(1, 1), a1 + hA, voffA);
;             PG8_WAIT_L(8); PG8_BAR; PG8_WAIT_L(0); PG8_MMA(0, 0, At, B0); PG8_BAR; PG8_SCHED;
;             PG8_LDB(B1, 0, 1); PG8_STAGE(PG8_SB(0, 0), b2, voffB);
;             PG8_BAR; PG8_WAIT_L(0); PG8_MMA(0, 1, At, B1); PG8_BAR;
;             PG8_LDA(At, 0, 1); PG8_STAGE(PG8_SA(0, 0), a2, voffA);
;             PG8_BAR; PG8_WAIT_L(0); PG8_MMA(1, 0, At, B0); PG8_BAR; PG8_SCHED;
.LBB0_125:
	ds_read_b128 v[146:149], v155
	ds_read_b128 v[160:163], v155 offset:1024
	ds_read_b128 v[170:173], v155 offset:2048
	ds_read_b128 v[174:177], v155 offset:3072
	s_add_u32 s34, s30, 0xfffc0080
	s_addc_u32 s35, s31, -1
	s_cmp_eq_u32 s44, 12
	s_cselect_b32 s37, s7, s35
	s_cselect_b32 s36, s23, s34
	s_cselect_b32 s35, s21, s43
	s_cselect_b32 s34, s33, s42
	v_lshl_add_u64 v[150:151], s[30:31], 0, v[138:139]
	s_add_i32 m0, s29, 0xc000
	ds_read_b128 v[178:181], v156
	ds_read_b128 v[182:185], v156 offset:1024
	ds_read_b128 v[186:189], v156 offset:2048
	ds_read_b128 v[190:193], v156 offset:3072
	ds_read_b128 v[194:197], v156 offset:4096
	ds_read_b128 v[198:201], v156 offset:5120
	ds_read_b128 v[202:205], v156 offset:6144
	ds_read_b128 v[206:209], v156 offset:7168
	global_load_lds_dwordx4 v[150:151], off
	v_lshl_add_u64 v[150:151], s[30:31], 0, v[136:137]
	s_add_i32 m0, s29, 0xe000
	s_nop 0
	global_load_lds_dwordx4 v[150:151], off
	s_waitcnt lgkmcnt(8)
	s_barrier
	s_waitcnt lgkmcnt(0)
	s_setprio 1
	s_waitcnt lgkmcnt(0)
	v_mfma_f32_16x16x32_bf16 v[124:127], v[146:149], v[178:181], v[124:127]
	v_mfma_f32_16x16x32_bf16 v[120:123], v[170:173], v[178:181], v[120:123]
	v_mfma_f32_16x16x32_bf16 v[108:111], v[146:149], v[186:189], v[108:111]
	v_mfma_f32_16x16x32_bf16 v[104:107], v[170:173], v[186:189], v[104:107]
	v_mfma_f32_16x16x32_bf16 v[92:95], v[146:149], v[194:197], v[92:95]
	v_mfma_f32_16x16x32_bf16 v[88:91], v[170:173], v[194:197], v[88:91]
	v_mfma_f32_16x16x32_bf16 v[76:79], v[146:149], v[202:205], v[76:79]
	v_mfma_f32_16x16x32_bf16 v[72:75], v[170:173], v[202:205], v[72:75]
	v_mfma_f32_16x16x32_bf16 v[124:127], v[160:163], v[182:185], v[124:127]
	v_mfma_f32_16x16x32_bf16 v[120:123], v[174:177], v[182:185], v[120:123]
	v_mfma_f32_16x16x32_bf16 v[108:111], v[160:163], v[190:193], v[108:111]
	v_mfma_f32_16x16x32_bf16 v[104:107], v[174:177], v[190:193], v[104:107]
	v_mfma_f32_16x16x32_bf16 v[92:95], v[160:163], v[198:201], v[92:95]
	v_mfma_f32_16x16x32_bf16 v[88:91], v[174:177], v[198:201], v[88:91]
	v_mfma_f32_16x16x32_bf16 v[76:79], v[160:163], v[206:209], v[76:79]
	v_mfma_f32_16x16x32_bf16 v[72:75], v[174:177], v[206:209], v[72:75]
	s_setprio 0
	s_barrier
	s_add_i32 s45, s59, s51
	v_lshl_add_u64 v[150:151], s[34:35], 0, v[130:131]
	s_mov_b32 m0, s45
	ds_read_b128 v[210:213], v157
	ds_read_b128 v[214:217], v157 offset:1024
	ds_read_b128 v[218:221], v157 offset:2048
	ds_read_b128 v[222:225], v157 offset:3072
	global_load_lds_dwordx4 v[150:151], off
	v_lshl_add_u64 v[164:165], s[34:35], 0, v[134:135]
	s_add_i32 m0, s45, 0x2000
	s_nop 0
	global_load_lds_dwordx4 v[164:165], off
	s_barrier
	s_waitcnt lgkmcnt(0)
	s_setprio 1
	s_waitcnt lgkmcnt(0)
	v_mfma_f32_16x16x32_bf16 v[116:119], v[210:213], v[178:181], v[116:119]
	v_mfma_f32_16x16x32_bf16 v[112:115], v[218:221], v[178:181], v[112:115]
	v_mfma_f32_16x16x32_bf16 v[100:103], v[210:213], v[186:189], v[100:103]
	v_mfma_f32_16x16x32_bf16 v[96:99], v[218:221], v[186:189], v[96:99]
	v_mfma_f32_16x16x32_bf16 v[84:87], v[210:213], v[194:197], v[84:87]
	v_mfma_f32_16x16x32_bf16 v[80:83], v[218:221], v[194:197], v[80:83]
	v_mfma_f32_16x16x32_bf16 v[68:71], v[210:213], v[202:205], v[68:71]
	v_mfma_f32_16x16x32_bf16 v[64:67], v[218:221], v[202:205], v[64:67]
	v_mfma_f32_16x16x32_bf16 v[116:119], v[214:217], v[182:185], v[116:119]
	v_mfma_f32_16x16x32_bf16 v[112:115], v[222:225], v[182:185], v[112:115]
	v_mfma_f32_16x16x32_bf16 v[100:103], v[214:217], v[190:193], v[100:103]
	v_mfma_f32_16x16x32_bf16 v[96:99], v[222:225], v[190:193], v[96:99]
	v_mfma_f32_16x16x32_bf16 v[84:87], v[214:217], v[198:201], v[84:87]
	v_mfma_f32_16x16x32_bf16 v[80:83], v[222:225], v[198:201], v[80:83]
	v_mfma_f32_16x16x32_bf16 v[68:71], v[214:217], v[206:209], v[68:71]
	v_mfma_f32_16x16x32_bf16 v[64:67], v[222:225], v[206:209], v[64:67]
	s_setprio 0
	s_mov_b32 m0, s29
	v_lshl_add_u64 v[226:227], s[36:37], 0, v[128:129]
	s_barrier
	ds_read_b128 v[178:181], v156 offset:16384
	ds_read_b128 v[182:185], v156 offset:17408
	ds_read_b128 v[186:189], v156 offset:18432
	ds_read_b128 v[190:193], v156 offset:19456
	ds_read_b128 v[194:197], v156 offset:20480
	ds_read_b128 v[198:201], v156 offset:21504
	ds_read_b128 v[202:205], v156 offset:22528
	ds_read_b128 v[206:209], v156 offset:23552
	global_load_lds_dwordx4 v[226:227], off
	v_lshl_add_u64 v[228:229], s[36:37], 0, v[132:133]
	s_mov_b32 m0, s52
	s_nop 0
	global_load_lds_dwordx4 v[228:229], off
	s_barrier
	s_waitcnt lgkmcnt(0)
	s_setprio 1
	s_waitcnt lgkmcnt(0)
	v_mfma_f32_16x16x32_bf16 v[60:63], v[146:149], v[178:181], v[60:63]
	v_mfma_f32_16x16x32_bf16 v[56:59], v[170:173], v[178:181], v[56:59]
	v_mfma_f32_16x16x32_bf16 v[44:47], v[146:149], v[186:189], v[44:47]
	v_mfma_f32_16x16x32_bf16 v[40:43], v[170:173], v[186:189], v[40:43]
	v_mfma_f32_16x16x32_bf16 v[28:31], v[146:149], v[194:197], v[28:31]
	v_mfma_f32_16x16x32_bf16 v[24:27], v[170:173], v[194:197], v[24:27]
	v_mfma_f32_16x16x32_bf16 v[12:15], v[146:149], v[202:205], v[12:15]
	v_mfma_f32_16x16x32_bf16 v[8:11], v[170:173], v[202:205], v[8:11]
	v_mfma_f32_16x16x32_bf16 v[60:63], v[160:163], v[182:185], v[60:63]
	v_mfma_f32_16x16x32_bf16 v[56:59], v[174:177], v[182:185], v[56:59]
	v_mfma_f32_16x16x32_bf16 v[44:47], v[160:163], v[190:193], v[44:47]
	v_mfma_f32_16x16x32_bf16 v[40:43], v[174:177], v[190:193], v[40:43]
	v_mfma_f32_16x16x32_bf16 v[28:31], v[160:163], v[198:201], v[28:31]
	v_mfma_f32_16x16x32_bf16 v[24:27], v[174:177], v[198:201], v[24:27]
	v_mfma_f32_16x16x32_bf16 v[12:15], v[160:163], v[206:209], v[12:15]
	v_mfma_f32_16x16x32_bf16 v[8:11], v[174:177], v[206:209], v[8:11]
	s_setprio 0
	s_barrier
; #define PG8_STAGE(bufoff, gbase, voff) do { _Pragma("unroll") for (int _i = 0; _i < 2; ++_i) \
;         __builtin_amdgcn_global_load_lds((const unsigned*)((const char*)(gbase) + (voff)[_i]), (LAS unsigned*)(lds + (bufoff) + ldsw + _i * 8192), 16, 0, 0); } while (0)
; #define PG8_LDA(dst, b, h) do { _Pragma("unroll") for (int m = 0; m < 4; ++m) _Pragma("unroll") for (int k = 0; k < 2; ++k) dst[m][k] = *(const LAS bf16x8*)(lds + PG8_SA(b, h) + aoff + m * 2048 + k * 1024); } while (0)
; #define PG8_LDB(dst, b, h) do { _Pragma("unroll") for (int n = 0; n < 2; ++n) _Pragma("unroll") for (int k = 0; k < 2; ++k) dst[n][k] = *(const LAS bf16x8*)(lds + PG8_SB(b, h) + boff + n * 2048 + k * 1024); } while (0)
; #define PG8_MMA(ai, bj, At, Bt) do { __builtin_amdgcn_s_setprio(1); _Pragma("unroll") for (int m = 0; m < 4; ++m) _Pragma("unroll") for (int n = 0; n < 2; ++n) _Pragma("unroll") for (int k = 0; k < 2; ++k) \
;         acc[ai][bj][m][n] = __builtin_amdgcn_mfma_f32_16x16x32_bf16(Bt[n][k], At[m][k], acc[ai][bj][m][n], 0, 0, 0); __builtin_amdgcn_s_setprio(0); } while (0)
; #define PG8_WAIT_V(n) asm volatile("s_waitcnt vmcnt(" #n ")" ::: "memory")
; #define PG8_WAIT_L(n) asm volatile("s_waitcnt lgkmcnt(" #n ")" ::: "memory")
; #define PG8_BAR __builtin_amdgcn_s_barrier()
; #define PG8_SCHED __builtin_amdgcn_sched_barrier(0)
;     ...
;             PG8_STAGE(PG8_SB(0, 1), b2 + hB, voffB);
;             PG8_WAIT_V(6); PG8_BAR; PG8_MMA(1, 1, At, B1); PG8_BAR;
;             PG8_LDB(B0, 1, 0); PG8_SCHED; PG8_LDA(At, 1, 0); PG8_STAGE(PG8_SA(0, 1), a2 + hA, voffA);
;             PG8_WAIT_L(8); PG8_BAR; PG8_WAIT_L(0); PG8_MMA(0, 0, At, B0); PG8_BAR; PG8_SCHED;
;             PG8_LDB(B1, 1, 1); PG8_STAGE(PG8_SB(1, 0), b3, voffB);
;             PG8_BAR; PG8_WAIT_L(0); PG8_MMA(0, 1, At, B1); PG8_BAR;
;             PG8_LDA(At, 1, 1); PG8_STAGE(PG8_SA(1, 0), a3, voffA);
	s_add_u32 s64, s34, 0x40000
	s_addc_u32 s65, s35, 0
	s_add_i32 s45, s60, s51
	v_lshl_add_u64 v[146:147], s[64:65], 0, v[130:131]
	s_mov_b32 m0, s45
	s_nop 0
	global_load_lds_dwordx4 v[146:147], off
	v_lshl_add_u64 v[146:147], s[64:65], 0, v[134:135]
	s_add_i32 m0, s45, 0x2000
	s_nop 0
	global_load_lds_dwordx4 v[146:147], off
	s_waitcnt vmcnt(6)
	s_barrier
	s_setprio 1
	v_mfma_f32_16x16x32_bf16 v[52:55], v[210:213], v[178:181], v[52:55]
	v_mfma_f32_16x16x32_bf16 v[48:51], v[218:221], v[178:181], v[48:51]
	v_mfma_f32_16x16x32_bf16 v[36:39], v[210:213], v[186:189], v[36:39]
	v_mfma_f32_16x16x32_bf16 v[32:35], v[218:221], v[186:189], v[32:35]
	v_mfma_f32_16x16x32_bf16 v[20:23], v[210:213], v[194:197], v[20:23]
	v_mfma_f32_16x16x32_bf16 v[16:19], v[218:221], v[194:197], v[16:19]
	v_mfma_f32_16x16x32_bf16 v[4:7], v[210:213], v[202:205], v[4:7]
	v_mfma_f32_16x16x32_bf16 v[0:3], v[218:221], v[202:205], v[0:3]
	v_mfma_f32_16x16x32_bf16 v[52:55], v[214:217], v[182:185], v[52:55]
	v_mfma_f32_16x16x32_bf16 v[48:51], v[222:225], v[182:185], v[48:51]
	v_mfma_f32_16x16x32_bf16 v[36:39], v[214:217], v[190:193], v[36:39]
	v_mfma_f32_16x16x32_bf16 v[32:35], v[222:225], v[190:193], v[32:35]
	v_mfma_f32_16x16x32_bf16 v[20:23], v[214:217], v[198:201], v[20:23]
	v_mfma_f32_16x16x32_bf16 v[16:19], v[222:225], v[198:201], v[16:19]
	v_mfma_f32_16x16x32_bf16 v[4:7], v[214:217], v[206:209], v[4:7]
	v_mfma_f32_16x16x32_bf16 v[0:3], v[222:225], v[206:209], v[0:3]
	s_setprio 0
	s_add_i32 s45, 0, 0x18000
	v_add_u32_e32 v159, s45, v153
	s_barrier
	ds_read_b128 v[146:149], v159
	ds_read_b128 v[160:163], v159 offset:1024
	ds_read_b128 v[170:173], v159 offset:2048
	ds_read_b128 v[174:177], v159 offset:3072
	s_add_u32 s36, s36, 0x40000
	s_addc_u32 s37, s37, 0
	s_mov_b32 m0, s53
	v_lshl_add_u64 v[210:211], s[36:37], 0, v[128:129]
	ds_read_b128 v[178:181], v156 offset:32768
	ds_read_b128 v[182:185], v156 offset:33792
	ds_read_b128 v[186:189], v156 offset:34816
	ds_read_b128 v[190:193], v156 offset:35840
	ds_read_b128 v[194:197], v156 offset:36864
	ds_read_b128 v[198:201], v156 offset:37888
	ds_read_b128 v[202:205], v156 offset:38912
	ds_read_b128 v[206:209], v156 offset:39936
	global_load_lds_dwordx4 v[210:211], off
	v_lshl_add_u64 v[210:211], s[36:37], 0, v[132:133]
	s_mov_b32 m0, s54
	s_nop 0
	global_load_lds_dwordx4 v[210:211], off
	s_waitcnt lgkmcnt(8)
	s_barrier
	s_waitcnt lgkmcnt(0)
	s_setprio 1
	s_waitcnt lgkmcnt(0)
	v_mfma_f32_16x16x32_bf16 v[124:127], v[146:149], v[178:181], v[124:127]
	v_mfma_f32_16x16x32_bf16 v[120:123], v[170:173], v[178:181], v[120:123]
	v_mfma_f32_16x16x32_bf16 v[108:111], v[146:149], v[186:189], v[108:111]
	v_mfma_f32_16x16x32_bf16 v[104:107], v[170:173], v[186:189], v[104:107]
	v_mfma_f32_16x16x32_bf16 v[92:95], v[146:149], v[194:197], v[92:95]
	v_mfma_f32_16x16x32_bf16 v[88:91], v[170:173], v[194:197], v[88:91]
	v_mfma_f32_16x16x32_bf16 v[76:79], v[146:149], v[202:205], v[76:79]
	v_mfma_f32_16x16x32_bf16 v[72:75], v[170:173], v[202:205], v[72:75]
	v_mfma_f32_16x16x32_bf16 v[124:127], v[160:163], v[182:185], v[124:127]
	v_mfma_f32_16x16x32_bf16 v[120:123], v[174:177], v[182:185], v[120:123]
	v_mfma_f32_16x16x32_bf16 v[108:111], v[160:163], v[190:193], v[108:111]
	v_mfma_f32_16x16x32_bf16 v[104:107], v[174:177], v[190:193], v[104:107]
	v_mfma_f32_16x16x32_bf16 v[92:95], v[160:163], v[198:201], v[92:95]
	v_mfma_f32_16x16x32_bf16 v[88:91], v[174:177], v[198:201], v[88:91]
	v_mfma_f32_16x16x32_bf16 v[76:79], v[160:163], v[206:209], v[76:79]
	v_mfma_f32_16x16x32_bf16 v[72:75], v[174:177], v[206:209], v[72:75]
	s_setprio 0
	s_barrier
	s_add_i32 s36, 0, 0x1c000
	s_add_i32 s37, s45, s51
	v_add_u32_e32 v159, s36, v153
	v_lshl_add_u64 v[150:151], v[150:151], 0, s[18:19]
	s_mov_b32 m0, s37
	ds_read_b128 v[210:213], v159
	ds_read_b128 v[214:217], v159 offset:1024
	ds_read_b128 v[218:221], v159 offset:2048
	ds_read_b128 v[222:225], v159 offset:3072
	global_load_lds_dwordx4 v[150:151], off
	v_lshl_add_u64 v[150:151], v[164:165], 0, s[18:19]
	s_add_i32 m0, s37, 0x2000
	s_nop 0
	global_load_lds_dwordx4 v[150:151], off
	s_barrier
	s_waitcnt lgkmcnt(0)
	s_setprio 1
	s_waitcnt lgkmcnt(0)
	v_mfma_f32_16x16x32_bf16 v[116:119], v[210:213], v[178:181], v[116:119]
	v_mfma_f32_16x16x32_bf16 v[112:115], v[218:221], v[178:181], v[112:115]
	v_mfma_f32_16x16x32_bf16 v[100:103], v[210:213], v[186:189], v[100:103]
	v_mfma_f32_16x16x32_bf16 v[96:99], v[218:221], v[186:189], v[96:99]
	v_mfma_f32_16x16x32_bf16 v[84:87], v[210:213], v[194:197], v[84:87]
	v_mfma_f32_16x16x32_bf16 v[80:83], v[218:221], v[194:197], v[80:83]
	v_mfma_f32_16x16x32_bf16 v[68:71], v[210:213], v[202:205], v[68:71]
	v_mfma_f32_16x16x32_bf16 v[64:67], v[218:221], v[202:205], v[64:67]
	v_mfma_f32_16x16x32_bf16 v[116:119], v[214:217], v[182:185], v[116:119]
	v_mfma_f32_16x16x32_bf16 v[112:115], v[222:225], v[182:185], v[112:115]
	v_mfma_f32_16x16x32_bf16 v[100:103], v[214:217], v[190:193], v[100:103]
	v_mfma_f32_16x16x32_bf16 v[96:99], v[222:225], v[190:193], v[96:99]
	v_mfma_f32_16x16x32_bf16 v[84:87], v[214:217], v[198:201], v[84:87]
	v_mfma_f32_16x16x32_bf16 v[80:83], v[222:225], v[198:201], v[80:83]
	v_mfma_f32_16x16x32_bf16 v[68:71], v[214:217], v[206:209], v[68:71]
	v_mfma_f32_16x16x32_bf16 v[64:67], v[222:225], v[206:209], v[64:67]
	s_setprio 0
	s_mov_b32 m0, s56
	v_lshl_add_u64 v[150:151], v[226:227], 0, s[18:19]
	s_barrier
	ds_read_b128 v[178:181], v156 offset:49152
	ds_read_b128 v[182:185], v156 offset:50176
	ds_read_b128 v[186:189], v156 offset:51200
	ds_read_b128 v[190:193], v156 offset:52224
	ds_read_b128 v[194:197], v156 offset:53248
	ds_read_b128 v[198:201], v156 offset:54272
	ds_read_b128 v[202:205], v156 offset:55296
	ds_read_b128 v[206:209], v156 offset:56320
	global_load_lds_dwordx4 v[150:151], off
	v_lshl_add_u64 v[150:151], v[228:229], 0, s[18:19]
	s_mov_b32 m0, s57
	s_nop 0
	global_load_lds_dwordx4 v[150:151], off
	s_barrier
; __device__ __forceinline__ float bflo(unsigned w) { return __uint_as_float(w << 16); }
; __device__ __forceinline__ float bfhi(unsigned w) { return __uint_as_float(w & 0xffff0000u); }
; __device__ __forceinline__ unsigned pk2(float lo, float hi) { unsigned r; asm volatile("v_cvt_pk_bf16_f32 %0, %1, %2" : "=v"(r) : "v"(lo), "v"(hi)); return r; }
; #define PG8_WAIT_V(n) asm volatile("s_waitcnt vmcnt(" #n ")" ::: "memory")
;     ...
;             PG8_BAR; PG8_WAIT_L(0); PG8_MMA(1, 0, At, B0); PG8_BAR; PG8_SCHED;
;             PG8_STAGE(PG8_SB(1, 1), b3 + hB, voffB);
;             PG8_WAIT_V(6); PG8_BAR; PG8_MMA(1, 1, At, B1); PG8_BAR;
;         }
; __device__ __forceinline__ float row_rstd(const float* ssq, int row) {
;     const f32x4* p = (const f32x4*)(ssq + (size_t)row * 16);
;     const f32x4 a = p[0], b = p[1], c = p[2], d = p[3];
;     const float s = ((a[0] + a[1]) + (a[2] + a[3])) + ((b[0] + b[1]) + (b[2] + b[3])) + ((c[0] + c[1]) + (c[2] + c[3])) + ((d[0] + d[1]) + (d[2] + d[3]));
;     return rsqrtf(s * (1.0f / 1024.0f) + 1e-6f);
; }
; __device__ __forceinline__ u32x4 pack8(const f32x4 v0, const f32x4 v1) { u32x4 w; w.x = pk2(v0[0], v0[1]); w.y = pk2(v0[2], v0[3]); w.z = pk2(v1[0], v1[1]); w.w = pk2(v1[2], v1[3]); return w; }
; __device__ __forceinline__ void unpack8(const u32x4 w, f32x4& v0, f32x4& v1) { v0 = (f32x4){bflo(w.x), bfhi(w.x), bflo(w.y), bfhi(w.y)}; v1 = (f32x4){bflo(w.z), bfhi(w.z), bflo(w.w), bfhi(w.w)}; }
;     __device__ __forceinline__ void operator()(const f32x4 (&acc)[2][2][4][2], const Unit& u, int wr, int wc, int fr, int fq) const {
;         const int row0 = u.pm * 256 + wr * 64 + fr, col0 = u.pn * 256 + wc * 32 + 8 * fq;
; #pragma unroll
;         for (int ai = 0; ai < 2; ++ai)
; #pragma unroll
;             for (int m = 0; m < 4; ++m) {
;                 const int row = row0 + ai * 128 + m * 16; const float rs = row_rstd(ssq, row);
;                 bf16_t* rowp = O + (size_t)row * ldc + col0;
; #pragma unroll
;                 for (int bj = 0; bj < 2; ++bj) { f32x4 v0 = acc[ai][bj][m][0] * rs, v1 = acc[ai][bj][m][1] * rs;
;                     if (ACT == 1) {
; #pragma unroll
;                         for (int j = 0; j < 4; ++j) { const float a = fmaxf(v0[j], 0.f), b = fmaxf(v1[j], 0.f); v0[j] = a * a; v1[j] = b * b; } }
;                     *(u32x4*)(rowp + bj * 128) = pack8(v0, v1); }
	s_waitcnt lgkmcnt(0)
	s_setprio 1
	s_waitcnt lgkmcnt(0)
	v_mfma_f32_16x16x32_bf16 v[60:63], v[146:149], v[178:181], v[60:63]
	v_mfma_f32_16x16x32_bf16 v[56:59], v[170:173], v[178:181], v[56:59]
	v_mfma_f32_16x16x32_bf16 v[44:47], v[146:149], v[186:189], v[44:47]
	v_mfma_f32_16x16x32_bf16 v[40:43], v[170:173], v[186:189], v[40:43]
	v_mfma_f32_16x16x32_bf16 v[28:31], v[146:149], v[194:197], v[28:31]
	v_mfma_f32_16x16x32_bf16 v[24:27], v[170:173], v[194:197], v[24:27]
	v_mfma_f32_16x16x32_bf16 v[12:15], v[146:149], v[202:205], v[12:15]
	v_mfma_f32_16x16x32_bf16 v[8:11], v[170:173], v[202:205], v[8:11]
	v_mfma_f32_16x16x32_bf16 v[60:63], v[160:163], v[182:185], v[60:63]
	v_mfma_f32_16x16x32_bf16 v[56:59], v[174:177], v[182:185], v[56:59]
	v_mfma_f32_16x16x32_bf16 v[44:47], v[160:163], v[190:193], v[44:47]
	v_mfma_f32_16x16x32_bf16 v[40:43], v[174:177], v[190:193], v[40:43]
	v_mfma_f32_16x16x32_bf16 v[28:31], v[160:163], v[198:201], v[28:31]
	v_mfma_f32_16x16x32_bf16 v[24:27], v[174:177], v[198:201], v[24:27]
	v_mfma_f32_16x16x32_bf16 v[12:15], v[160:163], v[206:209], v[12:15]
	v_mfma_f32_16x16x32_bf16 v[8:11], v[174:177], v[206:209], v[8:11]
	s_setprio 0
	s_barrier
	s_add_u32 s34, s34, 0x40080
	s_addc_u32 s35, s35, 0
	s_add_i32 s36, s36, s51
	v_lshl_add_u64 v[146:147], s[34:35], 0, v[130:131]
	s_mov_b32 m0, s36
	s_nop 0
	global_load_lds_dwordx4 v[146:147], off
	v_lshl_add_u64 v[146:147], s[34:35], 0, v[134:135]
	s_add_i32 m0, s36, 0x2000
	s_nop 0
	global_load_lds_dwordx4 v[146:147], off
	s_waitcnt vmcnt(6)
	s_barrier
	s_setprio 1
	v_mfma_f32_16x16x32_bf16 v[52:55], v[210:213], v[178:181], v[52:55]
	v_mfma_f32_16x16x32_bf16 v[48:51], v[218:221], v[178:181], v[48:51]
	v_mfma_f32_16x16x32_bf16 v[36:39], v[210:213], v[186:189], v[36:39]
	v_mfma_f32_16x16x32_bf16 v[32:35], v[218:221], v[186:189], v[32:35]
	v_mfma_f32_16x16x32_bf16 v[20:23], v[210:213], v[194:197], v[20:23]
	v_mfma_f32_16x16x32_bf16 v[16:19], v[218:221], v[194:197], v[16:19]
	v_mfma_f32_16x16x32_bf16 v[4:7], v[210:213], v[202:205], v[4:7]
	v_mfma_f32_16x16x32_bf16 v[0:3], v[218:221], v[202:205], v[0:3]
	v_mfma_f32_16x16x32_bf16 v[52:55], v[214:217], v[182:185], v[52:55]
	v_mfma_f32_16x16x32_bf16 v[48:51], v[222:225], v[182:185], v[48:51]
	v_mfma_f32_16x16x32_bf16 v[36:39], v[214:217], v[190:193], v[36:39]
	v_mfma_f32_16x16x32_bf16 v[32:35], v[222:225], v[190:193], v[32:35]
	v_mfma_f32_16x16x32_bf16 v[20:23], v[214:217], v[198:201], v[20:23]
	v_mfma_f32_16x16x32_bf16 v[16:19], v[222:225], v[198:201], v[16:19]
	v_mfma_f32_16x16x32_bf16 v[4:7], v[214:217], v[206:209], v[4:7]
	v_mfma_f32_16x16x32_bf16 v[0:3], v[222:225], v[206:209], v[0:3]
	s_setprio 0
	s_add_i32 s44, s44, 2
	s_add_u32 s42, s42, 0x100
	s_addc_u32 s43, s43, 0
	s_add_u32 s30, s30, 0x100
	s_addc_u32 s31, s31, 0
	s_cmp_gt_u32 s44, 13
	s_barrier
	s_cbranch_scc0 .LBB0_125
	v_lshl_add_u32 v150, s28, 8, v152
	v_ashrrev_i32_e32 v151, 31, v150
	v_lshlrev_b64 v[146:147], 6, v[150:151]
	v_lshl_add_u64 v[146:147], s[16:17], 0, v[146:147]
	v_subrev_u32_e32 v186, s16, v146
	v_add_u32_e32 v187, 0x0, v186
	global_load_dwordx4 v[188:191], v187, s[16:17]
	v_add_u32_e32 v187, 0x20, v186
	global_load_dwordx4 v[192:195], v187, s[16:17]
	v_add_u32_e32 v187, 0x10, v186
	global_load_dwordx4 v[196:199], v187, s[16:17]
	v_add_u32_e32 v187, 0x30, v186
	global_load_dwordx4 v[200:203], v187, s[16:17]
	v_add_u32_e32 v187, 0x400, v186
	global_load_dwordx4 v[204:207], v187, s[16:17]
	v_add_u32_e32 v187, 0x410, v186
	global_load_dwordx4 v[208:211], v187, s[16:17]
	v_add_u32_e32 v187, 0x420, v186
	global_load_dwordx4 v[212:215], v187, s[16:17]
	v_add_u32_e32 v187, 0x430, v186
	global_load_dwordx4 v[216:219], v187, s[16:17]
	v_add_u32_e32 v187, 0x800, v186
	global_load_dwordx4 v[220:223], v187, s[16:17]
	v_add_u32_e32 v187, 0x810, v186
	global_load_dwordx4 v[232:235], v187, s[16:17]
	v_add_u32_e32 v187, 0x820, v186
	global_load_dwordx4 v[236:239], v187, s[16:17]
	v_add_u32_e32 v187, 0x830, v186
	global_load_dwordx4 v[240:243], v187, s[16:17]
	v_lshl_or_b32 v148, s6, 8, v154
	v_mov_b64_e32 v[146:147], s[14:15]
	v_ashrrev_i32_e32 v149, 31, v148
	v_mad_i64_i32 v[164:165], s[6:7], v150, s62, v[146:147]
	v_or_b32_e32 v182, 16, v150
	v_lshlrev_b64 v[148:149], 1, v[148:149]
	v_ashrrev_i32_e32 v183, 31, v182
	s_mov_b64 s[34:35], s[24:25]
	s_mov_b32 s28, s22
	s_mov_b64 s[30:31], s[26:27]
	s_waitcnt vmcnt(8)
	v_pk_add_f32 v[160:161], v[188:189], v[190:191]
	v_pk_add_f32 v[170:171], v[192:193], v[194:195]
	v_pk_add_f32 v[172:173], v[196:197], v[198:199]
	v_pk_add_f32 v[174:175], v[200:201], v[202:203]
	v_pk_add_f32 v[160:161], v[160:161], v[170:171]
	v_pk_add_f32 v[172:173], v[172:173], v[174:175]
	v_pk_add_f32 v[160:161], v[160:161], v[172:173]
	v_add_f32_e32 v151, v160, v161
	s_nop 0
	s_nop 0
	v_fmamk_f32 v151, v151, 0x3a800000, v158
	s_nop 0
	s_nop 0
	v_lshl_add_u64 v[160:161], v[164:165], 0, v[148:149]
	s_nop 0
	s_nop 0
	v_rsq_f32_e32 v151, v151
	s_nop 0
	s_nop 0
	v_mov_b32_e32 v164, v151
	v_pk_mul_f32 v[126:127], v[126:127], v[164:165] op_sel_hi:[1,0]
	v_pk_mul_f32 v[124:125], v[124:125], v[164:165] op_sel_hi:[1,0]
	v_pk_mul_f32 v[122:123], v[122:123], v[164:165] op_sel_hi:[1,0]
	v_pk_mul_f32 v[120:121], v[120:121], v[164:165] op_sel_hi:[1,0]
	v_pk_mul_f32 v[118:119], v[118:119], v[164:165] op_sel_hi:[1,0]
	v_pk_mul_f32 v[116:117], v[116:117], v[164:165] op_sel_hi:[1,0]
	v_pk_mul_f32 v[170:171], v[114:115], v[164:165] op_sel_hi:[1,0]
	v_pk_mul_f32 v[164:165], v[112:113], v[164:165] op_sel_hi:[1,0]
	v_cvt_pk_bf16_f32 v112, v124, v125
	v_cvt_pk_bf16_f32 v113, v126, v127
	v_cvt_pk_bf16_f32 v114, v120, v121
	v_cvt_pk_bf16_f32 v115, v122, v123
	global_store_dwordx4 v[160:161], v[112:115], off sc1
	s_nop 1
	v_cvt_pk_bf16_f32 v112, v116, v117
	v_cvt_pk_bf16_f32 v113, v118, v119
	v_cvt_pk_bf16_f32 v114, v164, v165
	v_cvt_pk_bf16_f32 v115, v170, v171
	global_store_dwordx4 v[160:161], v[112:115], off offset:256 sc1
	s_nop 0
	v_or_b32_e32 v160, 32, v150
	v_mad_i64_i32 v[162:163], s[6:7], v182, s62, v[146:147]
	v_ashrrev_i32_e32 v161, 31, v160
	v_add_u32_e32 v187, 0xc00, v186
	global_load_dwordx4 v[188:191], v187, s[16:17]
	v_add_u32_e32 v187, 0xc10, v186
	global_load_dwordx4 v[192:195], v187, s[16:17]
	v_add_u32_e32 v187, 0xc20, v186
	global_load_dwordx4 v[196:199], v187, s[16:17]
	v_add_u32_e32 v187, 0xc30, v186
	global_load_dwordx4 v[200:203], v187, s[16:17]
	s_waitcnt vmcnt(10)
; __device__ __forceinline__ float bflo(unsigned w) { return __uint_as_float(w << 16); }
; __device__ __forceinline__ float bfhi(unsigned w) { return __uint_as_float(w & 0xffff0000u); }
; __device__ __forceinline__ unsigned pk2(float lo, float hi) { unsigned r; asm volatile("v_cvt_pk_bf16_f32 %0, %1, %2" : "=v"(r) : "v"(lo), "v"(hi)); return r; }
; __device__ __forceinline__ float row_rstd(const float* ssq, int row) {
;     const f32x4* p = (const f32x4*)(ssq + (size_t)row * 16);
;     const f32x4 a = p[0], b = p[1], c = p[2], d = p[3];
;     const float s = ((a[0] + a[1]) + (a[2] + a[3])) + ((b[0] + b[1]) + (b[2] + b[3])) + ((c[0] + c[1]) + (c[2] + c[3])) + ((d[0] + d[1]) + (d[2] + d[3]));
;     return rsqrtf(s * (1.0f / 1024.0f) + 1e-6f);
; }
; __device__ __forceinline__ u32x4 pack8(const f32x4 v0, const f32x4 v1) { u32x4 w; w.x = pk2(v0[0], v0[1]); w.y = pk2(v0[2], v0[3]); w.z = pk2(v1[0], v1[1]); w.w = pk2(v1[2], v1[3]); return w; }
; __device__ __forceinline__ void unpack8(const u32x4 w, f32x4& v0, f32x4& v1) { v0 = (f32x4){bflo(w.x), bfhi(w.x), bflo(w.y), bfhi(w.y)}; v1 = (f32x4){bflo(w.z), bfhi(w.z), bflo(w.w), bfhi(w.w)}; }
;     __device__ __forceinline__ void operator()(const f32x4 (&acc)[2][2][4][2], const Unit& u, int wr, int wc, int fr, int fq) const {
;         const int row0 = u.pm * 256 + wr * 64 + fr, col0 = u.pn * 256 + wc * 32 + 8 * fq;
; #pragma unroll
;         for (int ai = 0; ai < 2; ++ai)
; #pragma unroll
;             for (int m = 0; m < 4; ++m) {
;                 const int row = row0 + ai * 128 + m * 16; const float rs = row_rstd(ssq, row);
;                 bf16_t* rowp = O + (size_t)row * ldc + col0;
; #pragma unroll
;                 for (int bj = 0; bj < 2; ++bj) { f32x4 v0 = acc[ai][bj][m][0] * rs, v1 = acc[ai][bj][m][1] * rs;
;                     if (ACT == 1) {
; #pragma unroll
;                         for (int j = 0; j < 4; ++j) { const float a = fmaxf(v0[j], 0.f), b = fmaxf(v1[j], 0.f); v0[j] = a * a; v1[j] = b * b; } }
;                     *(u32x4*)(rowp + bj * 128) = pack8(v0, v1); }
	v_pk_add_f32 v[112:113], v[204:205], v[206:207]
	v_pk_add_f32 v[116:117], v[208:209], v[210:211]
	v_pk_add_f32 v[118:119], v[212:213], v[214:215]
	v_pk_add_f32 v[120:121], v[216:217], v[218:219]
	v_pk_add_f32 v[112:113], v[112:113], v[116:117]
	v_pk_add_f32 v[118:119], v[118:119], v[120:121]
	v_pk_add_f32 v[112:113], v[112:113], v[118:119]
	v_add_f32_e32 v112, v112, v113
	s_nop 0
	s_nop 0
	v_fmamk_f32 v112, v112, 0x3a800000, v158
	s_nop 0
	s_nop 0
	s_nop 1
	s_nop 0
	v_rsq_f32_e32 v116, v112
	v_lshl_add_u64 v[112:113], v[162:163], 0, v[148:149]
	s_nop 0
	s_nop 0
	v_pk_mul_f32 v[110:111], v[110:111], v[116:117] op_sel_hi:[1,0]
	v_pk_mul_f32 v[108:109], v[108:109], v[116:117] op_sel_hi:[1,0]
	v_pk_mul_f32 v[106:107], v[106:107], v[116:117] op_sel_hi:[1,0]
	v_pk_mul_f32 v[104:105], v[104:105], v[116:117] op_sel_hi:[1,0]
	v_pk_mul_f32 v[102:103], v[102:103], v[116:117] op_sel_hi:[1,0]
	v_pk_mul_f32 v[100:101], v[100:101], v[116:117] op_sel_hi:[1,0]
	v_pk_mul_f32 v[118:119], v[98:99], v[116:117] op_sel_hi:[1,0]
	v_pk_mul_f32 v[116:117], v[96:97], v[116:117] op_sel_hi:[1,0]
	v_cvt_pk_bf16_f32 v96, v108, v109
	v_cvt_pk_bf16_f32 v97, v110, v111
	v_cvt_pk_bf16_f32 v98, v104, v105
	v_cvt_pk_bf16_f32 v99, v106, v107
	global_store_dwordx4 v[112:113], v[96:99], off sc1
	s_nop 1
	v_cvt_pk_bf16_f32 v96, v100, v101
	v_cvt_pk_bf16_f32 v97, v102, v103
	v_cvt_pk_bf16_f32 v98, v116, v117
	v_cvt_pk_bf16_f32 v99, v118, v119
	global_store_dwordx4 v[112:113], v[96:99], off offset:256 sc1
	s_nop 0
	v_or_b32_e32 v112, 48, v150
	v_mad_i64_i32 v[114:115], s[6:7], v160, s62, v[146:147]
	v_ashrrev_i32_e32 v113, 31, v112
	v_add_u32_e32 v187, 0x2000, v186
	global_load_dwordx4 v[204:207], v187, s[16:17]
	v_add_u32_e32 v187, 0x2010, v186
	global_load_dwordx4 v[208:211], v187, s[16:17]
	v_add_u32_e32 v187, 0x2020, v186
	global_load_dwordx4 v[212:215], v187, s[16:17]
	v_add_u32_e32 v187, 0x2030, v186
	global_load_dwordx4 v[216:219], v187, s[16:17]
	s_waitcnt vmcnt(12)
	v_pk_add_f32 v[96:97], v[220:221], v[222:223]
	v_pk_add_f32 v[100:101], v[232:233], v[234:235]
	v_pk_add_f32 v[102:103], v[236:237], v[238:239]
	v_pk_add_f32 v[104:105], v[240:241], v[242:243]
	v_pk_add_f32 v[96:97], v[96:97], v[100:101]
	v_pk_add_f32 v[102:103], v[102:103], v[104:105]
	v_pk_add_f32 v[96:97], v[96:97], v[102:103]
	v_add_f32_e32 v96, v96, v97
	s_nop 0
	s_nop 0
	v_fmamk_f32 v96, v96, 0x3a800000, v158
	s_nop 0
	s_nop 0
	s_nop 1
	s_nop 0
	v_rsq_f32_e32 v100, v96
	v_lshl_add_u64 v[96:97], v[114:115], 0, v[148:149]
	s_nop 0
	s_nop 0
	v_pk_mul_f32 v[94:95], v[94:95], v[100:101] op_sel_hi:[1,0]
	v_pk_mul_f32 v[92:93], v[92:93], v[100:101] op_sel_hi:[1,0]
	v_pk_mul_f32 v[90:91], v[90:91], v[100:101] op_sel_hi:[1,0]
	v_pk_mul_f32 v[88:89], v[88:89], v[100:101] op_sel_hi:[1,0]
	v_pk_mul_f32 v[86:87], v[86:87], v[100:101] op_sel_hi:[1,0]
	v_pk_mul_f32 v[84:85], v[84:85], v[100:101] op_sel_hi:[1,0]
	v_pk_mul_f32 v[102:103], v[82:83], v[100:101] op_sel_hi:[1,0]
	v_pk_mul_f32 v[100:101], v[80:81], v[100:101] op_sel_hi:[1,0]
	v_cvt_pk_bf16_f32 v80, v92, v93
	v_cvt_pk_bf16_f32 v81, v94, v95
	v_cvt_pk_bf16_f32 v82, v88, v89
	v_cvt_pk_bf16_f32 v83, v90, v91
	global_store_dwordx4 v[96:97], v[80:83], off sc1
	s_nop 1
	v_cvt_pk_bf16_f32 v80, v84, v85
	v_cvt_pk_bf16_f32 v81, v86, v87
	v_cvt_pk_bf16_f32 v82, v100, v101
	v_cvt_pk_bf16_f32 v83, v102, v103
	global_store_dwordx4 v[96:97], v[80:83], off offset:256 sc1
	s_nop 0
	v_add_u32_e32 v96, 0x80, v150
	v_mad_i64_i32 v[98:99], s[6:7], v112, s62, v[146:147]
	v_ashrrev_i32_e32 v97, 31, v96
	v_add_u32_e32 v187, 0x2400, v186
	global_load_dwordx4 v[220:223], v187, s[16:17]
	v_add_u32_e32 v187, 0x2410, v186
	global_load_dwordx4 v[232:235], v187, s[16:17]
	v_add_u32_e32 v187, 0x2420, v186
	global_load_dwordx4 v[236:239], v187, s[16:17]
	v_add_u32_e32 v187, 0x2430, v186
	global_load_dwordx4 v[240:243], v187, s[16:17]
	s_waitcnt vmcnt(12)
	v_pk_add_f32 v[80:81], v[188:189], v[190:191]
	v_pk_add_f32 v[84:85], v[192:193], v[194:195]
	v_pk_add_f32 v[86:87], v[196:197], v[198:199]
	v_pk_add_f32 v[88:89], v[200:201], v[202:203]
	v_pk_add_f32 v[80:81], v[80:81], v[84:85]
	v_pk_add_f32 v[86:87], v[86:87], v[88:89]
	v_pk_add_f32 v[80:81], v[80:81], v[86:87]
	v_add_f32_e32 v80, v80, v81
	s_nop 0
	s_nop 0
	v_fmamk_f32 v80, v80, 0x3a800000, v158
	s_nop 0
	s_nop 0
	s_nop 1
	s_nop 0
	v_rsq_f32_e32 v84, v80
	v_lshl_add_u64 v[80:81], v[98:99], 0, v[148:149]
	s_nop 0
	s_nop 0
	v_pk_mul_f32 v[78:79], v[78:79], v[84:85] op_sel_hi:[1,0]
	v_pk_mul_f32 v[76:77], v[76:77], v[84:85] op_sel_hi:[1,0]
	v_pk_mul_f32 v[74:75], v[74:75], v[84:85] op_sel_hi:[1,0]
	v_pk_mul_f32 v[72:73], v[72:73], v[84:85] op_sel_hi:[1,0]
	v_pk_mul_f32 v[70:71], v[70:71], v[84:85] op_sel_hi:[1,0]
	v_pk_mul_f32 v[68:69], v[68:69], v[84:85] op_sel_hi:[1,0]
	v_pk_mul_f32 v[86:87], v[66:67], v[84:85] op_sel_hi:[1,0]
	v_pk_mul_f32 v[84:85], v[64:65], v[84:85] op_sel_hi:[1,0]
	v_cvt_pk_bf16_f32 v64, v76, v77
	v_cvt_pk_bf16_f32 v65, v78, v79
	v_cvt_pk_bf16_f32 v66, v72, v73
	v_cvt_pk_bf16_f32 v67, v74, v75
	global_store_dwordx4 v[80:81], v[64:67], off sc1
	s_nop 1
	v_cvt_pk_bf16_f32 v64, v68, v69
	v_cvt_pk_bf16_f32 v65, v70, v71
	v_cvt_pk_bf16_f32 v66, v84, v85
	v_cvt_pk_bf16_f32 v67, v86, v87
	global_store_dwordx4 v[80:81], v[64:67], off offset:256 sc1
	s_nop 0
	v_add_u32_e32 v80, 0x90, v150
	v_mad_i64_i32 v[82:83], s[6:7], v96, s62, v[146:147]
	v_ashrrev_i32_e32 v81, 31, v80
	v_add_u32_e32 v187, 0x2800, v186
	global_load_dwordx4 v[188:191], v187, s[16:17]
	v_add_u32_e32 v187, 0x2810, v186
	global_load_dwordx4 v[192:195], v187, s[16:17]
	v_add_u32_e32 v187, 0x2820, v186
	global_load_dwordx4 v[196:199], v187, s[16:17]
	v_add_u32_e32 v187, 0x2830, v186
	global_load_dwordx4 v[200:203], v187, s[16:17]
	s_waitcnt vmcnt(12)
; __device__ __forceinline__ float bflo(unsigned w) { return __uint_as_float(w << 16); }
; __device__ __forceinline__ float bfhi(unsigned w) { return __uint_as_float(w & 0xffff0000u); }
; __device__ __forceinline__ unsigned pk2(float lo, float hi) { unsigned r; asm volatile("v_cvt_pk_bf16_f32 %0, %1, %2" : "=v"(r) : "v"(lo), "v"(hi)); return r; }
; __device__ __forceinline__ float row_rstd(const float* ssq, int row) {
;     const f32x4* p = (const f32x4*)(ssq + (size_t)row * 16);
;     const f32x4 a = p[0], b = p[1], c = p[2], d = p[3];
;     const float s = ((a[0] + a[1]) + (a[2] + a[3])) + ((b[0] + b[1]) + (b[2] + b[3])) + ((c[0] + c[1]) + (c[2] + c[3])) + ((d[0] + d[1]) + (d[2] + d[3]));
;     return rsqrtf(s * (1.0f / 1024.0f) + 1e-6f);
; }
; __device__ __forceinline__ u32x4 pack8(const f32x4 v0, const f32x4 v1) { u32x4 w; w.x = pk2(v0[0], v0[1]); w.y = pk2(v0[2], v0[3]); w.z = pk2(v1[0], v1[1]); w.w = pk2(v1[2], v1[3]); return w; }
; __device__ __forceinline__ void unpack8(const u32x4 w, f32x4& v0, f32x4& v1) { v0 = (f32x4){bflo(w.x), bfhi(w.x), bflo(w.y), bfhi(w.y)}; v1 = (f32x4){bflo(w.z), bfhi(w.z), bflo(w.w), bfhi(w.w)}; }
;     __device__ __forceinline__ void operator()(const f32x4 (&acc)[2][2][4][2], const Unit& u, int wr, int wc, int fr, int fq) const {
;         const int row0 = u.pm * 256 + wr * 64 + fr, col0 = u.pn * 256 + wc * 32 + 8 * fq;
; #pragma unroll
;         for (int ai = 0; ai < 2; ++ai)
; #pragma unroll
;             for (int m = 0; m < 4; ++m) {
;                 const int row = row0 + ai * 128 + m * 16; const float rs = row_rstd(ssq, row);
;                 bf16_t* rowp = O + (size_t)row * ldc + col0;
; #pragma unroll
;                 for (int bj = 0; bj < 2; ++bj) { f32x4 v0 = acc[ai][bj][m][0] * rs, v1 = acc[ai][bj][m][1] * rs;
;                     if (ACT == 1) {
; #pragma unroll
;                         for (int j = 0; j < 4; ++j) { const float a = fmaxf(v0[j], 0.f), b = fmaxf(v1[j], 0.f); v0[j] = a * a; v1[j] = b * b; } }
;                     *(u32x4*)(rowp + bj * 128) = pack8(v0, v1); }
	v_pk_add_f32 v[64:65], v[204:205], v[206:207]
	v_pk_add_f32 v[68:69], v[208:209], v[210:211]
	v_pk_add_f32 v[70:71], v[212:213], v[214:215]
	v_pk_add_f32 v[72:73], v[216:217], v[218:219]
	v_pk_add_f32 v[64:65], v[64:65], v[68:69]
	v_pk_add_f32 v[70:71], v[70:71], v[72:73]
	v_pk_add_f32 v[64:65], v[64:65], v[70:71]
	v_add_f32_e32 v64, v64, v65
	s_nop 0
	s_nop 0
	v_fmamk_f32 v64, v64, 0x3a800000, v158
	s_nop 0
	s_nop 0
	s_nop 1
	s_nop 0
	v_rsq_f32_e32 v68, v64
	v_lshl_add_u64 v[64:65], v[82:83], 0, v[148:149]
	s_nop 0
	s_nop 0
	v_pk_mul_f32 v[62:63], v[62:63], v[68:69] op_sel_hi:[1,0]
	v_pk_mul_f32 v[60:61], v[60:61], v[68:69] op_sel_hi:[1,0]
	v_pk_mul_f32 v[58:59], v[58:59], v[68:69] op_sel_hi:[1,0]
	v_pk_mul_f32 v[56:57], v[56:57], v[68:69] op_sel_hi:[1,0]
	v_pk_mul_f32 v[54:55], v[54:55], v[68:69] op_sel_hi:[1,0]
	v_pk_mul_f32 v[52:53], v[52:53], v[68:69] op_sel_hi:[1,0]
	v_pk_mul_f32 v[70:71], v[50:51], v[68:69] op_sel_hi:[1,0]
	v_pk_mul_f32 v[68:69], v[48:49], v[68:69] op_sel_hi:[1,0]
	v_cvt_pk_bf16_f32 v48, v60, v61
	v_cvt_pk_bf16_f32 v49, v62, v63
	v_cvt_pk_bf16_f32 v50, v56, v57
	v_cvt_pk_bf16_f32 v51, v58, v59
	global_store_dwordx4 v[64:65], v[48:51], off sc1
	s_nop 1
	v_cvt_pk_bf16_f32 v48, v52, v53
	v_cvt_pk_bf16_f32 v49, v54, v55
	v_cvt_pk_bf16_f32 v50, v68, v69
	v_cvt_pk_bf16_f32 v51, v70, v71
	global_store_dwordx4 v[64:65], v[48:51], off offset:256 sc1
	s_nop 0
	v_add_u32_e32 v64, 0xa0, v150
	v_mad_i64_i32 v[66:67], s[6:7], v80, s62, v[146:147]
	v_ashrrev_i32_e32 v65, 31, v64
	v_add_u32_e32 v187, 0x2c00, v186
	global_load_dwordx4 v[204:207], v187, s[16:17]
	v_add_u32_e32 v187, 0x2c10, v186
	global_load_dwordx4 v[208:211], v187, s[16:17]
	v_add_u32_e32 v187, 0x2c20, v186
	global_load_dwordx4 v[212:215], v187, s[16:17]
	v_add_u32_e32 v187, 0x2c30, v186
	global_load_dwordx4 v[216:219], v187, s[16:17]
	s_waitcnt vmcnt(12)
	v_pk_add_f32 v[48:49], v[220:221], v[222:223]
	v_pk_add_f32 v[52:53], v[232:233], v[234:235]
	v_pk_add_f32 v[54:55], v[236:237], v[238:239]
	v_pk_add_f32 v[56:57], v[240:241], v[242:243]
	v_pk_add_f32 v[48:49], v[48:49], v[52:53]
	v_pk_add_f32 v[54:55], v[54:55], v[56:57]
	v_pk_add_f32 v[48:49], v[48:49], v[54:55]
	v_add_f32_e32 v48, v48, v49
	s_nop 0
	s_nop 0
	v_fmamk_f32 v48, v48, 0x3a800000, v158
	s_nop 0
	s_nop 0
	s_nop 1
	s_nop 0
	v_rsq_f32_e32 v52, v48
	v_lshl_add_u64 v[48:49], v[66:67], 0, v[148:149]
	s_nop 0
	s_nop 0
	v_pk_mul_f32 v[46:47], v[46:47], v[52:53] op_sel_hi:[1,0]
	v_pk_mul_f32 v[44:45], v[44:45], v[52:53] op_sel_hi:[1,0]
	v_pk_mul_f32 v[42:43], v[42:43], v[52:53] op_sel_hi:[1,0]
	v_pk_mul_f32 v[40:41], v[40:41], v[52:53] op_sel_hi:[1,0]
	v_pk_mul_f32 v[38:39], v[38:39], v[52:53] op_sel_hi:[1,0]
	v_pk_mul_f32 v[36:37], v[36:37], v[52:53] op_sel_hi:[1,0]
	v_pk_mul_f32 v[54:55], v[34:35], v[52:53] op_sel_hi:[1,0]
	v_pk_mul_f32 v[52:53], v[32:33], v[52:53] op_sel_hi:[1,0]
	v_cvt_pk_bf16_f32 v32, v44, v45
	v_cvt_pk_bf16_f32 v33, v46, v47
	v_cvt_pk_bf16_f32 v34, v40, v41
	v_cvt_pk_bf16_f32 v35, v42, v43
	global_store_dwordx4 v[48:49], v[32:35], off sc1
	s_nop 1
	v_cvt_pk_bf16_f32 v32, v36, v37
	v_cvt_pk_bf16_f32 v33, v38, v39
	v_cvt_pk_bf16_f32 v34, v52, v53
	v_cvt_pk_bf16_f32 v35, v54, v55
	global_store_dwordx4 v[48:49], v[32:35], off offset:256 sc1
	s_nop 0
	v_add_u32_e32 v48, 0xb0, v150
	v_mad_i64_i32 v[50:51], s[6:7], v64, s62, v[146:147]
	v_ashrrev_i32_e32 v49, 31, v48
	s_mov_b32 s6, s20
	s_waitcnt vmcnt(8)
	v_pk_add_f32 v[32:33], v[188:189], v[190:191]
	v_pk_add_f32 v[36:37], v[192:193], v[194:195]
	v_pk_add_f32 v[38:39], v[196:197], v[198:199]
	v_pk_add_f32 v[40:41], v[200:201], v[202:203]
	v_pk_add_f32 v[32:33], v[32:33], v[36:37]
	v_pk_add_f32 v[38:39], v[38:39], v[40:41]
	v_pk_add_f32 v[32:33], v[32:33], v[38:39]
	v_add_f32_e32 v32, v32, v33
	v_lshlrev_b64 v[34:35], 6, v[48:49]
	v_lshl_add_u64 v[34:35], s[16:17], 0, v[34:35]
	v_fmamk_f32 v32, v32, 0x3a800000, v158
	s_nop 0
	s_nop 0
	s_nop 1
	s_nop 0
	v_rsq_f32_e32 v36, v32
	v_lshl_add_u64 v[32:33], v[50:51], 0, v[148:149]
	s_nop 0
	s_nop 0
	v_pk_mul_f32 v[30:31], v[30:31], v[36:37] op_sel_hi:[1,0]
	v_pk_mul_f32 v[28:29], v[28:29], v[36:37] op_sel_hi:[1,0]
	v_pk_mul_f32 v[26:27], v[26:27], v[36:37] op_sel_hi:[1,0]
	v_pk_mul_f32 v[24:25], v[24:25], v[36:37] op_sel_hi:[1,0]
	v_pk_mul_f32 v[22:23], v[22:23], v[36:37] op_sel_hi:[1,0]
	v_pk_mul_f32 v[20:21], v[20:21], v[36:37] op_sel_hi:[1,0]
	v_pk_mul_f32 v[38:39], v[18:19], v[36:37] op_sel_hi:[1,0]
	v_pk_mul_f32 v[36:37], v[16:17], v[36:37] op_sel_hi:[1,0]
	v_cvt_pk_bf16_f32 v16, v28, v29
	v_cvt_pk_bf16_f32 v17, v30, v31
	v_cvt_pk_bf16_f32 v18, v24, v25
	v_cvt_pk_bf16_f32 v19, v26, v27
	global_store_dwordx4 v[32:33], v[16:19], off sc1
	s_and_b64 vcc, exec, s[8:9]
	s_nop 0
	v_cvt_pk_bf16_f32 v16, v20, v21
	v_cvt_pk_bf16_f32 v17, v22, v23
	v_cvt_pk_bf16_f32 v18, v36, v37
	v_cvt_pk_bf16_f32 v19, v38, v39
	global_store_dwordx4 v[32:33], v[16:19], off offset:256 sc1
	s_nop 0
	s_waitcnt vmcnt(4)
	v_pk_add_f32 v[16:17], v[204:205], v[206:207]
	v_pk_add_f32 v[18:19], v[208:209], v[210:211]
	v_pk_add_f32 v[20:21], v[212:213], v[214:215]
	v_pk_add_f32 v[22:23], v[216:217], v[218:219]
	v_pk_add_f32 v[16:17], v[16:17], v[18:19]
	v_pk_add_f32 v[20:21], v[20:21], v[22:23]
	v_pk_add_f32 v[16:17], v[16:17], v[20:21]
	v_add_f32_e32 v16, v16, v17
	s_nop 0
	s_nop 0
	v_fmamk_f32 v16, v16, 0x3a800000, v158
	v_mul_f32_e32 v17, 0x4b800000, v16
	v_cmp_gt_f32_e64 s[8:9], s61, v16
	s_nop 1
	v_cndmask_b32_e64 v16, v16, v17, s[8:9]
	v_rsq_f32_e32 v18, v16
	v_mad_i64_i32 v[16:17], s[24:25], v48, s62, v[146:147]
	v_lshl_add_u64 v[16:17], v[16:17], 0, v[148:149]
	v_mul_f32_e32 v19, 0x45800000, v18
	v_cndmask_b32_e64 v18, v18, v19, s[8:9]
	v_pk_mul_f32 v[14:15], v[14:15], v[18:19] op_sel_hi:[1,0]
	v_pk_mul_f32 v[12:13], v[12:13], v[18:19] op_sel_hi:[1,0]
	v_pk_mul_f32 v[10:11], v[10:11], v[18:19] op_sel_hi:[1,0]
	v_pk_mul_f32 v[8:9], v[8:9], v[18:19] op_sel_hi:[1,0]
	v_pk_mul_f32 v[6:7], v[6:7], v[18:19] op_sel_hi:[1,0]
	v_pk_mul_f32 v[4:5], v[4:5], v[18:19] op_sel_hi:[1,0]
	v_pk_mul_f32 v[20:21], v[2:3], v[18:19] op_sel_hi:[1,0]
	v_pk_mul_f32 v[18:19], v[0:1], v[18:19] op_sel_hi:[1,0]
	v_cvt_pk_bf16_f32 v0, v12, v13
	v_cvt_pk_bf16_f32 v1, v14, v15
	v_cvt_pk_bf16_f32 v2, v8, v9
	v_cvt_pk_bf16_f32 v3, v10, v11
	global_store_dwordx4 v[16:17], v[0:3], off sc1
	s_nop 1
	v_cvt_pk_bf16_f32 v0, v4, v5
	v_cvt_pk_bf16_f32 v1, v6, v7
	v_cvt_pk_bf16_f32 v2, v18, v19
	v_cvt_pk_bf16_f32 v3, v20, v21
	global_store_dwordx4 v[16:17], v[0:3], off offset:256 sc1
	s_cbranch_vccz .LBB0_118
	s_waitcnt vmcnt(0)
	s_cmpk_gt_u32 s40, 0xff
	s_cbranch_scc1 .LBB0_129
	s_barrier

; #define PG8_STAGE(bufoff, gbase, voff) do { _Pragma("unroll") for (int _i = 0; _i < 2; ++_i) \
;         __builtin_amdgcn_global_load_lds((const unsigned*)((const char*)(gbase) + (voff)[_i]), (LAS unsigned*)(lds + (bufoff) + ldsw + _i * 8192), 16, 0, 0); } while (0)
; #define PG8_LDA(dst, b, h) do { _Pragma("unroll") for (int m = 0; m < 4; ++m) _Pragma("unroll") for (int k = 0; k < 2; ++k) dst[m][k] = *(const LAS bf16x8*)(lds + PG8_SA(b, h) + aoff + m * 2048 + k * 1024); } while (0)
; #define PG8_LDB(dst, b, h) do { _Pragma("unroll") for (int n = 0; n < 2; ++n) _Pragma("unroll") for (int k = 0; k < 2; ++k) dst[n][k] = *(const LAS bf16x8*)(lds + PG8_SB(b, h) + boff + n * 2048 + k * 1024); } while (0)
; #define PG8_MMA(ai, bj, At, Bt) do { __builtin_amdgcn_s_setprio(1); _Pragma("unroll") for (int m = 0; m < 4; ++m) _Pragma("unroll") for (int n = 0; n < 2; ++n) _Pragma("unroll") for (int k = 0; k < 2; ++k) \
;         acc[ai][bj][m][n] = __builtin_amdgcn_mfma_f32_16x16x32_bf16(Bt[n][k], At[m][k], acc[ai][bj][m][n], 0, 0, 0); __builtin_amdgcn_s_setprio(0); } while (0)
; #define PG8_WAIT_L(n) asm volatile("s_waitcnt lgkmcnt(" #n ")" ::: "memory")
; #define PG8_BAR __builtin_amdgcn_s_barrier()
; #define PG8_SCHED __builtin_amdgcn_sched_barrier(0)
;     ...
;             PG8_LDB(B0, 0, 0); PG8_SCHED; PG8_LDA(At, 0, 0); PG8_STAGE(PG8_SA(1, 1), a1 + hA, voffA);
;             PG8_WAIT_L(8); PG8_BAR; PG8_WAIT_L(0); PG8_MMA(0, 0, At, B0); PG8_BAR; PG8_SCHED;
;             PG8_LDB(B1, 0, 1); PG8_STAGE(PG8_SB(0, 0), b2, voffB);
;             PG8_BAR; PG8_WAIT_L(0); PG8_MMA(0, 1, At, B1); PG8_BAR;
;             PG8_LDA(At, 0, 1); PG8_STAGE(PG8_SA(0, 0), a2, voffA);
;             PG8_BAR; PG8_WAIT_L(0); PG8_MMA(1, 0, At, B0); PG8_BAR; PG8_SCHED;
.LBB0_958:
	ds_read_b128 v[156:159], v151
	ds_read_b128 v[160:163], v151 offset:1024
	ds_read_b128 v[170:173], v151 offset:2048
	ds_read_b128 v[174:177], v151 offset:3072
	s_add_u32 s43, s40, 0xfffc0080
	s_addc_u32 s44, s41, -1
	s_cmp_eq_u32 s42, 12
	s_cselect_b32 s57, s7, s44
	s_cselect_b32 s56, s8, s43
	s_cselect_b32 s55, s9, s39
	s_cselect_b32 s54, s29, s33
	v_lshl_add_u64 v[146:147], s[40:41], 0, v[138:139]
	s_add_i32 m0, s61, 0xc000
	ds_read_b128 v[178:181], v152
	ds_read_b128 v[182:185], v152 offset:1024
	ds_read_b128 v[186:189], v152 offset:2048
	ds_read_b128 v[190:193], v152 offset:3072
	ds_read_b128 v[194:197], v152 offset:4096
	ds_read_b128 v[198:201], v152 offset:5120
	ds_read_b128 v[202:205], v152 offset:6144
	ds_read_b128 v[206:209], v152 offset:7168
	global_load_lds_dwordx4 v[146:147], off
	v_lshl_add_u64 v[146:147], s[40:41], 0, v[136:137]
	s_add_i32 m0, s61, 0xe000
	s_nop 0
	global_load_lds_dwordx4 v[146:147], off
	s_waitcnt lgkmcnt(8)
	s_barrier
	s_waitcnt lgkmcnt(0)
	s_setprio 1
	s_waitcnt lgkmcnt(0)
	v_mfma_f32_16x16x32_bf16 v[124:127], v[156:159], v[178:181], v[124:127]
	v_mfma_f32_16x16x32_bf16 v[120:123], v[170:173], v[178:181], v[120:123]
	v_mfma_f32_16x16x32_bf16 v[108:111], v[156:159], v[186:189], v[108:111]
	v_mfma_f32_16x16x32_bf16 v[104:107], v[170:173], v[186:189], v[104:107]
	v_mfma_f32_16x16x32_bf16 v[92:95], v[156:159], v[194:197], v[92:95]
	v_mfma_f32_16x16x32_bf16 v[88:91], v[170:173], v[194:197], v[88:91]
	v_mfma_f32_16x16x32_bf16 v[76:79], v[156:159], v[202:205], v[76:79]
	v_mfma_f32_16x16x32_bf16 v[72:75], v[170:173], v[202:205], v[72:75]
	v_mfma_f32_16x16x32_bf16 v[124:127], v[160:163], v[182:185], v[124:127]
	v_mfma_f32_16x16x32_bf16 v[120:123], v[174:177], v[182:185], v[120:123]
	v_mfma_f32_16x16x32_bf16 v[108:111], v[160:163], v[190:193], v[108:111]
	v_mfma_f32_16x16x32_bf16 v[104:107], v[174:177], v[190:193], v[104:107]
	v_mfma_f32_16x16x32_bf16 v[92:95], v[160:163], v[198:201], v[92:95]
	v_mfma_f32_16x16x32_bf16 v[88:91], v[174:177], v[198:201], v[88:91]
	v_mfma_f32_16x16x32_bf16 v[76:79], v[160:163], v[206:209], v[76:79]
	v_mfma_f32_16x16x32_bf16 v[72:75], v[174:177], v[206:209], v[72:75]
	s_setprio 0
	s_barrier
	s_add_i32 s43, s69, s60
	v_lshl_add_u64 v[146:147], s[54:55], 0, v[130:131]
	s_mov_b32 m0, s43
	ds_read_b128 v[210:213], v153
	ds_read_b128 v[214:217], v153 offset:1024
	ds_read_b128 v[218:221], v153 offset:2048
	ds_read_b128 v[222:225], v153 offset:3072
	global_load_lds_dwordx4 v[146:147], off
	v_lshl_add_u64 v[164:165], s[54:55], 0, v[134:135]
	s_add_i32 m0, s43, 0x2000
	s_nop 0
	global_load_lds_dwordx4 v[164:165], off
	s_barrier
	s_waitcnt lgkmcnt(0)
	s_setprio 1
	s_waitcnt lgkmcnt(0)
	v_mfma_f32_16x16x32_bf16 v[116:119], v[210:213], v[178:181], v[116:119]
	v_mfma_f32_16x16x32_bf16 v[112:115], v[218:221], v[178:181], v[112:115]
	v_mfma_f32_16x16x32_bf16 v[100:103], v[210:213], v[186:189], v[100:103]
	v_mfma_f32_16x16x32_bf16 v[96:99], v[218:221], v[186:189], v[96:99]
	v_mfma_f32_16x16x32_bf16 v[84:87], v[210:213], v[194:197], v[84:87]
	v_mfma_f32_16x16x32_bf16 v[80:83], v[218:221], v[194:197], v[80:83]
	v_mfma_f32_16x16x32_bf16 v[68:71], v[210:213], v[202:205], v[68:71]
	v_mfma_f32_16x16x32_bf16 v[64:67], v[218:221], v[202:205], v[64:67]
	v_mfma_f32_16x16x32_bf16 v[116:119], v[214:217], v[182:185], v[116:119]
	v_mfma_f32_16x16x32_bf16 v[112:115], v[222:225], v[182:185], v[112:115]
	v_mfma_f32_16x16x32_bf16 v[100:103], v[214:217], v[190:193], v[100:103]
	v_mfma_f32_16x16x32_bf16 v[96:99], v[222:225], v[190:193], v[96:99]
	v_mfma_f32_16x16x32_bf16 v[84:87], v[214:217], v[198:201], v[84:87]
	v_mfma_f32_16x16x32_bf16 v[80:83], v[222:225], v[198:201], v[80:83]
	v_mfma_f32_16x16x32_bf16 v[68:71], v[214:217], v[206:209], v[68:71]
	v_mfma_f32_16x16x32_bf16 v[64:67], v[222:225], v[206:209], v[64:67]
	s_setprio 0
	s_mov_b32 m0, s61
	v_lshl_add_u64 v[226:227], s[56:57], 0, v[128:129]
	s_barrier
	ds_read_b128 v[178:181], v152 offset:16384
	ds_read_b128 v[182:185], v152 offset:17408
	ds_read_b128 v[186:189], v152 offset:18432
	ds_read_b128 v[190:193], v152 offset:19456
	ds_read_b128 v[194:197], v152 offset:20480
	ds_read_b128 v[198:201], v152 offset:21504
	ds_read_b128 v[202:205], v152 offset:22528
	ds_read_b128 v[206:209], v152 offset:23552
	global_load_lds_dwordx4 v[226:227], off
	v_lshl_add_u64 v[228:229], s[56:57], 0, v[132:133]
	s_mov_b32 m0, s62
	s_nop 0
	global_load_lds_dwordx4 v[228:229], off
	s_barrier
	s_waitcnt lgkmcnt(0)
	s_setprio 1
	s_waitcnt lgkmcnt(0)
	v_mfma_f32_16x16x32_bf16 v[60:63], v[156:159], v[178:181], v[60:63]
	v_mfma_f32_16x16x32_bf16 v[56:59], v[170:173], v[178:181], v[56:59]
	v_mfma_f32_16x16x32_bf16 v[44:47], v[156:159], v[186:189], v[44:47]
	v_mfma_f32_16x16x32_bf16 v[40:43], v[170:173], v[186:189], v[40:43]
	v_mfma_f32_16x16x32_bf16 v[28:31], v[156:159], v[194:197], v[28:31]
	v_mfma_f32_16x16x32_bf16 v[24:27], v[170:173], v[194:197], v[24:27]
	v_mfma_f32_16x16x32_bf16 v[12:15], v[156:159], v[202:205], v[12:15]
	v_mfma_f32_16x16x32_bf16 v[8:11], v[170:173], v[202:205], v[8:11]
	v_mfma_f32_16x16x32_bf16 v[60:63], v[160:163], v[182:185], v[60:63]
	v_mfma_f32_16x16x32_bf16 v[56:59], v[174:177], v[182:185], v[56:59]
	v_mfma_f32_16x16x32_bf16 v[44:47], v[160:163], v[190:193], v[44:47]
	v_mfma_f32_16x16x32_bf16 v[40:43], v[174:177], v[190:193], v[40:43]
	v_mfma_f32_16x16x32_bf16 v[28:31], v[160:163], v[198:201], v[28:31]
	v_mfma_f32_16x16x32_bf16 v[24:27], v[174:177], v[198:201], v[24:27]
	v_mfma_f32_16x16x32_bf16 v[12:15], v[160:163], v[206:209], v[12:15]
	v_mfma_f32_16x16x32_bf16 v[8:11], v[174:177], v[206:209], v[8:11]
	s_setprio 0
	s_barrier
; #define PG8_STAGE(bufoff, gbase, voff) do { _Pragma("unroll") for (int _i = 0; _i < 2; ++_i) \
;         __builtin_amdgcn_global_load_lds((const unsigned*)((const char*)(gbase) + (voff)[_i]), (LAS unsigned*)(lds + (bufoff) + ldsw + _i * 8192), 16, 0, 0); } while (0)
; #define PG8_LDA(dst, b, h) do { _Pragma("unroll") for (int m = 0; m < 4; ++m) _Pragma("unroll") for (int k = 0; k < 2; ++k) dst[m][k] = *(const LAS bf16x8*)(lds + PG8_SA(b, h) + aoff + m * 2048 + k * 1024); } while (0)
; #define PG8_LDB(dst, b, h) do { _Pragma("unroll") for (int n = 0; n < 2; ++n) _Pragma("unroll") for (int k = 0; k < 2; ++k) dst[n][k] = *(const LAS bf16x8*)(lds + PG8_SB(b, h) + boff + n * 2048 + k * 1024); } while (0)
; #define PG8_MMA(ai, bj, At, Bt) do { __builtin_amdgcn_s_setprio(1); _Pragma("unroll") for (int m = 0; m < 4; ++m) _Pragma("unroll") for (int n = 0; n < 2; ++n) _Pragma("unroll") for (int k = 0; k < 2; ++k) \
;         acc[ai][bj][m][n] = __builtin_amdgcn_mfma_f32_16x16x32_bf16(Bt[n][k], At[m][k], acc[ai][bj][m][n], 0, 0, 0); __builtin_amdgcn_s_setprio(0); } while (0)
; #define PG8_WAIT_V(n) asm volatile("s_waitcnt vmcnt(" #n ")" ::: "memory")
; #define PG8_WAIT_L(n) asm volatile("s_waitcnt lgkmcnt(" #n ")" ::: "memory")
; #define PG8_BAR __builtin_amdgcn_s_barrier()
; #define PG8_SCHED __builtin_amdgcn_sched_barrier(0)
;     ...
;             PG8_STAGE(PG8_SB(0, 1), b2 + hB, voffB);
;             PG8_WAIT_V(6); PG8_BAR; PG8_MMA(1, 1, At, B1); PG8_BAR;
;             PG8_LDB(B0, 1, 0); PG8_SCHED; PG8_LDA(At, 1, 0); PG8_STAGE(PG8_SA(0, 1), a2 + hA, voffA);
;             PG8_WAIT_L(8); PG8_BAR; PG8_WAIT_L(0); PG8_MMA(0, 0, At, B0); PG8_BAR; PG8_SCHED;
;             PG8_LDB(B1, 1, 1); PG8_STAGE(PG8_SB(1, 0), b3, voffB);
;             PG8_BAR; PG8_WAIT_L(0); PG8_MMA(0, 1, At, B1); PG8_BAR;
;             PG8_LDA(At, 1, 1); PG8_STAGE(PG8_SA(1, 0), a3, voffA);
	s_add_u32 s44, s54, 0x40000
	s_addc_u32 s45, s55, 0
	s_add_i32 s43, s70, s60
	v_lshl_add_u64 v[156:157], s[44:45], 0, v[130:131]
	s_mov_b32 m0, s43
	s_nop 0
	global_load_lds_dwordx4 v[156:157], off
	v_lshl_add_u64 v[156:157], s[44:45], 0, v[134:135]
	s_add_i32 m0, s43, 0x2000
	s_nop 0
	global_load_lds_dwordx4 v[156:157], off
	s_waitcnt vmcnt(6)
	s_barrier
	s_setprio 1
	v_mfma_f32_16x16x32_bf16 v[52:55], v[210:213], v[178:181], v[52:55]
	v_mfma_f32_16x16x32_bf16 v[48:51], v[218:221], v[178:181], v[48:51]
	v_mfma_f32_16x16x32_bf16 v[36:39], v[210:213], v[186:189], v[36:39]
	v_mfma_f32_16x16x32_bf16 v[32:35], v[218:221], v[186:189], v[32:35]
	v_mfma_f32_16x16x32_bf16 v[20:23], v[210:213], v[194:197], v[20:23]
	v_mfma_f32_16x16x32_bf16 v[16:19], v[218:221], v[194:197], v[16:19]
	v_mfma_f32_16x16x32_bf16 v[4:7], v[210:213], v[202:205], v[4:7]
	v_mfma_f32_16x16x32_bf16 v[0:3], v[218:221], v[202:205], v[0:3]
	v_mfma_f32_16x16x32_bf16 v[52:55], v[214:217], v[182:185], v[52:55]
	v_mfma_f32_16x16x32_bf16 v[48:51], v[222:225], v[182:185], v[48:51]
	v_mfma_f32_16x16x32_bf16 v[36:39], v[214:217], v[190:193], v[36:39]
	v_mfma_f32_16x16x32_bf16 v[32:35], v[222:225], v[190:193], v[32:35]
	v_mfma_f32_16x16x32_bf16 v[20:23], v[214:217], v[198:201], v[20:23]
	v_mfma_f32_16x16x32_bf16 v[16:19], v[222:225], v[198:201], v[16:19]
	v_mfma_f32_16x16x32_bf16 v[4:7], v[214:217], v[206:209], v[4:7]
	v_mfma_f32_16x16x32_bf16 v[0:3], v[222:225], v[206:209], v[0:3]
	s_setprio 0
	s_add_i32 s43, 0, 0x18000
	v_add_u32_e32 v155, s43, v149
	s_barrier
	ds_read_b128 v[156:159], v155
	ds_read_b128 v[160:163], v155 offset:1024
	ds_read_b128 v[170:173], v155 offset:2048
	ds_read_b128 v[174:177], v155 offset:3072
	s_add_u32 s44, s56, 0x40000
	s_addc_u32 s45, s57, 0
	s_mov_b32 m0, s63
	v_lshl_add_u64 v[210:211], s[44:45], 0, v[128:129]
	ds_read_b128 v[178:181], v152 offset:32768
	ds_read_b128 v[182:185], v152 offset:33792
	ds_read_b128 v[186:189], v152 offset:34816
	ds_read_b128 v[190:193], v152 offset:35840
	ds_read_b128 v[194:197], v152 offset:36864
	ds_read_b128 v[198:201], v152 offset:37888
	ds_read_b128 v[202:205], v152 offset:38912
	ds_read_b128 v[206:209], v152 offset:39936
	global_load_lds_dwordx4 v[210:211], off
	v_lshl_add_u64 v[210:211], s[44:45], 0, v[132:133]
	s_mov_b32 m0, s64
	s_nop 0
	global_load_lds_dwordx4 v[210:211], off
	s_waitcnt lgkmcnt(8)
	s_barrier
	s_waitcnt lgkmcnt(0)
	s_setprio 1
	s_waitcnt lgkmcnt(0)
	v_mfma_f32_16x16x32_bf16 v[124:127], v[156:159], v[178:181], v[124:127]
	v_mfma_f32_16x16x32_bf16 v[120:123], v[170:173], v[178:181], v[120:123]
	v_mfma_f32_16x16x32_bf16 v[108:111], v[156:159], v[186:189], v[108:111]
	v_mfma_f32_16x16x32_bf16 v[104:107], v[170:173], v[186:189], v[104:107]
	v_mfma_f32_16x16x32_bf16 v[92:95], v[156:159], v[194:197], v[92:95]
	v_mfma_f32_16x16x32_bf16 v[88:91], v[170:173], v[194:197], v[88:91]
	v_mfma_f32_16x16x32_bf16 v[76:79], v[156:159], v[202:205], v[76:79]
	v_mfma_f32_16x16x32_bf16 v[72:75], v[170:173], v[202:205], v[72:75]
	v_mfma_f32_16x16x32_bf16 v[124:127], v[160:163], v[182:185], v[124:127]
	v_mfma_f32_16x16x32_bf16 v[120:123], v[174:177], v[182:185], v[120:123]
	v_mfma_f32_16x16x32_bf16 v[108:111], v[160:163], v[190:193], v[108:111]
	v_mfma_f32_16x16x32_bf16 v[104:107], v[174:177], v[190:193], v[104:107]
	v_mfma_f32_16x16x32_bf16 v[92:95], v[160:163], v[198:201], v[92:95]
	v_mfma_f32_16x16x32_bf16 v[88:91], v[174:177], v[198:201], v[88:91]
	v_mfma_f32_16x16x32_bf16 v[76:79], v[160:163], v[206:209], v[76:79]
	v_mfma_f32_16x16x32_bf16 v[72:75], v[174:177], v[206:209], v[72:75]
	s_setprio 0
	s_barrier
	s_add_i32 s56, 0, 0x1c000
	s_add_i32 s43, s43, s60
	v_add_u32_e32 v155, s56, v149
	v_lshl_add_u64 v[146:147], v[146:147], 0, s[30:31]
	s_mov_b32 m0, s43
	ds_read_b128 v[210:213], v155
	ds_read_b128 v[214:217], v155 offset:1024
	ds_read_b128 v[218:221], v155 offset:2048
	ds_read_b128 v[222:225], v155 offset:3072
	global_load_lds_dwordx4 v[146:147], off
	v_lshl_add_u64 v[146:147], v[164:165], 0, s[30:31]
	s_add_i32 m0, s43, 0x2000
	s_nop 0
	global_load_lds_dwordx4 v[146:147], off
	s_barrier
	s_waitcnt lgkmcnt(0)
	s_setprio 1
	s_waitcnt lgkmcnt(0)
	v_mfma_f32_16x16x32_bf16 v[116:119], v[210:213], v[178:181], v[116:119]
	v_mfma_f32_16x16x32_bf16 v[112:115], v[218:221], v[178:181], v[112:115]
	v_mfma_f32_16x16x32_bf16 v[100:103], v[210:213], v[186:189], v[100:103]
	v_mfma_f32_16x16x32_bf16 v[96:99], v[218:221], v[186:189], v[96:99]
	v_mfma_f32_16x16x32_bf16 v[84:87], v[210:213], v[194:197], v[84:87]
	v_mfma_f32_16x16x32_bf16 v[80:83], v[218:221], v[194:197], v[80:83]
	v_mfma_f32_16x16x32_bf16 v[68:71], v[210:213], v[202:205], v[68:71]
	v_mfma_f32_16x16x32_bf16 v[64:67], v[218:221], v[202:205], v[64:67]
	v_mfma_f32_16x16x32_bf16 v[116:119], v[214:217], v[182:185], v[116:119]
	v_mfma_f32_16x16x32_bf16 v[112:115], v[222:225], v[182:185], v[112:115]
	v_mfma_f32_16x16x32_bf16 v[100:103], v[214:217], v[190:193], v[100:103]
	v_mfma_f32_16x16x32_bf16 v[96:99], v[222:225], v[190:193], v[96:99]
	v_mfma_f32_16x16x32_bf16 v[84:87], v[214:217], v[198:201], v[84:87]
	v_mfma_f32_16x16x32_bf16 v[80:83], v[222:225], v[198:201], v[80:83]
	v_mfma_f32_16x16x32_bf16 v[68:71], v[214:217], v[206:209], v[68:71]
	v_mfma_f32_16x16x32_bf16 v[64:67], v[222:225], v[206:209], v[64:67]
	s_setprio 0
	s_mov_b32 m0, s66
	v_lshl_add_u64 v[146:147], v[226:227], 0, s[30:31]
	s_barrier
	ds_read_b128 v[178:181], v152 offset:49152
	ds_read_b128 v[182:185], v152 offset:50176
	ds_read_b128 v[186:189], v152 offset:51200
	ds_read_b128 v[190:193], v152 offset:52224
	ds_read_b128 v[194:197], v152 offset:53248
	ds_read_b128 v[198:201], v152 offset:54272
	ds_read_b128 v[202:205], v152 offset:55296
	ds_read_b128 v[206:209], v152 offset:56320
	global_load_lds_dwordx4 v[146:147], off
	v_lshl_add_u64 v[146:147], v[228:229], 0, s[30:31]
	s_mov_b32 m0, s67
	s_nop 0
	global_load_lds_dwordx4 v[146:147], off
	s_barrier
; #define PG8_STAGE(bufoff, gbase, voff) do { _Pragma("unroll") for (int _i = 0; _i < 2; ++_i) \
;         __builtin_amdgcn_global_load_lds((const unsigned*)((const char*)(gbase) + (voff)[_i]), (LAS unsigned*)(lds + (bufoff) + ldsw + _i * 8192), 16, 0, 0); } while (0)
; #define PG8_MMA(ai, bj, At, Bt) do { __builtin_amdgcn_s_setprio(1); _Pragma("unroll") for (int m = 0; m < 4; ++m) _Pragma("unroll") for (int n = 0; n < 2; ++n) _Pragma("unroll") for (int k = 0; k < 2; ++k) \
;         acc[ai][bj][m][n] = __builtin_amdgcn_mfma_f32_16x16x32_bf16(Bt[n][k], At[m][k], acc[ai][bj][m][n], 0, 0, 0); __builtin_amdgcn_s_setprio(0); } while (0)
; #define PG8_WAIT_V(n) asm volatile("s_waitcnt vmcnt(" #n ")" ::: "memory")
; #define PG8_WAIT_L(n) asm volatile("s_waitcnt lgkmcnt(" #n ")" ::: "memory")
; #define PG8_BAR __builtin_amdgcn_s_barrier()
; #define PG8_SCHED __builtin_amdgcn_sched_barrier(0)
;     ...
;             PG8_BAR; PG8_WAIT_L(0); PG8_MMA(1, 0, At, B0); PG8_BAR; PG8_SCHED;
;             PG8_STAGE(PG8_SB(1, 1), b3 + hB, voffB);
;             PG8_WAIT_V(6); PG8_BAR; PG8_MMA(1, 1, At, B1); PG8_BAR;
;         }
; __device__ __forceinline__ float row_rstd(const float* ssq, int row) {
;     const f32x4* p = (const f32x4*)(ssq + (size_t)row * 16);
;     const f32x4 a = p[0], b = p[1], c = p[2], d = p[3];
;     const float s = ((a[0] + a[1]) + (a[2] + a[3])) + ((b[0] + b[1]) + (b[2] + b[3])) + ((c[0] + c[1]) + (c[2] + c[3])) + ((d[0] + d[1]) + (d[2] + d[3]));
;     return rsqrtf(s * (1.0f / 1024.0f) + 1e-6f);
; }
	s_waitcnt lgkmcnt(0)
	s_setprio 1
	s_waitcnt lgkmcnt(0)
	v_mfma_f32_16x16x32_bf16 v[60:63], v[156:159], v[178:181], v[60:63]
	v_mfma_f32_16x16x32_bf16 v[56:59], v[170:173], v[178:181], v[56:59]
	v_mfma_f32_16x16x32_bf16 v[44:47], v[156:159], v[186:189], v[44:47]
	v_mfma_f32_16x16x32_bf16 v[40:43], v[170:173], v[186:189], v[40:43]
	v_mfma_f32_16x16x32_bf16 v[28:31], v[156:159], v[194:197], v[28:31]
	v_mfma_f32_16x16x32_bf16 v[24:27], v[170:173], v[194:197], v[24:27]
	v_mfma_f32_16x16x32_bf16 v[12:15], v[156:159], v[202:205], v[12:15]
	v_mfma_f32_16x16x32_bf16 v[8:11], v[170:173], v[202:205], v[8:11]
	v_mfma_f32_16x16x32_bf16 v[60:63], v[160:163], v[182:185], v[60:63]
	v_mfma_f32_16x16x32_bf16 v[56:59], v[174:177], v[182:185], v[56:59]
	v_mfma_f32_16x16x32_bf16 v[44:47], v[160:163], v[190:193], v[44:47]
	v_mfma_f32_16x16x32_bf16 v[40:43], v[174:177], v[190:193], v[40:43]
	v_mfma_f32_16x16x32_bf16 v[28:31], v[160:163], v[198:201], v[28:31]
	v_mfma_f32_16x16x32_bf16 v[24:27], v[174:177], v[198:201], v[24:27]
	v_mfma_f32_16x16x32_bf16 v[12:15], v[160:163], v[206:209], v[12:15]
	v_mfma_f32_16x16x32_bf16 v[8:11], v[174:177], v[206:209], v[8:11]
	s_setprio 0
	s_barrier
	s_add_u32 s44, s54, 0x40080
	s_addc_u32 s45, s55, 0
	s_add_i32 s43, s56, s60
	v_lshl_add_u64 v[146:147], s[44:45], 0, v[130:131]
	s_mov_b32 m0, s43
	s_nop 0
	global_load_lds_dwordx4 v[146:147], off
	v_lshl_add_u64 v[146:147], s[44:45], 0, v[134:135]
	s_add_i32 m0, s43, 0x2000
	s_nop 0
	global_load_lds_dwordx4 v[146:147], off
	s_waitcnt vmcnt(6)
	s_barrier
	s_setprio 1
	v_mfma_f32_16x16x32_bf16 v[52:55], v[210:213], v[178:181], v[52:55]
	v_mfma_f32_16x16x32_bf16 v[48:51], v[218:221], v[178:181], v[48:51]
	v_mfma_f32_16x16x32_bf16 v[36:39], v[210:213], v[186:189], v[36:39]
	v_mfma_f32_16x16x32_bf16 v[32:35], v[218:221], v[186:189], v[32:35]
	v_mfma_f32_16x16x32_bf16 v[20:23], v[210:213], v[194:197], v[20:23]
	v_mfma_f32_16x16x32_bf16 v[16:19], v[218:221], v[194:197], v[16:19]
	v_mfma_f32_16x16x32_bf16 v[4:7], v[210:213], v[202:205], v[4:7]
	v_mfma_f32_16x16x32_bf16 v[0:3], v[218:221], v[202:205], v[0:3]
	v_mfma_f32_16x16x32_bf16 v[52:55], v[214:217], v[182:185], v[52:55]
	v_mfma_f32_16x16x32_bf16 v[48:51], v[222:225], v[182:185], v[48:51]
	v_mfma_f32_16x16x32_bf16 v[36:39], v[214:217], v[190:193], v[36:39]
	v_mfma_f32_16x16x32_bf16 v[32:35], v[222:225], v[190:193], v[32:35]
	v_mfma_f32_16x16x32_bf16 v[20:23], v[214:217], v[198:201], v[20:23]
	v_mfma_f32_16x16x32_bf16 v[16:19], v[222:225], v[198:201], v[16:19]
	v_mfma_f32_16x16x32_bf16 v[4:7], v[214:217], v[206:209], v[4:7]
	v_mfma_f32_16x16x32_bf16 v[0:3], v[222:225], v[206:209], v[0:3]
	s_setprio 0
	s_add_i32 s42, s42, 2
	s_add_u32 s33, s33, 0x100
	s_addc_u32 s39, s39, 0
	s_add_u32 s40, s40, 0x100
	s_addc_u32 s41, s41, 0
	s_cmp_gt_u32 s42, 13
	s_barrier
	s_cbranch_scc0 .LBB0_958
	v_lshl_add_u32 v146, s75, 8, v148
	v_ashrrev_i32_e32 v147, 31, v146
	v_lshlrev_b64 v[156:157], 6, v[146:147]
	v_lshl_add_u64 v[164:165], s[26:27], 0, v[156:157]
	v_subrev_u32_e32 v180, s26, v164
	v_add_u32_e32 v181, 0x0, v180
	global_load_dwordx4 v[182:185], v181, s[26:27]
	v_add_u32_e32 v181, 0x10, v180
	global_load_dwordx4 v[186:189], v181, s[26:27]
	v_add_u32_e32 v181, 0x20, v180
	global_load_dwordx4 v[190:193], v181, s[26:27]
	v_add_u32_e32 v181, 0x30, v180
	global_load_dwordx4 v[194:197], v181, s[26:27]
	v_add_u32_e32 v181, 0x400, v180
	global_load_dwordx4 v[198:201], v181, s[26:27]
	v_add_u32_e32 v181, 0x410, v180
	global_load_dwordx4 v[202:205], v181, s[26:27]
	v_add_u32_e32 v181, 0x420, v180
	global_load_dwordx4 v[206:209], v181, s[26:27]
	v_add_u32_e32 v181, 0x430, v180
	global_load_dwordx4 v[210:213], v181, s[26:27]
	v_add_u32_e32 v181, 0x800, v180
	global_load_dwordx4 v[214:217], v181, s[26:27]
	v_add_u32_e32 v181, 0x810, v180
	global_load_dwordx4 v[218:221], v181, s[26:27]
	v_add_u32_e32 v181, 0x820, v180
	global_load_dwordx4 v[222:225], v181, s[26:27]
	v_add_u32_e32 v181, 0x830, v180
	global_load_dwordx4 v[232:235], v181, s[26:27]
	v_add_u32_e32 v181, 0xc00, v180
	global_load_dwordx4 v[236:239], v181, s[26:27]
	v_add_u32_e32 v181, 0xc10, v180
	global_load_dwordx4 v[240:243], v181, s[26:27]
	v_add_u32_e32 v181, 0xc20, v180
	global_load_dwordx4 v[244:247], v181, s[26:27]
	v_add_u32_e32 v181, 0xc30, v180
	global_load_dwordx4 v[248:251], v181, s[26:27]
	v_or_b32_e32 v164, 16, v146
	v_lshl_or_b32 v147, s6, 9, v150
	v_ashrrev_i32_e32 v165, 31, v164
	v_lshl_add_u32 v155, v146, 13, v147
	s_waitcnt vmcnt(12)
; __device__ __forceinline__ u32x4 pack8(const f32x4 v0, const f32x4 v1) { u32x4 w; w.x = pk2(v0[0], v0[1]); w.y = pk2(v0[2], v0[3]); w.z = pk2(v1[0], v1[1]); w.w = pk2(v1[2], v1[3]); return w; }
; __device__ __forceinline__ float row_rstd(const float* ssq, int row) {
;     const f32x4* p = (const f32x4*)(ssq + (size_t)row * 16);
;     const f32x4 a = p[0], b = p[1], c = p[2], d = p[3];
;     const float s = ((a[0] + a[1]) + (a[2] + a[3])) + ((b[0] + b[1]) + (b[2] + b[3])) + ((c[0] + c[1]) + (c[2] + c[3])) + ((d[0] + d[1]) + (d[2] + d[3]));
;     return rsqrtf(s * (1.0f / 1024.0f) + 1e-6f);
;     __device__ __forceinline__ void operator()(const f32x4 (&acc)[2][2][4][2], const Unit& u, int wr, int wc, int fr, int fq) const {
;         const __amdgpu_buffer_rsrc_t rsrc = __builtin_amdgcn_make_buffer_rsrc((void*)O, 0, T_ALL * DFF * 2, 0x00020000);
;         const int row0 = row_off + u.pm * 256 + wr * 64 + fr, col0 = u.pn * 256 + wc * 32 + 8 * fq;
; #pragma unroll
;         for (int ai = 0; ai < 2; ++ai)
; #pragma unroll
;             for (int m = 0; m < 4; ++m) {
;                 const int row = row0 + ai * 128 + m * 16; const float rs = row_rstd(ssq, row);
; #pragma unroll
;                 for (int bj = 0; bj < 2; ++bj) { f32x4 v0 = acc[ai][bj][m][0] * rs, v1 = acc[ai][bj][m][1] * rs;
; #pragma unroll
;                     for (int j = 0; j < 4; ++j) { const float a = fmaxf(v0[j], 0.f), b = fmaxf(v1[j], 0.f); v0[j] = a * a; v1[j] = b * b; }
;                     __builtin_amdgcn_raw_buffer_store_b128(pack8(v0, v1), rsrc, (unsigned)(((size_t)row * DFF + col0 + bj * 128) * 2), 0, 16  ); }
	v_pk_add_f32 v[156:157], v[182:183], v[184:185]
	v_pk_add_f32 v[158:159], v[186:187], v[188:189]
	v_pk_add_f32 v[160:161], v[190:191], v[192:193]
	v_pk_add_f32 v[162:163], v[194:195], v[196:197]
	v_pk_add_f32 v[156:157], v[156:157], v[158:159]
	v_pk_add_f32 v[160:161], v[160:161], v[162:163]
	v_pk_add_f32 v[156:157], v[156:157], v[160:161]
	v_add_f32_e32 v156, v156, v157
	s_nop 0
	s_nop 0
	v_fmamk_f32 v156, v156, 0x3a800000, v154
	s_nop 0
	s_nop 0
	s_nop 1
	s_nop 0
	v_rsq_f32_e32 v158, v156
	s_nop 0
	s_nop 0
	s_nop 0
	s_nop 0
	v_pk_mul_f32 v[126:127], v[126:127], v[158:159] op_sel_hi:[1,0]
	v_pk_mul_f32 v[124:125], v[124:125], v[158:159] op_sel_hi:[1,0]
	v_pk_mul_f32 v[122:123], v[122:123], v[158:159] op_sel_hi:[1,0]
	v_pk_mul_f32 v[120:121], v[120:121], v[158:159] op_sel_hi:[1,0]
	v_pk_mul_f32 v[114:115], v[114:115], v[158:159] op_sel_hi:[1,0]
	v_pk_mul_f32 v[112:113], v[112:113], v[158:159] op_sel_hi:[1,0]
	v_pk_mul_f32 v[118:119], v[118:119], v[158:159] op_sel_hi:[1,0]
	v_pk_mul_f32 v[116:117], v[116:117], v[158:159] op_sel_hi:[1,0]
	v_max_f32_e32 v124, 0, v124
	v_max_f32_e32 v120, 0, v120
	v_max_f32_e32 v125, 0, v125
	v_max_f32_e32 v121, 0, v121
	v_max_f32_e32 v126, 0, v126
	v_max_f32_e32 v122, 0, v122
	v_max_f32_e32 v127, 0, v127
	v_max_f32_e32 v123, 0, v123
	v_max_f32_e32 v112, 0, v112
	v_max_f32_e32 v113, 0, v113
	v_max_f32_e32 v114, 0, v114
	v_max_f32_e32 v115, 0, v115
	v_max_f32_e32 v116, 0, v116
	v_max_f32_e32 v117, 0, v117
	v_max_f32_e32 v118, 0, v118
	v_max_f32_e32 v119, 0, v119
	v_pk_mul_f32 v[124:125], v[124:125], v[124:125]
	v_pk_mul_f32 v[120:121], v[120:121], v[120:121]
	v_pk_mul_f32 v[126:127], v[126:127], v[126:127]
	v_pk_mul_f32 v[122:123], v[122:123], v[122:123]
	v_pk_mul_f32 v[158:159], v[112:113], v[112:113]
	v_pk_mul_f32 v[160:161], v[114:115], v[114:115]
	v_cvt_pk_bf16_f32 v112, v124, v125
	v_cvt_pk_bf16_f32 v113, v126, v127
	v_cvt_pk_bf16_f32 v114, v120, v121
	v_cvt_pk_bf16_f32 v115, v122, v123
	v_pk_mul_f32 v[116:117], v[116:117], v[116:117]
	v_pk_mul_f32 v[118:119], v[118:119], v[118:119]
	buffer_store_dwordx4 v[112:115], v155, s[16:19], 0 offen sc1
	s_nop 1
	v_cvt_pk_bf16_f32 v112, v116, v117
	v_cvt_pk_bf16_f32 v113, v118, v119
	v_cvt_pk_bf16_f32 v114, v158, v159
	v_cvt_pk_bf16_f32 v115, v160, v161
	buffer_store_dwordx4 v[112:115], v155, s[16:19], 0 offen offset:256 sc1
	s_nop 0
	v_or_b32_e32 v156, 32, v146
	v_ashrrev_i32_e32 v157, 31, v156
	v_lshl_add_u32 v155, v164, 13, v147
	v_add_u32_e32 v181, 0x2000, v180
	global_load_dwordx4 v[182:185], v181, s[26:27]
	v_add_u32_e32 v181, 0x2010, v180
	global_load_dwordx4 v[186:189], v181, s[26:27]
	v_add_u32_e32 v181, 0x2020, v180
	global_load_dwordx4 v[190:193], v181, s[26:27]
	v_add_u32_e32 v181, 0x2030, v180
	global_load_dwordx4 v[194:197], v181, s[26:27]
	s_waitcnt vmcnt(14)
	v_pk_add_f32 v[112:113], v[198:199], v[200:201]
	v_pk_add_f32 v[114:115], v[202:203], v[204:205]
	v_pk_add_f32 v[116:117], v[206:207], v[208:209]
	v_pk_add_f32 v[118:119], v[210:211], v[212:213]
	v_pk_add_f32 v[112:113], v[112:113], v[114:115]
	v_pk_add_f32 v[116:117], v[116:117], v[118:119]
	v_pk_add_f32 v[112:113], v[112:113], v[116:117]
	v_add_f32_e32 v112, v112, v113
	s_nop 0
	s_nop 0
	v_fmamk_f32 v112, v112, 0x3a800000, v154
	s_nop 0
	s_nop 0
	s_nop 1
	s_nop 0
	v_rsq_f32_e32 v114, v112
	s_nop 0
	s_nop 0
	s_nop 0
	s_nop 0
	v_pk_mul_f32 v[110:111], v[110:111], v[114:115] op_sel_hi:[1,0]
	v_pk_mul_f32 v[108:109], v[108:109], v[114:115] op_sel_hi:[1,0]
	v_pk_mul_f32 v[106:107], v[106:107], v[114:115] op_sel_hi:[1,0]
	v_pk_mul_f32 v[104:105], v[104:105], v[114:115] op_sel_hi:[1,0]
	v_pk_mul_f32 v[98:99], v[98:99], v[114:115] op_sel_hi:[1,0]
	v_pk_mul_f32 v[96:97], v[96:97], v[114:115] op_sel_hi:[1,0]
	v_pk_mul_f32 v[102:103], v[102:103], v[114:115] op_sel_hi:[1,0]
	v_pk_mul_f32 v[100:101], v[100:101], v[114:115] op_sel_hi:[1,0]
	v_max_f32_e32 v108, 0, v108
	v_max_f32_e32 v104, 0, v104
	v_max_f32_e32 v109, 0, v109
	v_max_f32_e32 v105, 0, v105
	v_max_f32_e32 v110, 0, v110
	v_max_f32_e32 v106, 0, v106
	v_max_f32_e32 v111, 0, v111
	v_max_f32_e32 v107, 0, v107
	v_max_f32_e32 v96, 0, v96
	v_max_f32_e32 v97, 0, v97
	v_max_f32_e32 v98, 0, v98
	v_max_f32_e32 v99, 0, v99
	v_max_f32_e32 v100, 0, v100
	v_max_f32_e32 v101, 0, v101
	v_max_f32_e32 v102, 0, v102
	v_max_f32_e32 v103, 0, v103
	v_pk_mul_f32 v[108:109], v[108:109], v[108:109]
	v_pk_mul_f32 v[104:105], v[104:105], v[104:105]
	v_pk_mul_f32 v[110:111], v[110:111], v[110:111]
	v_pk_mul_f32 v[106:107], v[106:107], v[106:107]
	v_pk_mul_f32 v[114:115], v[96:97], v[96:97]
	v_pk_mul_f32 v[116:117], v[98:99], v[98:99]
	v_cvt_pk_bf16_f32 v96, v108, v109
	v_cvt_pk_bf16_f32 v97, v110, v111
	v_cvt_pk_bf16_f32 v98, v104, v105
	v_cvt_pk_bf16_f32 v99, v106, v107
	v_pk_mul_f32 v[100:101], v[100:101], v[100:101]
	v_pk_mul_f32 v[102:103], v[102:103], v[102:103]
	buffer_store_dwordx4 v[96:99], v155, s[16:19], 0 offen sc1
	s_nop 1
	v_cvt_pk_bf16_f32 v96, v100, v101
	v_cvt_pk_bf16_f32 v97, v102, v103
	v_cvt_pk_bf16_f32 v98, v114, v115
	v_cvt_pk_bf16_f32 v99, v116, v117
	buffer_store_dwordx4 v[96:99], v155, s[16:19], 0 offen offset:256 sc1
	s_nop 0
	v_or_b32_e32 v112, 48, v146
	v_ashrrev_i32_e32 v113, 31, v112
	v_lshl_add_u32 v116, v156, 13, v147
	v_add_u32_e32 v181, 0x2400, v180
	global_load_dwordx4 v[198:201], v181, s[26:27]
	v_add_u32_e32 v181, 0x2410, v180
	global_load_dwordx4 v[202:205], v181, s[26:27]
	v_add_u32_e32 v181, 0x2420, v180
	global_load_dwordx4 v[206:209], v181, s[26:27]
	v_add_u32_e32 v181, 0x2430, v180
	global_load_dwordx4 v[210:213], v181, s[26:27]
	s_waitcnt vmcnt(16)
; __device__ __forceinline__ u32x4 pack8(const f32x4 v0, const f32x4 v1) { u32x4 w; w.x = pk2(v0[0], v0[1]); w.y = pk2(v0[2], v0[3]); w.z = pk2(v1[0], v1[1]); w.w = pk2(v1[2], v1[3]); return w; }
; __device__ __forceinline__ float row_rstd(const float* ssq, int row) {
;     const f32x4* p = (const f32x4*)(ssq + (size_t)row * 16);
;     const f32x4 a = p[0], b = p[1], c = p[2], d = p[3];
;     const float s = ((a[0] + a[1]) + (a[2] + a[3])) + ((b[0] + b[1]) + (b[2] + b[3])) + ((c[0] + c[1]) + (c[2] + c[3])) + ((d[0] + d[1]) + (d[2] + d[3]));
;     return rsqrtf(s * (1.0f / 1024.0f) + 1e-6f);
;     __device__ __forceinline__ void operator()(const f32x4 (&acc)[2][2][4][2], const Unit& u, int wr, int wc, int fr, int fq) const {
;         const __amdgpu_buffer_rsrc_t rsrc = __builtin_amdgcn_make_buffer_rsrc((void*)O, 0, T_ALL * DFF * 2, 0x00020000);
;         const int row0 = row_off + u.pm * 256 + wr * 64 + fr, col0 = u.pn * 256 + wc * 32 + 8 * fq;
; #pragma unroll
;         for (int ai = 0; ai < 2; ++ai)
; #pragma unroll
;             for (int m = 0; m < 4; ++m) {
;                 const int row = row0 + ai * 128 + m * 16; const float rs = row_rstd(ssq, row);
; #pragma unroll
;                 for (int bj = 0; bj < 2; ++bj) { f32x4 v0 = acc[ai][bj][m][0] * rs, v1 = acc[ai][bj][m][1] * rs;
; #pragma unroll
;                     for (int j = 0; j < 4; ++j) { const float a = fmaxf(v0[j], 0.f), b = fmaxf(v1[j], 0.f); v0[j] = a * a; v1[j] = b * b; }
;                     __builtin_amdgcn_raw_buffer_store_b128(pack8(v0, v1), rsrc, (unsigned)(((size_t)row * DFF + col0 + bj * 128) * 2), 0, 16  ); }
	v_pk_add_f32 v[96:97], v[214:215], v[216:217]
	v_pk_add_f32 v[98:99], v[218:219], v[220:221]
	v_pk_add_f32 v[100:101], v[222:223], v[224:225]
	v_pk_add_f32 v[102:103], v[232:233], v[234:235]
	v_pk_add_f32 v[96:97], v[96:97], v[98:99]
	v_pk_add_f32 v[100:101], v[100:101], v[102:103]
	v_pk_add_f32 v[96:97], v[96:97], v[100:101]
	v_add_f32_e32 v96, v96, v97
	s_nop 0
	s_nop 0
	v_fmamk_f32 v96, v96, 0x3a800000, v154
	s_nop 0
	s_nop 0
	s_nop 1
	s_nop 0
	v_rsq_f32_e32 v98, v96
	s_nop 0
	s_nop 0
	s_nop 0
	s_nop 0
	v_pk_mul_f32 v[94:95], v[94:95], v[98:99] op_sel_hi:[1,0]
	v_pk_mul_f32 v[92:93], v[92:93], v[98:99] op_sel_hi:[1,0]
	v_pk_mul_f32 v[90:91], v[90:91], v[98:99] op_sel_hi:[1,0]
	v_pk_mul_f32 v[88:89], v[88:89], v[98:99] op_sel_hi:[1,0]
	v_pk_mul_f32 v[82:83], v[82:83], v[98:99] op_sel_hi:[1,0]
	v_pk_mul_f32 v[80:81], v[80:81], v[98:99] op_sel_hi:[1,0]
	v_pk_mul_f32 v[86:87], v[86:87], v[98:99] op_sel_hi:[1,0]
	v_pk_mul_f32 v[84:85], v[84:85], v[98:99] op_sel_hi:[1,0]
	v_max_f32_e32 v92, 0, v92
	v_max_f32_e32 v88, 0, v88
	v_max_f32_e32 v93, 0, v93
	v_max_f32_e32 v89, 0, v89
	v_max_f32_e32 v94, 0, v94
	v_max_f32_e32 v90, 0, v90
	v_max_f32_e32 v95, 0, v95
	v_max_f32_e32 v91, 0, v91
	v_max_f32_e32 v80, 0, v80
	v_max_f32_e32 v81, 0, v81
	v_max_f32_e32 v82, 0, v82
	v_max_f32_e32 v83, 0, v83
	v_max_f32_e32 v84, 0, v84
	v_max_f32_e32 v85, 0, v85
	v_max_f32_e32 v86, 0, v86
	v_max_f32_e32 v87, 0, v87
	v_pk_mul_f32 v[92:93], v[92:93], v[92:93]
	v_pk_mul_f32 v[88:89], v[88:89], v[88:89]
	v_pk_mul_f32 v[94:95], v[94:95], v[94:95]
	v_pk_mul_f32 v[90:91], v[90:91], v[90:91]
	v_pk_mul_f32 v[98:99], v[80:81], v[80:81]
	v_pk_mul_f32 v[100:101], v[82:83], v[82:83]
	v_cvt_pk_bf16_f32 v80, v92, v93
	v_cvt_pk_bf16_f32 v81, v94, v95
	v_cvt_pk_bf16_f32 v82, v88, v89
	v_cvt_pk_bf16_f32 v83, v90, v91
	v_pk_mul_f32 v[84:85], v[84:85], v[84:85]
	v_pk_mul_f32 v[86:87], v[86:87], v[86:87]
	buffer_store_dwordx4 v[80:83], v116, s[16:19], 0 offen sc1
	s_nop 1
	v_cvt_pk_bf16_f32 v80, v84, v85
	v_cvt_pk_bf16_f32 v81, v86, v87
	v_cvt_pk_bf16_f32 v82, v98, v99
	v_cvt_pk_bf16_f32 v83, v100, v101
	buffer_store_dwordx4 v[80:83], v116, s[16:19], 0 offen offset:256 sc1
	s_nop 0
	v_add_u32_e32 v96, 0x80, v146
	v_ashrrev_i32_e32 v97, 31, v96
	v_lshl_add_u32 v100, v112, 13, v147
	v_add_u32_e32 v181, 0x2800, v180
	global_load_dwordx4 v[214:217], v181, s[26:27]
	v_add_u32_e32 v181, 0x2810, v180
	global_load_dwordx4 v[218:221], v181, s[26:27]
	v_add_u32_e32 v181, 0x2820, v180
	global_load_dwordx4 v[222:225], v181, s[26:27]
	v_add_u32_e32 v181, 0x2830, v180
	global_load_dwordx4 v[232:235], v181, s[26:27]
	s_waitcnt vmcnt(18)
	v_pk_add_f32 v[80:81], v[236:237], v[238:239]
	v_pk_add_f32 v[82:83], v[240:241], v[242:243]
	v_pk_add_f32 v[84:85], v[244:245], v[246:247]
	v_pk_add_f32 v[86:87], v[248:249], v[250:251]
	v_pk_add_f32 v[80:81], v[80:81], v[82:83]
	v_pk_add_f32 v[84:85], v[84:85], v[86:87]
	v_pk_add_f32 v[80:81], v[80:81], v[84:85]
	v_add_f32_e32 v80, v80, v81
	s_nop 0
	s_nop 0
	v_fmamk_f32 v80, v80, 0x3a800000, v154
	s_nop 0
	s_nop 0
	s_nop 1
	s_nop 0
	v_rsq_f32_e32 v82, v80
	s_nop 0
	s_nop 0
	s_nop 0
	s_nop 0
	v_pk_mul_f32 v[78:79], v[78:79], v[82:83] op_sel_hi:[1,0]
	v_pk_mul_f32 v[76:77], v[76:77], v[82:83] op_sel_hi:[1,0]
	v_pk_mul_f32 v[74:75], v[74:75], v[82:83] op_sel_hi:[1,0]
	v_pk_mul_f32 v[72:73], v[72:73], v[82:83] op_sel_hi:[1,0]
	v_pk_mul_f32 v[66:67], v[66:67], v[82:83] op_sel_hi:[1,0]
	v_pk_mul_f32 v[64:65], v[64:65], v[82:83] op_sel_hi:[1,0]
	v_pk_mul_f32 v[70:71], v[70:71], v[82:83] op_sel_hi:[1,0]
	v_pk_mul_f32 v[68:69], v[68:69], v[82:83] op_sel_hi:[1,0]
	v_max_f32_e32 v76, 0, v76
	v_max_f32_e32 v72, 0, v72
	v_max_f32_e32 v77, 0, v77
	v_max_f32_e32 v73, 0, v73
	v_max_f32_e32 v78, 0, v78
	v_max_f32_e32 v74, 0, v74
	v_max_f32_e32 v79, 0, v79
	v_max_f32_e32 v75, 0, v75
	v_max_f32_e32 v64, 0, v64
	v_max_f32_e32 v65, 0, v65
	v_max_f32_e32 v66, 0, v66
	v_max_f32_e32 v67, 0, v67
	v_max_f32_e32 v68, 0, v68
	v_max_f32_e32 v69, 0, v69
	v_max_f32_e32 v70, 0, v70
	v_max_f32_e32 v71, 0, v71
	v_pk_mul_f32 v[76:77], v[76:77], v[76:77]
	v_pk_mul_f32 v[72:73], v[72:73], v[72:73]
	v_pk_mul_f32 v[78:79], v[78:79], v[78:79]
	v_pk_mul_f32 v[74:75], v[74:75], v[74:75]
	v_pk_mul_f32 v[82:83], v[64:65], v[64:65]
	v_pk_mul_f32 v[84:85], v[66:67], v[66:67]
	v_cvt_pk_bf16_f32 v64, v76, v77
	v_cvt_pk_bf16_f32 v65, v78, v79
	v_cvt_pk_bf16_f32 v66, v72, v73
	v_cvt_pk_bf16_f32 v67, v74, v75
	v_pk_mul_f32 v[68:69], v[68:69], v[68:69]
	v_pk_mul_f32 v[70:71], v[70:71], v[70:71]
	buffer_store_dwordx4 v[64:67], v100, s[16:19], 0 offen sc1
	s_nop 1
	v_cvt_pk_bf16_f32 v64, v68, v69
	v_cvt_pk_bf16_f32 v65, v70, v71
	v_cvt_pk_bf16_f32 v66, v82, v83
	v_cvt_pk_bf16_f32 v67, v84, v85
	buffer_store_dwordx4 v[64:67], v100, s[16:19], 0 offen offset:256 sc1
	s_nop 0
	v_add_u32_e32 v80, 0x90, v146
	v_ashrrev_i32_e32 v81, 31, v80
	v_lshl_add_u32 v84, v96, 13, v147
	v_add_u32_e32 v181, 0x2c00, v180
	global_load_dwordx4 v[236:239], v181, s[26:27]
	v_add_u32_e32 v181, 0x2c10, v180
	global_load_dwordx4 v[240:243], v181, s[26:27]
	v_add_u32_e32 v181, 0x2c20, v180
	global_load_dwordx4 v[244:247], v181, s[26:27]
	v_add_u32_e32 v181, 0x2c30, v180
	global_load_dwordx4 v[248:251], v181, s[26:27]
	s_waitcnt vmcnt(18)
; __device__ __forceinline__ u32x4 pack8(const f32x4 v0, const f32x4 v1) { u32x4 w; w.x = pk2(v0[0], v0[1]); w.y = pk2(v0[2], v0[3]); w.z = pk2(v1[0], v1[1]); w.w = pk2(v1[2], v1[3]); return w; }
; __device__ __forceinline__ float row_rstd(const float* ssq, int row) {
;     const f32x4* p = (const f32x4*)(ssq + (size_t)row * 16);
;     const f32x4 a = p[0], b = p[1], c = p[2], d = p[3];
;     const float s = ((a[0] + a[1]) + (a[2] + a[3])) + ((b[0] + b[1]) + (b[2] + b[3])) + ((c[0] + c[1]) + (c[2] + c[3])) + ((d[0] + d[1]) + (d[2] + d[3]));
;     return rsqrtf(s * (1.0f / 1024.0f) + 1e-6f);
;     __device__ __forceinline__ void operator()(const f32x4 (&acc)[2][2][4][2], const Unit& u, int wr, int wc, int fr, int fq) const {
;         const __amdgpu_buffer_rsrc_t rsrc = __builtin_amdgcn_make_buffer_rsrc((void*)O, 0, T_ALL * DFF * 2, 0x00020000);
;         const int row0 = row_off + u.pm * 256 + wr * 64 + fr, col0 = u.pn * 256 + wc * 32 + 8 * fq;
; #pragma unroll
;         for (int ai = 0; ai < 2; ++ai)
; #pragma unroll
;             for (int m = 0; m < 4; ++m) {
;                 const int row = row0 + ai * 128 + m * 16; const float rs = row_rstd(ssq, row);
; #pragma unroll
;                 for (int bj = 0; bj < 2; ++bj) { f32x4 v0 = acc[ai][bj][m][0] * rs, v1 = acc[ai][bj][m][1] * rs;
; #pragma unroll
;                     for (int j = 0; j < 4; ++j) { const float a = fmaxf(v0[j], 0.f), b = fmaxf(v1[j], 0.f); v0[j] = a * a; v1[j] = b * b; }
;                     __builtin_amdgcn_raw_buffer_store_b128(pack8(v0, v1), rsrc, (unsigned)(((size_t)row * DFF + col0 + bj * 128) * 2), 0, 16  ); }
	v_pk_add_f32 v[64:65], v[182:183], v[184:185]
	v_pk_add_f32 v[66:67], v[186:187], v[188:189]
	v_pk_add_f32 v[68:69], v[190:191], v[192:193]
	v_pk_add_f32 v[70:71], v[194:195], v[196:197]
	v_pk_add_f32 v[64:65], v[64:65], v[66:67]
	v_pk_add_f32 v[68:69], v[68:69], v[70:71]
	v_pk_add_f32 v[64:65], v[64:65], v[68:69]
	v_add_f32_e32 v64, v64, v65
	s_nop 0
	s_nop 0
	v_fmamk_f32 v64, v64, 0x3a800000, v154
	s_nop 0
	s_nop 0
	s_nop 1
	s_nop 0
	v_rsq_f32_e32 v66, v64
	s_nop 0
	s_nop 0
	s_nop 0
	s_nop 0
	v_pk_mul_f32 v[62:63], v[62:63], v[66:67] op_sel_hi:[1,0]
	v_pk_mul_f32 v[60:61], v[60:61], v[66:67] op_sel_hi:[1,0]
	v_pk_mul_f32 v[58:59], v[58:59], v[66:67] op_sel_hi:[1,0]
	v_pk_mul_f32 v[56:57], v[56:57], v[66:67] op_sel_hi:[1,0]
	v_pk_mul_f32 v[50:51], v[50:51], v[66:67] op_sel_hi:[1,0]
	v_pk_mul_f32 v[48:49], v[48:49], v[66:67] op_sel_hi:[1,0]
	v_pk_mul_f32 v[54:55], v[54:55], v[66:67] op_sel_hi:[1,0]
	v_pk_mul_f32 v[52:53], v[52:53], v[66:67] op_sel_hi:[1,0]
	v_max_f32_e32 v60, 0, v60
	v_max_f32_e32 v56, 0, v56
	v_max_f32_e32 v61, 0, v61
	v_max_f32_e32 v57, 0, v57
	v_max_f32_e32 v62, 0, v62
	v_max_f32_e32 v58, 0, v58
	v_max_f32_e32 v63, 0, v63
	v_max_f32_e32 v59, 0, v59
	v_max_f32_e32 v48, 0, v48
	v_max_f32_e32 v49, 0, v49
	v_max_f32_e32 v50, 0, v50
	v_max_f32_e32 v51, 0, v51
	v_max_f32_e32 v52, 0, v52
	v_max_f32_e32 v53, 0, v53
	v_max_f32_e32 v54, 0, v54
	v_max_f32_e32 v55, 0, v55
	v_pk_mul_f32 v[60:61], v[60:61], v[60:61]
	v_pk_mul_f32 v[56:57], v[56:57], v[56:57]
	v_pk_mul_f32 v[62:63], v[62:63], v[62:63]
	v_pk_mul_f32 v[58:59], v[58:59], v[58:59]
	v_pk_mul_f32 v[66:67], v[48:49], v[48:49]
	v_pk_mul_f32 v[68:69], v[50:51], v[50:51]
	v_cvt_pk_bf16_f32 v48, v60, v61
	v_cvt_pk_bf16_f32 v49, v62, v63
	v_cvt_pk_bf16_f32 v50, v56, v57
	v_cvt_pk_bf16_f32 v51, v58, v59
	v_pk_mul_f32 v[52:53], v[52:53], v[52:53]
	v_pk_mul_f32 v[54:55], v[54:55], v[54:55]
	buffer_store_dwordx4 v[48:51], v84, s[16:19], 0 offen sc1
	s_nop 1
	v_cvt_pk_bf16_f32 v48, v52, v53
	v_cvt_pk_bf16_f32 v49, v54, v55
	v_cvt_pk_bf16_f32 v50, v66, v67
	v_cvt_pk_bf16_f32 v51, v68, v69
	buffer_store_dwordx4 v[48:51], v84, s[16:19], 0 offen offset:256 sc1
	s_nop 0
	v_add_u32_e32 v64, 0xa0, v146
	v_ashrrev_i32_e32 v65, 31, v64
	v_lshl_add_u32 v68, v80, 13, v147
	s_waitcnt vmcnt(14)
	v_pk_add_f32 v[48:49], v[198:199], v[200:201]
	v_pk_add_f32 v[50:51], v[202:203], v[204:205]
	v_pk_add_f32 v[52:53], v[206:207], v[208:209]
	v_pk_add_f32 v[54:55], v[210:211], v[212:213]
	v_pk_add_f32 v[48:49], v[48:49], v[50:51]
	v_pk_add_f32 v[52:53], v[52:53], v[54:55]
	v_pk_add_f32 v[48:49], v[48:49], v[52:53]
	v_add_f32_e32 v48, v48, v49
	s_nop 0
	s_nop 0
	v_fmamk_f32 v48, v48, 0x3a800000, v154
	s_nop 0
	s_nop 0
	s_nop 1
	s_nop 0
	v_rsq_f32_e32 v50, v48
	s_nop 0
	s_nop 0
	s_nop 0
	s_nop 0
	v_pk_mul_f32 v[46:47], v[46:47], v[50:51] op_sel_hi:[1,0]
	v_pk_mul_f32 v[44:45], v[44:45], v[50:51] op_sel_hi:[1,0]
	v_pk_mul_f32 v[42:43], v[42:43], v[50:51] op_sel_hi:[1,0]
	v_pk_mul_f32 v[40:41], v[40:41], v[50:51] op_sel_hi:[1,0]
	v_pk_mul_f32 v[34:35], v[34:35], v[50:51] op_sel_hi:[1,0]
	v_pk_mul_f32 v[32:33], v[32:33], v[50:51] op_sel_hi:[1,0]
	v_pk_mul_f32 v[38:39], v[38:39], v[50:51] op_sel_hi:[1,0]
	v_pk_mul_f32 v[36:37], v[36:37], v[50:51] op_sel_hi:[1,0]
	v_max_f32_e32 v44, 0, v44
	v_max_f32_e32 v40, 0, v40
	v_max_f32_e32 v45, 0, v45
	v_max_f32_e32 v41, 0, v41
	v_max_f32_e32 v46, 0, v46
	v_max_f32_e32 v42, 0, v42
	v_max_f32_e32 v47, 0, v47
	v_max_f32_e32 v43, 0, v43
	v_max_f32_e32 v32, 0, v32
	v_max_f32_e32 v33, 0, v33
	v_max_f32_e32 v34, 0, v34
	v_max_f32_e32 v35, 0, v35
	v_max_f32_e32 v36, 0, v36
	v_max_f32_e32 v37, 0, v37
	v_max_f32_e32 v38, 0, v38
	v_max_f32_e32 v39, 0, v39
	v_pk_mul_f32 v[44:45], v[44:45], v[44:45]
	v_pk_mul_f32 v[40:41], v[40:41], v[40:41]
	v_pk_mul_f32 v[46:47], v[46:47], v[46:47]
	v_pk_mul_f32 v[42:43], v[42:43], v[42:43]
	v_pk_mul_f32 v[50:51], v[32:33], v[32:33]
	v_pk_mul_f32 v[52:53], v[34:35], v[34:35]
	v_cvt_pk_bf16_f32 v32, v44, v45
	v_cvt_pk_bf16_f32 v33, v46, v47
	v_cvt_pk_bf16_f32 v34, v40, v41
	v_cvt_pk_bf16_f32 v35, v42, v43
	v_pk_mul_f32 v[36:37], v[36:37], v[36:37]
	v_pk_mul_f32 v[38:39], v[38:39], v[38:39]
	buffer_store_dwordx4 v[32:35], v68, s[16:19], 0 offen sc1
	s_nop 1
	v_cvt_pk_bf16_f32 v32, v36, v37
	v_cvt_pk_bf16_f32 v33, v38, v39
	v_cvt_pk_bf16_f32 v34, v50, v51
	v_cvt_pk_bf16_f32 v35, v52, v53
	buffer_store_dwordx4 v[32:35], v68, s[16:19], 0 offen offset:256 sc1
	s_nop 0
	v_add_u32_e32 v48, 0xb0, v146
	v_ashrrev_i32_e32 v49, 31, v48
	v_lshl_add_u32 v52, v64, 13, v147
	s_waitcnt vmcnt(10)
; __device__ __forceinline__ u32x4 pack8(const f32x4 v0, const f32x4 v1) { u32x4 w; w.x = pk2(v0[0], v0[1]); w.y = pk2(v0[2], v0[3]); w.z = pk2(v1[0], v1[1]); w.w = pk2(v1[2], v1[3]); return w; }
;     __device__ __forceinline__ void operator()(const f32x4 (&acc)[2][2][4][2], const Unit& u, int wr, int wc, int fr, int fq) const {
;         const __amdgpu_buffer_rsrc_t rsrc = __builtin_amdgcn_make_buffer_rsrc((void*)O, 0, T_ALL * DFF * 2, 0x00020000);
;         const int row0 = row_off + u.pm * 256 + wr * 64 + fr, col0 = u.pn * 256 + wc * 32 + 8 * fq;
; #pragma unroll
;         for (int ai = 0; ai < 2; ++ai)
; #pragma unroll
;             for (int m = 0; m < 4; ++m) {
;                 const int row = row0 + ai * 128 + m * 16; const float rs = row_rstd(ssq, row);
; #pragma unroll
;                 for (int bj = 0; bj < 2; ++bj) { f32x4 v0 = acc[ai][bj][m][0] * rs, v1 = acc[ai][bj][m][1] * rs;
; #pragma unroll
;                     for (int j = 0; j < 4; ++j) { const float a = fmaxf(v0[j], 0.f), b = fmaxf(v1[j], 0.f); v0[j] = a * a; v1[j] = b * b; }
;                     __builtin_amdgcn_raw_buffer_store_b128(pack8(v0, v1), rsrc, (unsigned)(((size_t)row * DFF + col0 + bj * 128) * 2), 0, 16  ); }
;             }
;         asm volatile("s_waitcnt vmcnt(0)" ::: "memory");
;         if (fr == 0 && fq == 0) (void)__hip_atomic_fetch_add(ready + 64 * (pm_off + u.pm), 1u, __ATOMIC_RELAXED, __HIP_MEMORY_SCOPE_AGENT);
	v_pk_add_f32 v[32:33], v[214:215], v[216:217]
	v_pk_add_f32 v[34:35], v[218:219], v[220:221]
	v_pk_add_f32 v[36:37], v[222:223], v[224:225]
	v_pk_add_f32 v[38:39], v[232:233], v[234:235]
	v_pk_add_f32 v[32:33], v[32:33], v[34:35]
	v_pk_add_f32 v[36:37], v[36:37], v[38:39]
	v_pk_add_f32 v[32:33], v[32:33], v[36:37]
	v_add_f32_e32 v32, v32, v33
	s_nop 0
	s_nop 0
	v_fmamk_f32 v32, v32, 0x3a800000, v154
	s_nop 0
	s_nop 0
	s_nop 1
	s_nop 0
	v_rsq_f32_e32 v34, v32
	v_lshlrev_b64 v[32:33], 6, v[48:49]
	v_lshl_add_u64 v[32:33], s[26:27], 0, v[32:33]
	s_nop 0
	s_nop 0
	v_pk_mul_f32 v[30:31], v[30:31], v[34:35] op_sel_hi:[1,0]
	v_pk_mul_f32 v[28:29], v[28:29], v[34:35] op_sel_hi:[1,0]
	v_pk_mul_f32 v[26:27], v[26:27], v[34:35] op_sel_hi:[1,0]
	v_pk_mul_f32 v[24:25], v[24:25], v[34:35] op_sel_hi:[1,0]
	v_pk_mul_f32 v[18:19], v[18:19], v[34:35] op_sel_hi:[1,0]
	v_pk_mul_f32 v[16:17], v[16:17], v[34:35] op_sel_hi:[1,0]
	v_pk_mul_f32 v[22:23], v[22:23], v[34:35] op_sel_hi:[1,0]
	v_pk_mul_f32 v[20:21], v[20:21], v[34:35] op_sel_hi:[1,0]
	v_max_f32_e32 v28, 0, v28
	v_max_f32_e32 v24, 0, v24
	v_max_f32_e32 v29, 0, v29
	v_max_f32_e32 v25, 0, v25
	v_max_f32_e32 v30, 0, v30
	v_max_f32_e32 v26, 0, v26
	v_max_f32_e32 v31, 0, v31
	v_max_f32_e32 v27, 0, v27
	v_max_f32_e32 v16, 0, v16
	v_max_f32_e32 v17, 0, v17
	v_max_f32_e32 v18, 0, v18
	v_max_f32_e32 v19, 0, v19
	v_max_f32_e32 v20, 0, v20
	v_max_f32_e32 v21, 0, v21
	v_max_f32_e32 v22, 0, v22
	v_max_f32_e32 v23, 0, v23
	v_pk_mul_f32 v[28:29], v[28:29], v[28:29]
	v_pk_mul_f32 v[24:25], v[24:25], v[24:25]
	v_pk_mul_f32 v[30:31], v[30:31], v[30:31]
	v_pk_mul_f32 v[26:27], v[26:27], v[26:27]
	v_pk_mul_f32 v[34:35], v[16:17], v[16:17]
	v_pk_mul_f32 v[36:37], v[18:19], v[18:19]
	v_cvt_pk_bf16_f32 v16, v28, v29
	v_cvt_pk_bf16_f32 v17, v30, v31
	v_cvt_pk_bf16_f32 v18, v24, v25
	v_cvt_pk_bf16_f32 v19, v26, v27
	v_pk_mul_f32 v[20:21], v[20:21], v[20:21]
	v_pk_mul_f32 v[22:23], v[22:23], v[22:23]
	buffer_store_dwordx4 v[16:19], v52, s[16:19], 0 offen sc1
	s_nop 1
	v_cvt_pk_bf16_f32 v16, v20, v21
	v_cvt_pk_bf16_f32 v17, v22, v23
	v_cvt_pk_bf16_f32 v18, v34, v35
	v_cvt_pk_bf16_f32 v19, v36, v37
	buffer_store_dwordx4 v[16:19], v52, s[16:19], 0 offen offset:256 sc1
	s_nop 0
	s_waitcnt vmcnt(6)
	v_pk_add_f32 v[16:17], v[236:237], v[238:239]
	v_pk_add_f32 v[18:19], v[240:241], v[242:243]
	v_pk_add_f32 v[20:21], v[244:245], v[246:247]
	v_pk_add_f32 v[22:23], v[248:249], v[250:251]
	v_pk_add_f32 v[16:17], v[16:17], v[18:19]
	v_pk_add_f32 v[20:21], v[20:21], v[22:23]
	v_pk_add_f32 v[16:17], v[16:17], v[20:21]
	v_add_f32_e32 v16, v16, v17
	s_nop 0
	s_nop 0
	v_fmamk_f32 v16, v16, 0x3a800000, v154
	s_nop 0
	s_nop 0
	s_nop 1
	s_nop 0
	v_rsq_f32_e32 v16, v16
	v_lshl_add_u32 v17, v48, 13, v147
	s_nop 0
	s_nop 0
	v_pk_mul_f32 v[14:15], v[14:15], v[16:17] op_sel_hi:[1,0]
	v_pk_mul_f32 v[12:13], v[12:13], v[16:17] op_sel_hi:[1,0]
	v_pk_mul_f32 v[10:11], v[10:11], v[16:17] op_sel_hi:[1,0]
	v_pk_mul_f32 v[8:9], v[8:9], v[16:17] op_sel_hi:[1,0]
	v_pk_mul_f32 v[2:3], v[2:3], v[16:17] op_sel_hi:[1,0]
	v_pk_mul_f32 v[0:1], v[0:1], v[16:17] op_sel_hi:[1,0]
	v_pk_mul_f32 v[6:7], v[6:7], v[16:17] op_sel_hi:[1,0]
	v_pk_mul_f32 v[4:5], v[4:5], v[16:17] op_sel_hi:[1,0]
	v_max_f32_e32 v12, 0, v12
	v_max_f32_e32 v8, 0, v8
	v_max_f32_e32 v13, 0, v13
	v_max_f32_e32 v9, 0, v9
	v_max_f32_e32 v14, 0, v14
	v_max_f32_e32 v10, 0, v10
	v_max_f32_e32 v15, 0, v15
	v_max_f32_e32 v11, 0, v11
	v_max_f32_e32 v0, 0, v0
	v_max_f32_e32 v1, 0, v1
	v_max_f32_e32 v2, 0, v2
	v_max_f32_e32 v3, 0, v3
	v_max_f32_e32 v4, 0, v4
	v_max_f32_e32 v5, 0, v5
	v_max_f32_e32 v6, 0, v6
	v_max_f32_e32 v7, 0, v7
	v_pk_mul_f32 v[12:13], v[12:13], v[12:13]
	v_pk_mul_f32 v[8:9], v[8:9], v[8:9]
	v_pk_mul_f32 v[14:15], v[14:15], v[14:15]
	v_pk_mul_f32 v[10:11], v[10:11], v[10:11]
	v_mul_f32_e32 v16, v0, v0
	v_mul_f32_e32 v18, v1, v1
	v_mul_f32_e32 v19, v2, v2
	v_mul_f32_e32 v20, v3, v3
	v_cvt_pk_bf16_f32 v0, v12, v13
	v_cvt_pk_bf16_f32 v1, v14, v15
	v_cvt_pk_bf16_f32 v2, v8, v9
	v_cvt_pk_bf16_f32 v3, v10, v11
	v_pk_mul_f32 v[4:5], v[4:5], v[4:5]
	v_pk_mul_f32 v[6:7], v[6:7], v[6:7]
	buffer_store_dwordx4 v[0:3], v17, s[16:19], 0 offen sc1
	s_nop 1
	v_cvt_pk_bf16_f32 v0, v4, v5
	v_cvt_pk_bf16_f32 v1, v6, v7
	v_cvt_pk_bf16_f32 v2, v16, v18
	v_cvt_pk_bf16_f32 v3, v19, v20
	buffer_store_dwordx4 v[0:3], v17, s[16:19], 0 offen offset:256 sc1
	s_waitcnt vmcnt(0)
	s_and_saveexec_b64 s[40:41], s[10:11]
	s_cbranch_execz .LBB0_950
	s_mov_b64 s[54:55], exec
	v_mbcnt_lo_u32_b32 v0, s54, 0
	v_mbcnt_hi_u32_b32 v0, s55, v0
	v_cmp_eq_u32_e32 vcc, 0, v0
	s_and_b64 s[6:7], exec, vcc
	s_mov_b64 exec, s[6:7]
	s_cbranch_execz .LBB0_950
	s_lshl_b32 s6, s75, 6
	s_ashr_i32 s7, s6, 31
	s_lshl_b64 s[6:7], s[6:7], 2
	s_add_u32 s6, s73, s6
	s_addc_u32 s7, s74, s7
	s_bcnt1_i32_b64 s8, s[54:55]
	v_mov_b32_e32 v0, s8
	global_atomic_add v131, v0, s[6:7]
	s_branch .LBB0_950

; #define PG8_STAGE(bufoff, gbase, voff) do { _Pragma("unroll") for (int _i = 0; _i < 2; ++_i) \
;         __builtin_amdgcn_global_load_lds((const unsigned*)((const char*)(gbase) + (voff)[_i]), (LAS unsigned*)(lds + (bufoff) + ldsw + _i * 8192), 16, 0, 0); } while (0)
; #define PG8_LDA(dst, b, h) do { _Pragma("unroll") for (int m = 0; m < 4; ++m) _Pragma("unroll") for (int k = 0; k < 2; ++k) dst[m][k] = *(const LAS bf16x8*)(lds + PG8_SA(b, h) + aoff + m * 2048 + k * 1024); } while (0)
; #define PG8_LDB(dst, b, h) do { _Pragma("unroll") for (int n = 0; n < 2; ++n) _Pragma("unroll") for (int k = 0; k < 2; ++k) dst[n][k] = *(const LAS bf16x8*)(lds + PG8_SB(b, h) + boff + n * 2048 + k * 1024); } while (0)
; #define PG8_MMA(ai, bj, At, Bt) do { __builtin_amdgcn_s_setprio(1); _Pragma("unroll") for (int m = 0; m < 4; ++m) _Pragma("unroll") for (int n = 0; n < 2; ++n) _Pragma("unroll") for (int k = 0; k < 2; ++k) \
;         acc[ai][bj][m][n] = __builtin_amdgcn_mfma_f32_16x16x32_bf16(Bt[n][k], At[m][k], acc[ai][bj][m][n], 0, 0, 0); __builtin_amdgcn_s_setprio(0); } while (0)
; #define PG8_WAIT_L(n) asm volatile("s_waitcnt lgkmcnt(" #n ")" ::: "memory")
; #define PG8_BAR __builtin_amdgcn_s_barrier()
; #define PG8_SCHED __builtin_amdgcn_sched_barrier(0)
;     ...
;             PG8_LDB(B0, 0, 0); PG8_SCHED; PG8_LDA(At, 0, 0); PG8_STAGE(PG8_SA(1, 1), a1 + hA, voffA);
;             PG8_WAIT_L(8); PG8_BAR; PG8_WAIT_L(0); PG8_MMA(0, 0, At, B0); PG8_BAR; PG8_SCHED;
;             PG8_LDB(B1, 0, 1); PG8_STAGE(PG8_SB(0, 0), b2, voffB);
;             PG8_BAR; PG8_WAIT_L(0); PG8_MMA(0, 1, At, B1); PG8_BAR;
;             PG8_LDA(At, 0, 1); PG8_STAGE(PG8_SA(0, 0), a2, voffA);
;             PG8_BAR; PG8_WAIT_L(0); PG8_MMA(1, 0, At, B0); PG8_BAR; PG8_SCHED;
.LBB0_981:
	ds_read_b128 v[150:153], v143
	ds_read_b128 v[154:157], v143 offset:1024
	ds_read_b128 v[158:161], v143 offset:2048
	ds_read_b128 v[162:165], v143 offset:3072
	s_add_u32 s40, s38, 0xfffc0080
	s_addc_u32 s41, s39, -1
	s_cmp_eq_u32 s42, 12
	s_cselect_b32 s55, s7, s41
	s_cselect_b32 s54, s8, s40
	s_cselect_b32 s41, s9, s35
	s_cselect_b32 s40, s25, s33
	v_lshl_add_u64 v[202:203], s[38:39], 0, v[138:139]
	s_add_i32 m0, s61, 0xc000
	ds_read_b128 v[170:173], v146
	ds_read_b128 v[174:177], v146 offset:1024
	ds_read_b128 v[178:181], v146 offset:2048
	ds_read_b128 v[182:185], v146 offset:3072
	ds_read_b128 v[186:189], v146 offset:4096
	ds_read_b128 v[190:193], v146 offset:5120
	ds_read_b128 v[194:197], v146 offset:6144
	ds_read_b128 v[198:201], v146 offset:7168
	global_load_lds_dwordx4 v[202:203], off
	v_lshl_add_u64 v[202:203], s[38:39], 0, v[136:137]
	s_add_i32 m0, s61, 0xe000
	s_nop 0
	global_load_lds_dwordx4 v[202:203], off
	s_waitcnt lgkmcnt(8)
	s_barrier
	s_waitcnt lgkmcnt(0)
	s_setprio 1
	s_waitcnt lgkmcnt(0)
	v_mfma_f32_16x16x32_bf16 v[124:127], v[150:153], v[170:173], v[124:127]
	v_mfma_f32_16x16x32_bf16 v[120:123], v[158:161], v[170:173], v[120:123]
	v_mfma_f32_16x16x32_bf16 v[108:111], v[150:153], v[178:181], v[108:111]
	v_mfma_f32_16x16x32_bf16 v[104:107], v[158:161], v[178:181], v[104:107]
	v_mfma_f32_16x16x32_bf16 v[92:95], v[150:153], v[186:189], v[92:95]
	v_mfma_f32_16x16x32_bf16 v[88:91], v[158:161], v[186:189], v[88:91]
	v_mfma_f32_16x16x32_bf16 v[76:79], v[150:153], v[194:197], v[76:79]
	v_mfma_f32_16x16x32_bf16 v[72:75], v[158:161], v[194:197], v[72:75]
	v_mfma_f32_16x16x32_bf16 v[124:127], v[154:157], v[174:177], v[124:127]
	v_mfma_f32_16x16x32_bf16 v[120:123], v[162:165], v[174:177], v[120:123]
	v_mfma_f32_16x16x32_bf16 v[108:111], v[154:157], v[182:185], v[108:111]
	v_mfma_f32_16x16x32_bf16 v[104:107], v[162:165], v[182:185], v[104:107]
	v_mfma_f32_16x16x32_bf16 v[92:95], v[154:157], v[190:193], v[92:95]
	v_mfma_f32_16x16x32_bf16 v[88:91], v[162:165], v[190:193], v[88:91]
	v_mfma_f32_16x16x32_bf16 v[76:79], v[154:157], v[198:201], v[76:79]
	v_mfma_f32_16x16x32_bf16 v[72:75], v[162:165], v[198:201], v[72:75]
	s_setprio 0
	s_barrier
	s_add_i32 s43, s69, s60
	v_lshl_add_u64 v[218:219], s[40:41], 0, v[130:131]
	s_mov_b32 m0, s43
	ds_read_b128 v[202:205], v147
	ds_read_b128 v[206:209], v147 offset:1024
	ds_read_b128 v[210:213], v147 offset:2048
	ds_read_b128 v[214:217], v147 offset:3072
	global_load_lds_dwordx4 v[218:219], off
	v_lshl_add_u64 v[220:221], s[40:41], 0, v[134:135]
	s_add_i32 m0, s43, 0x2000
	s_nop 0
	global_load_lds_dwordx4 v[220:221], off
	s_barrier
	s_waitcnt lgkmcnt(0)
	s_setprio 1
	s_waitcnt lgkmcnt(0)
	v_mfma_f32_16x16x32_bf16 v[116:119], v[202:205], v[170:173], v[116:119]
	v_mfma_f32_16x16x32_bf16 v[112:115], v[210:213], v[170:173], v[112:115]
	v_mfma_f32_16x16x32_bf16 v[100:103], v[202:205], v[178:181], v[100:103]
	v_mfma_f32_16x16x32_bf16 v[96:99], v[210:213], v[178:181], v[96:99]
	v_mfma_f32_16x16x32_bf16 v[84:87], v[202:205], v[186:189], v[84:87]
	v_mfma_f32_16x16x32_bf16 v[80:83], v[210:213], v[186:189], v[80:83]
	v_mfma_f32_16x16x32_bf16 v[68:71], v[202:205], v[194:197], v[68:71]
	v_mfma_f32_16x16x32_bf16 v[64:67], v[210:213], v[194:197], v[64:67]
	v_mfma_f32_16x16x32_bf16 v[116:119], v[206:209], v[174:177], v[116:119]
	v_mfma_f32_16x16x32_bf16 v[112:115], v[214:217], v[174:177], v[112:115]
	v_mfma_f32_16x16x32_bf16 v[100:103], v[206:209], v[182:185], v[100:103]
	v_mfma_f32_16x16x32_bf16 v[96:99], v[214:217], v[182:185], v[96:99]
	v_mfma_f32_16x16x32_bf16 v[84:87], v[206:209], v[190:193], v[84:87]
	v_mfma_f32_16x16x32_bf16 v[80:83], v[214:217], v[190:193], v[80:83]
	v_mfma_f32_16x16x32_bf16 v[68:71], v[206:209], v[198:201], v[68:71]
	v_mfma_f32_16x16x32_bf16 v[64:67], v[214:217], v[198:201], v[64:67]
	s_setprio 0
	s_mov_b32 m0, s61
	v_lshl_add_u64 v[222:223], s[54:55], 0, v[128:129]
	s_barrier
	ds_read_b128 v[170:173], v146 offset:16384
	ds_read_b128 v[174:177], v146 offset:17408
	ds_read_b128 v[178:181], v146 offset:18432
	ds_read_b128 v[182:185], v146 offset:19456
	ds_read_b128 v[186:189], v146 offset:20480
	ds_read_b128 v[190:193], v146 offset:21504
	ds_read_b128 v[194:197], v146 offset:22528
	ds_read_b128 v[198:201], v146 offset:23552
	global_load_lds_dwordx4 v[222:223], off
	v_lshl_add_u64 v[224:225], s[54:55], 0, v[132:133]
	s_mov_b32 m0, s62
	s_nop 0
	global_load_lds_dwordx4 v[224:225], off
	s_barrier
	s_waitcnt lgkmcnt(0)
	s_setprio 1
	s_waitcnt lgkmcnt(0)
	v_mfma_f32_16x16x32_bf16 v[60:63], v[150:153], v[170:173], v[60:63]
	v_mfma_f32_16x16x32_bf16 v[56:59], v[158:161], v[170:173], v[56:59]
	v_mfma_f32_16x16x32_bf16 v[44:47], v[150:153], v[178:181], v[44:47]
	v_mfma_f32_16x16x32_bf16 v[40:43], v[158:161], v[178:181], v[40:43]
	v_mfma_f32_16x16x32_bf16 v[28:31], v[150:153], v[186:189], v[28:31]
	v_mfma_f32_16x16x32_bf16 v[24:27], v[158:161], v[186:189], v[24:27]
	v_mfma_f32_16x16x32_bf16 v[12:15], v[150:153], v[194:197], v[12:15]
	v_mfma_f32_16x16x32_bf16 v[8:11], v[158:161], v[194:197], v[8:11]
	v_mfma_f32_16x16x32_bf16 v[60:63], v[154:157], v[174:177], v[60:63]
	v_mfma_f32_16x16x32_bf16 v[56:59], v[162:165], v[174:177], v[56:59]
	v_mfma_f32_16x16x32_bf16 v[44:47], v[154:157], v[182:185], v[44:47]
	v_mfma_f32_16x16x32_bf16 v[40:43], v[162:165], v[182:185], v[40:43]
	v_mfma_f32_16x16x32_bf16 v[28:31], v[154:157], v[190:193], v[28:31]
	v_mfma_f32_16x16x32_bf16 v[24:27], v[162:165], v[190:193], v[24:27]
	v_mfma_f32_16x16x32_bf16 v[12:15], v[154:157], v[198:201], v[12:15]
	v_mfma_f32_16x16x32_bf16 v[8:11], v[162:165], v[198:201], v[8:11]
	s_setprio 0
	s_barrier
; #define PG8_STAGE(bufoff, gbase, voff) do { _Pragma("unroll") for (int _i = 0; _i < 2; ++_i) \
;         __builtin_amdgcn_global_load_lds((const unsigned*)((const char*)(gbase) + (voff)[_i]), (LAS unsigned*)(lds + (bufoff) + ldsw + _i * 8192), 16, 0, 0); } while (0)
; #define PG8_LDA(dst, b, h) do { _Pragma("unroll") for (int m = 0; m < 4; ++m) _Pragma("unroll") for (int k = 0; k < 2; ++k) dst[m][k] = *(const LAS bf16x8*)(lds + PG8_SA(b, h) + aoff + m * 2048 + k * 1024); } while (0)
; #define PG8_LDB(dst, b, h) do { _Pragma("unroll") for (int n = 0; n < 2; ++n) _Pragma("unroll") for (int k = 0; k < 2; ++k) dst[n][k] = *(const LAS bf16x8*)(lds + PG8_SB(b, h) + boff + n * 2048 + k * 1024); } while (0)
; #define PG8_MMA(ai, bj, At, Bt) do { __builtin_amdgcn_s_setprio(1); _Pragma("unroll") for (int m = 0; m < 4; ++m) _Pragma("unroll") for (int n = 0; n < 2; ++n) _Pragma("unroll") for (int k = 0; k < 2; ++k) \
;         acc[ai][bj][m][n] = __builtin_amdgcn_mfma_f32_16x16x32_bf16(Bt[n][k], At[m][k], acc[ai][bj][m][n], 0, 0, 0); __builtin_amdgcn_s_setprio(0); } while (0)
; #define PG8_WAIT_V(n) asm volatile("s_waitcnt vmcnt(" #n ")" ::: "memory")
; #define PG8_WAIT_L(n) asm volatile("s_waitcnt lgkmcnt(" #n ")" ::: "memory")
; #define PG8_BAR __builtin_amdgcn_s_barrier()
; #define PG8_SCHED __builtin_amdgcn_sched_barrier(0)
;     ...
;             PG8_STAGE(PG8_SB(0, 1), b2 + hB, voffB);
;             PG8_WAIT_V(6); PG8_BAR; PG8_MMA(1, 1, At, B1); PG8_BAR;
;             PG8_LDB(B0, 1, 0); PG8_SCHED; PG8_LDA(At, 1, 0); PG8_STAGE(PG8_SA(0, 1), a2 + hA, voffA);
;             PG8_WAIT_L(8); PG8_BAR; PG8_WAIT_L(0); PG8_MMA(0, 0, At, B0); PG8_BAR; PG8_SCHED;
;             PG8_LDB(B1, 1, 1); PG8_STAGE(PG8_SB(1, 0), b3, voffB);
;             PG8_BAR; PG8_WAIT_L(0); PG8_MMA(0, 1, At, B1); PG8_BAR;
;             PG8_LDA(At, 1, 1); PG8_STAGE(PG8_SA(1, 0), a3, voffA);
	s_add_u32 s44, s40, 0x40000
	s_addc_u32 s45, s41, 0
	s_add_i32 s43, s70, s60
	v_lshl_add_u64 v[150:151], s[44:45], 0, v[130:131]
	s_mov_b32 m0, s43
	s_nop 0
	global_load_lds_dwordx4 v[150:151], off
	v_lshl_add_u64 v[150:151], s[44:45], 0, v[134:135]
	s_add_i32 m0, s43, 0x2000
	s_nop 0
	global_load_lds_dwordx4 v[150:151], off
	s_waitcnt vmcnt(6)
	s_barrier
	s_setprio 1
	v_mfma_f32_16x16x32_bf16 v[52:55], v[202:205], v[170:173], v[52:55]
	v_mfma_f32_16x16x32_bf16 v[48:51], v[210:213], v[170:173], v[48:51]
	v_mfma_f32_16x16x32_bf16 v[36:39], v[202:205], v[178:181], v[36:39]
	v_mfma_f32_16x16x32_bf16 v[32:35], v[210:213], v[178:181], v[32:35]
	v_mfma_f32_16x16x32_bf16 v[20:23], v[202:205], v[186:189], v[20:23]
	v_mfma_f32_16x16x32_bf16 v[16:19], v[210:213], v[186:189], v[16:19]
	v_mfma_f32_16x16x32_bf16 v[4:7], v[202:205], v[194:197], v[4:7]
	v_mfma_f32_16x16x32_bf16 v[0:3], v[210:213], v[194:197], v[0:3]
	v_mfma_f32_16x16x32_bf16 v[52:55], v[206:209], v[174:177], v[52:55]
	v_mfma_f32_16x16x32_bf16 v[48:51], v[214:217], v[174:177], v[48:51]
	v_mfma_f32_16x16x32_bf16 v[36:39], v[206:209], v[182:185], v[36:39]
	v_mfma_f32_16x16x32_bf16 v[32:35], v[214:217], v[182:185], v[32:35]
	v_mfma_f32_16x16x32_bf16 v[20:23], v[206:209], v[190:193], v[20:23]
	v_mfma_f32_16x16x32_bf16 v[16:19], v[214:217], v[190:193], v[16:19]
	v_mfma_f32_16x16x32_bf16 v[4:7], v[206:209], v[198:201], v[4:7]
	v_mfma_f32_16x16x32_bf16 v[0:3], v[214:217], v[198:201], v[0:3]
	s_setprio 0
	s_add_i32 s43, 0, 0x18000
	v_add_u32_e32 v149, s43, v141
	s_barrier
	ds_read_b128 v[150:153], v149
	ds_read_b128 v[154:157], v149 offset:1024
	ds_read_b128 v[158:161], v149 offset:2048
	ds_read_b128 v[162:165], v149 offset:3072
	s_add_u32 s44, s54, 0x40000
	s_addc_u32 s45, s55, 0
	s_mov_b32 m0, s63
	v_lshl_add_u64 v[202:203], s[44:45], 0, v[128:129]
	ds_read_b128 v[170:173], v146 offset:32768
	ds_read_b128 v[174:177], v146 offset:33792
	ds_read_b128 v[178:181], v146 offset:34816
	ds_read_b128 v[182:185], v146 offset:35840
	ds_read_b128 v[186:189], v146 offset:36864
	ds_read_b128 v[190:193], v146 offset:37888
	ds_read_b128 v[194:197], v146 offset:38912
	ds_read_b128 v[198:201], v146 offset:39936
	global_load_lds_dwordx4 v[202:203], off
	v_lshl_add_u64 v[202:203], s[44:45], 0, v[132:133]
	s_mov_b32 m0, s64
	s_nop 0
	global_load_lds_dwordx4 v[202:203], off
	s_waitcnt lgkmcnt(8)
	s_barrier
	s_waitcnt lgkmcnt(0)
	s_setprio 1
	s_waitcnt lgkmcnt(0)
	v_mfma_f32_16x16x32_bf16 v[124:127], v[150:153], v[170:173], v[124:127]
	v_mfma_f32_16x16x32_bf16 v[120:123], v[158:161], v[170:173], v[120:123]
	v_mfma_f32_16x16x32_bf16 v[108:111], v[150:153], v[178:181], v[108:111]
	v_mfma_f32_16x16x32_bf16 v[104:107], v[158:161], v[178:181], v[104:107]
	v_mfma_f32_16x16x32_bf16 v[92:95], v[150:153], v[186:189], v[92:95]
	v_mfma_f32_16x16x32_bf16 v[88:91], v[158:161], v[186:189], v[88:91]
	v_mfma_f32_16x16x32_bf16 v[76:79], v[150:153], v[194:197], v[76:79]
	v_mfma_f32_16x16x32_bf16 v[72:75], v[158:161], v[194:197], v[72:75]
	v_mfma_f32_16x16x32_bf16 v[124:127], v[154:157], v[174:177], v[124:127]
	v_mfma_f32_16x16x32_bf16 v[120:123], v[162:165], v[174:177], v[120:123]
	v_mfma_f32_16x16x32_bf16 v[108:111], v[154:157], v[182:185], v[108:111]
	v_mfma_f32_16x16x32_bf16 v[104:107], v[162:165], v[182:185], v[104:107]
	v_mfma_f32_16x16x32_bf16 v[92:95], v[154:157], v[190:193], v[92:95]
	v_mfma_f32_16x16x32_bf16 v[88:91], v[162:165], v[190:193], v[88:91]
	v_mfma_f32_16x16x32_bf16 v[76:79], v[154:157], v[198:201], v[76:79]
	v_mfma_f32_16x16x32_bf16 v[72:75], v[162:165], v[198:201], v[72:75]
	s_setprio 0
	s_barrier
	s_add_i32 s44, 0, 0x1c000
	s_add_i32 s43, s43, s60
	v_add_u32_e32 v149, s44, v141
	v_lshl_add_u64 v[218:219], v[218:219], 0, s[26:27]
	s_mov_b32 m0, s43
	ds_read_b128 v[202:205], v149
	ds_read_b128 v[206:209], v149 offset:1024
	ds_read_b128 v[210:213], v149 offset:2048
	ds_read_b128 v[214:217], v149 offset:3072
	global_load_lds_dwordx4 v[218:219], off
	v_lshl_add_u64 v[218:219], v[220:221], 0, s[26:27]
	s_add_i32 m0, s43, 0x2000
	s_nop 0
	global_load_lds_dwordx4 v[218:219], off
	s_barrier
	s_waitcnt lgkmcnt(0)
	s_setprio 1
	s_waitcnt lgkmcnt(0)
	v_mfma_f32_16x16x32_bf16 v[116:119], v[202:205], v[170:173], v[116:119]
	v_mfma_f32_16x16x32_bf16 v[112:115], v[210:213], v[170:173], v[112:115]
	v_mfma_f32_16x16x32_bf16 v[100:103], v[202:205], v[178:181], v[100:103]
	v_mfma_f32_16x16x32_bf16 v[96:99], v[210:213], v[178:181], v[96:99]
	v_mfma_f32_16x16x32_bf16 v[84:87], v[202:205], v[186:189], v[84:87]
	v_mfma_f32_16x16x32_bf16 v[80:83], v[210:213], v[186:189], v[80:83]
	v_mfma_f32_16x16x32_bf16 v[68:71], v[202:205], v[194:197], v[68:71]
	v_mfma_f32_16x16x32_bf16 v[64:67], v[210:213], v[194:197], v[64:67]
	v_mfma_f32_16x16x32_bf16 v[116:119], v[206:209], v[174:177], v[116:119]
	v_mfma_f32_16x16x32_bf16 v[112:115], v[214:217], v[174:177], v[112:115]
	v_mfma_f32_16x16x32_bf16 v[100:103], v[206:209], v[182:185], v[100:103]
	v_mfma_f32_16x16x32_bf16 v[96:99], v[214:217], v[182:185], v[96:99]
	v_mfma_f32_16x16x32_bf16 v[84:87], v[206:209], v[190:193], v[84:87]
	v_mfma_f32_16x16x32_bf16 v[80:83], v[214:217], v[190:193], v[80:83]
	v_mfma_f32_16x16x32_bf16 v[68:71], v[206:209], v[198:201], v[68:71]
	v_mfma_f32_16x16x32_bf16 v[64:67], v[214:217], v[198:201], v[64:67]
	s_setprio 0
	s_mov_b32 m0, s66
	v_lshl_add_u64 v[218:219], v[222:223], 0, s[26:27]
	s_barrier
	ds_read_b128 v[170:173], v146 offset:49152
	ds_read_b128 v[174:177], v146 offset:50176
	ds_read_b128 v[178:181], v146 offset:51200
	ds_read_b128 v[182:185], v146 offset:52224
	ds_read_b128 v[186:189], v146 offset:53248
	ds_read_b128 v[190:193], v146 offset:54272
	ds_read_b128 v[194:197], v146 offset:55296
	ds_read_b128 v[198:201], v146 offset:56320
	global_load_lds_dwordx4 v[218:219], off
	v_lshl_add_u64 v[218:219], v[224:225], 0, s[26:27]
	s_mov_b32 m0, s67
	s_nop 0
	global_load_lds_dwordx4 v[218:219], off
	s_barrier
; #define PG8_STAGE(bufoff, gbase, voff) do { _Pragma("unroll") for (int _i = 0; _i < 2; ++_i) \
;         __builtin_amdgcn_global_load_lds((const unsigned*)((const char*)(gbase) + (voff)[_i]), (LAS unsigned*)(lds + (bufoff) + ldsw + _i * 8192), 16, 0, 0); } while (0)
; #define PG8_MMA(ai, bj, At, Bt) do { __builtin_amdgcn_s_setprio(1); _Pragma("unroll") for (int m = 0; m < 4; ++m) _Pragma("unroll") for (int n = 0; n < 2; ++n) _Pragma("unroll") for (int k = 0; k < 2; ++k) \
;         acc[ai][bj][m][n] = __builtin_amdgcn_mfma_f32_16x16x32_bf16(Bt[n][k], At[m][k], acc[ai][bj][m][n], 0, 0, 0); __builtin_amdgcn_s_setprio(0); } while (0)
; #define PG8_WAIT_V(n) asm volatile("s_waitcnt vmcnt(" #n ")" ::: "memory")
; #define PG8_WAIT_L(n) asm volatile("s_waitcnt lgkmcnt(" #n ")" ::: "memory")
; #define PG8_BAR __builtin_amdgcn_s_barrier()
; #define PG8_SCHED __builtin_amdgcn_sched_barrier(0)
;     ...
;             PG8_BAR; PG8_WAIT_L(0); PG8_MMA(1, 0, At, B0); PG8_BAR; PG8_SCHED;
;             PG8_STAGE(PG8_SB(1, 1), b3 + hB, voffB);
;             PG8_WAIT_V(6); PG8_BAR; PG8_MMA(1, 1, At, B1); PG8_BAR;
;         }
; __device__ __forceinline__ float row_rstd(const float* ssq, int row) {
;     const f32x4* p = (const f32x4*)(ssq + (size_t)row * 16);
;     const f32x4 a = p[0], b = p[1], c = p[2], d = p[3];
;     const float s = ((a[0] + a[1]) + (a[2] + a[3])) + ((b[0] + b[1]) + (b[2] + b[3])) + ((c[0] + c[1]) + (c[2] + c[3])) + ((d[0] + d[1]) + (d[2] + d[3]));
;     return rsqrtf(s * (1.0f / 1024.0f) + 1e-6f);
; }
	s_waitcnt lgkmcnt(0)
	s_setprio 1
	s_waitcnt lgkmcnt(0)
	v_mfma_f32_16x16x32_bf16 v[60:63], v[150:153], v[170:173], v[60:63]
	v_mfma_f32_16x16x32_bf16 v[56:59], v[158:161], v[170:173], v[56:59]
	v_mfma_f32_16x16x32_bf16 v[44:47], v[150:153], v[178:181], v[44:47]
	v_mfma_f32_16x16x32_bf16 v[40:43], v[158:161], v[178:181], v[40:43]
	v_mfma_f32_16x16x32_bf16 v[28:31], v[150:153], v[186:189], v[28:31]
	v_mfma_f32_16x16x32_bf16 v[24:27], v[158:161], v[186:189], v[24:27]
	v_mfma_f32_16x16x32_bf16 v[12:15], v[150:153], v[194:197], v[12:15]
	v_mfma_f32_16x16x32_bf16 v[8:11], v[158:161], v[194:197], v[8:11]
	v_mfma_f32_16x16x32_bf16 v[60:63], v[154:157], v[174:177], v[60:63]
	v_mfma_f32_16x16x32_bf16 v[56:59], v[162:165], v[174:177], v[56:59]
	v_mfma_f32_16x16x32_bf16 v[44:47], v[154:157], v[182:185], v[44:47]
	v_mfma_f32_16x16x32_bf16 v[40:43], v[162:165], v[182:185], v[40:43]
	v_mfma_f32_16x16x32_bf16 v[28:31], v[154:157], v[190:193], v[28:31]
	v_mfma_f32_16x16x32_bf16 v[24:27], v[162:165], v[190:193], v[24:27]
	v_mfma_f32_16x16x32_bf16 v[12:15], v[154:157], v[198:201], v[12:15]
	v_mfma_f32_16x16x32_bf16 v[8:11], v[162:165], v[198:201], v[8:11]
	s_setprio 0
	s_barrier
	s_add_u32 s40, s40, 0x40080
	s_addc_u32 s41, s41, 0
	s_add_i32 s43, s44, s60
	v_lshl_add_u64 v[150:151], s[40:41], 0, v[130:131]
	s_mov_b32 m0, s43
	s_nop 0
	global_load_lds_dwordx4 v[150:151], off
	v_lshl_add_u64 v[150:151], s[40:41], 0, v[134:135]
	s_add_i32 m0, s43, 0x2000
	s_nop 0
	global_load_lds_dwordx4 v[150:151], off
	s_waitcnt vmcnt(6)
	s_barrier
	s_setprio 1
	v_mfma_f32_16x16x32_bf16 v[52:55], v[202:205], v[170:173], v[52:55]
	v_mfma_f32_16x16x32_bf16 v[48:51], v[210:213], v[170:173], v[48:51]
	v_mfma_f32_16x16x32_bf16 v[36:39], v[202:205], v[178:181], v[36:39]
	v_mfma_f32_16x16x32_bf16 v[32:35], v[210:213], v[178:181], v[32:35]
	v_mfma_f32_16x16x32_bf16 v[20:23], v[202:205], v[186:189], v[20:23]
	v_mfma_f32_16x16x32_bf16 v[16:19], v[210:213], v[186:189], v[16:19]
	v_mfma_f32_16x16x32_bf16 v[4:7], v[202:205], v[194:197], v[4:7]
	v_mfma_f32_16x16x32_bf16 v[0:3], v[210:213], v[194:197], v[0:3]
	v_mfma_f32_16x16x32_bf16 v[52:55], v[206:209], v[174:177], v[52:55]
	v_mfma_f32_16x16x32_bf16 v[48:51], v[214:217], v[174:177], v[48:51]
	v_mfma_f32_16x16x32_bf16 v[36:39], v[206:209], v[182:185], v[36:39]
	v_mfma_f32_16x16x32_bf16 v[32:35], v[214:217], v[182:185], v[32:35]
	v_mfma_f32_16x16x32_bf16 v[20:23], v[206:209], v[190:193], v[20:23]
	v_mfma_f32_16x16x32_bf16 v[16:19], v[214:217], v[190:193], v[16:19]
	v_mfma_f32_16x16x32_bf16 v[4:7], v[206:209], v[198:201], v[4:7]
	v_mfma_f32_16x16x32_bf16 v[0:3], v[214:217], v[198:201], v[0:3]
	s_setprio 0
	s_add_i32 s42, s42, 2
	s_add_u32 s33, s33, 0x100
	s_addc_u32 s35, s35, 0
	s_add_u32 s38, s38, 0x100
	s_addc_u32 s39, s39, 0
	s_cmp_gt_u32 s42, 13
	s_barrier
	s_cbranch_scc0 .LBB0_981
	v_lshl_add_u32 v150, s75, 8, v140
	v_add_u32_e32 v164, 0x4000, v150
	v_ashrrev_i32_e32 v165, 31, v164
	v_lshlrev_b64 v[152:153], 6, v[164:165]
	v_lshl_add_u64 v[170:171], s[18:19], 0, v[152:153]
	v_subrev_u32_e32 v176, s18, v170
	v_add_u32_e32 v177, 0x0, v176
	global_load_dwordx4 v[178:181], v177, s[18:19]
	v_add_u32_e32 v177, 0x10, v176
	global_load_dwordx4 v[182:185], v177, s[18:19]
	v_add_u32_e32 v177, 0x20, v176
	global_load_dwordx4 v[186:189], v177, s[18:19]
	v_add_u32_e32 v177, 0x30, v176
	global_load_dwordx4 v[190:193], v177, s[18:19]
	v_add_u32_e32 v177, 0x400, v176
	global_load_dwordx4 v[194:197], v177, s[18:19]
	v_add_u32_e32 v177, 0x410, v176
	global_load_dwordx4 v[198:201], v177, s[18:19]
	v_add_u32_e32 v177, 0x420, v176
	global_load_dwordx4 v[202:205], v177, s[18:19]
	v_add_u32_e32 v177, 0x430, v176
	global_load_dwordx4 v[206:209], v177, s[18:19]
	v_add_u32_e32 v177, 0x800, v176
	global_load_dwordx4 v[210:213], v177, s[18:19]
	v_add_u32_e32 v177, 0x810, v176
	global_load_dwordx4 v[214:217], v177, s[18:19]
	v_add_u32_e32 v177, 0x820, v176
	global_load_dwordx4 v[232:235], v177, s[18:19]
	v_add_u32_e32 v177, 0x830, v176
	global_load_dwordx4 v[236:239], v177, s[18:19]
	v_add_u32_e32 v177, 0xc00, v176
	global_load_dwordx4 v[240:243], v177, s[18:19]
	v_add_u32_e32 v177, 0xc10, v176
	global_load_dwordx4 v[244:247], v177, s[18:19]
	v_add_u32_e32 v177, 0xc20, v176
	global_load_dwordx4 v[248:251], v177, s[18:19]
	v_add_u32_e32 v177, 0xc30, v176
	global_load_dwordx4 v[252:255], v177, s[18:19]
	s_nop 0
	v_lshl_or_b32 v149, s6, 9, v142
	v_lshl_add_u32 v151, v164, 13, v149
	v_add_u32_e32 v174, 0x4010, v150
	v_ashrrev_i32_e32 v175, 31, v174
	s_waitcnt vmcnt(12)
; __device__ __forceinline__ u32x4 pack8(const f32x4 v0, const f32x4 v1) { u32x4 w; w.x = pk2(v0[0], v0[1]); w.y = pk2(v0[2], v0[3]); w.z = pk2(v1[0], v1[1]); w.w = pk2(v1[2], v1[3]); return w; }
; __device__ __forceinline__ float row_rstd(const float* ssq, int row) {
;     const f32x4* p = (const f32x4*)(ssq + (size_t)row * 16);
;     const f32x4 a = p[0], b = p[1], c = p[2], d = p[3];
;     const float s = ((a[0] + a[1]) + (a[2] + a[3])) + ((b[0] + b[1]) + (b[2] + b[3])) + ((c[0] + c[1]) + (c[2] + c[3])) + ((d[0] + d[1]) + (d[2] + d[3]));
;     return rsqrtf(s * (1.0f / 1024.0f) + 1e-6f);
;     __device__ __forceinline__ void operator()(const f32x4 (&acc)[2][2][4][2], const Unit& u, int wr, int wc, int fr, int fq) const {
;         const __amdgpu_buffer_rsrc_t rsrc = __builtin_amdgcn_make_buffer_rsrc((void*)O, 0, T_ALL * DFF * 2, 0x00020000);
;         const int row0 = row_off + u.pm * 256 + wr * 64 + fr, col0 = u.pn * 256 + wc * 32 + 8 * fq;
; #pragma unroll
;         for (int ai = 0; ai < 2; ++ai)
; #pragma unroll
;             for (int m = 0; m < 4; ++m) {
;                 const int row = row0 + ai * 128 + m * 16; const float rs = row_rstd(ssq, row);
; #pragma unroll
;                 for (int bj = 0; bj < 2; ++bj) { f32x4 v0 = acc[ai][bj][m][0] * rs, v1 = acc[ai][bj][m][1] * rs;
; #pragma unroll
;                     for (int j = 0; j < 4; ++j) { const float a = fmaxf(v0[j], 0.f), b = fmaxf(v1[j], 0.f); v0[j] = a * a; v1[j] = b * b; }
;                     __builtin_amdgcn_raw_buffer_store_b128(pack8(v0, v1), rsrc, (unsigned)(((size_t)row * DFF + col0 + bj * 128) * 2), 0, 16  ); }
	v_pk_add_f32 v[152:153], v[178:179], v[180:181]
	v_pk_add_f32 v[154:155], v[182:183], v[184:185]
	v_pk_add_f32 v[156:157], v[186:187], v[188:189]
	v_pk_add_f32 v[158:159], v[190:191], v[192:193]
	v_pk_add_f32 v[152:153], v[152:153], v[154:155]
	v_pk_add_f32 v[156:157], v[156:157], v[158:159]
	v_pk_add_f32 v[152:153], v[152:153], v[156:157]
	v_add_f32_e32 v152, v152, v153
	s_nop 0
	s_nop 0
	v_fmamk_f32 v152, v152, 0x3a800000, v148
	s_nop 0
	s_nop 0
	s_nop 1
	s_nop 0
	v_rsq_f32_e32 v154, v152
	s_nop 0
	s_nop 0
	s_nop 0
	s_nop 0
	v_pk_mul_f32 v[126:127], v[126:127], v[154:155] op_sel_hi:[1,0]
	v_pk_mul_f32 v[124:125], v[124:125], v[154:155] op_sel_hi:[1,0]
	v_pk_mul_f32 v[122:123], v[122:123], v[154:155] op_sel_hi:[1,0]
	v_pk_mul_f32 v[120:121], v[120:121], v[154:155] op_sel_hi:[1,0]
	v_pk_mul_f32 v[114:115], v[114:115], v[154:155] op_sel_hi:[1,0]
	v_pk_mul_f32 v[112:113], v[112:113], v[154:155] op_sel_hi:[1,0]
	v_pk_mul_f32 v[118:119], v[118:119], v[154:155] op_sel_hi:[1,0]
	v_pk_mul_f32 v[116:117], v[116:117], v[154:155] op_sel_hi:[1,0]
	v_max_f32_e32 v124, 0, v124
	v_max_f32_e32 v120, 0, v120
	v_max_f32_e32 v125, 0, v125
	v_max_f32_e32 v121, 0, v121
	v_max_f32_e32 v126, 0, v126
	v_max_f32_e32 v122, 0, v122
	v_max_f32_e32 v127, 0, v127
	v_max_f32_e32 v123, 0, v123
	v_max_f32_e32 v112, 0, v112
	v_max_f32_e32 v113, 0, v113
	v_max_f32_e32 v114, 0, v114
	v_max_f32_e32 v115, 0, v115
	v_max_f32_e32 v116, 0, v116
	v_max_f32_e32 v117, 0, v117
	v_max_f32_e32 v118, 0, v118
	v_max_f32_e32 v119, 0, v119
	v_pk_mul_f32 v[124:125], v[124:125], v[124:125]
	v_pk_mul_f32 v[120:121], v[120:121], v[120:121]
	v_pk_mul_f32 v[126:127], v[126:127], v[126:127]
	v_pk_mul_f32 v[122:123], v[122:123], v[122:123]
	v_pk_mul_f32 v[154:155], v[112:113], v[112:113]
	v_pk_mul_f32 v[156:157], v[114:115], v[114:115]
	v_cvt_pk_bf16_f32 v112, v124, v125
	v_cvt_pk_bf16_f32 v113, v126, v127
	v_cvt_pk_bf16_f32 v114, v120, v121
	v_cvt_pk_bf16_f32 v115, v122, v123
	v_pk_mul_f32 v[116:117], v[116:117], v[116:117]
	v_pk_mul_f32 v[118:119], v[118:119], v[118:119]
	buffer_store_dwordx4 v[112:115], v151, s[12:15], 0 offen sc1
	s_nop 1
	v_cvt_pk_bf16_f32 v112, v116, v117
	v_cvt_pk_bf16_f32 v113, v118, v119
	v_cvt_pk_bf16_f32 v114, v154, v155
	v_cvt_pk_bf16_f32 v115, v156, v157
	buffer_store_dwordx4 v[112:115], v151, s[12:15], 0 offen offset:256 sc1
	s_nop 0
	v_add_u32_e32 v152, 0x4020, v150
	v_ashrrev_i32_e32 v153, 31, v152
	v_lshl_add_u32 v151, v174, 13, v149
	v_add_u32_e32 v177, 0x2000, v176
	global_load_dwordx4 v[178:181], v177, s[18:19]
	v_add_u32_e32 v177, 0x2010, v176
	global_load_dwordx4 v[182:185], v177, s[18:19]
	v_add_u32_e32 v177, 0x2020, v176
	global_load_dwordx4 v[186:189], v177, s[18:19]
	v_add_u32_e32 v177, 0x2030, v176
	global_load_dwordx4 v[190:193], v177, s[18:19]
	s_waitcnt vmcnt(14)
	v_pk_add_f32 v[112:113], v[194:195], v[196:197]
	v_pk_add_f32 v[114:115], v[198:199], v[200:201]
	v_pk_add_f32 v[116:117], v[202:203], v[204:205]
	v_pk_add_f32 v[118:119], v[206:207], v[208:209]
	v_pk_add_f32 v[112:113], v[112:113], v[114:115]
	v_pk_add_f32 v[116:117], v[116:117], v[118:119]
	v_pk_add_f32 v[112:113], v[112:113], v[116:117]
	v_add_f32_e32 v112, v112, v113
	s_nop 0
	s_nop 0
	v_fmamk_f32 v112, v112, 0x3a800000, v148
	s_nop 0
	s_nop 0
	s_nop 1
	s_nop 0
	v_rsq_f32_e32 v114, v112
	s_nop 0
	s_nop 0
	s_nop 0
	s_nop 0
	v_pk_mul_f32 v[110:111], v[110:111], v[114:115] op_sel_hi:[1,0]
	v_pk_mul_f32 v[108:109], v[108:109], v[114:115] op_sel_hi:[1,0]
	v_pk_mul_f32 v[106:107], v[106:107], v[114:115] op_sel_hi:[1,0]
	v_pk_mul_f32 v[104:105], v[104:105], v[114:115] op_sel_hi:[1,0]
	v_pk_mul_f32 v[98:99], v[98:99], v[114:115] op_sel_hi:[1,0]
	v_pk_mul_f32 v[96:97], v[96:97], v[114:115] op_sel_hi:[1,0]
	v_pk_mul_f32 v[102:103], v[102:103], v[114:115] op_sel_hi:[1,0]
	v_pk_mul_f32 v[100:101], v[100:101], v[114:115] op_sel_hi:[1,0]
	v_max_f32_e32 v108, 0, v108
	v_max_f32_e32 v104, 0, v104
	v_max_f32_e32 v109, 0, v109
	v_max_f32_e32 v105, 0, v105
	v_max_f32_e32 v110, 0, v110
	v_max_f32_e32 v106, 0, v106
	v_max_f32_e32 v111, 0, v111
	v_max_f32_e32 v107, 0, v107
	v_max_f32_e32 v96, 0, v96
	v_max_f32_e32 v97, 0, v97
	v_max_f32_e32 v98, 0, v98
	v_max_f32_e32 v99, 0, v99
	v_max_f32_e32 v100, 0, v100
	v_max_f32_e32 v101, 0, v101
	v_max_f32_e32 v102, 0, v102
	v_max_f32_e32 v103, 0, v103
	v_pk_mul_f32 v[108:109], v[108:109], v[108:109]
	v_pk_mul_f32 v[104:105], v[104:105], v[104:105]
	v_pk_mul_f32 v[110:111], v[110:111], v[110:111]
	v_pk_mul_f32 v[106:107], v[106:107], v[106:107]
	v_pk_mul_f32 v[114:115], v[96:97], v[96:97]
	v_pk_mul_f32 v[116:117], v[98:99], v[98:99]
	v_cvt_pk_bf16_f32 v96, v108, v109
	v_cvt_pk_bf16_f32 v97, v110, v111
	v_cvt_pk_bf16_f32 v98, v104, v105
	v_cvt_pk_bf16_f32 v99, v106, v107
	v_pk_mul_f32 v[100:101], v[100:101], v[100:101]
	v_pk_mul_f32 v[102:103], v[102:103], v[102:103]
	buffer_store_dwordx4 v[96:99], v151, s[12:15], 0 offen sc1
	s_nop 1
	v_cvt_pk_bf16_f32 v96, v100, v101
	v_cvt_pk_bf16_f32 v97, v102, v103
	v_cvt_pk_bf16_f32 v98, v114, v115
	v_cvt_pk_bf16_f32 v99, v116, v117
	buffer_store_dwordx4 v[96:99], v151, s[12:15], 0 offen offset:256 sc1
	s_nop 0
	v_add_u32_e32 v112, 0x4030, v150
	v_ashrrev_i32_e32 v113, 31, v112
	v_lshl_add_u32 v116, v152, 13, v149
	v_add_u32_e32 v177, 0x2400, v176
	global_load_dwordx4 v[194:197], v177, s[18:19]
	v_add_u32_e32 v177, 0x2410, v176
	global_load_dwordx4 v[198:201], v177, s[18:19]
	v_add_u32_e32 v177, 0x2420, v176
	global_load_dwordx4 v[202:205], v177, s[18:19]
	v_add_u32_e32 v177, 0x2430, v176
	global_load_dwordx4 v[206:209], v177, s[18:19]
	s_waitcnt vmcnt(16)
; __device__ __forceinline__ u32x4 pack8(const f32x4 v0, const f32x4 v1) { u32x4 w; w.x = pk2(v0[0], v0[1]); w.y = pk2(v0[2], v0[3]); w.z = pk2(v1[0], v1[1]); w.w = pk2(v1[2], v1[3]); return w; }
; __device__ __forceinline__ float row_rstd(const float* ssq, int row) {
;     const f32x4* p = (const f32x4*)(ssq + (size_t)row * 16);
;     const f32x4 a = p[0], b = p[1], c = p[2], d = p[3];
;     const float s = ((a[0] + a[1]) + (a[2] + a[3])) + ((b[0] + b[1]) + (b[2] + b[3])) + ((c[0] + c[1]) + (c[2] + c[3])) + ((d[0] + d[1]) + (d[2] + d[3]));
;     return rsqrtf(s * (1.0f / 1024.0f) + 1e-6f);
;     __device__ __forceinline__ void operator()(const f32x4 (&acc)[2][2][4][2], const Unit& u, int wr, int wc, int fr, int fq) const {
;         const __amdgpu_buffer_rsrc_t rsrc = __builtin_amdgcn_make_buffer_rsrc((void*)O, 0, T_ALL * DFF * 2, 0x00020000);
;         const int row0 = row_off + u.pm * 256 + wr * 64 + fr, col0 = u.pn * 256 + wc * 32 + 8 * fq;
; #pragma unroll
;         for (int ai = 0; ai < 2; ++ai)
; #pragma unroll
;             for (int m = 0; m < 4; ++m) {
;                 const int row = row0 + ai * 128 + m * 16; const float rs = row_rstd(ssq, row);
; #pragma unroll
;                 for (int bj = 0; bj < 2; ++bj) { f32x4 v0 = acc[ai][bj][m][0] * rs, v1 = acc[ai][bj][m][1] * rs;
; #pragma unroll
;                     for (int j = 0; j < 4; ++j) { const float a = fmaxf(v0[j], 0.f), b = fmaxf(v1[j], 0.f); v0[j] = a * a; v1[j] = b * b; }
;                     __builtin_amdgcn_raw_buffer_store_b128(pack8(v0, v1), rsrc, (unsigned)(((size_t)row * DFF + col0 + bj * 128) * 2), 0, 16  ); }
	v_pk_add_f32 v[96:97], v[210:211], v[212:213]
	v_pk_add_f32 v[98:99], v[214:215], v[216:217]
	v_pk_add_f32 v[100:101], v[232:233], v[234:235]
	v_pk_add_f32 v[102:103], v[236:237], v[238:239]
	v_pk_add_f32 v[96:97], v[96:97], v[98:99]
	v_pk_add_f32 v[100:101], v[100:101], v[102:103]
	v_pk_add_f32 v[96:97], v[96:97], v[100:101]
	v_add_f32_e32 v96, v96, v97
	s_nop 0
	s_nop 0
	v_fmamk_f32 v96, v96, 0x3a800000, v148
	s_nop 0
	s_nop 0
	s_nop 1
	s_nop 0
	v_rsq_f32_e32 v98, v96
	s_nop 0
	s_nop 0
	s_nop 0
	s_nop 0
	v_pk_mul_f32 v[94:95], v[94:95], v[98:99] op_sel_hi:[1,0]
	v_pk_mul_f32 v[92:93], v[92:93], v[98:99] op_sel_hi:[1,0]
	v_pk_mul_f32 v[90:91], v[90:91], v[98:99] op_sel_hi:[1,0]
	v_pk_mul_f32 v[88:89], v[88:89], v[98:99] op_sel_hi:[1,0]
	v_pk_mul_f32 v[82:83], v[82:83], v[98:99] op_sel_hi:[1,0]
	v_pk_mul_f32 v[80:81], v[80:81], v[98:99] op_sel_hi:[1,0]
	v_pk_mul_f32 v[86:87], v[86:87], v[98:99] op_sel_hi:[1,0]
	v_pk_mul_f32 v[84:85], v[84:85], v[98:99] op_sel_hi:[1,0]
	v_max_f32_e32 v92, 0, v92
	v_max_f32_e32 v88, 0, v88
	v_max_f32_e32 v93, 0, v93
	v_max_f32_e32 v89, 0, v89
	v_max_f32_e32 v94, 0, v94
	v_max_f32_e32 v90, 0, v90
	v_max_f32_e32 v95, 0, v95
	v_max_f32_e32 v91, 0, v91
	v_max_f32_e32 v80, 0, v80
	v_max_f32_e32 v81, 0, v81
	v_max_f32_e32 v82, 0, v82
	v_max_f32_e32 v83, 0, v83
	v_max_f32_e32 v84, 0, v84
	v_max_f32_e32 v85, 0, v85
	v_max_f32_e32 v86, 0, v86
	v_max_f32_e32 v87, 0, v87
	v_pk_mul_f32 v[92:93], v[92:93], v[92:93]
	v_pk_mul_f32 v[88:89], v[88:89], v[88:89]
	v_pk_mul_f32 v[94:95], v[94:95], v[94:95]
	v_pk_mul_f32 v[90:91], v[90:91], v[90:91]
	v_pk_mul_f32 v[98:99], v[80:81], v[80:81]
	v_pk_mul_f32 v[100:101], v[82:83], v[82:83]
	v_cvt_pk_bf16_f32 v80, v92, v93
	v_cvt_pk_bf16_f32 v81, v94, v95
	v_cvt_pk_bf16_f32 v82, v88, v89
	v_cvt_pk_bf16_f32 v83, v90, v91
	v_pk_mul_f32 v[84:85], v[84:85], v[84:85]
	v_pk_mul_f32 v[86:87], v[86:87], v[86:87]
	buffer_store_dwordx4 v[80:83], v116, s[12:15], 0 offen sc1
	s_nop 1
	v_cvt_pk_bf16_f32 v80, v84, v85
	v_cvt_pk_bf16_f32 v81, v86, v87
	v_cvt_pk_bf16_f32 v82, v98, v99
	v_cvt_pk_bf16_f32 v83, v100, v101
	buffer_store_dwordx4 v[80:83], v116, s[12:15], 0 offen offset:256 sc1
	s_nop 0
	v_add_u32_e32 v96, 0x4080, v150
	v_ashrrev_i32_e32 v97, 31, v96
	v_lshl_add_u32 v100, v112, 13, v149
	v_add_u32_e32 v177, 0x2800, v176
	global_load_dwordx4 v[210:213], v177, s[18:19]
	v_add_u32_e32 v177, 0x2810, v176
	global_load_dwordx4 v[214:217], v177, s[18:19]
	v_add_u32_e32 v177, 0x2820, v176
	global_load_dwordx4 v[232:235], v177, s[18:19]
	v_add_u32_e32 v177, 0x2830, v176
	global_load_dwordx4 v[236:239], v177, s[18:19]
	s_waitcnt vmcnt(18)
	v_pk_add_f32 v[80:81], v[240:241], v[242:243]
	v_pk_add_f32 v[82:83], v[244:245], v[246:247]
	v_pk_add_f32 v[84:85], v[248:249], v[250:251]
	v_pk_add_f32 v[86:87], v[252:253], v[254:255]
	v_pk_add_f32 v[80:81], v[80:81], v[82:83]
	v_pk_add_f32 v[84:85], v[84:85], v[86:87]
	v_pk_add_f32 v[80:81], v[80:81], v[84:85]
	v_add_f32_e32 v80, v80, v81
	s_nop 0
	s_nop 0
	v_fmamk_f32 v80, v80, 0x3a800000, v148
	s_nop 0
	s_nop 0
	s_nop 1
	s_nop 0
	v_rsq_f32_e32 v82, v80
	s_nop 0
	s_nop 0
	s_nop 0
	s_nop 0
	v_pk_mul_f32 v[78:79], v[78:79], v[82:83] op_sel_hi:[1,0]
	v_pk_mul_f32 v[76:77], v[76:77], v[82:83] op_sel_hi:[1,0]
	v_pk_mul_f32 v[74:75], v[74:75], v[82:83] op_sel_hi:[1,0]
	v_pk_mul_f32 v[72:73], v[72:73], v[82:83] op_sel_hi:[1,0]
	v_pk_mul_f32 v[66:67], v[66:67], v[82:83] op_sel_hi:[1,0]
	v_pk_mul_f32 v[64:65], v[64:65], v[82:83] op_sel_hi:[1,0]
	v_pk_mul_f32 v[70:71], v[70:71], v[82:83] op_sel_hi:[1,0]
	v_pk_mul_f32 v[68:69], v[68:69], v[82:83] op_sel_hi:[1,0]
	v_max_f32_e32 v76, 0, v76
	v_max_f32_e32 v72, 0, v72
	v_max_f32_e32 v77, 0, v77
	v_max_f32_e32 v73, 0, v73
	v_max_f32_e32 v78, 0, v78
	v_max_f32_e32 v74, 0, v74
	v_max_f32_e32 v79, 0, v79
	v_max_f32_e32 v75, 0, v75
	v_max_f32_e32 v64, 0, v64
	v_max_f32_e32 v65, 0, v65
	v_max_f32_e32 v66, 0, v66
	v_max_f32_e32 v67, 0, v67
	v_max_f32_e32 v68, 0, v68
	v_max_f32_e32 v69, 0, v69
	v_max_f32_e32 v70, 0, v70
	v_max_f32_e32 v71, 0, v71
	v_pk_mul_f32 v[76:77], v[76:77], v[76:77]
	v_pk_mul_f32 v[72:73], v[72:73], v[72:73]
	v_pk_mul_f32 v[78:79], v[78:79], v[78:79]
	v_pk_mul_f32 v[74:75], v[74:75], v[74:75]
	v_pk_mul_f32 v[82:83], v[64:65], v[64:65]
	v_pk_mul_f32 v[84:85], v[66:67], v[66:67]
	v_cvt_pk_bf16_f32 v64, v76, v77
	v_cvt_pk_bf16_f32 v65, v78, v79
	v_cvt_pk_bf16_f32 v66, v72, v73
	v_cvt_pk_bf16_f32 v67, v74, v75
	v_pk_mul_f32 v[68:69], v[68:69], v[68:69]
	v_pk_mul_f32 v[70:71], v[70:71], v[70:71]
	buffer_store_dwordx4 v[64:67], v100, s[12:15], 0 offen sc1
	s_nop 1
	v_cvt_pk_bf16_f32 v64, v68, v69
	v_cvt_pk_bf16_f32 v65, v70, v71
	v_cvt_pk_bf16_f32 v66, v82, v83
	v_cvt_pk_bf16_f32 v67, v84, v85
	buffer_store_dwordx4 v[64:67], v100, s[12:15], 0 offen offset:256 sc1
	s_nop 0
	v_add_u32_e32 v80, 0x4090, v150
	v_ashrrev_i32_e32 v81, 31, v80
	v_lshl_add_u32 v84, v96, 13, v149
	v_add_u32_e32 v177, 0x2c00, v176
	global_load_dwordx4 v[240:243], v177, s[18:19]
	v_add_u32_e32 v177, 0x2c10, v176
	global_load_dwordx4 v[244:247], v177, s[18:19]
	v_add_u32_e32 v177, 0x2c20, v176
	global_load_dwordx4 v[248:251], v177, s[18:19]
	v_add_u32_e32 v177, 0x2c30, v176
	global_load_dwordx4 v[252:255], v177, s[18:19]
	s_waitcnt vmcnt(18)
; __device__ __forceinline__ u32x4 pack8(const f32x4 v0, const f32x4 v1) { u32x4 w; w.x = pk2(v0[0], v0[1]); w.y = pk2(v0[2], v0[3]); w.z = pk2(v1[0], v1[1]); w.w = pk2(v1[2], v1[3]); return w; }
; __device__ __forceinline__ float row_rstd(const float* ssq, int row) {
;     const f32x4* p = (const f32x4*)(ssq + (size_t)row * 16);
;     const f32x4 a = p[0], b = p[1], c = p[2], d = p[3];
;     const float s = ((a[0] + a[1]) + (a[2] + a[3])) + ((b[0] + b[1]) + (b[2] + b[3])) + ((c[0] + c[1]) + (c[2] + c[3])) + ((d[0] + d[1]) + (d[2] + d[3]));
;     return rsqrtf(s * (1.0f / 1024.0f) + 1e-6f);
;     __device__ __forceinline__ void operator()(const f32x4 (&acc)[2][2][4][2], const Unit& u, int wr, int wc, int fr, int fq) const {
;         const __amdgpu_buffer_rsrc_t rsrc = __builtin_amdgcn_make_buffer_rsrc((void*)O, 0, T_ALL * DFF * 2, 0x00020000);
;         const int row0 = row_off + u.pm * 256 + wr * 64 + fr, col0 = u.pn * 256 + wc * 32 + 8 * fq;
; #pragma unroll
;         for (int ai = 0; ai < 2; ++ai)
; #pragma unroll
;             for (int m = 0; m < 4; ++m) {
;                 const int row = row0 + ai * 128 + m * 16; const float rs = row_rstd(ssq, row);
; #pragma unroll
;                 for (int bj = 0; bj < 2; ++bj) { f32x4 v0 = acc[ai][bj][m][0] * rs, v1 = acc[ai][bj][m][1] * rs;
; #pragma unroll
;                     for (int j = 0; j < 4; ++j) { const float a = fmaxf(v0[j], 0.f), b = fmaxf(v1[j], 0.f); v0[j] = a * a; v1[j] = b * b; }
;                     __builtin_amdgcn_raw_buffer_store_b128(pack8(v0, v1), rsrc, (unsigned)(((size_t)row * DFF + col0 + bj * 128) * 2), 0, 16  ); }
	v_pk_add_f32 v[64:65], v[178:179], v[180:181]
	v_pk_add_f32 v[66:67], v[182:183], v[184:185]
	v_pk_add_f32 v[68:69], v[186:187], v[188:189]
	v_pk_add_f32 v[70:71], v[190:191], v[192:193]
	v_pk_add_f32 v[64:65], v[64:65], v[66:67]
	v_pk_add_f32 v[68:69], v[68:69], v[70:71]
	v_pk_add_f32 v[64:65], v[64:65], v[68:69]
	v_add_f32_e32 v64, v64, v65
	s_nop 0
	s_nop 0
	v_fmamk_f32 v64, v64, 0x3a800000, v148
	s_nop 0
	s_nop 0
	s_nop 1
	s_nop 0
	v_rsq_f32_e32 v66, v64
	s_nop 0
	s_nop 0
	s_nop 0
	s_nop 0
	v_pk_mul_f32 v[62:63], v[62:63], v[66:67] op_sel_hi:[1,0]
	v_pk_mul_f32 v[60:61], v[60:61], v[66:67] op_sel_hi:[1,0]
	v_pk_mul_f32 v[58:59], v[58:59], v[66:67] op_sel_hi:[1,0]
	v_pk_mul_f32 v[56:57], v[56:57], v[66:67] op_sel_hi:[1,0]
	v_pk_mul_f32 v[50:51], v[50:51], v[66:67] op_sel_hi:[1,0]
	v_pk_mul_f32 v[48:49], v[48:49], v[66:67] op_sel_hi:[1,0]
	v_pk_mul_f32 v[54:55], v[54:55], v[66:67] op_sel_hi:[1,0]
	v_pk_mul_f32 v[52:53], v[52:53], v[66:67] op_sel_hi:[1,0]
	v_max_f32_e32 v60, 0, v60
	v_max_f32_e32 v56, 0, v56
	v_max_f32_e32 v61, 0, v61
	v_max_f32_e32 v57, 0, v57
	v_max_f32_e32 v62, 0, v62
	v_max_f32_e32 v58, 0, v58
	v_max_f32_e32 v63, 0, v63
	v_max_f32_e32 v59, 0, v59
	v_max_f32_e32 v48, 0, v48
	v_max_f32_e32 v49, 0, v49
	v_max_f32_e32 v50, 0, v50
	v_max_f32_e32 v51, 0, v51
	v_max_f32_e32 v52, 0, v52
	v_max_f32_e32 v53, 0, v53
	v_max_f32_e32 v54, 0, v54
	v_max_f32_e32 v55, 0, v55
	v_pk_mul_f32 v[60:61], v[60:61], v[60:61]
	v_pk_mul_f32 v[56:57], v[56:57], v[56:57]
	v_pk_mul_f32 v[62:63], v[62:63], v[62:63]
	v_pk_mul_f32 v[58:59], v[58:59], v[58:59]
	v_pk_mul_f32 v[66:67], v[48:49], v[48:49]
	v_pk_mul_f32 v[68:69], v[50:51], v[50:51]
	v_cvt_pk_bf16_f32 v48, v60, v61
	v_cvt_pk_bf16_f32 v49, v62, v63
	v_cvt_pk_bf16_f32 v50, v56, v57
	v_cvt_pk_bf16_f32 v51, v58, v59
	v_pk_mul_f32 v[52:53], v[52:53], v[52:53]
	v_pk_mul_f32 v[54:55], v[54:55], v[54:55]
	buffer_store_dwordx4 v[48:51], v84, s[12:15], 0 offen sc1
	s_nop 1
	v_cvt_pk_bf16_f32 v48, v52, v53
	v_cvt_pk_bf16_f32 v49, v54, v55
	v_cvt_pk_bf16_f32 v50, v66, v67
	v_cvt_pk_bf16_f32 v51, v68, v69
	buffer_store_dwordx4 v[48:51], v84, s[12:15], 0 offen offset:256 sc1
	s_nop 0
	v_add_u32_e32 v64, 0x40a0, v150
	v_ashrrev_i32_e32 v65, 31, v64
	v_lshl_add_u32 v68, v80, 13, v149
	s_waitcnt vmcnt(14)
	v_pk_add_f32 v[48:49], v[194:195], v[196:197]
	v_pk_add_f32 v[50:51], v[198:199], v[200:201]
	v_pk_add_f32 v[52:53], v[202:203], v[204:205]
	v_pk_add_f32 v[54:55], v[206:207], v[208:209]
	v_pk_add_f32 v[48:49], v[48:49], v[50:51]
	v_pk_add_f32 v[52:53], v[52:53], v[54:55]
	v_pk_add_f32 v[48:49], v[48:49], v[52:53]
	v_add_f32_e32 v48, v48, v49
	s_nop 0
	s_nop 0
	v_fmamk_f32 v48, v48, 0x3a800000, v148
	s_nop 0
	s_nop 0
	s_nop 1
	s_nop 0
	v_rsq_f32_e32 v50, v48
	s_nop 0
	s_nop 0
	s_nop 0
	s_nop 0
	v_pk_mul_f32 v[46:47], v[46:47], v[50:51] op_sel_hi:[1,0]
	v_pk_mul_f32 v[44:45], v[44:45], v[50:51] op_sel_hi:[1,0]
	v_pk_mul_f32 v[42:43], v[42:43], v[50:51] op_sel_hi:[1,0]
	v_pk_mul_f32 v[40:41], v[40:41], v[50:51] op_sel_hi:[1,0]
	v_pk_mul_f32 v[34:35], v[34:35], v[50:51] op_sel_hi:[1,0]
	v_pk_mul_f32 v[32:33], v[32:33], v[50:51] op_sel_hi:[1,0]
	v_pk_mul_f32 v[38:39], v[38:39], v[50:51] op_sel_hi:[1,0]
	v_pk_mul_f32 v[36:37], v[36:37], v[50:51] op_sel_hi:[1,0]
	v_max_f32_e32 v44, 0, v44
	v_max_f32_e32 v40, 0, v40
	v_max_f32_e32 v45, 0, v45
	v_max_f32_e32 v41, 0, v41
	v_max_f32_e32 v46, 0, v46
	v_max_f32_e32 v42, 0, v42
	v_max_f32_e32 v47, 0, v47
	v_max_f32_e32 v43, 0, v43
	v_max_f32_e32 v32, 0, v32
	v_max_f32_e32 v33, 0, v33
	v_max_f32_e32 v34, 0, v34
	v_max_f32_e32 v35, 0, v35
	v_max_f32_e32 v36, 0, v36
	v_max_f32_e32 v37, 0, v37
	v_max_f32_e32 v38, 0, v38
	v_max_f32_e32 v39, 0, v39
	v_pk_mul_f32 v[44:45], v[44:45], v[44:45]
	v_pk_mul_f32 v[40:41], v[40:41], v[40:41]
	v_pk_mul_f32 v[46:47], v[46:47], v[46:47]
	v_pk_mul_f32 v[42:43], v[42:43], v[42:43]
	v_pk_mul_f32 v[50:51], v[32:33], v[32:33]
	v_pk_mul_f32 v[52:53], v[34:35], v[34:35]
	v_cvt_pk_bf16_f32 v32, v44, v45
	v_cvt_pk_bf16_f32 v33, v46, v47
	v_cvt_pk_bf16_f32 v34, v40, v41
	v_cvt_pk_bf16_f32 v35, v42, v43
	v_pk_mul_f32 v[36:37], v[36:37], v[36:37]
	v_pk_mul_f32 v[38:39], v[38:39], v[38:39]
	buffer_store_dwordx4 v[32:35], v68, s[12:15], 0 offen sc1
	s_nop 1
	v_cvt_pk_bf16_f32 v32, v36, v37
	v_cvt_pk_bf16_f32 v33, v38, v39
	v_cvt_pk_bf16_f32 v34, v50, v51
	v_cvt_pk_bf16_f32 v35, v52, v53
	buffer_store_dwordx4 v[32:35], v68, s[12:15], 0 offen offset:256 sc1
	s_nop 0
	v_add_u32_e32 v48, 0x40b0, v150
	v_ashrrev_i32_e32 v49, 31, v48
	v_lshl_add_u32 v52, v64, 13, v149
	s_waitcnt vmcnt(10)
; __device__ __forceinline__ u32x4 pack8(const f32x4 v0, const f32x4 v1) { u32x4 w; w.x = pk2(v0[0], v0[1]); w.y = pk2(v0[2], v0[3]); w.z = pk2(v1[0], v1[1]); w.w = pk2(v1[2], v1[3]); return w; }
;     __device__ __forceinline__ void operator()(const f32x4 (&acc)[2][2][4][2], const Unit& u, int wr, int wc, int fr, int fq) const {
;         const __amdgpu_buffer_rsrc_t rsrc = __builtin_amdgcn_make_buffer_rsrc((void*)O, 0, T_ALL * DFF * 2, 0x00020000);
;         const int row0 = row_off + u.pm * 256 + wr * 64 + fr, col0 = u.pn * 256 + wc * 32 + 8 * fq;
; #pragma unroll
;         for (int ai = 0; ai < 2; ++ai)
; #pragma unroll
;             for (int m = 0; m < 4; ++m) {
;                 const int row = row0 + ai * 128 + m * 16; const float rs = row_rstd(ssq, row);
; #pragma unroll
;                 for (int bj = 0; bj < 2; ++bj) { f32x4 v0 = acc[ai][bj][m][0] * rs, v1 = acc[ai][bj][m][1] * rs;
; #pragma unroll
;                     for (int j = 0; j < 4; ++j) { const float a = fmaxf(v0[j], 0.f), b = fmaxf(v1[j], 0.f); v0[j] = a * a; v1[j] = b * b; }
;                     __builtin_amdgcn_raw_buffer_store_b128(pack8(v0, v1), rsrc, (unsigned)(((size_t)row * DFF + col0 + bj * 128) * 2), 0, 16  ); }
;             }
;         asm volatile("s_waitcnt vmcnt(0)" ::: "memory");
;         if (fr == 0 && fq == 0) (void)__hip_atomic_fetch_add(ready + 64 * (pm_off + u.pm), 1u, __ATOMIC_RELAXED, __HIP_MEMORY_SCOPE_AGENT);
	v_pk_add_f32 v[32:33], v[210:211], v[212:213]
	v_pk_add_f32 v[34:35], v[214:215], v[216:217]
	v_pk_add_f32 v[36:37], v[232:233], v[234:235]
	v_pk_add_f32 v[38:39], v[236:237], v[238:239]
	v_pk_add_f32 v[32:33], v[32:33], v[34:35]
	v_pk_add_f32 v[36:37], v[36:37], v[38:39]
	v_pk_add_f32 v[32:33], v[32:33], v[36:37]
	v_add_f32_e32 v32, v32, v33
	s_nop 0
	s_nop 0
	v_fmamk_f32 v32, v32, 0x3a800000, v148
	s_nop 0
	s_nop 0
	s_nop 1
	s_nop 0
	v_rsq_f32_e32 v34, v32
	v_lshlrev_b64 v[32:33], 6, v[48:49]
	v_lshl_add_u64 v[32:33], s[18:19], 0, v[32:33]
	s_nop 0
	s_nop 0
	v_pk_mul_f32 v[30:31], v[30:31], v[34:35] op_sel_hi:[1,0]
	v_pk_mul_f32 v[28:29], v[28:29], v[34:35] op_sel_hi:[1,0]
	v_pk_mul_f32 v[26:27], v[26:27], v[34:35] op_sel_hi:[1,0]
	v_pk_mul_f32 v[24:25], v[24:25], v[34:35] op_sel_hi:[1,0]
	v_pk_mul_f32 v[18:19], v[18:19], v[34:35] op_sel_hi:[1,0]
	v_pk_mul_f32 v[16:17], v[16:17], v[34:35] op_sel_hi:[1,0]
	v_pk_mul_f32 v[22:23], v[22:23], v[34:35] op_sel_hi:[1,0]
	v_pk_mul_f32 v[20:21], v[20:21], v[34:35] op_sel_hi:[1,0]
	v_max_f32_e32 v28, 0, v28
	v_max_f32_e32 v24, 0, v24
	v_max_f32_e32 v29, 0, v29
	v_max_f32_e32 v25, 0, v25
	v_max_f32_e32 v30, 0, v30
	v_max_f32_e32 v26, 0, v26
	v_max_f32_e32 v31, 0, v31
	v_max_f32_e32 v27, 0, v27
	v_max_f32_e32 v16, 0, v16
	v_max_f32_e32 v17, 0, v17
	v_max_f32_e32 v18, 0, v18
	v_max_f32_e32 v19, 0, v19
	v_max_f32_e32 v20, 0, v20
	v_max_f32_e32 v21, 0, v21
	v_max_f32_e32 v22, 0, v22
	v_max_f32_e32 v23, 0, v23
	v_pk_mul_f32 v[28:29], v[28:29], v[28:29]
	v_pk_mul_f32 v[24:25], v[24:25], v[24:25]
	v_pk_mul_f32 v[30:31], v[30:31], v[30:31]
	v_pk_mul_f32 v[26:27], v[26:27], v[26:27]
	v_pk_mul_f32 v[34:35], v[16:17], v[16:17]
	v_pk_mul_f32 v[36:37], v[18:19], v[18:19]
	v_cvt_pk_bf16_f32 v16, v28, v29
	v_cvt_pk_bf16_f32 v17, v30, v31
	v_cvt_pk_bf16_f32 v18, v24, v25
	v_cvt_pk_bf16_f32 v19, v26, v27
	v_pk_mul_f32 v[20:21], v[20:21], v[20:21]
	v_pk_mul_f32 v[22:23], v[22:23], v[22:23]
	buffer_store_dwordx4 v[16:19], v52, s[12:15], 0 offen sc1
	s_nop 1
	v_cvt_pk_bf16_f32 v16, v20, v21
	v_cvt_pk_bf16_f32 v17, v22, v23
	v_cvt_pk_bf16_f32 v18, v34, v35
	v_cvt_pk_bf16_f32 v19, v36, v37
	buffer_store_dwordx4 v[16:19], v52, s[12:15], 0 offen offset:256 sc1
	s_nop 0
	s_waitcnt vmcnt(6)
	v_pk_add_f32 v[16:17], v[240:241], v[242:243]
	v_pk_add_f32 v[18:19], v[244:245], v[246:247]
	v_pk_add_f32 v[20:21], v[248:249], v[250:251]
	v_pk_add_f32 v[22:23], v[252:253], v[254:255]
	v_pk_add_f32 v[16:17], v[16:17], v[18:19]
	v_pk_add_f32 v[20:21], v[20:21], v[22:23]
	v_pk_add_f32 v[16:17], v[16:17], v[20:21]
	v_add_f32_e32 v16, v16, v17
	s_nop 0
	s_nop 0
	v_fmamk_f32 v16, v16, 0x3a800000, v148
	s_nop 0
	s_nop 0
	s_nop 1
	s_nop 0
	v_rsq_f32_e32 v16, v16
	v_lshl_add_u32 v17, v48, 13, v149
	s_nop 0
	s_nop 0
	v_pk_mul_f32 v[14:15], v[14:15], v[16:17] op_sel_hi:[1,0]
	v_pk_mul_f32 v[12:13], v[12:13], v[16:17] op_sel_hi:[1,0]
	v_pk_mul_f32 v[10:11], v[10:11], v[16:17] op_sel_hi:[1,0]
	v_pk_mul_f32 v[8:9], v[8:9], v[16:17] op_sel_hi:[1,0]
	v_pk_mul_f32 v[2:3], v[2:3], v[16:17] op_sel_hi:[1,0]
	v_pk_mul_f32 v[0:1], v[0:1], v[16:17] op_sel_hi:[1,0]
	v_pk_mul_f32 v[6:7], v[6:7], v[16:17] op_sel_hi:[1,0]
	v_pk_mul_f32 v[4:5], v[4:5], v[16:17] op_sel_hi:[1,0]
	v_max_f32_e32 v12, 0, v12
	v_max_f32_e32 v8, 0, v8
	v_max_f32_e32 v13, 0, v13
	v_max_f32_e32 v9, 0, v9
	v_max_f32_e32 v14, 0, v14
	v_max_f32_e32 v10, 0, v10
	v_max_f32_e32 v15, 0, v15
	v_max_f32_e32 v11, 0, v11
	v_max_f32_e32 v0, 0, v0
	v_max_f32_e32 v1, 0, v1
	v_max_f32_e32 v2, 0, v2
	v_max_f32_e32 v3, 0, v3
	v_max_f32_e32 v4, 0, v4
	v_max_f32_e32 v5, 0, v5
	v_max_f32_e32 v6, 0, v6
	v_max_f32_e32 v7, 0, v7
	v_pk_mul_f32 v[12:13], v[12:13], v[12:13]
	v_pk_mul_f32 v[8:9], v[8:9], v[8:9]
	v_pk_mul_f32 v[14:15], v[14:15], v[14:15]
	v_pk_mul_f32 v[10:11], v[10:11], v[10:11]
	v_mul_f32_e32 v16, v0, v0
	v_mul_f32_e32 v18, v1, v1
	v_mul_f32_e32 v19, v2, v2
	v_mul_f32_e32 v20, v3, v3
	v_cvt_pk_bf16_f32 v0, v12, v13
	v_cvt_pk_bf16_f32 v1, v14, v15
	v_cvt_pk_bf16_f32 v2, v8, v9
	v_cvt_pk_bf16_f32 v3, v10, v11
	v_pk_mul_f32 v[4:5], v[4:5], v[4:5]
	v_pk_mul_f32 v[6:7], v[6:7], v[6:7]
	buffer_store_dwordx4 v[0:3], v17, s[12:15], 0 offen sc1
	s_nop 1
	v_cvt_pk_bf16_f32 v0, v4, v5
	v_cvt_pk_bf16_f32 v1, v6, v7
	v_cvt_pk_bf16_f32 v2, v16, v18
	v_cvt_pk_bf16_f32 v3, v19, v20
	buffer_store_dwordx4 v[0:3], v17, s[12:15], 0 offen offset:256 sc1
	s_waitcnt vmcnt(0)
	s_and_saveexec_b64 s[38:39], s[10:11]
	s_cbranch_execz .LBB0_973
	s_mov_b64 s[40:41], exec
	v_mbcnt_lo_u32_b32 v0, s40, 0
	v_mbcnt_hi_u32_b32 v0, s41, v0
	v_cmp_eq_u32_e32 vcc, 0, v0
	s_and_b64 s[6:7], exec, vcc
	s_mov_b64 exec, s[6:7]
	s_cbranch_execz .LBB0_973
	s_lshl_b32 s6, s75, 6
	s_addk_i32 s6, 0x1000
	s_ashr_i32 s7, s6, 31
	s_lshl_b64 s[6:7], s[6:7], 2
	s_add_u32 s6, s73, s6
	s_addc_u32 s7, s74, s7
	s_bcnt1_i32_b64 s8, s[40:41]
	v_mov_b32_e32 v0, s8
	global_atomic_add v131, v0, s[6:7]
	s_branch .LBB0_973

; #define PG8_STAGE(bufoff, gbase, voff) do { _Pragma("unroll") for (int _i = 0; _i < 2; ++_i) \
;         __builtin_amdgcn_global_load_lds((const unsigned*)((const char*)(gbase) + (voff)[_i]), (LAS unsigned*)(lds + (bufoff) + ldsw + _i * 8192), 16, 0, 0); } while (0)
; #define PG8_LDA(dst, b, h) do { _Pragma("unroll") for (int m = 0; m < 4; ++m) _Pragma("unroll") for (int k = 0; k < 2; ++k) dst[m][k] = *(const LAS bf16x8*)(lds + PG8_SA(b, h) + aoff + m * 2048 + k * 1024); } while (0)
; #define PG8_LDB(dst, b, h) do { _Pragma("unroll") for (int n = 0; n < 2; ++n) _Pragma("unroll") for (int k = 0; k < 2; ++k) dst[n][k] = *(const LAS bf16x8*)(lds + PG8_SB(b, h) + boff + n * 2048 + k * 1024); } while (0)
; #define PG8_MMA(ai, bj, At, Bt) do { __builtin_amdgcn_s_setprio(1); _Pragma("unroll") for (int m = 0; m < 4; ++m) _Pragma("unroll") for (int n = 0; n < 2; ++n) _Pragma("unroll") for (int k = 0; k < 2; ++k) \
;         acc[ai][bj][m][n] = __builtin_amdgcn_mfma_f32_16x16x32_bf16(Bt[n][k], At[m][k], acc[ai][bj][m][n], 0, 0, 0); __builtin_amdgcn_s_setprio(0); } while (0)
; #define PG8_WAIT_L(n) asm volatile("s_waitcnt lgkmcnt(" #n ")" ::: "memory")
; #define PG8_BAR __builtin_amdgcn_s_barrier()
; #define PG8_SCHED __builtin_amdgcn_sched_barrier(0)
;     ...
;             PG8_LDB(B0, 0, 0); PG8_SCHED; PG8_LDA(At, 0, 0); PG8_STAGE(PG8_SA(1, 1), a1 + hA, voffA);
;             PG8_WAIT_L(8); PG8_BAR; PG8_WAIT_L(0); PG8_MMA(0, 0, At, B0); PG8_BAR; PG8_SCHED;
;             PG8_LDB(B1, 0, 1); PG8_STAGE(PG8_SB(0, 0), b2, voffB);
;             PG8_BAR; PG8_WAIT_L(0); PG8_MMA(0, 1, At, B1); PG8_BAR;
;             PG8_LDA(At, 0, 1); PG8_STAGE(PG8_SA(0, 0), a2, voffA);
;             PG8_BAR; PG8_WAIT_L(0); PG8_MMA(1, 0, At, B0); PG8_BAR; PG8_SCHED;
.LBB0_1288:
	ds_read_b128 v[146:149], v155
	ds_read_b128 v[160:163], v155 offset:1024
	ds_read_b128 v[170:173], v155 offset:2048
	ds_read_b128 v[174:177], v155 offset:3072
	s_add_u32 s36, s34, 0xfffc0080
	s_addc_u32 s37, s35, -1
	s_cmp_eq_u32 s42, 12
	s_cselect_b32 s39, s7, s37
	s_cselect_b32 s38, s8, s36
	s_cselect_b32 s37, s9, s33
	s_cselect_b32 s36, s23, s25
	v_lshl_add_u64 v[150:151], s[34:35], 0, v[138:139]
	s_add_i32 m0, s31, 0xc000
	ds_read_b128 v[178:181], v156
	ds_read_b128 v[182:185], v156 offset:1024
	ds_read_b128 v[186:189], v156 offset:2048
	ds_read_b128 v[190:193], v156 offset:3072
	ds_read_b128 v[194:197], v156 offset:4096
	ds_read_b128 v[198:201], v156 offset:5120
	ds_read_b128 v[202:205], v156 offset:6144
	ds_read_b128 v[206:209], v156 offset:7168
	global_load_lds_dwordx4 v[150:151], off
	v_lshl_add_u64 v[150:151], s[34:35], 0, v[136:137]
	s_add_i32 m0, s31, 0xe000
	s_nop 0
	global_load_lds_dwordx4 v[150:151], off
	s_waitcnt lgkmcnt(8)
	s_barrier
	s_waitcnt lgkmcnt(0)
	s_setprio 1
	s_waitcnt lgkmcnt(0)
	v_mfma_f32_16x16x32_bf16 v[124:127], v[146:149], v[178:181], v[124:127]
	v_mfma_f32_16x16x32_bf16 v[120:123], v[170:173], v[178:181], v[120:123]
	v_mfma_f32_16x16x32_bf16 v[108:111], v[146:149], v[186:189], v[108:111]
	v_mfma_f32_16x16x32_bf16 v[104:107], v[170:173], v[186:189], v[104:107]
	v_mfma_f32_16x16x32_bf16 v[92:95], v[146:149], v[194:197], v[92:95]
	v_mfma_f32_16x16x32_bf16 v[88:91], v[170:173], v[194:197], v[88:91]
	v_mfma_f32_16x16x32_bf16 v[76:79], v[146:149], v[202:205], v[76:79]
	v_mfma_f32_16x16x32_bf16 v[72:75], v[170:173], v[202:205], v[72:75]
	v_mfma_f32_16x16x32_bf16 v[124:127], v[160:163], v[182:185], v[124:127]
	v_mfma_f32_16x16x32_bf16 v[120:123], v[174:177], v[182:185], v[120:123]
	v_mfma_f32_16x16x32_bf16 v[108:111], v[160:163], v[190:193], v[108:111]
	v_mfma_f32_16x16x32_bf16 v[104:107], v[174:177], v[190:193], v[104:107]
	v_mfma_f32_16x16x32_bf16 v[92:95], v[160:163], v[198:201], v[92:95]
	v_mfma_f32_16x16x32_bf16 v[88:91], v[174:177], v[198:201], v[88:91]
	v_mfma_f32_16x16x32_bf16 v[76:79], v[160:163], v[206:209], v[76:79]
	v_mfma_f32_16x16x32_bf16 v[72:75], v[174:177], v[206:209], v[72:75]
	s_setprio 0
	s_barrier
	s_add_i32 s43, s63, s55
	v_lshl_add_u64 v[150:151], s[36:37], 0, v[130:131]
	s_mov_b32 m0, s43
	ds_read_b128 v[210:213], v157
	ds_read_b128 v[214:217], v157 offset:1024
	ds_read_b128 v[218:221], v157 offset:2048
	ds_read_b128 v[222:225], v157 offset:3072
	global_load_lds_dwordx4 v[150:151], off
	v_lshl_add_u64 v[164:165], s[36:37], 0, v[134:135]
	s_add_i32 m0, s43, 0x2000
	s_nop 0
	global_load_lds_dwordx4 v[164:165], off
	s_barrier
	s_waitcnt lgkmcnt(0)
	s_setprio 1
	s_waitcnt lgkmcnt(0)
	v_mfma_f32_16x16x32_bf16 v[116:119], v[210:213], v[178:181], v[116:119]
	v_mfma_f32_16x16x32_bf16 v[112:115], v[218:221], v[178:181], v[112:115]
	v_mfma_f32_16x16x32_bf16 v[100:103], v[210:213], v[186:189], v[100:103]
	v_mfma_f32_16x16x32_bf16 v[96:99], v[218:221], v[186:189], v[96:99]
	v_mfma_f32_16x16x32_bf16 v[84:87], v[210:213], v[194:197], v[84:87]
	v_mfma_f32_16x16x32_bf16 v[80:83], v[218:221], v[194:197], v[80:83]
	v_mfma_f32_16x16x32_bf16 v[68:71], v[210:213], v[202:205], v[68:71]
	v_mfma_f32_16x16x32_bf16 v[64:67], v[218:221], v[202:205], v[64:67]
	v_mfma_f32_16x16x32_bf16 v[116:119], v[214:217], v[182:185], v[116:119]
	v_mfma_f32_16x16x32_bf16 v[112:115], v[222:225], v[182:185], v[112:115]
	v_mfma_f32_16x16x32_bf16 v[100:103], v[214:217], v[190:193], v[100:103]
	v_mfma_f32_16x16x32_bf16 v[96:99], v[222:225], v[190:193], v[96:99]
	v_mfma_f32_16x16x32_bf16 v[84:87], v[214:217], v[198:201], v[84:87]
	v_mfma_f32_16x16x32_bf16 v[80:83], v[222:225], v[198:201], v[80:83]
	v_mfma_f32_16x16x32_bf16 v[68:71], v[214:217], v[206:209], v[68:71]
	v_mfma_f32_16x16x32_bf16 v[64:67], v[222:225], v[206:209], v[64:67]
	s_setprio 0
	s_mov_b32 m0, s31
	v_lshl_add_u64 v[226:227], s[38:39], 0, v[128:129]
	s_barrier
	ds_read_b128 v[178:181], v156 offset:16384
	ds_read_b128 v[182:185], v156 offset:17408
	ds_read_b128 v[186:189], v156 offset:18432
	ds_read_b128 v[190:193], v156 offset:19456
	ds_read_b128 v[194:197], v156 offset:20480
	ds_read_b128 v[198:201], v156 offset:21504
	ds_read_b128 v[202:205], v156 offset:22528
	ds_read_b128 v[206:209], v156 offset:23552
	global_load_lds_dwordx4 v[226:227], off
	v_lshl_add_u64 v[228:229], s[38:39], 0, v[132:133]
	s_mov_b32 m0, s56
	s_nop 0
	global_load_lds_dwordx4 v[228:229], off
	s_barrier
	s_waitcnt lgkmcnt(0)
	s_setprio 1
	s_waitcnt lgkmcnt(0)
	v_mfma_f32_16x16x32_bf16 v[60:63], v[146:149], v[178:181], v[60:63]
	v_mfma_f32_16x16x32_bf16 v[56:59], v[170:173], v[178:181], v[56:59]
	v_mfma_f32_16x16x32_bf16 v[44:47], v[146:149], v[186:189], v[44:47]
	v_mfma_f32_16x16x32_bf16 v[40:43], v[170:173], v[186:189], v[40:43]
	v_mfma_f32_16x16x32_bf16 v[28:31], v[146:149], v[194:197], v[28:31]
	v_mfma_f32_16x16x32_bf16 v[24:27], v[170:173], v[194:197], v[24:27]
	v_mfma_f32_16x16x32_bf16 v[12:15], v[146:149], v[202:205], v[12:15]
	v_mfma_f32_16x16x32_bf16 v[8:11], v[170:173], v[202:205], v[8:11]
	v_mfma_f32_16x16x32_bf16 v[60:63], v[160:163], v[182:185], v[60:63]
	v_mfma_f32_16x16x32_bf16 v[56:59], v[174:177], v[182:185], v[56:59]
	v_mfma_f32_16x16x32_bf16 v[44:47], v[160:163], v[190:193], v[44:47]
	v_mfma_f32_16x16x32_bf16 v[40:43], v[174:177], v[190:193], v[40:43]
	v_mfma_f32_16x16x32_bf16 v[28:31], v[160:163], v[198:201], v[28:31]
	v_mfma_f32_16x16x32_bf16 v[24:27], v[174:177], v[198:201], v[24:27]
	v_mfma_f32_16x16x32_bf16 v[12:15], v[160:163], v[206:209], v[12:15]
	v_mfma_f32_16x16x32_bf16 v[8:11], v[174:177], v[206:209], v[8:11]
	s_setprio 0
	s_barrier
; #define PG8_STAGE(bufoff, gbase, voff) do { _Pragma("unroll") for (int _i = 0; _i < 2; ++_i) \
;         __builtin_amdgcn_global_load_lds((const unsigned*)((const char*)(gbase) + (voff)[_i]), (LAS unsigned*)(lds + (bufoff) + ldsw + _i * 8192), 16, 0, 0); } while (0)
; #define PG8_LDA(dst, b, h) do { _Pragma("unroll") for (int m = 0; m < 4; ++m) _Pragma("unroll") for (int k = 0; k < 2; ++k) dst[m][k] = *(const LAS bf16x8*)(lds + PG8_SA(b, h) + aoff + m * 2048 + k * 1024); } while (0)
; #define PG8_LDB(dst, b, h) do { _Pragma("unroll") for (int n = 0; n < 2; ++n) _Pragma("unroll") for (int k = 0; k < 2; ++k) dst[n][k] = *(const LAS bf16x8*)(lds + PG8_SB(b, h) + boff + n * 2048 + k * 1024); } while (0)
; #define PG8_MMA(ai, bj, At, Bt) do { __builtin_amdgcn_s_setprio(1); _Pragma("unroll") for (int m = 0; m < 4; ++m) _Pragma("unroll") for (int n = 0; n < 2; ++n) _Pragma("unroll") for (int k = 0; k < 2; ++k) \
;         acc[ai][bj][m][n] = __builtin_amdgcn_mfma_f32_16x16x32_bf16(Bt[n][k], At[m][k], acc[ai][bj][m][n], 0, 0, 0); __builtin_amdgcn_s_setprio(0); } while (0)
; #define PG8_WAIT_V(n) asm volatile("s_waitcnt vmcnt(" #n ")" ::: "memory")
; #define PG8_WAIT_L(n) asm volatile("s_waitcnt lgkmcnt(" #n ")" ::: "memory")
; #define PG8_BAR __builtin_amdgcn_s_barrier()
; #define PG8_SCHED __builtin_amdgcn_sched_barrier(0)
;     ...
;             PG8_STAGE(PG8_SB(0, 1), b2 + hB, voffB);
;             PG8_WAIT_V(6); PG8_BAR; PG8_MMA(1, 1, At, B1); PG8_BAR;
;             PG8_LDB(B0, 1, 0); PG8_SCHED; PG8_LDA(At, 1, 0); PG8_STAGE(PG8_SA(0, 1), a2 + hA, voffA);
;             PG8_WAIT_L(8); PG8_BAR; PG8_WAIT_L(0); PG8_MMA(0, 0, At, B0); PG8_BAR; PG8_SCHED;
;             PG8_LDB(B1, 1, 1); PG8_STAGE(PG8_SB(1, 0), b3, voffB);
;             PG8_BAR; PG8_WAIT_L(0); PG8_MMA(0, 1, At, B1); PG8_BAR;
;             PG8_LDA(At, 1, 1); PG8_STAGE(PG8_SA(1, 0), a3, voffA);
	s_add_u32 s44, s36, 0x40000
	s_addc_u32 s45, s37, 0
	s_add_i32 s43, s64, s55
	v_lshl_add_u64 v[146:147], s[44:45], 0, v[130:131]
	s_mov_b32 m0, s43
	s_nop 0
	global_load_lds_dwordx4 v[146:147], off
	v_lshl_add_u64 v[146:147], s[44:45], 0, v[134:135]
	s_add_i32 m0, s43, 0x2000
	s_nop 0
	global_load_lds_dwordx4 v[146:147], off
	s_waitcnt vmcnt(6)
	s_barrier
	s_setprio 1
	v_mfma_f32_16x16x32_bf16 v[52:55], v[210:213], v[178:181], v[52:55]
	v_mfma_f32_16x16x32_bf16 v[48:51], v[218:221], v[178:181], v[48:51]
	v_mfma_f32_16x16x32_bf16 v[36:39], v[210:213], v[186:189], v[36:39]
	v_mfma_f32_16x16x32_bf16 v[32:35], v[218:221], v[186:189], v[32:35]
	v_mfma_f32_16x16x32_bf16 v[20:23], v[210:213], v[194:197], v[20:23]
	v_mfma_f32_16x16x32_bf16 v[16:19], v[218:221], v[194:197], v[16:19]
	v_mfma_f32_16x16x32_bf16 v[4:7], v[210:213], v[202:205], v[4:7]
	v_mfma_f32_16x16x32_bf16 v[0:3], v[218:221], v[202:205], v[0:3]
	v_mfma_f32_16x16x32_bf16 v[52:55], v[214:217], v[182:185], v[52:55]
	v_mfma_f32_16x16x32_bf16 v[48:51], v[222:225], v[182:185], v[48:51]
	v_mfma_f32_16x16x32_bf16 v[36:39], v[214:217], v[190:193], v[36:39]
	v_mfma_f32_16x16x32_bf16 v[32:35], v[222:225], v[190:193], v[32:35]
	v_mfma_f32_16x16x32_bf16 v[20:23], v[214:217], v[198:201], v[20:23]
	v_mfma_f32_16x16x32_bf16 v[16:19], v[222:225], v[198:201], v[16:19]
	v_mfma_f32_16x16x32_bf16 v[4:7], v[214:217], v[206:209], v[4:7]
	v_mfma_f32_16x16x32_bf16 v[0:3], v[222:225], v[206:209], v[0:3]
	s_setprio 0
	s_add_i32 s43, 0, 0x18000
	v_add_u32_e32 v159, s43, v153
	s_barrier
	ds_read_b128 v[146:149], v159
	ds_read_b128 v[160:163], v159 offset:1024
	ds_read_b128 v[170:173], v159 offset:2048
	ds_read_b128 v[174:177], v159 offset:3072
	s_add_u32 s38, s38, 0x40000
	s_addc_u32 s39, s39, 0
	s_mov_b32 m0, s57
	v_lshl_add_u64 v[210:211], s[38:39], 0, v[128:129]
	ds_read_b128 v[178:181], v156 offset:32768
	ds_read_b128 v[182:185], v156 offset:33792
	ds_read_b128 v[186:189], v156 offset:34816
	ds_read_b128 v[190:193], v156 offset:35840
	ds_read_b128 v[194:197], v156 offset:36864
	ds_read_b128 v[198:201], v156 offset:37888
	ds_read_b128 v[202:205], v156 offset:38912
	ds_read_b128 v[206:209], v156 offset:39936
	global_load_lds_dwordx4 v[210:211], off
	v_lshl_add_u64 v[210:211], s[38:39], 0, v[132:133]
	s_mov_b32 m0, s58
	s_nop 0
	global_load_lds_dwordx4 v[210:211], off
	s_waitcnt lgkmcnt(8)
	s_barrier
	s_waitcnt lgkmcnt(0)
	s_setprio 1
	s_waitcnt lgkmcnt(0)
	v_mfma_f32_16x16x32_bf16 v[124:127], v[146:149], v[178:181], v[124:127]
	v_mfma_f32_16x16x32_bf16 v[120:123], v[170:173], v[178:181], v[120:123]
	v_mfma_f32_16x16x32_bf16 v[108:111], v[146:149], v[186:189], v[108:111]
	v_mfma_f32_16x16x32_bf16 v[104:107], v[170:173], v[186:189], v[104:107]
	v_mfma_f32_16x16x32_bf16 v[92:95], v[146:149], v[194:197], v[92:95]
	v_mfma_f32_16x16x32_bf16 v[88:91], v[170:173], v[194:197], v[88:91]
	v_mfma_f32_16x16x32_bf16 v[76:79], v[146:149], v[202:205], v[76:79]
	v_mfma_f32_16x16x32_bf16 v[72:75], v[170:173], v[202:205], v[72:75]
	v_mfma_f32_16x16x32_bf16 v[124:127], v[160:163], v[182:185], v[124:127]
	v_mfma_f32_16x16x32_bf16 v[120:123], v[174:177], v[182:185], v[120:123]
	v_mfma_f32_16x16x32_bf16 v[108:111], v[160:163], v[190:193], v[108:111]
	v_mfma_f32_16x16x32_bf16 v[104:107], v[174:177], v[190:193], v[104:107]
	v_mfma_f32_16x16x32_bf16 v[92:95], v[160:163], v[198:201], v[92:95]
	v_mfma_f32_16x16x32_bf16 v[88:91], v[174:177], v[198:201], v[88:91]
	v_mfma_f32_16x16x32_bf16 v[76:79], v[160:163], v[206:209], v[76:79]
	v_mfma_f32_16x16x32_bf16 v[72:75], v[174:177], v[206:209], v[72:75]
	s_setprio 0
	s_barrier
	s_add_i32 s38, 0, 0x1c000
	s_add_i32 s39, s43, s55
	v_add_u32_e32 v159, s38, v153
	v_lshl_add_u64 v[150:151], v[150:151], 0, s[20:21]
	s_mov_b32 m0, s39
	ds_read_b128 v[210:213], v159
	ds_read_b128 v[214:217], v159 offset:1024
	ds_read_b128 v[218:221], v159 offset:2048
	ds_read_b128 v[222:225], v159 offset:3072
	global_load_lds_dwordx4 v[150:151], off
	v_lshl_add_u64 v[150:151], v[164:165], 0, s[20:21]
	s_add_i32 m0, s39, 0x2000
	s_nop 0
	global_load_lds_dwordx4 v[150:151], off
	s_barrier
	s_waitcnt lgkmcnt(0)
	s_setprio 1
	s_waitcnt lgkmcnt(0)
	v_mfma_f32_16x16x32_bf16 v[116:119], v[210:213], v[178:181], v[116:119]
	v_mfma_f32_16x16x32_bf16 v[112:115], v[218:221], v[178:181], v[112:115]
	v_mfma_f32_16x16x32_bf16 v[100:103], v[210:213], v[186:189], v[100:103]
	v_mfma_f32_16x16x32_bf16 v[96:99], v[218:221], v[186:189], v[96:99]
	v_mfma_f32_16x16x32_bf16 v[84:87], v[210:213], v[194:197], v[84:87]
	v_mfma_f32_16x16x32_bf16 v[80:83], v[218:221], v[194:197], v[80:83]
	v_mfma_f32_16x16x32_bf16 v[68:71], v[210:213], v[202:205], v[68:71]
	v_mfma_f32_16x16x32_bf16 v[64:67], v[218:221], v[202:205], v[64:67]
	v_mfma_f32_16x16x32_bf16 v[116:119], v[214:217], v[182:185], v[116:119]
	v_mfma_f32_16x16x32_bf16 v[112:115], v[222:225], v[182:185], v[112:115]
	v_mfma_f32_16x16x32_bf16 v[100:103], v[214:217], v[190:193], v[100:103]
	v_mfma_f32_16x16x32_bf16 v[96:99], v[222:225], v[190:193], v[96:99]
	v_mfma_f32_16x16x32_bf16 v[84:87], v[214:217], v[198:201], v[84:87]
	v_mfma_f32_16x16x32_bf16 v[80:83], v[222:225], v[198:201], v[80:83]
	v_mfma_f32_16x16x32_bf16 v[68:71], v[214:217], v[206:209], v[68:71]
	v_mfma_f32_16x16x32_bf16 v[64:67], v[222:225], v[206:209], v[64:67]
	s_setprio 0
	s_mov_b32 m0, s60
	v_lshl_add_u64 v[150:151], v[226:227], 0, s[20:21]
	s_barrier
	ds_read_b128 v[178:181], v156 offset:49152
	ds_read_b128 v[182:185], v156 offset:50176
	ds_read_b128 v[186:189], v156 offset:51200
	ds_read_b128 v[190:193], v156 offset:52224
	ds_read_b128 v[194:197], v156 offset:53248
	ds_read_b128 v[198:201], v156 offset:54272
	ds_read_b128 v[202:205], v156 offset:55296
	ds_read_b128 v[206:209], v156 offset:56320
	global_load_lds_dwordx4 v[150:151], off
	v_lshl_add_u64 v[150:151], v[228:229], 0, s[20:21]
	s_mov_b32 m0, s61
	s_nop 0
	global_load_lds_dwordx4 v[150:151], off
	s_barrier
; __device__ __forceinline__ float bflo(unsigned w) { return __uint_as_float(w << 16); }
;     ...
;             PG8_WAIT_L(8); PG8_BAR; PG8_WAIT_L(0); PG8_MMA(0, 0, At, B0); PG8_BAR; PG8_SCHED;
;             PG8_LDB(B1, 1, 1); PG8_STAGE(PG8_SB(1, 0), b3, voffB);
;             PG8_BAR; PG8_WAIT_L(0); PG8_MMA(0, 1, At, B1); PG8_BAR;
;             PG8_LDA(At, 1, 1); PG8_STAGE(PG8_SA(1, 0), a3, voffA);
;             PG8_BAR; PG8_WAIT_L(0); PG8_MMA(1, 0, At, B0); PG8_BAR; PG8_SCHED;
;             PG8_STAGE(PG8_SB(1, 1), b3 + hB, voffB);
;             PG8_WAIT_V(6); PG8_BAR; PG8_MMA(1, 1, At, B1); PG8_BAR;
;         }
;         E(acc, cur, wr, wc, fr, fq);
; __device__ __forceinline__ float row_rstd(const float* ssq, int row) {
;     const f32x4* p = (const f32x4*)(ssq + (size_t)row * 16);
;     const f32x4 a = p[0], b = p[1], c = p[2], d = p[3];
;     const float s = ((a[0] + a[1]) + (a[2] + a[3])) + ((b[0] + b[1]) + (b[2] + b[3])) + ((c[0] + c[1]) + (c[2] + c[3])) + ((d[0] + d[1]) + (d[2] + d[3]));
;     return rsqrtf(s * (1.0f / 1024.0f) + 1e-6f);
; }
; __device__ __forceinline__ u32x4 pack8(const f32x4 v0, const f32x4 v1) { u32x4 w; w.x = pk2(v0[0], v0[1]); w.y = pk2(v0[2], v0[3]); w.z = pk2(v1[0], v1[1]); w.w = pk2(v1[2], v1[3]); return w; }
; __device__ __forceinline__ void unpack8(const u32x4 w, f32x4& v0, f32x4& v1) { v0 = (f32x4){bflo(w.x), bfhi(w.x), bflo(w.y), bfhi(w.y)}; v1 = (f32x4){bflo(w.z), bfhi(w.z), bflo(w.w), bfhi(w.w)}; }
;     __device__ __forceinline__ void operator()(const f32x4 (&acc)[2][2][4][2], const Unit& u, int wr, int wc, int fr, int fq) const {
;         const int row0 = u.pm * 256 + wr * 64 + fr, col0 = u.pn * 256 + wc * 32 + 8 * fq;
; #pragma unroll
;         for (int ai = 0; ai < 2; ++ai)
; #pragma unroll
;             for (int m = 0; m < 4; ++m) {
;                 const int row = row0 + ai * 128 + m * 16; const float rs = row_rstd(ssq, row);
;                 bf16_t* rowp = O + (size_t)row * ldc + col0;
; #pragma unroll
;                 for (int bj = 0; bj < 2; ++bj) { f32x4 v0 = acc[ai][bj][m][0] * rs, v1 = acc[ai][bj][m][1] * rs;
;                     if (ACT == 1) {
; #pragma unroll
;                         for (int j = 0; j < 4; ++j) { const float a = fmaxf(v0[j], 0.f), b = fmaxf(v1[j], 0.f); v0[j] = a * a; v1[j] = b * b; } }
;                     *(u32x4*)(rowp + bj * 128) = pack8(v0, v1); }
	s_waitcnt lgkmcnt(0)
	s_setprio 1
	s_waitcnt lgkmcnt(0)
	v_mfma_f32_16x16x32_bf16 v[60:63], v[146:149], v[178:181], v[60:63]
	v_mfma_f32_16x16x32_bf16 v[56:59], v[170:173], v[178:181], v[56:59]
	v_mfma_f32_16x16x32_bf16 v[44:47], v[146:149], v[186:189], v[44:47]
	v_mfma_f32_16x16x32_bf16 v[40:43], v[170:173], v[186:189], v[40:43]
	v_mfma_f32_16x16x32_bf16 v[28:31], v[146:149], v[194:197], v[28:31]
	v_mfma_f32_16x16x32_bf16 v[24:27], v[170:173], v[194:197], v[24:27]
	v_mfma_f32_16x16x32_bf16 v[12:15], v[146:149], v[202:205], v[12:15]
	v_mfma_f32_16x16x32_bf16 v[8:11], v[170:173], v[202:205], v[8:11]
	v_mfma_f32_16x16x32_bf16 v[60:63], v[160:163], v[182:185], v[60:63]
	v_mfma_f32_16x16x32_bf16 v[56:59], v[174:177], v[182:185], v[56:59]
	v_mfma_f32_16x16x32_bf16 v[44:47], v[160:163], v[190:193], v[44:47]
	v_mfma_f32_16x16x32_bf16 v[40:43], v[174:177], v[190:193], v[40:43]
	v_mfma_f32_16x16x32_bf16 v[28:31], v[160:163], v[198:201], v[28:31]
	v_mfma_f32_16x16x32_bf16 v[24:27], v[174:177], v[198:201], v[24:27]
	v_mfma_f32_16x16x32_bf16 v[12:15], v[160:163], v[206:209], v[12:15]
	v_mfma_f32_16x16x32_bf16 v[8:11], v[174:177], v[206:209], v[8:11]
	s_setprio 0
	s_barrier
	s_add_u32 s36, s36, 0x40080
	s_addc_u32 s37, s37, 0
	s_add_i32 s38, s38, s55
	v_lshl_add_u64 v[146:147], s[36:37], 0, v[130:131]
	s_mov_b32 m0, s38
	s_nop 0
	global_load_lds_dwordx4 v[146:147], off
	v_lshl_add_u64 v[146:147], s[36:37], 0, v[134:135]
	s_add_i32 m0, s38, 0x2000
	s_nop 0
	global_load_lds_dwordx4 v[146:147], off
	s_waitcnt vmcnt(6)
	s_barrier
	s_setprio 1
	v_mfma_f32_16x16x32_bf16 v[52:55], v[210:213], v[178:181], v[52:55]
	v_mfma_f32_16x16x32_bf16 v[48:51], v[218:221], v[178:181], v[48:51]
	v_mfma_f32_16x16x32_bf16 v[36:39], v[210:213], v[186:189], v[36:39]
	v_mfma_f32_16x16x32_bf16 v[32:35], v[218:221], v[186:189], v[32:35]
	v_mfma_f32_16x16x32_bf16 v[20:23], v[210:213], v[194:197], v[20:23]
	v_mfma_f32_16x16x32_bf16 v[16:19], v[218:221], v[194:197], v[16:19]
	v_mfma_f32_16x16x32_bf16 v[4:7], v[210:213], v[202:205], v[4:7]
	v_mfma_f32_16x16x32_bf16 v[0:3], v[218:221], v[202:205], v[0:3]
	v_mfma_f32_16x16x32_bf16 v[52:55], v[214:217], v[182:185], v[52:55]
	v_mfma_f32_16x16x32_bf16 v[48:51], v[222:225], v[182:185], v[48:51]
	v_mfma_f32_16x16x32_bf16 v[36:39], v[214:217], v[190:193], v[36:39]
	v_mfma_f32_16x16x32_bf16 v[32:35], v[222:225], v[190:193], v[32:35]
	v_mfma_f32_16x16x32_bf16 v[20:23], v[214:217], v[198:201], v[20:23]
	v_mfma_f32_16x16x32_bf16 v[16:19], v[222:225], v[198:201], v[16:19]
	v_mfma_f32_16x16x32_bf16 v[4:7], v[214:217], v[206:209], v[4:7]
	v_mfma_f32_16x16x32_bf16 v[0:3], v[222:225], v[206:209], v[0:3]
	s_setprio 0
	s_add_i32 s42, s42, 2
	s_add_u32 s25, s25, 0x100
	s_addc_u32 s33, s33, 0
	s_add_u32 s34, s34, 0x100
	s_addc_u32 s35, s35, 0
	s_cmp_gt_u32 s42, 13
	s_barrier
	s_cbranch_scc0 .LBB0_1288
	v_lshl_add_u32 v150, s30, 8, v152
	v_ashrrev_i32_e32 v151, 31, v150
	v_lshlrev_b64 v[146:147], 6, v[150:151]
	v_lshl_add_u64 v[146:147], s[18:19], 0, v[146:147]
	v_subrev_u32_e32 v186, s18, v146
	v_add_u32_e32 v187, 0x0, v186
	global_load_dwordx4 v[188:191], v187, s[18:19]
	v_add_u32_e32 v187, 0x10, v186
	global_load_dwordx4 v[192:195], v187, s[18:19]
	v_add_u32_e32 v187, 0x20, v186
	global_load_dwordx4 v[196:199], v187, s[18:19]
	v_add_u32_e32 v187, 0x30, v186
	global_load_dwordx4 v[200:203], v187, s[18:19]
	v_add_u32_e32 v187, 0x400, v186
	global_load_dwordx4 v[204:207], v187, s[18:19]
	v_add_u32_e32 v187, 0x410, v186
	global_load_dwordx4 v[208:211], v187, s[18:19]
	v_add_u32_e32 v187, 0x420, v186
	global_load_dwordx4 v[212:215], v187, s[18:19]
	v_add_u32_e32 v187, 0x430, v186
	global_load_dwordx4 v[216:219], v187, s[18:19]
	v_add_u32_e32 v187, 0x800, v186
	global_load_dwordx4 v[220:223], v187, s[18:19]
	v_add_u32_e32 v187, 0x810, v186
	global_load_dwordx4 v[232:235], v187, s[18:19]
	v_add_u32_e32 v187, 0x820, v186
	global_load_dwordx4 v[236:239], v187, s[18:19]
	v_add_u32_e32 v187, 0x830, v186
	global_load_dwordx4 v[240:243], v187, s[18:19]
	v_lshl_or_b32 v148, s6, 8, v154
	v_mov_b64_e32 v[146:147], s[16:17]
	v_ashrrev_i32_e32 v149, 31, v148
	v_mad_i64_i32 v[164:165], s[6:7], v150, s66, v[146:147]
	v_or_b32_e32 v182, 16, v150
	v_lshlrev_b64 v[148:149], 1, v[148:149]
	v_ashrrev_i32_e32 v183, 31, v182
	s_mov_b32 s30, s24
	s_mov_b64 s[34:35], s[28:29]
	s_mov_b64 s[36:37], s[26:27]
	s_waitcnt vmcnt(8)
	v_pk_add_f32 v[160:161], v[188:189], v[190:191]
	v_pk_add_f32 v[170:171], v[192:193], v[194:195]
	v_pk_add_f32 v[172:173], v[196:197], v[198:199]
	v_pk_add_f32 v[174:175], v[200:201], v[202:203]
	v_pk_add_f32 v[160:161], v[160:161], v[170:171]
	v_pk_add_f32 v[172:173], v[172:173], v[174:175]
	v_pk_add_f32 v[160:161], v[160:161], v[172:173]
	v_add_f32_e32 v151, v160, v161
	s_nop 0
	s_nop 0
	v_fmamk_f32 v151, v151, 0x3a800000, v158
	s_nop 0
	s_nop 0
	v_lshl_add_u64 v[160:161], v[164:165], 0, v[148:149]
	s_nop 0
	s_nop 0
	v_rsq_f32_e32 v151, v151
	s_nop 0
	s_nop 0
	v_mov_b32_e32 v164, v151
	v_pk_mul_f32 v[126:127], v[126:127], v[164:165] op_sel_hi:[1,0]
	v_pk_mul_f32 v[124:125], v[124:125], v[164:165] op_sel_hi:[1,0]
	v_pk_mul_f32 v[122:123], v[122:123], v[164:165] op_sel_hi:[1,0]
	v_pk_mul_f32 v[120:121], v[120:121], v[164:165] op_sel_hi:[1,0]
	v_pk_mul_f32 v[118:119], v[118:119], v[164:165] op_sel_hi:[1,0]
	v_pk_mul_f32 v[116:117], v[116:117], v[164:165] op_sel_hi:[1,0]
	v_pk_mul_f32 v[170:171], v[114:115], v[164:165] op_sel_hi:[1,0]
	v_pk_mul_f32 v[164:165], v[112:113], v[164:165] op_sel_hi:[1,0]
	v_cvt_pk_bf16_f32 v112, v124, v125
	v_cvt_pk_bf16_f32 v113, v126, v127
	v_cvt_pk_bf16_f32 v114, v120, v121
	v_cvt_pk_bf16_f32 v115, v122, v123
	global_store_dwordx4 v[160:161], v[112:115], off sc1
	s_nop 1
	v_cvt_pk_bf16_f32 v112, v116, v117
	v_cvt_pk_bf16_f32 v113, v118, v119
	v_cvt_pk_bf16_f32 v114, v164, v165
	v_cvt_pk_bf16_f32 v115, v170, v171
	global_store_dwordx4 v[160:161], v[112:115], off offset:256 sc1
	s_nop 0
	v_or_b32_e32 v160, 32, v150
	v_mad_i64_i32 v[162:163], s[6:7], v182, s66, v[146:147]
	v_ashrrev_i32_e32 v161, 31, v160
	v_add_u32_e32 v187, 0xc00, v186
	global_load_dwordx4 v[188:191], v187, s[18:19]
	v_add_u32_e32 v187, 0xc10, v186
	global_load_dwordx4 v[192:195], v187, s[18:19]
	v_add_u32_e32 v187, 0xc20, v186
	global_load_dwordx4 v[196:199], v187, s[18:19]
	v_add_u32_e32 v187, 0xc30, v186
	global_load_dwordx4 v[200:203], v187, s[18:19]
	s_waitcnt vmcnt(10)
; __device__ __forceinline__ float bflo(unsigned w) { return __uint_as_float(w << 16); }
; __device__ __forceinline__ float bfhi(unsigned w) { return __uint_as_float(w & 0xffff0000u); }
; __device__ __forceinline__ unsigned pk2(float lo, float hi) { unsigned r; asm volatile("v_cvt_pk_bf16_f32 %0, %1, %2" : "=v"(r) : "v"(lo), "v"(hi)); return r; }
; __device__ __forceinline__ float row_rstd(const float* ssq, int row) {
;     const f32x4* p = (const f32x4*)(ssq + (size_t)row * 16);
;     const f32x4 a = p[0], b = p[1], c = p[2], d = p[3];
;     const float s = ((a[0] + a[1]) + (a[2] + a[3])) + ((b[0] + b[1]) + (b[2] + b[3])) + ((c[0] + c[1]) + (c[2] + c[3])) + ((d[0] + d[1]) + (d[2] + d[3]));
;     return rsqrtf(s * (1.0f / 1024.0f) + 1e-6f);
; }
; __device__ __forceinline__ u32x4 pack8(const f32x4 v0, const f32x4 v1) { u32x4 w; w.x = pk2(v0[0], v0[1]); w.y = pk2(v0[2], v0[3]); w.z = pk2(v1[0], v1[1]); w.w = pk2(v1[2], v1[3]); return w; }
; __device__ __forceinline__ void unpack8(const u32x4 w, f32x4& v0, f32x4& v1) { v0 = (f32x4){bflo(w.x), bfhi(w.x), bflo(w.y), bfhi(w.y)}; v1 = (f32x4){bflo(w.z), bfhi(w.z), bflo(w.w), bfhi(w.w)}; }
;     __device__ __forceinline__ void operator()(const f32x4 (&acc)[2][2][4][2], const Unit& u, int wr, int wc, int fr, int fq) const {
;         const int row0 = u.pm * 256 + wr * 64 + fr, col0 = u.pn * 256 + wc * 32 + 8 * fq;
; #pragma unroll
;         for (int ai = 0; ai < 2; ++ai)
; #pragma unroll
;             for (int m = 0; m < 4; ++m) {
;                 const int row = row0 + ai * 128 + m * 16; const float rs = row_rstd(ssq, row);
;                 bf16_t* rowp = O + (size_t)row * ldc + col0;
; #pragma unroll
;                 for (int bj = 0; bj < 2; ++bj) { f32x4 v0 = acc[ai][bj][m][0] * rs, v1 = acc[ai][bj][m][1] * rs;
;                     if (ACT == 1) {
; #pragma unroll
;                         for (int j = 0; j < 4; ++j) { const float a = fmaxf(v0[j], 0.f), b = fmaxf(v1[j], 0.f); v0[j] = a * a; v1[j] = b * b; } }
;                     *(u32x4*)(rowp + bj * 128) = pack8(v0, v1); }
	v_pk_add_f32 v[112:113], v[204:205], v[206:207]
	v_pk_add_f32 v[116:117], v[208:209], v[210:211]
	v_pk_add_f32 v[118:119], v[212:213], v[214:215]
	v_pk_add_f32 v[120:121], v[216:217], v[218:219]
	v_pk_add_f32 v[112:113], v[112:113], v[116:117]
	v_pk_add_f32 v[118:119], v[118:119], v[120:121]
	v_pk_add_f32 v[112:113], v[112:113], v[118:119]
	v_add_f32_e32 v112, v112, v113
	s_nop 0
	s_nop 0
	v_fmamk_f32 v112, v112, 0x3a800000, v158
	s_nop 0
	s_nop 0
	s_nop 1
	s_nop 0
	v_rsq_f32_e32 v116, v112
	v_lshl_add_u64 v[112:113], v[162:163], 0, v[148:149]
	s_nop 0
	s_nop 0
	v_pk_mul_f32 v[110:111], v[110:111], v[116:117] op_sel_hi:[1,0]
	v_pk_mul_f32 v[108:109], v[108:109], v[116:117] op_sel_hi:[1,0]
	v_pk_mul_f32 v[106:107], v[106:107], v[116:117] op_sel_hi:[1,0]
	v_pk_mul_f32 v[104:105], v[104:105], v[116:117] op_sel_hi:[1,0]
	v_pk_mul_f32 v[102:103], v[102:103], v[116:117] op_sel_hi:[1,0]
	v_pk_mul_f32 v[100:101], v[100:101], v[116:117] op_sel_hi:[1,0]
	v_pk_mul_f32 v[118:119], v[98:99], v[116:117] op_sel_hi:[1,0]
	v_pk_mul_f32 v[116:117], v[96:97], v[116:117] op_sel_hi:[1,0]
	v_cvt_pk_bf16_f32 v96, v108, v109
	v_cvt_pk_bf16_f32 v97, v110, v111
	v_cvt_pk_bf16_f32 v98, v104, v105
	v_cvt_pk_bf16_f32 v99, v106, v107
	global_store_dwordx4 v[112:113], v[96:99], off sc1
	s_nop 1
	v_cvt_pk_bf16_f32 v96, v100, v101
	v_cvt_pk_bf16_f32 v97, v102, v103
	v_cvt_pk_bf16_f32 v98, v116, v117
	v_cvt_pk_bf16_f32 v99, v118, v119
	global_store_dwordx4 v[112:113], v[96:99], off offset:256 sc1
	s_nop 0
	v_or_b32_e32 v112, 48, v150
	v_mad_i64_i32 v[114:115], s[6:7], v160, s66, v[146:147]
	v_ashrrev_i32_e32 v113, 31, v112
	v_add_u32_e32 v187, 0x2000, v186
	global_load_dwordx4 v[204:207], v187, s[18:19]
	v_add_u32_e32 v187, 0x2010, v186
	global_load_dwordx4 v[208:211], v187, s[18:19]
	v_add_u32_e32 v187, 0x2020, v186
	global_load_dwordx4 v[212:215], v187, s[18:19]
	v_add_u32_e32 v187, 0x2030, v186
	global_load_dwordx4 v[216:219], v187, s[18:19]
	s_waitcnt vmcnt(12)
	v_pk_add_f32 v[96:97], v[220:221], v[222:223]
	v_pk_add_f32 v[100:101], v[232:233], v[234:235]
	v_pk_add_f32 v[102:103], v[236:237], v[238:239]
	v_pk_add_f32 v[104:105], v[240:241], v[242:243]
	v_pk_add_f32 v[96:97], v[96:97], v[100:101]
	v_pk_add_f32 v[102:103], v[102:103], v[104:105]
	v_pk_add_f32 v[96:97], v[96:97], v[102:103]
	v_add_f32_e32 v96, v96, v97
	s_nop 0
	s_nop 0
	v_fmamk_f32 v96, v96, 0x3a800000, v158
	s_nop 0
	s_nop 0
	s_nop 1
	s_nop 0
	v_rsq_f32_e32 v100, v96
	v_lshl_add_u64 v[96:97], v[114:115], 0, v[148:149]
	s_nop 0
	s_nop 0
	v_pk_mul_f32 v[94:95], v[94:95], v[100:101] op_sel_hi:[1,0]
	v_pk_mul_f32 v[92:93], v[92:93], v[100:101] op_sel_hi:[1,0]
	v_pk_mul_f32 v[90:91], v[90:91], v[100:101] op_sel_hi:[1,0]
	v_pk_mul_f32 v[88:89], v[88:89], v[100:101] op_sel_hi:[1,0]
	v_pk_mul_f32 v[86:87], v[86:87], v[100:101] op_sel_hi:[1,0]
	v_pk_mul_f32 v[84:85], v[84:85], v[100:101] op_sel_hi:[1,0]
	v_pk_mul_f32 v[102:103], v[82:83], v[100:101] op_sel_hi:[1,0]
	v_pk_mul_f32 v[100:101], v[80:81], v[100:101] op_sel_hi:[1,0]
	v_cvt_pk_bf16_f32 v80, v92, v93
	v_cvt_pk_bf16_f32 v81, v94, v95
	v_cvt_pk_bf16_f32 v82, v88, v89
	v_cvt_pk_bf16_f32 v83, v90, v91
	global_store_dwordx4 v[96:97], v[80:83], off sc1
	s_nop 1
	v_cvt_pk_bf16_f32 v80, v84, v85
	v_cvt_pk_bf16_f32 v81, v86, v87
	v_cvt_pk_bf16_f32 v82, v100, v101
	v_cvt_pk_bf16_f32 v83, v102, v103
	global_store_dwordx4 v[96:97], v[80:83], off offset:256 sc1
	s_nop 0
	v_add_u32_e32 v96, 0x80, v150
	v_mad_i64_i32 v[98:99], s[6:7], v112, s66, v[146:147]
	v_ashrrev_i32_e32 v97, 31, v96
	v_add_u32_e32 v187, 0x2400, v186
	global_load_dwordx4 v[220:223], v187, s[18:19]
	v_add_u32_e32 v187, 0x2410, v186
	global_load_dwordx4 v[232:235], v187, s[18:19]
	v_add_u32_e32 v187, 0x2420, v186
	global_load_dwordx4 v[236:239], v187, s[18:19]
	v_add_u32_e32 v187, 0x2430, v186
	global_load_dwordx4 v[240:243], v187, s[18:19]
	s_waitcnt vmcnt(12)
	v_pk_add_f32 v[80:81], v[188:189], v[190:191]
	v_pk_add_f32 v[84:85], v[192:193], v[194:195]
	v_pk_add_f32 v[86:87], v[196:197], v[198:199]
	v_pk_add_f32 v[88:89], v[200:201], v[202:203]
	v_pk_add_f32 v[80:81], v[80:81], v[84:85]
	v_pk_add_f32 v[86:87], v[86:87], v[88:89]
	v_pk_add_f32 v[80:81], v[80:81], v[86:87]
	v_add_f32_e32 v80, v80, v81
	s_nop 0
	s_nop 0
	v_fmamk_f32 v80, v80, 0x3a800000, v158
	s_nop 0
	s_nop 0
	s_nop 1
	s_nop 0
	v_rsq_f32_e32 v84, v80
	v_lshl_add_u64 v[80:81], v[98:99], 0, v[148:149]
	s_nop 0
	s_nop 0
	v_pk_mul_f32 v[78:79], v[78:79], v[84:85] op_sel_hi:[1,0]
	v_pk_mul_f32 v[76:77], v[76:77], v[84:85] op_sel_hi:[1,0]
	v_pk_mul_f32 v[74:75], v[74:75], v[84:85] op_sel_hi:[1,0]
	v_pk_mul_f32 v[72:73], v[72:73], v[84:85] op_sel_hi:[1,0]
	v_pk_mul_f32 v[70:71], v[70:71], v[84:85] op_sel_hi:[1,0]
	v_pk_mul_f32 v[68:69], v[68:69], v[84:85] op_sel_hi:[1,0]
	v_pk_mul_f32 v[86:87], v[66:67], v[84:85] op_sel_hi:[1,0]
	v_pk_mul_f32 v[84:85], v[64:65], v[84:85] op_sel_hi:[1,0]
	v_cvt_pk_bf16_f32 v64, v76, v77
	v_cvt_pk_bf16_f32 v65, v78, v79
	v_cvt_pk_bf16_f32 v66, v72, v73
	v_cvt_pk_bf16_f32 v67, v74, v75
	global_store_dwordx4 v[80:81], v[64:67], off sc1
	s_nop 1
	v_cvt_pk_bf16_f32 v64, v68, v69
	v_cvt_pk_bf16_f32 v65, v70, v71
	v_cvt_pk_bf16_f32 v66, v84, v85
	v_cvt_pk_bf16_f32 v67, v86, v87
	global_store_dwordx4 v[80:81], v[64:67], off offset:256 sc1
	s_nop 0
	v_add_u32_e32 v80, 0x90, v150
	v_mad_i64_i32 v[82:83], s[6:7], v96, s66, v[146:147]
	v_ashrrev_i32_e32 v81, 31, v80
	v_add_u32_e32 v187, 0x2800, v186
	global_load_dwordx4 v[188:191], v187, s[18:19]
	v_add_u32_e32 v187, 0x2810, v186
	global_load_dwordx4 v[192:195], v187, s[18:19]
	v_add_u32_e32 v187, 0x2820, v186
	global_load_dwordx4 v[196:199], v187, s[18:19]
	v_add_u32_e32 v187, 0x2830, v186
	global_load_dwordx4 v[200:203], v187, s[18:19]
	s_waitcnt vmcnt(12)
; __device__ __forceinline__ float bflo(unsigned w) { return __uint_as_float(w << 16); }
; __device__ __forceinline__ float bfhi(unsigned w) { return __uint_as_float(w & 0xffff0000u); }
; __device__ __forceinline__ unsigned pk2(float lo, float hi) { unsigned r; asm volatile("v_cvt_pk_bf16_f32 %0, %1, %2" : "=v"(r) : "v"(lo), "v"(hi)); return r; }
; __device__ __forceinline__ float row_rstd(const float* ssq, int row) {
;     const f32x4* p = (const f32x4*)(ssq + (size_t)row * 16);
;     const f32x4 a = p[0], b = p[1], c = p[2], d = p[3];
;     const float s = ((a[0] + a[1]) + (a[2] + a[3])) + ((b[0] + b[1]) + (b[2] + b[3])) + ((c[0] + c[1]) + (c[2] + c[3])) + ((d[0] + d[1]) + (d[2] + d[3]));
;     return rsqrtf(s * (1.0f / 1024.0f) + 1e-6f);
; }
; __device__ __forceinline__ u32x4 pack8(const f32x4 v0, const f32x4 v1) { u32x4 w; w.x = pk2(v0[0], v0[1]); w.y = pk2(v0[2], v0[3]); w.z = pk2(v1[0], v1[1]); w.w = pk2(v1[2], v1[3]); return w; }
; __device__ __forceinline__ void unpack8(const u32x4 w, f32x4& v0, f32x4& v1) { v0 = (f32x4){bflo(w.x), bfhi(w.x), bflo(w.y), bfhi(w.y)}; v1 = (f32x4){bflo(w.z), bfhi(w.z), bflo(w.w), bfhi(w.w)}; }
;     __device__ __forceinline__ void operator()(const f32x4 (&acc)[2][2][4][2], const Unit& u, int wr, int wc, int fr, int fq) const {
;         const int row0 = u.pm * 256 + wr * 64 + fr, col0 = u.pn * 256 + wc * 32 + 8 * fq;
; #pragma unroll
;         for (int ai = 0; ai < 2; ++ai)
; #pragma unroll
;             for (int m = 0; m < 4; ++m) {
;                 const int row = row0 + ai * 128 + m * 16; const float rs = row_rstd(ssq, row);
;                 bf16_t* rowp = O + (size_t)row * ldc + col0;
; #pragma unroll
;                 for (int bj = 0; bj < 2; ++bj) { f32x4 v0 = acc[ai][bj][m][0] * rs, v1 = acc[ai][bj][m][1] * rs;
;                     if (ACT == 1) {
; #pragma unroll
;                         for (int j = 0; j < 4; ++j) { const float a = fmaxf(v0[j], 0.f), b = fmaxf(v1[j], 0.f); v0[j] = a * a; v1[j] = b * b; } }
;                     *(u32x4*)(rowp + bj * 128) = pack8(v0, v1); }
	v_pk_add_f32 v[64:65], v[204:205], v[206:207]
	v_pk_add_f32 v[68:69], v[208:209], v[210:211]
	v_pk_add_f32 v[70:71], v[212:213], v[214:215]
	v_pk_add_f32 v[72:73], v[216:217], v[218:219]
	v_pk_add_f32 v[64:65], v[64:65], v[68:69]
	v_pk_add_f32 v[70:71], v[70:71], v[72:73]
	v_pk_add_f32 v[64:65], v[64:65], v[70:71]
	v_add_f32_e32 v64, v64, v65
	s_nop 0
	s_nop 0
	v_fmamk_f32 v64, v64, 0x3a800000, v158
	s_nop 0
	s_nop 0
	s_nop 1
	s_nop 0
	v_rsq_f32_e32 v68, v64
	v_lshl_add_u64 v[64:65], v[82:83], 0, v[148:149]
	s_nop 0
	s_nop 0
	v_pk_mul_f32 v[62:63], v[62:63], v[68:69] op_sel_hi:[1,0]
	v_pk_mul_f32 v[60:61], v[60:61], v[68:69] op_sel_hi:[1,0]
	v_pk_mul_f32 v[58:59], v[58:59], v[68:69] op_sel_hi:[1,0]
	v_pk_mul_f32 v[56:57], v[56:57], v[68:69] op_sel_hi:[1,0]
	v_pk_mul_f32 v[54:55], v[54:55], v[68:69] op_sel_hi:[1,0]
	v_pk_mul_f32 v[52:53], v[52:53], v[68:69] op_sel_hi:[1,0]
	v_pk_mul_f32 v[70:71], v[50:51], v[68:69] op_sel_hi:[1,0]
	v_pk_mul_f32 v[68:69], v[48:49], v[68:69] op_sel_hi:[1,0]
	v_cvt_pk_bf16_f32 v48, v60, v61
	v_cvt_pk_bf16_f32 v49, v62, v63
	v_cvt_pk_bf16_f32 v50, v56, v57
	v_cvt_pk_bf16_f32 v51, v58, v59
	global_store_dwordx4 v[64:65], v[48:51], off sc1
	s_nop 1
	v_cvt_pk_bf16_f32 v48, v52, v53
	v_cvt_pk_bf16_f32 v49, v54, v55
	v_cvt_pk_bf16_f32 v50, v68, v69
	v_cvt_pk_bf16_f32 v51, v70, v71
	global_store_dwordx4 v[64:65], v[48:51], off offset:256 sc1
	s_nop 0
	v_add_u32_e32 v64, 0xa0, v150
	v_mad_i64_i32 v[66:67], s[6:7], v80, s66, v[146:147]
	v_ashrrev_i32_e32 v65, 31, v64
	v_add_u32_e32 v187, 0x2c00, v186
	global_load_dwordx4 v[204:207], v187, s[18:19]
	v_add_u32_e32 v187, 0x2c10, v186
	global_load_dwordx4 v[208:211], v187, s[18:19]
	v_add_u32_e32 v187, 0x2c20, v186
	global_load_dwordx4 v[212:215], v187, s[18:19]
	v_add_u32_e32 v187, 0x2c30, v186
	global_load_dwordx4 v[216:219], v187, s[18:19]
	s_waitcnt vmcnt(12)
	v_pk_add_f32 v[48:49], v[220:221], v[222:223]
	v_pk_add_f32 v[52:53], v[232:233], v[234:235]
	v_pk_add_f32 v[54:55], v[236:237], v[238:239]
	v_pk_add_f32 v[56:57], v[240:241], v[242:243]
	v_pk_add_f32 v[48:49], v[48:49], v[52:53]
	v_pk_add_f32 v[54:55], v[54:55], v[56:57]
	v_pk_add_f32 v[48:49], v[48:49], v[54:55]
	v_add_f32_e32 v48, v48, v49
	s_nop 0
	s_nop 0
	v_fmamk_f32 v48, v48, 0x3a800000, v158
	s_nop 0
	s_nop 0
	s_nop 1
	s_nop 0
	v_rsq_f32_e32 v52, v48
	v_lshl_add_u64 v[48:49], v[66:67], 0, v[148:149]
	s_nop 0
	s_nop 0
	v_pk_mul_f32 v[46:47], v[46:47], v[52:53] op_sel_hi:[1,0]
	v_pk_mul_f32 v[44:45], v[44:45], v[52:53] op_sel_hi:[1,0]
	v_pk_mul_f32 v[42:43], v[42:43], v[52:53] op_sel_hi:[1,0]
	v_pk_mul_f32 v[40:41], v[40:41], v[52:53] op_sel_hi:[1,0]
	v_pk_mul_f32 v[38:39], v[38:39], v[52:53] op_sel_hi:[1,0]
	v_pk_mul_f32 v[36:37], v[36:37], v[52:53] op_sel_hi:[1,0]
	v_pk_mul_f32 v[54:55], v[34:35], v[52:53] op_sel_hi:[1,0]
	v_pk_mul_f32 v[52:53], v[32:33], v[52:53] op_sel_hi:[1,0]
	v_cvt_pk_bf16_f32 v32, v44, v45
	v_cvt_pk_bf16_f32 v33, v46, v47
	v_cvt_pk_bf16_f32 v34, v40, v41
	v_cvt_pk_bf16_f32 v35, v42, v43
	global_store_dwordx4 v[48:49], v[32:35], off sc1
	s_nop 1
	v_cvt_pk_bf16_f32 v32, v36, v37
	v_cvt_pk_bf16_f32 v33, v38, v39
	v_cvt_pk_bf16_f32 v34, v52, v53
	v_cvt_pk_bf16_f32 v35, v54, v55
	global_store_dwordx4 v[48:49], v[32:35], off offset:256 sc1
	s_nop 0
	v_add_u32_e32 v48, 0xb0, v150
	v_mad_i64_i32 v[50:51], s[6:7], v64, s66, v[146:147]
	v_ashrrev_i32_e32 v49, 31, v48
	s_mov_b32 s6, s22
	s_waitcnt vmcnt(8)
	v_pk_add_f32 v[32:33], v[188:189], v[190:191]
	v_pk_add_f32 v[36:37], v[192:193], v[194:195]
	v_pk_add_f32 v[38:39], v[196:197], v[198:199]
	v_pk_add_f32 v[40:41], v[200:201], v[202:203]
	v_pk_add_f32 v[32:33], v[32:33], v[36:37]
	v_pk_add_f32 v[38:39], v[38:39], v[40:41]
	v_pk_add_f32 v[32:33], v[32:33], v[38:39]
	v_add_f32_e32 v32, v32, v33
	v_lshlrev_b64 v[34:35], 6, v[48:49]
	v_lshl_add_u64 v[34:35], s[18:19], 0, v[34:35]
	v_fmamk_f32 v32, v32, 0x3a800000, v158
	s_nop 0
	s_nop 0
	s_nop 1
	s_nop 0
	v_rsq_f32_e32 v36, v32
	v_lshl_add_u64 v[32:33], v[50:51], 0, v[148:149]
	s_nop 0
	s_nop 0
	v_pk_mul_f32 v[30:31], v[30:31], v[36:37] op_sel_hi:[1,0]
	v_pk_mul_f32 v[28:29], v[28:29], v[36:37] op_sel_hi:[1,0]
	v_pk_mul_f32 v[26:27], v[26:27], v[36:37] op_sel_hi:[1,0]
	v_pk_mul_f32 v[24:25], v[24:25], v[36:37] op_sel_hi:[1,0]
	v_pk_mul_f32 v[22:23], v[22:23], v[36:37] op_sel_hi:[1,0]
	v_pk_mul_f32 v[20:21], v[20:21], v[36:37] op_sel_hi:[1,0]
	v_pk_mul_f32 v[38:39], v[18:19], v[36:37] op_sel_hi:[1,0]
	v_pk_mul_f32 v[36:37], v[16:17], v[36:37] op_sel_hi:[1,0]
	v_cvt_pk_bf16_f32 v16, v28, v29
	v_cvt_pk_bf16_f32 v17, v30, v31
	v_cvt_pk_bf16_f32 v18, v24, v25
	v_cvt_pk_bf16_f32 v19, v26, v27
	global_store_dwordx4 v[32:33], v[16:19], off sc1
	s_and_b64 vcc, exec, s[10:11]
	s_nop 0
	v_cvt_pk_bf16_f32 v16, v20, v21
	v_cvt_pk_bf16_f32 v17, v22, v23
	v_cvt_pk_bf16_f32 v18, v36, v37
	v_cvt_pk_bf16_f32 v19, v38, v39
	global_store_dwordx4 v[32:33], v[16:19], off offset:256 sc1
	s_nop 0
	s_waitcnt vmcnt(4)
	v_pk_add_f32 v[16:17], v[204:205], v[206:207]
	v_pk_add_f32 v[18:19], v[208:209], v[210:211]
	v_pk_add_f32 v[20:21], v[212:213], v[214:215]
	v_pk_add_f32 v[22:23], v[216:217], v[218:219]
	v_pk_add_f32 v[16:17], v[16:17], v[18:19]
	v_pk_add_f32 v[20:21], v[20:21], v[22:23]
	v_pk_add_f32 v[16:17], v[16:17], v[20:21]
	v_add_f32_e32 v16, v16, v17
	s_nop 0
	s_nop 0
	v_fmamk_f32 v16, v16, 0x3a800000, v158
	v_mul_f32_e32 v17, 0x4b800000, v16
	v_cmp_gt_f32_e64 s[10:11], s65, v16
	s_nop 1
	v_cndmask_b32_e64 v16, v16, v17, s[10:11]
	v_rsq_f32_e32 v18, v16
	v_mad_i64_i32 v[16:17], s[8:9], v48, s66, v[146:147]
	v_lshl_add_u64 v[16:17], v[16:17], 0, v[148:149]
	v_mul_f32_e32 v19, 0x45800000, v18
	v_cndmask_b32_e64 v18, v18, v19, s[10:11]
	v_pk_mul_f32 v[14:15], v[14:15], v[18:19] op_sel_hi:[1,0]
	v_pk_mul_f32 v[12:13], v[12:13], v[18:19] op_sel_hi:[1,0]
	v_pk_mul_f32 v[10:11], v[10:11], v[18:19] op_sel_hi:[1,0]
	v_pk_mul_f32 v[8:9], v[8:9], v[18:19] op_sel_hi:[1,0]
	v_pk_mul_f32 v[6:7], v[6:7], v[18:19] op_sel_hi:[1,0]
	v_pk_mul_f32 v[4:5], v[4:5], v[18:19] op_sel_hi:[1,0]
	v_pk_mul_f32 v[20:21], v[2:3], v[18:19] op_sel_hi:[1,0]
	v_pk_mul_f32 v[18:19], v[0:1], v[18:19] op_sel_hi:[1,0]
	v_cvt_pk_bf16_f32 v0, v12, v13
	v_cvt_pk_bf16_f32 v1, v14, v15
	v_cvt_pk_bf16_f32 v2, v8, v9
	v_cvt_pk_bf16_f32 v3, v10, v11
	global_store_dwordx4 v[16:17], v[0:3], off sc1
	s_nop 1
	v_cvt_pk_bf16_f32 v0, v4, v5
	v_cvt_pk_bf16_f32 v1, v6, v7
	v_cvt_pk_bf16_f32 v2, v18, v19
	v_cvt_pk_bf16_f32 v3, v20, v21
	global_store_dwordx4 v[16:17], v[0:3], off offset:256 sc1
	s_cbranch_vccz .LBB0_1281
	s_waitcnt vmcnt(0)
	s_cmpk_gt_u32 s53, 0xff
	s_cbranch_scc1 .LBB0_1292
	s_barrier

; #define PG8_STAGE(bufoff, gbase, voff) do { _Pragma("unroll") for (int _i = 0; _i < 2; ++_i) \
;         __builtin_amdgcn_global_load_lds((const unsigned*)((const char*)(gbase) + (voff)[_i]), (LAS unsigned*)(lds + (bufoff) + ldsw + _i * 8192), 16, 0, 0); } while (0)
; #define PG8_LDA(dst, b, h) do { _Pragma("unroll") for (int m = 0; m < 4; ++m) _Pragma("unroll") for (int k = 0; k < 2; ++k) dst[m][k] = *(const LAS bf16x8*)(lds + PG8_SA(b, h) + aoff + m * 2048 + k * 1024); } while (0)
; #define PG8_LDB(dst, b, h) do { _Pragma("unroll") for (int n = 0; n < 2; ++n) _Pragma("unroll") for (int k = 0; k < 2; ++k) dst[n][k] = *(const LAS bf16x8*)(lds + PG8_SB(b, h) + boff + n * 2048 + k * 1024); } while (0)
; #define PG8_MMA(ai, bj, At, Bt) do { __builtin_amdgcn_s_setprio(1); _Pragma("unroll") for (int m = 0; m < 4; ++m) _Pragma("unroll") for (int n = 0; n < 2; ++n) _Pragma("unroll") for (int k = 0; k < 2; ++k) \
;         acc[ai][bj][m][n] = __builtin_amdgcn_mfma_f32_16x16x32_bf16(Bt[n][k], At[m][k], acc[ai][bj][m][n], 0, 0, 0); __builtin_amdgcn_s_setprio(0); } while (0)
; #define PG8_WAIT_V(n) asm volatile("s_waitcnt vmcnt(" #n ")" ::: "memory")
;     ...
;         for (int t = 0; t < nt; t += 2) {
;             const bool last = (t == nt - 2);
;             const char* a1 = cA + (size_t)(t + 1) * kstep;
;             const char* a2 = last ? nA : cA + (size_t)(t + 2) * kstep; const char* b2 = last ? nB : cB + (size_t)(t + 2) * kstep;
;             const char* a3 = a2 + kstep; const char* b3 = b2 + kstep;
;             if (last && has_next) PG8_A_READY(nxt);
;             PG8_LDB(B0, 0, 0); PG8_SCHED; PG8_LDA(At, 0, 0); PG8_STAGE(PG8_SA(1, 1), a1 + hA, voffA);
;             PG8_WAIT_L(8); PG8_BAR; PG8_WAIT_L(0); PG8_MMA(0, 0, At, B0); PG8_BAR; PG8_SCHED;
;             PG8_LDB(B1, 0, 1); PG8_STAGE(PG8_SB(0, 0), b2, voffB);
;             PG8_BAR; PG8_WAIT_L(0); PG8_MMA(0, 1, At, B1); PG8_BAR;
;             PG8_LDA(At, 0, 1); PG8_STAGE(PG8_SA(0, 0), a2, voffA);
;             PG8_BAR; PG8_WAIT_L(0); PG8_MMA(1, 0, At, B0); PG8_BAR; PG8_SCHED;
;             PG8_STAGE(PG8_SB(0, 1), b2 + hB, voffB);
;             PG8_WAIT_V(6); PG8_BAR; PG8_MMA(1, 1, At, B1); PG8_BAR;
;             PG8_LDB(B0, 1, 0); PG8_SCHED; PG8_LDA(At, 1, 0); PG8_STAGE(PG8_SA(0, 1), a2 + hA, voffA);
;             PG8_WAIT_L(8); PG8_BAR; PG8_WAIT_L(0); PG8_MMA(0, 0, At, B0); PG8_BAR; PG8_SCHED;
.LBB0_2099:
	ds_read_b128 v[156:159], v151
	ds_read_b128 v[160:163], v151 offset:1024
	ds_read_b128 v[170:173], v151 offset:2048
	ds_read_b128 v[174:177], v151 offset:3072
	s_add_u32 s38, s36, 0xfffc0080
	s_addc_u32 s39, s37, -1
	s_cmp_eq_u32 s71, 12
	s_cselect_b32 s41, s25, s39
	s_cselect_b32 s40, s44, s38
	s_cselect_b32 s39, s35, s70
	s_cselect_b32 s38, s45, s69
	v_lshl_add_u64 v[146:147], s[36:37], 0, v[138:139]
	s_add_i32 m0, s53, 0xc000
	ds_read_b128 v[178:181], v152
	ds_read_b128 v[182:185], v152 offset:1024
	ds_read_b128 v[186:189], v152 offset:2048
	ds_read_b128 v[190:193], v152 offset:3072
	ds_read_b128 v[194:197], v152 offset:4096
	ds_read_b128 v[198:201], v152 offset:5120
	ds_read_b128 v[202:205], v152 offset:6144
	ds_read_b128 v[206:209], v152 offset:7168
	global_load_lds_dwordx4 v[146:147], off
	v_lshl_add_u64 v[146:147], s[36:37], 0, v[136:137]
	s_add_i32 m0, s53, 0xe000
	s_nop 0
	global_load_lds_dwordx4 v[146:147], off
	s_waitcnt lgkmcnt(8)
	s_barrier
	s_waitcnt lgkmcnt(0)
	s_setprio 1
	s_waitcnt lgkmcnt(0)
	v_mfma_f32_16x16x32_bf16 v[124:127], v[156:159], v[178:181], v[124:127]
	v_mfma_f32_16x16x32_bf16 v[120:123], v[170:173], v[178:181], v[120:123]
	v_mfma_f32_16x16x32_bf16 v[108:111], v[156:159], v[186:189], v[108:111]
	v_mfma_f32_16x16x32_bf16 v[104:107], v[170:173], v[186:189], v[104:107]
	v_mfma_f32_16x16x32_bf16 v[92:95], v[156:159], v[194:197], v[92:95]
	v_mfma_f32_16x16x32_bf16 v[88:91], v[170:173], v[194:197], v[88:91]
	v_mfma_f32_16x16x32_bf16 v[76:79], v[156:159], v[202:205], v[76:79]
	v_mfma_f32_16x16x32_bf16 v[72:75], v[170:173], v[202:205], v[72:75]
	v_mfma_f32_16x16x32_bf16 v[124:127], v[160:163], v[182:185], v[124:127]
	v_mfma_f32_16x16x32_bf16 v[120:123], v[174:177], v[182:185], v[120:123]
	v_mfma_f32_16x16x32_bf16 v[108:111], v[160:163], v[190:193], v[108:111]
	v_mfma_f32_16x16x32_bf16 v[104:107], v[174:177], v[190:193], v[104:107]
	v_mfma_f32_16x16x32_bf16 v[92:95], v[160:163], v[198:201], v[92:95]
	v_mfma_f32_16x16x32_bf16 v[88:91], v[174:177], v[198:201], v[88:91]
	v_mfma_f32_16x16x32_bf16 v[76:79], v[160:163], v[206:209], v[76:79]
	v_mfma_f32_16x16x32_bf16 v[72:75], v[174:177], v[206:209], v[72:75]
	s_setprio 0
	s_barrier
	s_add_i32 s72, s61, s52
	v_lshl_add_u64 v[146:147], s[38:39], 0, v[130:131]
	s_mov_b32 m0, s72
	ds_read_b128 v[210:213], v153
	ds_read_b128 v[214:217], v153 offset:1024
	ds_read_b128 v[218:221], v153 offset:2048
	ds_read_b128 v[222:225], v153 offset:3072
	global_load_lds_dwordx4 v[146:147], off
	v_lshl_add_u64 v[164:165], s[38:39], 0, v[134:135]
	s_add_i32 m0, s72, 0x2000
	s_nop 0
	global_load_lds_dwordx4 v[164:165], off
	s_barrier
	s_waitcnt lgkmcnt(0)
	s_setprio 1
	s_waitcnt lgkmcnt(0)
	v_mfma_f32_16x16x32_bf16 v[116:119], v[210:213], v[178:181], v[116:119]
	v_mfma_f32_16x16x32_bf16 v[112:115], v[218:221], v[178:181], v[112:115]
	v_mfma_f32_16x16x32_bf16 v[100:103], v[210:213], v[186:189], v[100:103]
	v_mfma_f32_16x16x32_bf16 v[96:99], v[218:221], v[186:189], v[96:99]
	v_mfma_f32_16x16x32_bf16 v[84:87], v[210:213], v[194:197], v[84:87]
	v_mfma_f32_16x16x32_bf16 v[80:83], v[218:221], v[194:197], v[80:83]
	v_mfma_f32_16x16x32_bf16 v[68:71], v[210:213], v[202:205], v[68:71]
	v_mfma_f32_16x16x32_bf16 v[64:67], v[218:221], v[202:205], v[64:67]
	v_mfma_f32_16x16x32_bf16 v[116:119], v[214:217], v[182:185], v[116:119]
	v_mfma_f32_16x16x32_bf16 v[112:115], v[222:225], v[182:185], v[112:115]
	v_mfma_f32_16x16x32_bf16 v[100:103], v[214:217], v[190:193], v[100:103]
	v_mfma_f32_16x16x32_bf16 v[96:99], v[222:225], v[190:193], v[96:99]
	v_mfma_f32_16x16x32_bf16 v[84:87], v[214:217], v[198:201], v[84:87]
	v_mfma_f32_16x16x32_bf16 v[80:83], v[222:225], v[198:201], v[80:83]
	v_mfma_f32_16x16x32_bf16 v[68:71], v[214:217], v[206:209], v[68:71]
	v_mfma_f32_16x16x32_bf16 v[64:67], v[222:225], v[206:209], v[64:67]
	s_setprio 0
	s_mov_b32 m0, s53
	v_lshl_add_u64 v[226:227], s[40:41], 0, v[128:129]
	s_barrier
	ds_read_b128 v[178:181], v152 offset:16384
	ds_read_b128 v[182:185], v152 offset:17408
	ds_read_b128 v[186:189], v152 offset:18432
	ds_read_b128 v[190:193], v152 offset:19456
	ds_read_b128 v[194:197], v152 offset:20480
	ds_read_b128 v[198:201], v152 offset:21504
	ds_read_b128 v[202:205], v152 offset:22528
	ds_read_b128 v[206:209], v152 offset:23552
	global_load_lds_dwordx4 v[226:227], off
	v_lshl_add_u64 v[228:229], s[40:41], 0, v[132:133]
	s_mov_b32 m0, s54
	s_nop 0
	global_load_lds_dwordx4 v[228:229], off
	s_barrier
	s_waitcnt lgkmcnt(0)
	s_setprio 1
	s_waitcnt lgkmcnt(0)
	v_mfma_f32_16x16x32_bf16 v[60:63], v[156:159], v[178:181], v[60:63]
	v_mfma_f32_16x16x32_bf16 v[56:59], v[170:173], v[178:181], v[56:59]
	v_mfma_f32_16x16x32_bf16 v[44:47], v[156:159], v[186:189], v[44:47]
	v_mfma_f32_16x16x32_bf16 v[40:43], v[170:173], v[186:189], v[40:43]
	v_mfma_f32_16x16x32_bf16 v[28:31], v[156:159], v[194:197], v[28:31]
	v_mfma_f32_16x16x32_bf16 v[24:27], v[170:173], v[194:197], v[24:27]
	v_mfma_f32_16x16x32_bf16 v[12:15], v[156:159], v[202:205], v[12:15]
	v_mfma_f32_16x16x32_bf16 v[8:11], v[170:173], v[202:205], v[8:11]
	v_mfma_f32_16x16x32_bf16 v[60:63], v[160:163], v[182:185], v[60:63]
	v_mfma_f32_16x16x32_bf16 v[56:59], v[174:177], v[182:185], v[56:59]
	v_mfma_f32_16x16x32_bf16 v[44:47], v[160:163], v[190:193], v[44:47]
	v_mfma_f32_16x16x32_bf16 v[40:43], v[174:177], v[190:193], v[40:43]
	v_mfma_f32_16x16x32_bf16 v[28:31], v[160:163], v[198:201], v[28:31]
	v_mfma_f32_16x16x32_bf16 v[24:27], v[174:177], v[198:201], v[24:27]
	v_mfma_f32_16x16x32_bf16 v[12:15], v[160:163], v[206:209], v[12:15]
	v_mfma_f32_16x16x32_bf16 v[8:11], v[174:177], v[206:209], v[8:11]
	s_setprio 0
	s_barrier
; #define PG8_STAGE(bufoff, gbase, voff) do { _Pragma("unroll") for (int _i = 0; _i < 2; ++_i) \
;         __builtin_amdgcn_global_load_lds((const unsigned*)((const char*)(gbase) + (voff)[_i]), (LAS unsigned*)(lds + (bufoff) + ldsw + _i * 8192), 16, 0, 0); } while (0)
; #define PG8_LDA(dst, b, h) do { _Pragma("unroll") for (int m = 0; m < 4; ++m) _Pragma("unroll") for (int k = 0; k < 2; ++k) dst[m][k] = *(const LAS bf16x8*)(lds + PG8_SA(b, h) + aoff + m * 2048 + k * 1024); } while (0)
; #define PG8_LDB(dst, b, h) do { _Pragma("unroll") for (int n = 0; n < 2; ++n) _Pragma("unroll") for (int k = 0; k < 2; ++k) dst[n][k] = *(const LAS bf16x8*)(lds + PG8_SB(b, h) + boff + n * 2048 + k * 1024); } while (0)
; #define PG8_MMA(ai, bj, At, Bt) do { __builtin_amdgcn_s_setprio(1); _Pragma("unroll") for (int m = 0; m < 4; ++m) _Pragma("unroll") for (int n = 0; n < 2; ++n) _Pragma("unroll") for (int k = 0; k < 2; ++k) \
;         acc[ai][bj][m][n] = __builtin_amdgcn_mfma_f32_16x16x32_bf16(Bt[n][k], At[m][k], acc[ai][bj][m][n], 0, 0, 0); __builtin_amdgcn_s_setprio(0); } while (0)
; #define PG8_WAIT_V(n) asm volatile("s_waitcnt vmcnt(" #n ")" ::: "memory")
; #define PG8_WAIT_L(n) asm volatile("s_waitcnt lgkmcnt(" #n ")" ::: "memory")
; #define PG8_BAR __builtin_amdgcn_s_barrier()
; #define PG8_SCHED __builtin_amdgcn_sched_barrier(0)
;     ...
;             PG8_LDA(At, 0, 1); PG8_STAGE(PG8_SA(0, 0), a2, voffA);
;             PG8_BAR; PG8_WAIT_L(0); PG8_MMA(1, 0, At, B0); PG8_BAR; PG8_SCHED;
;             PG8_STAGE(PG8_SB(0, 1), b2 + hB, voffB);
;             PG8_WAIT_V(6); PG8_BAR; PG8_MMA(1, 1, At, B1); PG8_BAR;
;             PG8_LDB(B0, 1, 0); PG8_SCHED; PG8_LDA(At, 1, 0); PG8_STAGE(PG8_SA(0, 1), a2 + hA, voffA);
;             PG8_WAIT_L(8); PG8_BAR; PG8_WAIT_L(0); PG8_MMA(0, 0, At, B0); PG8_BAR; PG8_SCHED;
;             PG8_LDB(B1, 1, 1); PG8_STAGE(PG8_SB(1, 0), b3, voffB);
;             PG8_BAR; PG8_WAIT_L(0); PG8_MMA(0, 1, At, B1); PG8_BAR;
;             PG8_LDA(At, 1, 1); PG8_STAGE(PG8_SA(1, 0), a3, voffA);
;             PG8_BAR; PG8_WAIT_L(0); PG8_MMA(1, 0, At, B0); PG8_BAR; PG8_SCHED;
	s_add_u32 s72, s38, 0x40000
	s_addc_u32 s73, s39, 0
	s_add_i32 s74, s62, s52
	v_lshl_add_u64 v[156:157], s[72:73], 0, v[130:131]
	s_mov_b32 m0, s74
	s_nop 0
	global_load_lds_dwordx4 v[156:157], off
	v_lshl_add_u64 v[156:157], s[72:73], 0, v[134:135]
	s_add_i32 m0, s74, 0x2000
	s_nop 0
	global_load_lds_dwordx4 v[156:157], off
	s_waitcnt vmcnt(6)
	s_barrier
	s_setprio 1
	v_mfma_f32_16x16x32_bf16 v[52:55], v[210:213], v[178:181], v[52:55]
	v_mfma_f32_16x16x32_bf16 v[48:51], v[218:221], v[178:181], v[48:51]
	v_mfma_f32_16x16x32_bf16 v[36:39], v[210:213], v[186:189], v[36:39]
	v_mfma_f32_16x16x32_bf16 v[32:35], v[218:221], v[186:189], v[32:35]
	v_mfma_f32_16x16x32_bf16 v[20:23], v[210:213], v[194:197], v[20:23]
	v_mfma_f32_16x16x32_bf16 v[16:19], v[218:221], v[194:197], v[16:19]
	v_mfma_f32_16x16x32_bf16 v[4:7], v[210:213], v[202:205], v[4:7]
	v_mfma_f32_16x16x32_bf16 v[0:3], v[218:221], v[202:205], v[0:3]
	v_mfma_f32_16x16x32_bf16 v[52:55], v[214:217], v[182:185], v[52:55]
	v_mfma_f32_16x16x32_bf16 v[48:51], v[222:225], v[182:185], v[48:51]
	v_mfma_f32_16x16x32_bf16 v[36:39], v[214:217], v[190:193], v[36:39]
	v_mfma_f32_16x16x32_bf16 v[32:35], v[222:225], v[190:193], v[32:35]
	v_mfma_f32_16x16x32_bf16 v[20:23], v[214:217], v[198:201], v[20:23]
	v_mfma_f32_16x16x32_bf16 v[16:19], v[222:225], v[198:201], v[16:19]
	v_mfma_f32_16x16x32_bf16 v[4:7], v[214:217], v[206:209], v[4:7]
	v_mfma_f32_16x16x32_bf16 v[0:3], v[222:225], v[206:209], v[0:3]
	s_setprio 0
	s_add_i32 s72, 0, 0x18000
	v_add_u32_e32 v155, s72, v149
	s_barrier
	ds_read_b128 v[156:159], v155
	ds_read_b128 v[160:163], v155 offset:1024
	ds_read_b128 v[170:173], v155 offset:2048
	ds_read_b128 v[174:177], v155 offset:3072
	s_add_u32 s40, s40, 0x40000
	s_addc_u32 s41, s41, 0
	s_mov_b32 m0, s55
	v_lshl_add_u64 v[210:211], s[40:41], 0, v[128:129]
	ds_read_b128 v[178:181], v152 offset:32768
	ds_read_b128 v[182:185], v152 offset:33792
	ds_read_b128 v[186:189], v152 offset:34816
	ds_read_b128 v[190:193], v152 offset:35840
	ds_read_b128 v[194:197], v152 offset:36864
	ds_read_b128 v[198:201], v152 offset:37888
	ds_read_b128 v[202:205], v152 offset:38912
	ds_read_b128 v[206:209], v152 offset:39936
	global_load_lds_dwordx4 v[210:211], off
	v_lshl_add_u64 v[210:211], s[40:41], 0, v[132:133]
	s_mov_b32 m0, s56
	s_nop 0
	global_load_lds_dwordx4 v[210:211], off
	s_waitcnt lgkmcnt(8)
	s_barrier
	s_waitcnt lgkmcnt(0)
	s_setprio 1
	s_waitcnt lgkmcnt(0)
	v_mfma_f32_16x16x32_bf16 v[124:127], v[156:159], v[178:181], v[124:127]
	v_mfma_f32_16x16x32_bf16 v[120:123], v[170:173], v[178:181], v[120:123]
	v_mfma_f32_16x16x32_bf16 v[108:111], v[156:159], v[186:189], v[108:111]
	v_mfma_f32_16x16x32_bf16 v[104:107], v[170:173], v[186:189], v[104:107]
	v_mfma_f32_16x16x32_bf16 v[92:95], v[156:159], v[194:197], v[92:95]
	v_mfma_f32_16x16x32_bf16 v[88:91], v[170:173], v[194:197], v[88:91]
	v_mfma_f32_16x16x32_bf16 v[76:79], v[156:159], v[202:205], v[76:79]
	v_mfma_f32_16x16x32_bf16 v[72:75], v[170:173], v[202:205], v[72:75]
	v_mfma_f32_16x16x32_bf16 v[124:127], v[160:163], v[182:185], v[124:127]
	v_mfma_f32_16x16x32_bf16 v[120:123], v[174:177], v[182:185], v[120:123]
	v_mfma_f32_16x16x32_bf16 v[108:111], v[160:163], v[190:193], v[108:111]
	v_mfma_f32_16x16x32_bf16 v[104:107], v[174:177], v[190:193], v[104:107]
	v_mfma_f32_16x16x32_bf16 v[92:95], v[160:163], v[198:201], v[92:95]
	v_mfma_f32_16x16x32_bf16 v[88:91], v[174:177], v[198:201], v[88:91]
	v_mfma_f32_16x16x32_bf16 v[76:79], v[160:163], v[206:209], v[76:79]
	v_mfma_f32_16x16x32_bf16 v[72:75], v[174:177], v[206:209], v[72:75]
	s_setprio 0
	s_barrier
	s_add_i32 s40, 0, 0x1c000
	s_add_i32 s41, s72, s52
	v_add_u32_e32 v155, s40, v149
	v_lshl_add_u64 v[146:147], v[146:147], 0, s[26:27]
	s_mov_b32 m0, s41
	ds_read_b128 v[210:213], v155
	ds_read_b128 v[214:217], v155 offset:1024
	ds_read_b128 v[218:221], v155 offset:2048
	ds_read_b128 v[222:225], v155 offset:3072
	global_load_lds_dwordx4 v[146:147], off
	v_lshl_add_u64 v[146:147], v[164:165], 0, s[26:27]
	s_add_i32 m0, s41, 0x2000
	s_nop 0
	global_load_lds_dwordx4 v[146:147], off
	s_barrier
	s_waitcnt lgkmcnt(0)
	s_setprio 1
	s_waitcnt lgkmcnt(0)
	v_mfma_f32_16x16x32_bf16 v[116:119], v[210:213], v[178:181], v[116:119]
	v_mfma_f32_16x16x32_bf16 v[112:115], v[218:221], v[178:181], v[112:115]
	v_mfma_f32_16x16x32_bf16 v[100:103], v[210:213], v[186:189], v[100:103]
	v_mfma_f32_16x16x32_bf16 v[96:99], v[218:221], v[186:189], v[96:99]
	v_mfma_f32_16x16x32_bf16 v[84:87], v[210:213], v[194:197], v[84:87]
	v_mfma_f32_16x16x32_bf16 v[80:83], v[218:221], v[194:197], v[80:83]
	v_mfma_f32_16x16x32_bf16 v[68:71], v[210:213], v[202:205], v[68:71]
	v_mfma_f32_16x16x32_bf16 v[64:67], v[218:221], v[202:205], v[64:67]
	v_mfma_f32_16x16x32_bf16 v[116:119], v[214:217], v[182:185], v[116:119]
	v_mfma_f32_16x16x32_bf16 v[112:115], v[222:225], v[182:185], v[112:115]
	v_mfma_f32_16x16x32_bf16 v[100:103], v[214:217], v[190:193], v[100:103]
	v_mfma_f32_16x16x32_bf16 v[96:99], v[222:225], v[190:193], v[96:99]
	v_mfma_f32_16x16x32_bf16 v[84:87], v[214:217], v[198:201], v[84:87]
	v_mfma_f32_16x16x32_bf16 v[80:83], v[222:225], v[198:201], v[80:83]
	v_mfma_f32_16x16x32_bf16 v[68:71], v[214:217], v[206:209], v[68:71]
	v_mfma_f32_16x16x32_bf16 v[64:67], v[222:225], v[206:209], v[64:67]
	s_setprio 0
	s_mov_b32 m0, s58
	v_lshl_add_u64 v[146:147], v[226:227], 0, s[26:27]
	s_barrier
	ds_read_b128 v[178:181], v152 offset:49152
	ds_read_b128 v[182:185], v152 offset:50176
	ds_read_b128 v[186:189], v152 offset:51200
	ds_read_b128 v[190:193], v152 offset:52224
	ds_read_b128 v[194:197], v152 offset:53248
	ds_read_b128 v[198:201], v152 offset:54272
	ds_read_b128 v[202:205], v152 offset:55296
	ds_read_b128 v[206:209], v152 offset:56320
	global_load_lds_dwordx4 v[146:147], off
	v_lshl_add_u64 v[146:147], v[228:229], 0, s[26:27]
	s_mov_b32 m0, s59
	s_nop 0
	global_load_lds_dwordx4 v[146:147], off
	s_barrier
; #define PG8_STAGE(bufoff, gbase, voff) do { _Pragma("unroll") for (int _i = 0; _i < 2; ++_i) \
;         __builtin_amdgcn_global_load_lds((const unsigned*)((const char*)(gbase) + (voff)[_i]), (LAS unsigned*)(lds + (bufoff) + ldsw + _i * 8192), 16, 0, 0); } while (0)
; #define PG8_LDA(dst, b, h) do { _Pragma("unroll") for (int m = 0; m < 4; ++m) _Pragma("unroll") for (int k = 0; k < 2; ++k) dst[m][k] = *(const LAS bf16x8*)(lds + PG8_SA(b, h) + aoff + m * 2048 + k * 1024); } while (0)
; #define PG8_MMA(ai, bj, At, Bt) do { __builtin_amdgcn_s_setprio(1); _Pragma("unroll") for (int m = 0; m < 4; ++m) _Pragma("unroll") for (int n = 0; n < 2; ++n) _Pragma("unroll") for (int k = 0; k < 2; ++k) \
;         acc[ai][bj][m][n] = __builtin_amdgcn_mfma_f32_16x16x32_bf16(Bt[n][k], At[m][k], acc[ai][bj][m][n], 0, 0, 0); __builtin_amdgcn_s_setprio(0); } while (0)
; #define PG8_WAIT_V(n) asm volatile("s_waitcnt vmcnt(" #n ")" ::: "memory")
; #define PG8_WAIT_L(n) asm volatile("s_waitcnt lgkmcnt(" #n ")" ::: "memory")
; #define PG8_BAR __builtin_amdgcn_s_barrier()
; #define PG8_SCHED __builtin_amdgcn_sched_barrier(0)
;     ...
;             PG8_BAR; PG8_WAIT_L(0); PG8_MMA(0, 1, At, B1); PG8_BAR;
;             PG8_LDA(At, 1, 1); PG8_STAGE(PG8_SA(1, 0), a3, voffA);
;             PG8_BAR; PG8_WAIT_L(0); PG8_MMA(1, 0, At, B0); PG8_BAR; PG8_SCHED;
;             PG8_STAGE(PG8_SB(1, 1), b3 + hB, voffB);
;             PG8_WAIT_V(6); PG8_BAR; PG8_MMA(1, 1, At, B1); PG8_BAR;
;         }
;         E(acc, cur, wr, wc, fr, fq);
; __device__ __forceinline__ float row_rstd(const float* ssq, int row) {
;     const f32x4* p = (const f32x4*)(ssq + (size_t)row * 16);
;     const f32x4 a = p[0], b = p[1], c = p[2], d = p[3];
	s_waitcnt lgkmcnt(0)
	s_setprio 1
	s_waitcnt lgkmcnt(0)
	v_mfma_f32_16x16x32_bf16 v[60:63], v[156:159], v[178:181], v[60:63]
	v_mfma_f32_16x16x32_bf16 v[56:59], v[170:173], v[178:181], v[56:59]
	v_mfma_f32_16x16x32_bf16 v[44:47], v[156:159], v[186:189], v[44:47]
	v_mfma_f32_16x16x32_bf16 v[40:43], v[170:173], v[186:189], v[40:43]
	v_mfma_f32_16x16x32_bf16 v[28:31], v[156:159], v[194:197], v[28:31]
	v_mfma_f32_16x16x32_bf16 v[24:27], v[170:173], v[194:197], v[24:27]
	v_mfma_f32_16x16x32_bf16 v[12:15], v[156:159], v[202:205], v[12:15]
	v_mfma_f32_16x16x32_bf16 v[8:11], v[170:173], v[202:205], v[8:11]
	v_mfma_f32_16x16x32_bf16 v[60:63], v[160:163], v[182:185], v[60:63]
	v_mfma_f32_16x16x32_bf16 v[56:59], v[174:177], v[182:185], v[56:59]
	v_mfma_f32_16x16x32_bf16 v[44:47], v[160:163], v[190:193], v[44:47]
	v_mfma_f32_16x16x32_bf16 v[40:43], v[174:177], v[190:193], v[40:43]
	v_mfma_f32_16x16x32_bf16 v[28:31], v[160:163], v[198:201], v[28:31]
	v_mfma_f32_16x16x32_bf16 v[24:27], v[174:177], v[198:201], v[24:27]
	v_mfma_f32_16x16x32_bf16 v[12:15], v[160:163], v[206:209], v[12:15]
	v_mfma_f32_16x16x32_bf16 v[8:11], v[174:177], v[206:209], v[8:11]
	s_setprio 0
	s_barrier
	s_add_u32 s38, s38, 0x40080
	s_addc_u32 s39, s39, 0
	s_add_i32 s40, s40, s52
	v_lshl_add_u64 v[146:147], s[38:39], 0, v[130:131]
	s_mov_b32 m0, s40
	s_nop 0
	global_load_lds_dwordx4 v[146:147], off
	v_lshl_add_u64 v[146:147], s[38:39], 0, v[134:135]
	s_add_i32 m0, s40, 0x2000
	s_nop 0
	global_load_lds_dwordx4 v[146:147], off
	s_waitcnt vmcnt(6)
	s_barrier
	s_setprio 1
	v_mfma_f32_16x16x32_bf16 v[52:55], v[210:213], v[178:181], v[52:55]
	v_mfma_f32_16x16x32_bf16 v[48:51], v[218:221], v[178:181], v[48:51]
	v_mfma_f32_16x16x32_bf16 v[36:39], v[210:213], v[186:189], v[36:39]
	v_mfma_f32_16x16x32_bf16 v[32:35], v[218:221], v[186:189], v[32:35]
	v_mfma_f32_16x16x32_bf16 v[20:23], v[210:213], v[194:197], v[20:23]
	v_mfma_f32_16x16x32_bf16 v[16:19], v[218:221], v[194:197], v[16:19]
	v_mfma_f32_16x16x32_bf16 v[4:7], v[210:213], v[202:205], v[4:7]
	v_mfma_f32_16x16x32_bf16 v[0:3], v[218:221], v[202:205], v[0:3]
	v_mfma_f32_16x16x32_bf16 v[52:55], v[214:217], v[182:185], v[52:55]
	v_mfma_f32_16x16x32_bf16 v[48:51], v[222:225], v[182:185], v[48:51]
	v_mfma_f32_16x16x32_bf16 v[36:39], v[214:217], v[190:193], v[36:39]
	v_mfma_f32_16x16x32_bf16 v[32:35], v[222:225], v[190:193], v[32:35]
	v_mfma_f32_16x16x32_bf16 v[20:23], v[214:217], v[198:201], v[20:23]
	v_mfma_f32_16x16x32_bf16 v[16:19], v[222:225], v[198:201], v[16:19]
	v_mfma_f32_16x16x32_bf16 v[4:7], v[214:217], v[206:209], v[4:7]
	v_mfma_f32_16x16x32_bf16 v[0:3], v[222:225], v[206:209], v[0:3]
	s_setprio 0
	s_add_i32 s71, s71, 2
	s_add_u32 s69, s69, 0x100
	s_addc_u32 s70, s70, 0
	s_add_u32 s36, s36, 0x100
	s_addc_u32 s37, s37, 0
	s_cmp_gt_u32 s71, 13
	s_barrier
	s_cbranch_scc0 .LBB0_2099
	v_lshl_add_u32 v146, s68, 8, v148
	v_ashrrev_i32_e32 v147, 31, v146
	v_lshlrev_b64 v[156:157], 6, v[146:147]
	v_lshl_add_u64 v[164:165], s[22:23], 0, v[156:157]
	v_subrev_u32_e32 v180, s22, v164
	v_add_u32_e32 v181, 0x0, v180
	global_load_dwordx4 v[182:185], v181, s[22:23]
	v_add_u32_e32 v181, 0x10, v180
	global_load_dwordx4 v[186:189], v181, s[22:23]
	v_add_u32_e32 v181, 0x20, v180
	global_load_dwordx4 v[190:193], v181, s[22:23]
	v_add_u32_e32 v181, 0x30, v180
	global_load_dwordx4 v[194:197], v181, s[22:23]
	v_add_u32_e32 v181, 0x400, v180
	global_load_dwordx4 v[198:201], v181, s[22:23]
	v_add_u32_e32 v181, 0x410, v180
	global_load_dwordx4 v[202:205], v181, s[22:23]
	v_add_u32_e32 v181, 0x420, v180
	global_load_dwordx4 v[206:209], v181, s[22:23]
	v_add_u32_e32 v181, 0x430, v180
	global_load_dwordx4 v[210:213], v181, s[22:23]
	v_add_u32_e32 v181, 0x800, v180
	global_load_dwordx4 v[214:217], v181, s[22:23]
	v_add_u32_e32 v181, 0x810, v180
	global_load_dwordx4 v[218:221], v181, s[22:23]
	v_add_u32_e32 v181, 0x820, v180
	global_load_dwordx4 v[222:225], v181, s[22:23]
	v_add_u32_e32 v181, 0x830, v180
	global_load_dwordx4 v[232:235], v181, s[22:23]
	v_add_u32_e32 v181, 0xc00, v180
	global_load_dwordx4 v[236:239], v181, s[22:23]
	v_add_u32_e32 v181, 0xc10, v180
	global_load_dwordx4 v[240:243], v181, s[22:23]
	v_add_u32_e32 v181, 0xc20, v180
	global_load_dwordx4 v[244:247], v181, s[22:23]
	v_add_u32_e32 v181, 0xc30, v180
	global_load_dwordx4 v[248:251], v181, s[22:23]
	v_or_b32_e32 v164, 16, v146
	v_lshl_or_b32 v147, s33, 9, v150
	v_ashrrev_i32_e32 v165, 31, v164
	v_lshl_add_u32 v155, v146, 13, v147
	s_waitcnt vmcnt(12)
; __device__ __forceinline__ u32x4 pack8(const f32x4 v0, const f32x4 v1) { u32x4 w; w.x = pk2(v0[0], v0[1]); w.y = pk2(v0[2], v0[3]); w.z = pk2(v1[0], v1[1]); w.w = pk2(v1[2], v1[3]); return w; }
; __device__ __forceinline__ float row_rstd(const float* ssq, int row) {
;     const f32x4* p = (const f32x4*)(ssq + (size_t)row * 16);
;     const f32x4 a = p[0], b = p[1], c = p[2], d = p[3];
;     const float s = ((a[0] + a[1]) + (a[2] + a[3])) + ((b[0] + b[1]) + (b[2] + b[3])) + ((c[0] + c[1]) + (c[2] + c[3])) + ((d[0] + d[1]) + (d[2] + d[3]));
;     return rsqrtf(s * (1.0f / 1024.0f) + 1e-6f);
;     __device__ __forceinline__ void operator()(const f32x4 (&acc)[2][2][4][2], const Unit& u, int wr, int wc, int fr, int fq) const {
;         const __amdgpu_buffer_rsrc_t rsrc = __builtin_amdgcn_make_buffer_rsrc((void*)O, 0, T_ALL * DFF * 2, 0x00020000);
;         const int row0 = row_off + u.pm * 256 + wr * 64 + fr, col0 = u.pn * 256 + wc * 32 + 8 * fq;
; #pragma unroll
;         for (int ai = 0; ai < 2; ++ai)
; #pragma unroll
;             for (int m = 0; m < 4; ++m) {
;                 const int row = row0 + ai * 128 + m * 16; const float rs = row_rstd(ssq, row);
; #pragma unroll
;                 for (int bj = 0; bj < 2; ++bj) { f32x4 v0 = acc[ai][bj][m][0] * rs, v1 = acc[ai][bj][m][1] * rs;
; #pragma unroll
;                     for (int j = 0; j < 4; ++j) { const float a = fmaxf(v0[j], 0.f), b = fmaxf(v1[j], 0.f); v0[j] = a * a; v1[j] = b * b; }
;                     __builtin_amdgcn_raw_buffer_store_b128(pack8(v0, v1), rsrc, (unsigned)(((size_t)row * DFF + col0 + bj * 128) * 2), 0, 16  ); }
	v_pk_add_f32 v[156:157], v[182:183], v[184:185]
	v_pk_add_f32 v[158:159], v[186:187], v[188:189]
	v_pk_add_f32 v[160:161], v[190:191], v[192:193]
	v_pk_add_f32 v[162:163], v[194:195], v[196:197]
	v_pk_add_f32 v[156:157], v[156:157], v[158:159]
	v_pk_add_f32 v[160:161], v[160:161], v[162:163]
	v_pk_add_f32 v[156:157], v[156:157], v[160:161]
	v_add_f32_e32 v156, v156, v157
	s_nop 0
	s_nop 0
	v_fmamk_f32 v156, v156, 0x3a800000, v154
	s_nop 0
	s_nop 0
	s_nop 1
	s_nop 0
	v_rsq_f32_e32 v158, v156
	s_nop 0
	s_nop 0
	s_nop 0
	s_nop 0
	v_pk_mul_f32 v[126:127], v[126:127], v[158:159] op_sel_hi:[1,0]
	v_pk_mul_f32 v[124:125], v[124:125], v[158:159] op_sel_hi:[1,0]
	v_pk_mul_f32 v[122:123], v[122:123], v[158:159] op_sel_hi:[1,0]
	v_pk_mul_f32 v[120:121], v[120:121], v[158:159] op_sel_hi:[1,0]
	v_pk_mul_f32 v[114:115], v[114:115], v[158:159] op_sel_hi:[1,0]
	v_pk_mul_f32 v[112:113], v[112:113], v[158:159] op_sel_hi:[1,0]
	v_pk_mul_f32 v[118:119], v[118:119], v[158:159] op_sel_hi:[1,0]
	v_pk_mul_f32 v[116:117], v[116:117], v[158:159] op_sel_hi:[1,0]
	v_max_f32_e32 v124, 0, v124
	v_max_f32_e32 v120, 0, v120
	v_max_f32_e32 v125, 0, v125
	v_max_f32_e32 v121, 0, v121
	v_max_f32_e32 v126, 0, v126
	v_max_f32_e32 v122, 0, v122
	v_max_f32_e32 v127, 0, v127
	v_max_f32_e32 v123, 0, v123
	v_max_f32_e32 v112, 0, v112
	v_max_f32_e32 v113, 0, v113
	v_max_f32_e32 v114, 0, v114
	v_max_f32_e32 v115, 0, v115
	v_max_f32_e32 v116, 0, v116
	v_max_f32_e32 v117, 0, v117
	v_max_f32_e32 v118, 0, v118
	v_max_f32_e32 v119, 0, v119
	v_pk_mul_f32 v[124:125], v[124:125], v[124:125]
	v_pk_mul_f32 v[120:121], v[120:121], v[120:121]
	v_pk_mul_f32 v[126:127], v[126:127], v[126:127]
	v_pk_mul_f32 v[122:123], v[122:123], v[122:123]
	v_pk_mul_f32 v[158:159], v[112:113], v[112:113]
	v_pk_mul_f32 v[160:161], v[114:115], v[114:115]
	v_cvt_pk_bf16_f32 v112, v124, v125
	v_cvt_pk_bf16_f32 v113, v126, v127
	v_cvt_pk_bf16_f32 v114, v120, v121
	v_cvt_pk_bf16_f32 v115, v122, v123
	v_pk_mul_f32 v[116:117], v[116:117], v[116:117]
	v_pk_mul_f32 v[118:119], v[118:119], v[118:119]
	buffer_store_dwordx4 v[112:115], v155, s[12:15], 0 offen sc1
	s_nop 1
	v_cvt_pk_bf16_f32 v112, v116, v117
	v_cvt_pk_bf16_f32 v113, v118, v119
	v_cvt_pk_bf16_f32 v114, v158, v159
	v_cvt_pk_bf16_f32 v115, v160, v161
	buffer_store_dwordx4 v[112:115], v155, s[12:15], 0 offen offset:256 sc1
	s_nop 0
	v_or_b32_e32 v156, 32, v146
	v_ashrrev_i32_e32 v157, 31, v156
	v_lshl_add_u32 v155, v164, 13, v147
	v_add_u32_e32 v181, 0x2000, v180
	global_load_dwordx4 v[182:185], v181, s[22:23]
	v_add_u32_e32 v181, 0x2010, v180
	global_load_dwordx4 v[186:189], v181, s[22:23]
	v_add_u32_e32 v181, 0x2020, v180
	global_load_dwordx4 v[190:193], v181, s[22:23]
	v_add_u32_e32 v181, 0x2030, v180
	global_load_dwordx4 v[194:197], v181, s[22:23]
	s_waitcnt vmcnt(14)
	v_pk_add_f32 v[112:113], v[198:199], v[200:201]
	v_pk_add_f32 v[114:115], v[202:203], v[204:205]
	v_pk_add_f32 v[116:117], v[206:207], v[208:209]
	v_pk_add_f32 v[118:119], v[210:211], v[212:213]
	v_pk_add_f32 v[112:113], v[112:113], v[114:115]
	v_pk_add_f32 v[116:117], v[116:117], v[118:119]
	v_pk_add_f32 v[112:113], v[112:113], v[116:117]
	v_add_f32_e32 v112, v112, v113
	s_nop 0
	s_nop 0
	v_fmamk_f32 v112, v112, 0x3a800000, v154
	s_nop 0
	s_nop 0
	s_nop 1
	s_nop 0
	v_rsq_f32_e32 v114, v112
	s_nop 0
	s_nop 0
	s_nop 0
	s_nop 0
	v_pk_mul_f32 v[110:111], v[110:111], v[114:115] op_sel_hi:[1,0]
	v_pk_mul_f32 v[108:109], v[108:109], v[114:115] op_sel_hi:[1,0]
	v_pk_mul_f32 v[106:107], v[106:107], v[114:115] op_sel_hi:[1,0]
	v_pk_mul_f32 v[104:105], v[104:105], v[114:115] op_sel_hi:[1,0]
	v_pk_mul_f32 v[98:99], v[98:99], v[114:115] op_sel_hi:[1,0]
	v_pk_mul_f32 v[96:97], v[96:97], v[114:115] op_sel_hi:[1,0]
	v_pk_mul_f32 v[102:103], v[102:103], v[114:115] op_sel_hi:[1,0]
	v_pk_mul_f32 v[100:101], v[100:101], v[114:115] op_sel_hi:[1,0]
	v_max_f32_e32 v108, 0, v108
	v_max_f32_e32 v104, 0, v104
	v_max_f32_e32 v109, 0, v109
	v_max_f32_e32 v105, 0, v105
	v_max_f32_e32 v110, 0, v110
	v_max_f32_e32 v106, 0, v106
	v_max_f32_e32 v111, 0, v111
	v_max_f32_e32 v107, 0, v107
	v_max_f32_e32 v96, 0, v96
	v_max_f32_e32 v97, 0, v97
	v_max_f32_e32 v98, 0, v98
	v_max_f32_e32 v99, 0, v99
	v_max_f32_e32 v100, 0, v100
	v_max_f32_e32 v101, 0, v101
	v_max_f32_e32 v102, 0, v102
	v_max_f32_e32 v103, 0, v103
	v_pk_mul_f32 v[108:109], v[108:109], v[108:109]
	v_pk_mul_f32 v[104:105], v[104:105], v[104:105]
	v_pk_mul_f32 v[110:111], v[110:111], v[110:111]
	v_pk_mul_f32 v[106:107], v[106:107], v[106:107]
	v_pk_mul_f32 v[114:115], v[96:97], v[96:97]
	v_pk_mul_f32 v[116:117], v[98:99], v[98:99]
	v_cvt_pk_bf16_f32 v96, v108, v109
	v_cvt_pk_bf16_f32 v97, v110, v111
	v_cvt_pk_bf16_f32 v98, v104, v105
	v_cvt_pk_bf16_f32 v99, v106, v107
	v_pk_mul_f32 v[100:101], v[100:101], v[100:101]
	v_pk_mul_f32 v[102:103], v[102:103], v[102:103]
	buffer_store_dwordx4 v[96:99], v155, s[12:15], 0 offen sc1
	s_nop 1
	v_cvt_pk_bf16_f32 v96, v100, v101
	v_cvt_pk_bf16_f32 v97, v102, v103
	v_cvt_pk_bf16_f32 v98, v114, v115
	v_cvt_pk_bf16_f32 v99, v116, v117
	buffer_store_dwordx4 v[96:99], v155, s[12:15], 0 offen offset:256 sc1
	s_nop 0
	v_or_b32_e32 v112, 48, v146
	v_ashrrev_i32_e32 v113, 31, v112
	v_lshl_add_u32 v116, v156, 13, v147
	v_add_u32_e32 v181, 0x2400, v180
	global_load_dwordx4 v[198:201], v181, s[22:23]
	v_add_u32_e32 v181, 0x2410, v180
	global_load_dwordx4 v[202:205], v181, s[22:23]
	v_add_u32_e32 v181, 0x2420, v180
	global_load_dwordx4 v[206:209], v181, s[22:23]
	v_add_u32_e32 v181, 0x2430, v180
	global_load_dwordx4 v[210:213], v181, s[22:23]
	s_waitcnt vmcnt(16)
; __device__ __forceinline__ u32x4 pack8(const f32x4 v0, const f32x4 v1) { u32x4 w; w.x = pk2(v0[0], v0[1]); w.y = pk2(v0[2], v0[3]); w.z = pk2(v1[0], v1[1]); w.w = pk2(v1[2], v1[3]); return w; }
; __device__ __forceinline__ float row_rstd(const float* ssq, int row) {
;     const f32x4* p = (const f32x4*)(ssq + (size_t)row * 16);
;     const f32x4 a = p[0], b = p[1], c = p[2], d = p[3];
;     const float s = ((a[0] + a[1]) + (a[2] + a[3])) + ((b[0] + b[1]) + (b[2] + b[3])) + ((c[0] + c[1]) + (c[2] + c[3])) + ((d[0] + d[1]) + (d[2] + d[3]));
;     return rsqrtf(s * (1.0f / 1024.0f) + 1e-6f);
;     __device__ __forceinline__ void operator()(const f32x4 (&acc)[2][2][4][2], const Unit& u, int wr, int wc, int fr, int fq) const {
;         const __amdgpu_buffer_rsrc_t rsrc = __builtin_amdgcn_make_buffer_rsrc((void*)O, 0, T_ALL * DFF * 2, 0x00020000);
;         const int row0 = row_off + u.pm * 256 + wr * 64 + fr, col0 = u.pn * 256 + wc * 32 + 8 * fq;
; #pragma unroll
;         for (int ai = 0; ai < 2; ++ai)
; #pragma unroll
;             for (int m = 0; m < 4; ++m) {
;                 const int row = row0 + ai * 128 + m * 16; const float rs = row_rstd(ssq, row);
; #pragma unroll
;                 for (int bj = 0; bj < 2; ++bj) { f32x4 v0 = acc[ai][bj][m][0] * rs, v1 = acc[ai][bj][m][1] * rs;
; #pragma unroll
;                     for (int j = 0; j < 4; ++j) { const float a = fmaxf(v0[j], 0.f), b = fmaxf(v1[j], 0.f); v0[j] = a * a; v1[j] = b * b; }
;                     __builtin_amdgcn_raw_buffer_store_b128(pack8(v0, v1), rsrc, (unsigned)(((size_t)row * DFF + col0 + bj * 128) * 2), 0, 16  ); }
	v_pk_add_f32 v[96:97], v[214:215], v[216:217]
	v_pk_add_f32 v[98:99], v[218:219], v[220:221]
	v_pk_add_f32 v[100:101], v[222:223], v[224:225]
	v_pk_add_f32 v[102:103], v[232:233], v[234:235]
	v_pk_add_f32 v[96:97], v[96:97], v[98:99]
	v_pk_add_f32 v[100:101], v[100:101], v[102:103]
	v_pk_add_f32 v[96:97], v[96:97], v[100:101]
	v_add_f32_e32 v96, v96, v97
	s_nop 0
	s_nop 0
	v_fmamk_f32 v96, v96, 0x3a800000, v154
	s_nop 0
	s_nop 0
	s_nop 1
	s_nop 0
	v_rsq_f32_e32 v98, v96
	s_nop 0
	s_nop 0
	s_nop 0
	s_nop 0
	v_pk_mul_f32 v[94:95], v[94:95], v[98:99] op_sel_hi:[1,0]
	v_pk_mul_f32 v[92:93], v[92:93], v[98:99] op_sel_hi:[1,0]
	v_pk_mul_f32 v[90:91], v[90:91], v[98:99] op_sel_hi:[1,0]
	v_pk_mul_f32 v[88:89], v[88:89], v[98:99] op_sel_hi:[1,0]
	v_pk_mul_f32 v[82:83], v[82:83], v[98:99] op_sel_hi:[1,0]
	v_pk_mul_f32 v[80:81], v[80:81], v[98:99] op_sel_hi:[1,0]
	v_pk_mul_f32 v[86:87], v[86:87], v[98:99] op_sel_hi:[1,0]
	v_pk_mul_f32 v[84:85], v[84:85], v[98:99] op_sel_hi:[1,0]
	v_max_f32_e32 v92, 0, v92
	v_max_f32_e32 v88, 0, v88
	v_max_f32_e32 v93, 0, v93
	v_max_f32_e32 v89, 0, v89
	v_max_f32_e32 v94, 0, v94
	v_max_f32_e32 v90, 0, v90
	v_max_f32_e32 v95, 0, v95
	v_max_f32_e32 v91, 0, v91
	v_max_f32_e32 v80, 0, v80
	v_max_f32_e32 v81, 0, v81
	v_max_f32_e32 v82, 0, v82
	v_max_f32_e32 v83, 0, v83
	v_max_f32_e32 v84, 0, v84
	v_max_f32_e32 v85, 0, v85
	v_max_f32_e32 v86, 0, v86
	v_max_f32_e32 v87, 0, v87
	v_pk_mul_f32 v[92:93], v[92:93], v[92:93]
	v_pk_mul_f32 v[88:89], v[88:89], v[88:89]
	v_pk_mul_f32 v[94:95], v[94:95], v[94:95]
	v_pk_mul_f32 v[90:91], v[90:91], v[90:91]
	v_pk_mul_f32 v[98:99], v[80:81], v[80:81]
	v_pk_mul_f32 v[100:101], v[82:83], v[82:83]
	v_cvt_pk_bf16_f32 v80, v92, v93
	v_cvt_pk_bf16_f32 v81, v94, v95
	v_cvt_pk_bf16_f32 v82, v88, v89
	v_cvt_pk_bf16_f32 v83, v90, v91
	v_pk_mul_f32 v[84:85], v[84:85], v[84:85]
	v_pk_mul_f32 v[86:87], v[86:87], v[86:87]
	buffer_store_dwordx4 v[80:83], v116, s[12:15], 0 offen sc1
	s_nop 1
	v_cvt_pk_bf16_f32 v80, v84, v85
	v_cvt_pk_bf16_f32 v81, v86, v87
	v_cvt_pk_bf16_f32 v82, v98, v99
	v_cvt_pk_bf16_f32 v83, v100, v101
	buffer_store_dwordx4 v[80:83], v116, s[12:15], 0 offen offset:256 sc1
	s_nop 0
	v_add_u32_e32 v96, 0x80, v146
	v_ashrrev_i32_e32 v97, 31, v96
	v_lshl_add_u32 v100, v112, 13, v147
	v_add_u32_e32 v181, 0x2800, v180
	global_load_dwordx4 v[214:217], v181, s[22:23]
	v_add_u32_e32 v181, 0x2810, v180
	global_load_dwordx4 v[218:221], v181, s[22:23]
	v_add_u32_e32 v181, 0x2820, v180
	global_load_dwordx4 v[222:225], v181, s[22:23]
	v_add_u32_e32 v181, 0x2830, v180
	global_load_dwordx4 v[232:235], v181, s[22:23]
	s_waitcnt vmcnt(18)
	v_pk_add_f32 v[80:81], v[236:237], v[238:239]
	v_pk_add_f32 v[82:83], v[240:241], v[242:243]
	v_pk_add_f32 v[84:85], v[244:245], v[246:247]
	v_pk_add_f32 v[86:87], v[248:249], v[250:251]
	v_pk_add_f32 v[80:81], v[80:81], v[82:83]
	v_pk_add_f32 v[84:85], v[84:85], v[86:87]
	v_pk_add_f32 v[80:81], v[80:81], v[84:85]
	v_add_f32_e32 v80, v80, v81
	s_nop 0
	s_nop 0
	v_fmamk_f32 v80, v80, 0x3a800000, v154
	s_nop 0
	s_nop 0
	s_nop 1
	s_nop 0
	v_rsq_f32_e32 v82, v80
	s_nop 0
	s_nop 0
	s_nop 0
	s_nop 0
	v_pk_mul_f32 v[78:79], v[78:79], v[82:83] op_sel_hi:[1,0]
	v_pk_mul_f32 v[76:77], v[76:77], v[82:83] op_sel_hi:[1,0]
	v_pk_mul_f32 v[74:75], v[74:75], v[82:83] op_sel_hi:[1,0]
	v_pk_mul_f32 v[72:73], v[72:73], v[82:83] op_sel_hi:[1,0]
	v_pk_mul_f32 v[66:67], v[66:67], v[82:83] op_sel_hi:[1,0]
	v_pk_mul_f32 v[64:65], v[64:65], v[82:83] op_sel_hi:[1,0]
	v_pk_mul_f32 v[70:71], v[70:71], v[82:83] op_sel_hi:[1,0]
	v_pk_mul_f32 v[68:69], v[68:69], v[82:83] op_sel_hi:[1,0]
	v_max_f32_e32 v76, 0, v76
	v_max_f32_e32 v72, 0, v72
	v_max_f32_e32 v77, 0, v77
	v_max_f32_e32 v73, 0, v73
	v_max_f32_e32 v78, 0, v78
	v_max_f32_e32 v74, 0, v74
	v_max_f32_e32 v79, 0, v79
	v_max_f32_e32 v75, 0, v75
	v_max_f32_e32 v64, 0, v64
	v_max_f32_e32 v65, 0, v65
	v_max_f32_e32 v66, 0, v66
	v_max_f32_e32 v67, 0, v67
	v_max_f32_e32 v68, 0, v68
	v_max_f32_e32 v69, 0, v69
	v_max_f32_e32 v70, 0, v70
	v_max_f32_e32 v71, 0, v71
	v_pk_mul_f32 v[76:77], v[76:77], v[76:77]
	v_pk_mul_f32 v[72:73], v[72:73], v[72:73]
	v_pk_mul_f32 v[78:79], v[78:79], v[78:79]
	v_pk_mul_f32 v[74:75], v[74:75], v[74:75]
	v_pk_mul_f32 v[82:83], v[64:65], v[64:65]
	v_pk_mul_f32 v[84:85], v[66:67], v[66:67]
	v_cvt_pk_bf16_f32 v64, v76, v77
	v_cvt_pk_bf16_f32 v65, v78, v79
	v_cvt_pk_bf16_f32 v66, v72, v73
	v_cvt_pk_bf16_f32 v67, v74, v75
	v_pk_mul_f32 v[68:69], v[68:69], v[68:69]
	v_pk_mul_f32 v[70:71], v[70:71], v[70:71]
	buffer_store_dwordx4 v[64:67], v100, s[12:15], 0 offen sc1
	s_nop 1
	v_cvt_pk_bf16_f32 v64, v68, v69
	v_cvt_pk_bf16_f32 v65, v70, v71
	v_cvt_pk_bf16_f32 v66, v82, v83
	v_cvt_pk_bf16_f32 v67, v84, v85
	buffer_store_dwordx4 v[64:67], v100, s[12:15], 0 offen offset:256 sc1
	s_nop 0
	v_add_u32_e32 v80, 0x90, v146
	v_ashrrev_i32_e32 v81, 31, v80
	v_lshl_add_u32 v84, v96, 13, v147
	v_add_u32_e32 v181, 0x2c00, v180
	global_load_dwordx4 v[236:239], v181, s[22:23]
	v_add_u32_e32 v181, 0x2c10, v180
	global_load_dwordx4 v[240:243], v181, s[22:23]
	v_add_u32_e32 v181, 0x2c20, v180
	global_load_dwordx4 v[244:247], v181, s[22:23]
	v_add_u32_e32 v181, 0x2c30, v180
	global_load_dwordx4 v[248:251], v181, s[22:23]
	s_waitcnt vmcnt(18)
; __device__ __forceinline__ u32x4 pack8(const f32x4 v0, const f32x4 v1) { u32x4 w; w.x = pk2(v0[0], v0[1]); w.y = pk2(v0[2], v0[3]); w.z = pk2(v1[0], v1[1]); w.w = pk2(v1[2], v1[3]); return w; }
; __device__ __forceinline__ float row_rstd(const float* ssq, int row) {
;     const f32x4* p = (const f32x4*)(ssq + (size_t)row * 16);
;     const f32x4 a = p[0], b = p[1], c = p[2], d = p[3];
;     const float s = ((a[0] + a[1]) + (a[2] + a[3])) + ((b[0] + b[1]) + (b[2] + b[3])) + ((c[0] + c[1]) + (c[2] + c[3])) + ((d[0] + d[1]) + (d[2] + d[3]));
;     return rsqrtf(s * (1.0f / 1024.0f) + 1e-6f);
;     __device__ __forceinline__ void operator()(const f32x4 (&acc)[2][2][4][2], const Unit& u, int wr, int wc, int fr, int fq) const {
;         const __amdgpu_buffer_rsrc_t rsrc = __builtin_amdgcn_make_buffer_rsrc((void*)O, 0, T_ALL * DFF * 2, 0x00020000);
;         const int row0 = row_off + u.pm * 256 + wr * 64 + fr, col0 = u.pn * 256 + wc * 32 + 8 * fq;
; #pragma unroll
;         for (int ai = 0; ai < 2; ++ai)
; #pragma unroll
;             for (int m = 0; m < 4; ++m) {
;                 const int row = row0 + ai * 128 + m * 16; const float rs = row_rstd(ssq, row);
; #pragma unroll
;                 for (int bj = 0; bj < 2; ++bj) { f32x4 v0 = acc[ai][bj][m][0] * rs, v1 = acc[ai][bj][m][1] * rs;
; #pragma unroll
;                     for (int j = 0; j < 4; ++j) { const float a = fmaxf(v0[j], 0.f), b = fmaxf(v1[j], 0.f); v0[j] = a * a; v1[j] = b * b; }
;                     __builtin_amdgcn_raw_buffer_store_b128(pack8(v0, v1), rsrc, (unsigned)(((size_t)row * DFF + col0 + bj * 128) * 2), 0, 16  ); }
	v_pk_add_f32 v[64:65], v[182:183], v[184:185]
	v_pk_add_f32 v[66:67], v[186:187], v[188:189]
	v_pk_add_f32 v[68:69], v[190:191], v[192:193]
	v_pk_add_f32 v[70:71], v[194:195], v[196:197]
	v_pk_add_f32 v[64:65], v[64:65], v[66:67]
	v_pk_add_f32 v[68:69], v[68:69], v[70:71]
	v_pk_add_f32 v[64:65], v[64:65], v[68:69]
	v_add_f32_e32 v64, v64, v65
	s_nop 0
	s_nop 0
	v_fmamk_f32 v64, v64, 0x3a800000, v154
	s_nop 0
	s_nop 0
	s_nop 1
	s_nop 0
	v_rsq_f32_e32 v66, v64
	s_nop 0
	s_nop 0
	s_nop 0
	s_nop 0
	v_pk_mul_f32 v[62:63], v[62:63], v[66:67] op_sel_hi:[1,0]
	v_pk_mul_f32 v[60:61], v[60:61], v[66:67] op_sel_hi:[1,0]
	v_pk_mul_f32 v[58:59], v[58:59], v[66:67] op_sel_hi:[1,0]
	v_pk_mul_f32 v[56:57], v[56:57], v[66:67] op_sel_hi:[1,0]
	v_pk_mul_f32 v[50:51], v[50:51], v[66:67] op_sel_hi:[1,0]
	v_pk_mul_f32 v[48:49], v[48:49], v[66:67] op_sel_hi:[1,0]
	v_pk_mul_f32 v[54:55], v[54:55], v[66:67] op_sel_hi:[1,0]
	v_pk_mul_f32 v[52:53], v[52:53], v[66:67] op_sel_hi:[1,0]
	v_max_f32_e32 v60, 0, v60
	v_max_f32_e32 v56, 0, v56
	v_max_f32_e32 v61, 0, v61
	v_max_f32_e32 v57, 0, v57
	v_max_f32_e32 v62, 0, v62
	v_max_f32_e32 v58, 0, v58
	v_max_f32_e32 v63, 0, v63
	v_max_f32_e32 v59, 0, v59
	v_max_f32_e32 v48, 0, v48
	v_max_f32_e32 v49, 0, v49
	v_max_f32_e32 v50, 0, v50
	v_max_f32_e32 v51, 0, v51
	v_max_f32_e32 v52, 0, v52
	v_max_f32_e32 v53, 0, v53
	v_max_f32_e32 v54, 0, v54
	v_max_f32_e32 v55, 0, v55
	v_pk_mul_f32 v[60:61], v[60:61], v[60:61]
	v_pk_mul_f32 v[56:57], v[56:57], v[56:57]
	v_pk_mul_f32 v[62:63], v[62:63], v[62:63]
	v_pk_mul_f32 v[58:59], v[58:59], v[58:59]
	v_pk_mul_f32 v[66:67], v[48:49], v[48:49]
	v_pk_mul_f32 v[68:69], v[50:51], v[50:51]
	v_cvt_pk_bf16_f32 v48, v60, v61
	v_cvt_pk_bf16_f32 v49, v62, v63
	v_cvt_pk_bf16_f32 v50, v56, v57
	v_cvt_pk_bf16_f32 v51, v58, v59
	v_pk_mul_f32 v[52:53], v[52:53], v[52:53]
	v_pk_mul_f32 v[54:55], v[54:55], v[54:55]
	buffer_store_dwordx4 v[48:51], v84, s[12:15], 0 offen sc1
	s_nop 1
	v_cvt_pk_bf16_f32 v48, v52, v53
	v_cvt_pk_bf16_f32 v49, v54, v55
	v_cvt_pk_bf16_f32 v50, v66, v67
	v_cvt_pk_bf16_f32 v51, v68, v69
	buffer_store_dwordx4 v[48:51], v84, s[12:15], 0 offen offset:256 sc1
	s_nop 0
	v_add_u32_e32 v64, 0xa0, v146
	v_ashrrev_i32_e32 v65, 31, v64
	v_lshl_add_u32 v68, v80, 13, v147
	s_waitcnt vmcnt(14)
	v_pk_add_f32 v[48:49], v[198:199], v[200:201]
	v_pk_add_f32 v[50:51], v[202:203], v[204:205]
	v_pk_add_f32 v[52:53], v[206:207], v[208:209]
	v_pk_add_f32 v[54:55], v[210:211], v[212:213]
	v_pk_add_f32 v[48:49], v[48:49], v[50:51]
	v_pk_add_f32 v[52:53], v[52:53], v[54:55]
	v_pk_add_f32 v[48:49], v[48:49], v[52:53]
	v_add_f32_e32 v48, v48, v49
	s_nop 0
	s_nop 0
	v_fmamk_f32 v48, v48, 0x3a800000, v154
	s_nop 0
	s_nop 0
	s_nop 1
	s_nop 0
	v_rsq_f32_e32 v50, v48
	s_nop 0
	s_nop 0
	s_nop 0
	s_nop 0
	v_pk_mul_f32 v[46:47], v[46:47], v[50:51] op_sel_hi:[1,0]
	v_pk_mul_f32 v[44:45], v[44:45], v[50:51] op_sel_hi:[1,0]
	v_pk_mul_f32 v[42:43], v[42:43], v[50:51] op_sel_hi:[1,0]
	v_pk_mul_f32 v[40:41], v[40:41], v[50:51] op_sel_hi:[1,0]
	v_pk_mul_f32 v[34:35], v[34:35], v[50:51] op_sel_hi:[1,0]
	v_pk_mul_f32 v[32:33], v[32:33], v[50:51] op_sel_hi:[1,0]
	v_pk_mul_f32 v[38:39], v[38:39], v[50:51] op_sel_hi:[1,0]
	v_pk_mul_f32 v[36:37], v[36:37], v[50:51] op_sel_hi:[1,0]
	v_max_f32_e32 v44, 0, v44
	v_max_f32_e32 v40, 0, v40
	v_max_f32_e32 v45, 0, v45
	v_max_f32_e32 v41, 0, v41
	v_max_f32_e32 v46, 0, v46
	v_max_f32_e32 v42, 0, v42
	v_max_f32_e32 v47, 0, v47
	v_max_f32_e32 v43, 0, v43
	v_max_f32_e32 v32, 0, v32
	v_max_f32_e32 v33, 0, v33
	v_max_f32_e32 v34, 0, v34
	v_max_f32_e32 v35, 0, v35
	v_max_f32_e32 v36, 0, v36
	v_max_f32_e32 v37, 0, v37
	v_max_f32_e32 v38, 0, v38
	v_max_f32_e32 v39, 0, v39
	v_pk_mul_f32 v[44:45], v[44:45], v[44:45]
	v_pk_mul_f32 v[40:41], v[40:41], v[40:41]
	v_pk_mul_f32 v[46:47], v[46:47], v[46:47]
	v_pk_mul_f32 v[42:43], v[42:43], v[42:43]
	v_pk_mul_f32 v[50:51], v[32:33], v[32:33]
	v_pk_mul_f32 v[52:53], v[34:35], v[34:35]
	v_cvt_pk_bf16_f32 v32, v44, v45
	v_cvt_pk_bf16_f32 v33, v46, v47
	v_cvt_pk_bf16_f32 v34, v40, v41
	v_cvt_pk_bf16_f32 v35, v42, v43
	v_pk_mul_f32 v[36:37], v[36:37], v[36:37]
	v_pk_mul_f32 v[38:39], v[38:39], v[38:39]
	buffer_store_dwordx4 v[32:35], v68, s[12:15], 0 offen sc1
	s_nop 1
	v_cvt_pk_bf16_f32 v32, v36, v37
	v_cvt_pk_bf16_f32 v33, v38, v39
	v_cvt_pk_bf16_f32 v34, v50, v51
	v_cvt_pk_bf16_f32 v35, v52, v53
	buffer_store_dwordx4 v[32:35], v68, s[12:15], 0 offen offset:256 sc1
	s_nop 0
	v_add_u32_e32 v48, 0xb0, v146
	v_ashrrev_i32_e32 v49, 31, v48
	v_lshl_add_u32 v52, v64, 13, v147
	s_waitcnt vmcnt(10)
; __device__ __forceinline__ u32x4 pack8(const f32x4 v0, const f32x4 v1) { u32x4 w; w.x = pk2(v0[0], v0[1]); w.y = pk2(v0[2], v0[3]); w.z = pk2(v1[0], v1[1]); w.w = pk2(v1[2], v1[3]); return w; }
; __device__ __forceinline__ float row_rstd(const float* ssq, int row) {
;     const f32x4* p = (const f32x4*)(ssq + (size_t)row * 16);
;     const f32x4 a = p[0], b = p[1], c = p[2], d = p[3];
;     const float s = ((a[0] + a[1]) + (a[2] + a[3])) + ((b[0] + b[1]) + (b[2] + b[3])) + ((c[0] + c[1]) + (c[2] + c[3])) + ((d[0] + d[1]) + (d[2] + d[3]));
;     return rsqrtf(s * (1.0f / 1024.0f) + 1e-6f);
;     __device__ __forceinline__ void operator()(const f32x4 (&acc)[2][2][4][2], const Unit& u, int wr, int wc, int fr, int fq) const {
;         const __amdgpu_buffer_rsrc_t rsrc = __builtin_amdgcn_make_buffer_rsrc((void*)O, 0, T_ALL * DFF * 2, 0x00020000);
;         const int row0 = row_off + u.pm * 256 + wr * 64 + fr, col0 = u.pn * 256 + wc * 32 + 8 * fq;
; #pragma unroll
;         for (int ai = 0; ai < 2; ++ai)
; #pragma unroll
;             for (int m = 0; m < 4; ++m) {
;                 const int row = row0 + ai * 128 + m * 16; const float rs = row_rstd(ssq, row);
; #pragma unroll
;                 for (int bj = 0; bj < 2; ++bj) { f32x4 v0 = acc[ai][bj][m][0] * rs, v1 = acc[ai][bj][m][1] * rs;
; #pragma unroll
;                     for (int j = 0; j < 4; ++j) { const float a = fmaxf(v0[j], 0.f), b = fmaxf(v1[j], 0.f); v0[j] = a * a; v1[j] = b * b; }
;                     __builtin_amdgcn_raw_buffer_store_b128(pack8(v0, v1), rsrc, (unsigned)(((size_t)row * DFF + col0 + bj * 128) * 2), 0, 16  ); }
;             }
;         asm volatile("s_waitcnt vmcnt(0)" ::: "memory");
;         if (fr == 0 && fq == 0) (void)__hip_atomic_fetch_add(ready + 64 * (pm_off + u.pm), 1u, __ATOMIC_RELAXED, __HIP_MEMORY_SCOPE_AGENT);
	v_pk_add_f32 v[32:33], v[214:215], v[216:217]
	v_pk_add_f32 v[34:35], v[218:219], v[220:221]
	v_pk_add_f32 v[36:37], v[222:223], v[224:225]
	v_pk_add_f32 v[38:39], v[232:233], v[234:235]
	v_pk_add_f32 v[32:33], v[32:33], v[34:35]
	v_pk_add_f32 v[36:37], v[36:37], v[38:39]
	v_pk_add_f32 v[32:33], v[32:33], v[36:37]
	v_add_f32_e32 v32, v32, v33
	s_nop 0
	s_nop 0
	v_fmamk_f32 v32, v32, 0x3a800000, v154
	s_nop 0
	s_nop 0
	s_nop 1
	s_nop 0
	v_rsq_f32_e32 v34, v32
	v_lshlrev_b64 v[32:33], 6, v[48:49]
	v_lshl_add_u64 v[32:33], s[22:23], 0, v[32:33]
	s_nop 0
	s_nop 0
	v_pk_mul_f32 v[30:31], v[30:31], v[34:35] op_sel_hi:[1,0]
	v_pk_mul_f32 v[28:29], v[28:29], v[34:35] op_sel_hi:[1,0]
	v_pk_mul_f32 v[26:27], v[26:27], v[34:35] op_sel_hi:[1,0]
	v_pk_mul_f32 v[24:25], v[24:25], v[34:35] op_sel_hi:[1,0]
	v_pk_mul_f32 v[18:19], v[18:19], v[34:35] op_sel_hi:[1,0]
	v_pk_mul_f32 v[16:17], v[16:17], v[34:35] op_sel_hi:[1,0]
	v_pk_mul_f32 v[22:23], v[22:23], v[34:35] op_sel_hi:[1,0]
	v_pk_mul_f32 v[20:21], v[20:21], v[34:35] op_sel_hi:[1,0]
	v_max_f32_e32 v28, 0, v28
	v_max_f32_e32 v24, 0, v24
	v_max_f32_e32 v29, 0, v29
	v_max_f32_e32 v25, 0, v25
	v_max_f32_e32 v30, 0, v30
	v_max_f32_e32 v26, 0, v26
	v_max_f32_e32 v31, 0, v31
	v_max_f32_e32 v27, 0, v27
	v_max_f32_e32 v16, 0, v16
	v_max_f32_e32 v17, 0, v17
	v_max_f32_e32 v18, 0, v18
	v_max_f32_e32 v19, 0, v19
	v_max_f32_e32 v20, 0, v20
	v_max_f32_e32 v21, 0, v21
	v_max_f32_e32 v22, 0, v22
	v_max_f32_e32 v23, 0, v23
	v_pk_mul_f32 v[28:29], v[28:29], v[28:29]
	v_pk_mul_f32 v[24:25], v[24:25], v[24:25]
	v_pk_mul_f32 v[30:31], v[30:31], v[30:31]
	v_pk_mul_f32 v[26:27], v[26:27], v[26:27]
	v_pk_mul_f32 v[34:35], v[16:17], v[16:17]
	v_pk_mul_f32 v[36:37], v[18:19], v[18:19]
	v_cvt_pk_bf16_f32 v16, v28, v29
	v_cvt_pk_bf16_f32 v17, v30, v31
	v_cvt_pk_bf16_f32 v18, v24, v25
	v_cvt_pk_bf16_f32 v19, v26, v27
	v_pk_mul_f32 v[20:21], v[20:21], v[20:21]
	v_pk_mul_f32 v[22:23], v[22:23], v[22:23]
	buffer_store_dwordx4 v[16:19], v52, s[12:15], 0 offen sc1
	s_nop 1
	v_cvt_pk_bf16_f32 v16, v20, v21
	v_cvt_pk_bf16_f32 v17, v22, v23
	v_cvt_pk_bf16_f32 v18, v34, v35
	v_cvt_pk_bf16_f32 v19, v36, v37
	buffer_store_dwordx4 v[16:19], v52, s[12:15], 0 offen offset:256 sc1
	s_nop 0
	s_waitcnt vmcnt(6)
	v_pk_add_f32 v[16:17], v[236:237], v[238:239]
	v_pk_add_f32 v[18:19], v[240:241], v[242:243]
	v_pk_add_f32 v[20:21], v[244:245], v[246:247]
	v_pk_add_f32 v[22:23], v[248:249], v[250:251]
	v_pk_add_f32 v[16:17], v[16:17], v[18:19]
	v_pk_add_f32 v[20:21], v[20:21], v[22:23]
	v_pk_add_f32 v[16:17], v[16:17], v[20:21]
	v_add_f32_e32 v16, v16, v17
	s_nop 0
	s_nop 0
	v_fmamk_f32 v16, v16, 0x3a800000, v154
	s_nop 0
	s_nop 0
	s_nop 1
	s_nop 0
	v_rsq_f32_e32 v16, v16
	v_lshl_add_u32 v17, v48, 13, v147
	s_nop 0
	s_nop 0
	v_pk_mul_f32 v[14:15], v[14:15], v[16:17] op_sel_hi:[1,0]
	v_pk_mul_f32 v[12:13], v[12:13], v[16:17] op_sel_hi:[1,0]
	v_pk_mul_f32 v[10:11], v[10:11], v[16:17] op_sel_hi:[1,0]
	v_pk_mul_f32 v[8:9], v[8:9], v[16:17] op_sel_hi:[1,0]
	v_pk_mul_f32 v[2:3], v[2:3], v[16:17] op_sel_hi:[1,0]
	v_pk_mul_f32 v[0:1], v[0:1], v[16:17] op_sel_hi:[1,0]
	v_pk_mul_f32 v[6:7], v[6:7], v[16:17] op_sel_hi:[1,0]
	v_pk_mul_f32 v[4:5], v[4:5], v[16:17] op_sel_hi:[1,0]
	v_max_f32_e32 v12, 0, v12
	v_max_f32_e32 v8, 0, v8
	v_max_f32_e32 v13, 0, v13
	v_max_f32_e32 v9, 0, v9
	v_max_f32_e32 v14, 0, v14
	v_max_f32_e32 v10, 0, v10
	v_max_f32_e32 v15, 0, v15
	v_max_f32_e32 v11, 0, v11
	v_max_f32_e32 v0, 0, v0
	v_max_f32_e32 v1, 0, v1
	v_max_f32_e32 v2, 0, v2
	v_max_f32_e32 v3, 0, v3
	v_max_f32_e32 v4, 0, v4
	v_max_f32_e32 v5, 0, v5
	v_max_f32_e32 v6, 0, v6
	v_max_f32_e32 v7, 0, v7
	v_pk_mul_f32 v[12:13], v[12:13], v[12:13]
	v_pk_mul_f32 v[8:9], v[8:9], v[8:9]
	v_pk_mul_f32 v[14:15], v[14:15], v[14:15]
	v_pk_mul_f32 v[10:11], v[10:11], v[10:11]
	v_mul_f32_e32 v16, v0, v0
	v_mul_f32_e32 v18, v1, v1
	v_mul_f32_e32 v19, v2, v2
	v_mul_f32_e32 v20, v3, v3
	v_cvt_pk_bf16_f32 v0, v12, v13
	v_cvt_pk_bf16_f32 v1, v14, v15
	v_cvt_pk_bf16_f32 v2, v8, v9
	v_cvt_pk_bf16_f32 v3, v10, v11
	v_pk_mul_f32 v[4:5], v[4:5], v[4:5]
	v_pk_mul_f32 v[6:7], v[6:7], v[6:7]
	buffer_store_dwordx4 v[0:3], v17, s[12:15], 0 offen sc1
	s_nop 1
	v_cvt_pk_bf16_f32 v0, v4, v5
	v_cvt_pk_bf16_f32 v1, v6, v7
	v_cvt_pk_bf16_f32 v2, v16, v18
	v_cvt_pk_bf16_f32 v3, v19, v20
	buffer_store_dwordx4 v[0:3], v17, s[12:15], 0 offen offset:256 sc1
	s_waitcnt vmcnt(0)
	s_and_saveexec_b64 s[36:37], s[6:7]
	s_cbranch_execz .LBB0_2091
	s_mov_b64 s[38:39], exec
	v_mbcnt_lo_u32_b32 v0, s38, 0
	v_mbcnt_hi_u32_b32 v0, s39, v0
	v_cmp_eq_u32_e32 vcc, 0, v0
	s_and_b64 s[40:41], exec, vcc
	s_mov_b64 exec, s[40:41]
	s_cbranch_execz .LBB0_2091
	s_lshl_b32 s40, s68, 6
	s_ashr_i32 s41, s40, 31
	s_lshl_b64 s[40:41], s[40:41], 2
	s_add_u32 s40, s66, s40
	s_addc_u32 s41, s67, s41
	s_bcnt1_i32_b64 s25, s[38:39]
	v_mov_b32_e32 v0, s25
	global_atomic_add v131, v0, s[40:41]
	s_branch .LBB0_2091

; #define PG8_STAGE(bufoff, gbase, voff) do { _Pragma("unroll") for (int _i = 0; _i < 2; ++_i) \
;         __builtin_amdgcn_global_load_lds((const unsigned*)((const char*)(gbase) + (voff)[_i]), (LAS unsigned*)(lds + (bufoff) + ldsw + _i * 8192), 16, 0, 0); } while (0)
; #define PG8_LDA(dst, b, h) do { _Pragma("unroll") for (int m = 0; m < 4; ++m) _Pragma("unroll") for (int k = 0; k < 2; ++k) dst[m][k] = *(const LAS bf16x8*)(lds + PG8_SA(b, h) + aoff + m * 2048 + k * 1024); } while (0)
; #define PG8_LDB(dst, b, h) do { _Pragma("unroll") for (int n = 0; n < 2; ++n) _Pragma("unroll") for (int k = 0; k < 2; ++k) dst[n][k] = *(const LAS bf16x8*)(lds + PG8_SB(b, h) + boff + n * 2048 + k * 1024); } while (0)
; #define PG8_MMA(ai, bj, At, Bt) do { __builtin_amdgcn_s_setprio(1); _Pragma("unroll") for (int m = 0; m < 4; ++m) _Pragma("unroll") for (int n = 0; n < 2; ++n) _Pragma("unroll") for (int k = 0; k < 2; ++k) \
;         acc[ai][bj][m][n] = __builtin_amdgcn_mfma_f32_16x16x32_bf16(Bt[n][k], At[m][k], acc[ai][bj][m][n], 0, 0, 0); __builtin_amdgcn_s_setprio(0); } while (0)
; #define PG8_WAIT_V(n) asm volatile("s_waitcnt vmcnt(" #n ")" ::: "memory")
;     ...
;         for (int t = 0; t < nt; t += 2) {
;             const bool last = (t == nt - 2);
;             const char* a1 = cA + (size_t)(t + 1) * kstep;
;             const char* a2 = last ? nA : cA + (size_t)(t + 2) * kstep; const char* b2 = last ? nB : cB + (size_t)(t + 2) * kstep;
;             const char* a3 = a2 + kstep; const char* b3 = b2 + kstep;
;             if (last && has_next) PG8_A_READY(nxt);
;             PG8_LDB(B0, 0, 0); PG8_SCHED; PG8_LDA(At, 0, 0); PG8_STAGE(PG8_SA(1, 1), a1 + hA, voffA);
;             PG8_WAIT_L(8); PG8_BAR; PG8_WAIT_L(0); PG8_MMA(0, 0, At, B0); PG8_BAR; PG8_SCHED;
;             PG8_LDB(B1, 0, 1); PG8_STAGE(PG8_SB(0, 0), b2, voffB);
;             PG8_BAR; PG8_WAIT_L(0); PG8_MMA(0, 1, At, B1); PG8_BAR;
;             PG8_LDA(At, 0, 1); PG8_STAGE(PG8_SA(0, 0), a2, voffA);
;             PG8_BAR; PG8_WAIT_L(0); PG8_MMA(1, 0, At, B0); PG8_BAR; PG8_SCHED;
;             PG8_STAGE(PG8_SB(0, 1), b2 + hB, voffB);
;             PG8_WAIT_V(6); PG8_BAR; PG8_MMA(1, 1, At, B1); PG8_BAR;
;             PG8_LDB(B0, 1, 0); PG8_SCHED; PG8_LDA(At, 1, 0); PG8_STAGE(PG8_SA(0, 1), a2 + hA, voffA);
;             PG8_WAIT_L(8); PG8_BAR; PG8_WAIT_L(0); PG8_MMA(0, 0, At, B0); PG8_BAR; PG8_SCHED;
.LBB0_2122:
	ds_read_b128 v[150:153], v143
	ds_read_b128 v[154:157], v143 offset:1024
	ds_read_b128 v[158:161], v143 offset:2048
	ds_read_b128 v[162:165], v143 offset:3072
	s_add_u32 s36, s34, 0xfffc0080
	s_addc_u32 s37, s35, -1
	s_cmp_eq_u32 s71, 12
	s_cselect_b32 s39, s21, s37
	s_cselect_b32 s38, s44, s36
	s_cselect_b32 s37, s29, s70
	s_cselect_b32 s36, s45, s69
	v_lshl_add_u64 v[202:203], s[34:35], 0, v[138:139]
	s_add_i32 m0, s53, 0xc000
	ds_read_b128 v[170:173], v146
	ds_read_b128 v[174:177], v146 offset:1024
	ds_read_b128 v[178:181], v146 offset:2048
	ds_read_b128 v[182:185], v146 offset:3072
	ds_read_b128 v[186:189], v146 offset:4096
	ds_read_b128 v[190:193], v146 offset:5120
	ds_read_b128 v[194:197], v146 offset:6144
	ds_read_b128 v[198:201], v146 offset:7168
	global_load_lds_dwordx4 v[202:203], off
	v_lshl_add_u64 v[202:203], s[34:35], 0, v[136:137]
	s_add_i32 m0, s53, 0xe000
	s_nop 0
	global_load_lds_dwordx4 v[202:203], off
	s_waitcnt lgkmcnt(8)
	s_barrier
	s_waitcnt lgkmcnt(0)
	s_setprio 1
	s_waitcnt lgkmcnt(0)
	v_mfma_f32_16x16x32_bf16 v[124:127], v[150:153], v[170:173], v[124:127]
	v_mfma_f32_16x16x32_bf16 v[120:123], v[158:161], v[170:173], v[120:123]
	v_mfma_f32_16x16x32_bf16 v[108:111], v[150:153], v[178:181], v[108:111]
	v_mfma_f32_16x16x32_bf16 v[104:107], v[158:161], v[178:181], v[104:107]
	v_mfma_f32_16x16x32_bf16 v[92:95], v[150:153], v[186:189], v[92:95]
	v_mfma_f32_16x16x32_bf16 v[88:91], v[158:161], v[186:189], v[88:91]
	v_mfma_f32_16x16x32_bf16 v[76:79], v[150:153], v[194:197], v[76:79]
	v_mfma_f32_16x16x32_bf16 v[72:75], v[158:161], v[194:197], v[72:75]
	v_mfma_f32_16x16x32_bf16 v[124:127], v[154:157], v[174:177], v[124:127]
	v_mfma_f32_16x16x32_bf16 v[120:123], v[162:165], v[174:177], v[120:123]
	v_mfma_f32_16x16x32_bf16 v[108:111], v[154:157], v[182:185], v[108:111]
	v_mfma_f32_16x16x32_bf16 v[104:107], v[162:165], v[182:185], v[104:107]
	v_mfma_f32_16x16x32_bf16 v[92:95], v[154:157], v[190:193], v[92:95]
	v_mfma_f32_16x16x32_bf16 v[88:91], v[162:165], v[190:193], v[88:91]
	v_mfma_f32_16x16x32_bf16 v[76:79], v[154:157], v[198:201], v[76:79]
	v_mfma_f32_16x16x32_bf16 v[72:75], v[162:165], v[198:201], v[72:75]
	s_setprio 0
	s_barrier
	s_add_i32 s72, s61, s52
	v_lshl_add_u64 v[218:219], s[36:37], 0, v[130:131]
	s_mov_b32 m0, s72
	ds_read_b128 v[202:205], v147
	ds_read_b128 v[206:209], v147 offset:1024
	ds_read_b128 v[210:213], v147 offset:2048
	ds_read_b128 v[214:217], v147 offset:3072
	global_load_lds_dwordx4 v[218:219], off
	v_lshl_add_u64 v[220:221], s[36:37], 0, v[134:135]
	s_add_i32 m0, s72, 0x2000
	s_nop 0
	global_load_lds_dwordx4 v[220:221], off
	s_barrier
	s_waitcnt lgkmcnt(0)
	s_setprio 1
	s_waitcnt lgkmcnt(0)
	v_mfma_f32_16x16x32_bf16 v[116:119], v[202:205], v[170:173], v[116:119]
	v_mfma_f32_16x16x32_bf16 v[112:115], v[210:213], v[170:173], v[112:115]
	v_mfma_f32_16x16x32_bf16 v[100:103], v[202:205], v[178:181], v[100:103]
	v_mfma_f32_16x16x32_bf16 v[96:99], v[210:213], v[178:181], v[96:99]
	v_mfma_f32_16x16x32_bf16 v[84:87], v[202:205], v[186:189], v[84:87]
	v_mfma_f32_16x16x32_bf16 v[80:83], v[210:213], v[186:189], v[80:83]
	v_mfma_f32_16x16x32_bf16 v[68:71], v[202:205], v[194:197], v[68:71]
	v_mfma_f32_16x16x32_bf16 v[64:67], v[210:213], v[194:197], v[64:67]
	v_mfma_f32_16x16x32_bf16 v[116:119], v[206:209], v[174:177], v[116:119]
	v_mfma_f32_16x16x32_bf16 v[112:115], v[214:217], v[174:177], v[112:115]
	v_mfma_f32_16x16x32_bf16 v[100:103], v[206:209], v[182:185], v[100:103]
	v_mfma_f32_16x16x32_bf16 v[96:99], v[214:217], v[182:185], v[96:99]
	v_mfma_f32_16x16x32_bf16 v[84:87], v[206:209], v[190:193], v[84:87]
	v_mfma_f32_16x16x32_bf16 v[80:83], v[214:217], v[190:193], v[80:83]
	v_mfma_f32_16x16x32_bf16 v[68:71], v[206:209], v[198:201], v[68:71]
	v_mfma_f32_16x16x32_bf16 v[64:67], v[214:217], v[198:201], v[64:67]
	s_setprio 0
	s_mov_b32 m0, s53
	v_lshl_add_u64 v[222:223], s[38:39], 0, v[128:129]
	s_barrier
	ds_read_b128 v[170:173], v146 offset:16384
	ds_read_b128 v[174:177], v146 offset:17408
	ds_read_b128 v[178:181], v146 offset:18432
	ds_read_b128 v[182:185], v146 offset:19456
	ds_read_b128 v[186:189], v146 offset:20480
	ds_read_b128 v[190:193], v146 offset:21504
	ds_read_b128 v[194:197], v146 offset:22528
	ds_read_b128 v[198:201], v146 offset:23552
	global_load_lds_dwordx4 v[222:223], off
	v_lshl_add_u64 v[224:225], s[38:39], 0, v[132:133]
	s_mov_b32 m0, s54
	s_nop 0
	global_load_lds_dwordx4 v[224:225], off
	s_barrier
	s_waitcnt lgkmcnt(0)
	s_setprio 1
	s_waitcnt lgkmcnt(0)
	v_mfma_f32_16x16x32_bf16 v[60:63], v[150:153], v[170:173], v[60:63]
	v_mfma_f32_16x16x32_bf16 v[56:59], v[158:161], v[170:173], v[56:59]
	v_mfma_f32_16x16x32_bf16 v[44:47], v[150:153], v[178:181], v[44:47]
	v_mfma_f32_16x16x32_bf16 v[40:43], v[158:161], v[178:181], v[40:43]
	v_mfma_f32_16x16x32_bf16 v[28:31], v[150:153], v[186:189], v[28:31]
	v_mfma_f32_16x16x32_bf16 v[24:27], v[158:161], v[186:189], v[24:27]
	v_mfma_f32_16x16x32_bf16 v[12:15], v[150:153], v[194:197], v[12:15]
	v_mfma_f32_16x16x32_bf16 v[8:11], v[158:161], v[194:197], v[8:11]
	v_mfma_f32_16x16x32_bf16 v[60:63], v[154:157], v[174:177], v[60:63]
	v_mfma_f32_16x16x32_bf16 v[56:59], v[162:165], v[174:177], v[56:59]
	v_mfma_f32_16x16x32_bf16 v[44:47], v[154:157], v[182:185], v[44:47]
	v_mfma_f32_16x16x32_bf16 v[40:43], v[162:165], v[182:185], v[40:43]
	v_mfma_f32_16x16x32_bf16 v[28:31], v[154:157], v[190:193], v[28:31]
	v_mfma_f32_16x16x32_bf16 v[24:27], v[162:165], v[190:193], v[24:27]
	v_mfma_f32_16x16x32_bf16 v[12:15], v[154:157], v[198:201], v[12:15]
	v_mfma_f32_16x16x32_bf16 v[8:11], v[162:165], v[198:201], v[8:11]
	s_setprio 0
	s_barrier
; #define PG8_STAGE(bufoff, gbase, voff) do { _Pragma("unroll") for (int _i = 0; _i < 2; ++_i) \
;         __builtin_amdgcn_global_load_lds((const unsigned*)((const char*)(gbase) + (voff)[_i]), (LAS unsigned*)(lds + (bufoff) + ldsw + _i * 8192), 16, 0, 0); } while (0)
; #define PG8_LDA(dst, b, h) do { _Pragma("unroll") for (int m = 0; m < 4; ++m) _Pragma("unroll") for (int k = 0; k < 2; ++k) dst[m][k] = *(const LAS bf16x8*)(lds + PG8_SA(b, h) + aoff + m * 2048 + k * 1024); } while (0)
; #define PG8_LDB(dst, b, h) do { _Pragma("unroll") for (int n = 0; n < 2; ++n) _Pragma("unroll") for (int k = 0; k < 2; ++k) dst[n][k] = *(const LAS bf16x8*)(lds + PG8_SB(b, h) + boff + n * 2048 + k * 1024); } while (0)
; #define PG8_MMA(ai, bj, At, Bt) do { __builtin_amdgcn_s_setprio(1); _Pragma("unroll") for (int m = 0; m < 4; ++m) _Pragma("unroll") for (int n = 0; n < 2; ++n) _Pragma("unroll") for (int k = 0; k < 2; ++k) \
;         acc[ai][bj][m][n] = __builtin_amdgcn_mfma_f32_16x16x32_bf16(Bt[n][k], At[m][k], acc[ai][bj][m][n], 0, 0, 0); __builtin_amdgcn_s_setprio(0); } while (0)
; #define PG8_WAIT_V(n) asm volatile("s_waitcnt vmcnt(" #n ")" ::: "memory")
; #define PG8_WAIT_L(n) asm volatile("s_waitcnt lgkmcnt(" #n ")" ::: "memory")
; #define PG8_BAR __builtin_amdgcn_s_barrier()
; #define PG8_SCHED __builtin_amdgcn_sched_barrier(0)
;     ...
;             PG8_LDA(At, 0, 1); PG8_STAGE(PG8_SA(0, 0), a2, voffA);
;             PG8_BAR; PG8_WAIT_L(0); PG8_MMA(1, 0, At, B0); PG8_BAR; PG8_SCHED;
;             PG8_STAGE(PG8_SB(0, 1), b2 + hB, voffB);
;             PG8_WAIT_V(6); PG8_BAR; PG8_MMA(1, 1, At, B1); PG8_BAR;
;             PG8_LDB(B0, 1, 0); PG8_SCHED; PG8_LDA(At, 1, 0); PG8_STAGE(PG8_SA(0, 1), a2 + hA, voffA);
;             PG8_WAIT_L(8); PG8_BAR; PG8_WAIT_L(0); PG8_MMA(0, 0, At, B0); PG8_BAR; PG8_SCHED;
;             PG8_LDB(B1, 1, 1); PG8_STAGE(PG8_SB(1, 0), b3, voffB);
;             PG8_BAR; PG8_WAIT_L(0); PG8_MMA(0, 1, At, B1); PG8_BAR;
;             PG8_LDA(At, 1, 1); PG8_STAGE(PG8_SA(1, 0), a3, voffA);
;             PG8_BAR; PG8_WAIT_L(0); PG8_MMA(1, 0, At, B0); PG8_BAR; PG8_SCHED;
	s_add_u32 s72, s36, 0x40000
	s_addc_u32 s73, s37, 0
	s_add_i32 s74, s62, s52
	v_lshl_add_u64 v[150:151], s[72:73], 0, v[130:131]
	s_mov_b32 m0, s74
	s_nop 0
	global_load_lds_dwordx4 v[150:151], off
	v_lshl_add_u64 v[150:151], s[72:73], 0, v[134:135]
	s_add_i32 m0, s74, 0x2000
	s_nop 0
	global_load_lds_dwordx4 v[150:151], off
	s_waitcnt vmcnt(6)
	s_barrier
	s_setprio 1
	v_mfma_f32_16x16x32_bf16 v[52:55], v[202:205], v[170:173], v[52:55]
	v_mfma_f32_16x16x32_bf16 v[48:51], v[210:213], v[170:173], v[48:51]
	v_mfma_f32_16x16x32_bf16 v[36:39], v[202:205], v[178:181], v[36:39]
	v_mfma_f32_16x16x32_bf16 v[32:35], v[210:213], v[178:181], v[32:35]
	v_mfma_f32_16x16x32_bf16 v[20:23], v[202:205], v[186:189], v[20:23]
	v_mfma_f32_16x16x32_bf16 v[16:19], v[210:213], v[186:189], v[16:19]
	v_mfma_f32_16x16x32_bf16 v[4:7], v[202:205], v[194:197], v[4:7]
	v_mfma_f32_16x16x32_bf16 v[0:3], v[210:213], v[194:197], v[0:3]
	v_mfma_f32_16x16x32_bf16 v[52:55], v[206:209], v[174:177], v[52:55]
	v_mfma_f32_16x16x32_bf16 v[48:51], v[214:217], v[174:177], v[48:51]
	v_mfma_f32_16x16x32_bf16 v[36:39], v[206:209], v[182:185], v[36:39]
	v_mfma_f32_16x16x32_bf16 v[32:35], v[214:217], v[182:185], v[32:35]
	v_mfma_f32_16x16x32_bf16 v[20:23], v[206:209], v[190:193], v[20:23]
	v_mfma_f32_16x16x32_bf16 v[16:19], v[214:217], v[190:193], v[16:19]
	v_mfma_f32_16x16x32_bf16 v[4:7], v[206:209], v[198:201], v[4:7]
	v_mfma_f32_16x16x32_bf16 v[0:3], v[214:217], v[198:201], v[0:3]
	s_setprio 0
	s_add_i32 s72, 0, 0x18000
	v_add_u32_e32 v149, s72, v141
	s_barrier
	ds_read_b128 v[150:153], v149
	ds_read_b128 v[154:157], v149 offset:1024
	ds_read_b128 v[158:161], v149 offset:2048
	ds_read_b128 v[162:165], v149 offset:3072
	s_add_u32 s38, s38, 0x40000
	s_addc_u32 s39, s39, 0
	s_mov_b32 m0, s55
	v_lshl_add_u64 v[202:203], s[38:39], 0, v[128:129]
	ds_read_b128 v[170:173], v146 offset:32768
	ds_read_b128 v[174:177], v146 offset:33792
	ds_read_b128 v[178:181], v146 offset:34816
	ds_read_b128 v[182:185], v146 offset:35840
	ds_read_b128 v[186:189], v146 offset:36864
	ds_read_b128 v[190:193], v146 offset:37888
	ds_read_b128 v[194:197], v146 offset:38912
	ds_read_b128 v[198:201], v146 offset:39936
	global_load_lds_dwordx4 v[202:203], off
	v_lshl_add_u64 v[202:203], s[38:39], 0, v[132:133]
	s_mov_b32 m0, s56
	s_nop 0
	global_load_lds_dwordx4 v[202:203], off
	s_waitcnt lgkmcnt(8)
	s_barrier
	s_waitcnt lgkmcnt(0)
	s_setprio 1
	s_waitcnt lgkmcnt(0)
	v_mfma_f32_16x16x32_bf16 v[124:127], v[150:153], v[170:173], v[124:127]
	v_mfma_f32_16x16x32_bf16 v[120:123], v[158:161], v[170:173], v[120:123]
	v_mfma_f32_16x16x32_bf16 v[108:111], v[150:153], v[178:181], v[108:111]
	v_mfma_f32_16x16x32_bf16 v[104:107], v[158:161], v[178:181], v[104:107]
	v_mfma_f32_16x16x32_bf16 v[92:95], v[150:153], v[186:189], v[92:95]
	v_mfma_f32_16x16x32_bf16 v[88:91], v[158:161], v[186:189], v[88:91]
	v_mfma_f32_16x16x32_bf16 v[76:79], v[150:153], v[194:197], v[76:79]
	v_mfma_f32_16x16x32_bf16 v[72:75], v[158:161], v[194:197], v[72:75]
	v_mfma_f32_16x16x32_bf16 v[124:127], v[154:157], v[174:177], v[124:127]
	v_mfma_f32_16x16x32_bf16 v[120:123], v[162:165], v[174:177], v[120:123]
	v_mfma_f32_16x16x32_bf16 v[108:111], v[154:157], v[182:185], v[108:111]
	v_mfma_f32_16x16x32_bf16 v[104:107], v[162:165], v[182:185], v[104:107]
	v_mfma_f32_16x16x32_bf16 v[92:95], v[154:157], v[190:193], v[92:95]
	v_mfma_f32_16x16x32_bf16 v[88:91], v[162:165], v[190:193], v[88:91]
	v_mfma_f32_16x16x32_bf16 v[76:79], v[154:157], v[198:201], v[76:79]
	v_mfma_f32_16x16x32_bf16 v[72:75], v[162:165], v[198:201], v[72:75]
	s_setprio 0
	s_barrier
	s_add_i32 s38, 0, 0x1c000
	s_add_i32 s39, s72, s52
	v_add_u32_e32 v149, s38, v141
	v_lshl_add_u64 v[218:219], v[218:219], 0, s[22:23]
	s_mov_b32 m0, s39
	ds_read_b128 v[202:205], v149
	ds_read_b128 v[206:209], v149 offset:1024
	ds_read_b128 v[210:213], v149 offset:2048
	ds_read_b128 v[214:217], v149 offset:3072
	global_load_lds_dwordx4 v[218:219], off
	v_lshl_add_u64 v[218:219], v[220:221], 0, s[22:23]
	s_add_i32 m0, s39, 0x2000
	s_nop 0
	global_load_lds_dwordx4 v[218:219], off
	s_barrier
	s_waitcnt lgkmcnt(0)
	s_setprio 1
	s_waitcnt lgkmcnt(0)
	v_mfma_f32_16x16x32_bf16 v[116:119], v[202:205], v[170:173], v[116:119]
	v_mfma_f32_16x16x32_bf16 v[112:115], v[210:213], v[170:173], v[112:115]
	v_mfma_f32_16x16x32_bf16 v[100:103], v[202:205], v[178:181], v[100:103]
	v_mfma_f32_16x16x32_bf16 v[96:99], v[210:213], v[178:181], v[96:99]
	v_mfma_f32_16x16x32_bf16 v[84:87], v[202:205], v[186:189], v[84:87]
	v_mfma_f32_16x16x32_bf16 v[80:83], v[210:213], v[186:189], v[80:83]
	v_mfma_f32_16x16x32_bf16 v[68:71], v[202:205], v[194:197], v[68:71]
	v_mfma_f32_16x16x32_bf16 v[64:67], v[210:213], v[194:197], v[64:67]
	v_mfma_f32_16x16x32_bf16 v[116:119], v[206:209], v[174:177], v[116:119]
	v_mfma_f32_16x16x32_bf16 v[112:115], v[214:217], v[174:177], v[112:115]
	v_mfma_f32_16x16x32_bf16 v[100:103], v[206:209], v[182:185], v[100:103]
	v_mfma_f32_16x16x32_bf16 v[96:99], v[214:217], v[182:185], v[96:99]
	v_mfma_f32_16x16x32_bf16 v[84:87], v[206:209], v[190:193], v[84:87]
	v_mfma_f32_16x16x32_bf16 v[80:83], v[214:217], v[190:193], v[80:83]
	v_mfma_f32_16x16x32_bf16 v[68:71], v[206:209], v[198:201], v[68:71]
	v_mfma_f32_16x16x32_bf16 v[64:67], v[214:217], v[198:201], v[64:67]
	s_setprio 0
	s_mov_b32 m0, s58
	v_lshl_add_u64 v[218:219], v[222:223], 0, s[22:23]
	s_barrier
	ds_read_b128 v[170:173], v146 offset:49152
	ds_read_b128 v[174:177], v146 offset:50176
	ds_read_b128 v[178:181], v146 offset:51200
	ds_read_b128 v[182:185], v146 offset:52224
	ds_read_b128 v[186:189], v146 offset:53248
	ds_read_b128 v[190:193], v146 offset:54272
	ds_read_b128 v[194:197], v146 offset:55296
	ds_read_b128 v[198:201], v146 offset:56320
	global_load_lds_dwordx4 v[218:219], off
	v_lshl_add_u64 v[218:219], v[224:225], 0, s[22:23]
	s_mov_b32 m0, s59
	s_nop 0
	global_load_lds_dwordx4 v[218:219], off
	s_barrier
; #define PG8_STAGE(bufoff, gbase, voff) do { _Pragma("unroll") for (int _i = 0; _i < 2; ++_i) \
;         __builtin_amdgcn_global_load_lds((const unsigned*)((const char*)(gbase) + (voff)[_i]), (LAS unsigned*)(lds + (bufoff) + ldsw + _i * 8192), 16, 0, 0); } while (0)
; #define PG8_LDA(dst, b, h) do { _Pragma("unroll") for (int m = 0; m < 4; ++m) _Pragma("unroll") for (int k = 0; k < 2; ++k) dst[m][k] = *(const LAS bf16x8*)(lds + PG8_SA(b, h) + aoff + m * 2048 + k * 1024); } while (0)
; #define PG8_MMA(ai, bj, At, Bt) do { __builtin_amdgcn_s_setprio(1); _Pragma("unroll") for (int m = 0; m < 4; ++m) _Pragma("unroll") for (int n = 0; n < 2; ++n) _Pragma("unroll") for (int k = 0; k < 2; ++k) \
;         acc[ai][bj][m][n] = __builtin_amdgcn_mfma_f32_16x16x32_bf16(Bt[n][k], At[m][k], acc[ai][bj][m][n], 0, 0, 0); __builtin_amdgcn_s_setprio(0); } while (0)
; #define PG8_WAIT_V(n) asm volatile("s_waitcnt vmcnt(" #n ")" ::: "memory")
; #define PG8_WAIT_L(n) asm volatile("s_waitcnt lgkmcnt(" #n ")" ::: "memory")
; #define PG8_BAR __builtin_amdgcn_s_barrier()
; #define PG8_SCHED __builtin_amdgcn_sched_barrier(0)
;     ...
;             PG8_BAR; PG8_WAIT_L(0); PG8_MMA(0, 1, At, B1); PG8_BAR;
;             PG8_LDA(At, 1, 1); PG8_STAGE(PG8_SA(1, 0), a3, voffA);
;             PG8_BAR; PG8_WAIT_L(0); PG8_MMA(1, 0, At, B0); PG8_BAR; PG8_SCHED;
;             PG8_STAGE(PG8_SB(1, 1), b3 + hB, voffB);
;             PG8_WAIT_V(6); PG8_BAR; PG8_MMA(1, 1, At, B1); PG8_BAR;
;         }
;         E(acc, cur, wr, wc, fr, fq);
; __device__ __forceinline__ float row_rstd(const float* ssq, int row) {
;     const f32x4* p = (const f32x4*)(ssq + (size_t)row * 16);
;     const f32x4 a = p[0], b = p[1], c = p[2], d = p[3];
	s_waitcnt lgkmcnt(0)
	s_setprio 1
	s_waitcnt lgkmcnt(0)
	v_mfma_f32_16x16x32_bf16 v[60:63], v[150:153], v[170:173], v[60:63]
	v_mfma_f32_16x16x32_bf16 v[56:59], v[158:161], v[170:173], v[56:59]
	v_mfma_f32_16x16x32_bf16 v[44:47], v[150:153], v[178:181], v[44:47]
	v_mfma_f32_16x16x32_bf16 v[40:43], v[158:161], v[178:181], v[40:43]
	v_mfma_f32_16x16x32_bf16 v[28:31], v[150:153], v[186:189], v[28:31]
	v_mfma_f32_16x16x32_bf16 v[24:27], v[158:161], v[186:189], v[24:27]
	v_mfma_f32_16x16x32_bf16 v[12:15], v[150:153], v[194:197], v[12:15]
	v_mfma_f32_16x16x32_bf16 v[8:11], v[158:161], v[194:197], v[8:11]
	v_mfma_f32_16x16x32_bf16 v[60:63], v[154:157], v[174:177], v[60:63]
	v_mfma_f32_16x16x32_bf16 v[56:59], v[162:165], v[174:177], v[56:59]
	v_mfma_f32_16x16x32_bf16 v[44:47], v[154:157], v[182:185], v[44:47]
	v_mfma_f32_16x16x32_bf16 v[40:43], v[162:165], v[182:185], v[40:43]
	v_mfma_f32_16x16x32_bf16 v[28:31], v[154:157], v[190:193], v[28:31]
	v_mfma_f32_16x16x32_bf16 v[24:27], v[162:165], v[190:193], v[24:27]
	v_mfma_f32_16x16x32_bf16 v[12:15], v[154:157], v[198:201], v[12:15]
	v_mfma_f32_16x16x32_bf16 v[8:11], v[162:165], v[198:201], v[8:11]
	s_setprio 0
	s_barrier
	s_add_u32 s36, s36, 0x40080
	s_addc_u32 s37, s37, 0
	s_add_i32 s38, s38, s52
	v_lshl_add_u64 v[150:151], s[36:37], 0, v[130:131]
	s_mov_b32 m0, s38
	s_nop 0
	global_load_lds_dwordx4 v[150:151], off
	v_lshl_add_u64 v[150:151], s[36:37], 0, v[134:135]
	s_add_i32 m0, s38, 0x2000
	s_nop 0
	global_load_lds_dwordx4 v[150:151], off
	s_waitcnt vmcnt(6)
	s_barrier
	s_setprio 1
	v_mfma_f32_16x16x32_bf16 v[52:55], v[202:205], v[170:173], v[52:55]
	v_mfma_f32_16x16x32_bf16 v[48:51], v[210:213], v[170:173], v[48:51]
	v_mfma_f32_16x16x32_bf16 v[36:39], v[202:205], v[178:181], v[36:39]
	v_mfma_f32_16x16x32_bf16 v[32:35], v[210:213], v[178:181], v[32:35]
	v_mfma_f32_16x16x32_bf16 v[20:23], v[202:205], v[186:189], v[20:23]
	v_mfma_f32_16x16x32_bf16 v[16:19], v[210:213], v[186:189], v[16:19]
	v_mfma_f32_16x16x32_bf16 v[4:7], v[202:205], v[194:197], v[4:7]
	v_mfma_f32_16x16x32_bf16 v[0:3], v[210:213], v[194:197], v[0:3]
	v_mfma_f32_16x16x32_bf16 v[52:55], v[206:209], v[174:177], v[52:55]
	v_mfma_f32_16x16x32_bf16 v[48:51], v[214:217], v[174:177], v[48:51]
	v_mfma_f32_16x16x32_bf16 v[36:39], v[206:209], v[182:185], v[36:39]
	v_mfma_f32_16x16x32_bf16 v[32:35], v[214:217], v[182:185], v[32:35]
	v_mfma_f32_16x16x32_bf16 v[20:23], v[206:209], v[190:193], v[20:23]
	v_mfma_f32_16x16x32_bf16 v[16:19], v[214:217], v[190:193], v[16:19]
	v_mfma_f32_16x16x32_bf16 v[4:7], v[206:209], v[198:201], v[4:7]
	v_mfma_f32_16x16x32_bf16 v[0:3], v[214:217], v[198:201], v[0:3]
	s_setprio 0
	s_add_i32 s71, s71, 2
	s_add_u32 s69, s69, 0x100
	s_addc_u32 s70, s70, 0
	s_add_u32 s34, s34, 0x100
	s_addc_u32 s35, s35, 0
	s_cmp_gt_u32 s71, 13
	s_barrier
	s_cbranch_scc0 .LBB0_2122
	v_lshl_add_u32 v150, s68, 8, v140
	v_add_u32_e32 v164, 0x4000, v150
	v_ashrrev_i32_e32 v165, 31, v164
	v_lshlrev_b64 v[152:153], 6, v[164:165]
	v_lshl_add_u64 v[170:171], s[14:15], 0, v[152:153]
	v_subrev_u32_e32 v176, s14, v170
	v_add_u32_e32 v177, 0x0, v176
	global_load_dwordx4 v[178:181], v177, s[14:15]
	v_add_u32_e32 v177, 0x10, v176
	global_load_dwordx4 v[182:185], v177, s[14:15]
	v_add_u32_e32 v177, 0x20, v176
	global_load_dwordx4 v[186:189], v177, s[14:15]
	v_add_u32_e32 v177, 0x30, v176
	global_load_dwordx4 v[190:193], v177, s[14:15]
	v_add_u32_e32 v177, 0x400, v176
	global_load_dwordx4 v[194:197], v177, s[14:15]
	v_add_u32_e32 v177, 0x410, v176
	global_load_dwordx4 v[198:201], v177, s[14:15]
	v_add_u32_e32 v177, 0x420, v176
	global_load_dwordx4 v[202:205], v177, s[14:15]
	v_add_u32_e32 v177, 0x430, v176
	global_load_dwordx4 v[206:209], v177, s[14:15]
	v_add_u32_e32 v177, 0x800, v176
	global_load_dwordx4 v[210:213], v177, s[14:15]
	v_add_u32_e32 v177, 0x810, v176
	global_load_dwordx4 v[214:217], v177, s[14:15]
	v_add_u32_e32 v177, 0x820, v176
	global_load_dwordx4 v[232:235], v177, s[14:15]
	v_add_u32_e32 v177, 0x830, v176
	global_load_dwordx4 v[236:239], v177, s[14:15]
	v_add_u32_e32 v177, 0xc00, v176
	global_load_dwordx4 v[240:243], v177, s[14:15]
	v_add_u32_e32 v177, 0xc10, v176
	global_load_dwordx4 v[244:247], v177, s[14:15]
	v_add_u32_e32 v177, 0xc20, v176
	global_load_dwordx4 v[248:251], v177, s[14:15]
	v_add_u32_e32 v177, 0xc30, v176
	global_load_dwordx4 v[252:255], v177, s[14:15]
	s_nop 0
	v_lshl_or_b32 v149, s33, 9, v142
	v_lshl_add_u32 v151, v164, 13, v149
	v_add_u32_e32 v174, 0x4010, v150
	v_ashrrev_i32_e32 v175, 31, v174
	s_waitcnt vmcnt(12)
; __device__ __forceinline__ u32x4 pack8(const f32x4 v0, const f32x4 v1) { u32x4 w; w.x = pk2(v0[0], v0[1]); w.y = pk2(v0[2], v0[3]); w.z = pk2(v1[0], v1[1]); w.w = pk2(v1[2], v1[3]); return w; }
; __device__ __forceinline__ float row_rstd(const float* ssq, int row) {
;     const f32x4* p = (const f32x4*)(ssq + (size_t)row * 16);
;     const f32x4 a = p[0], b = p[1], c = p[2], d = p[3];
;     const float s = ((a[0] + a[1]) + (a[2] + a[3])) + ((b[0] + b[1]) + (b[2] + b[3])) + ((c[0] + c[1]) + (c[2] + c[3])) + ((d[0] + d[1]) + (d[2] + d[3]));
;     return rsqrtf(s * (1.0f / 1024.0f) + 1e-6f);
;     __device__ __forceinline__ void operator()(const f32x4 (&acc)[2][2][4][2], const Unit& u, int wr, int wc, int fr, int fq) const {
;         const __amdgpu_buffer_rsrc_t rsrc = __builtin_amdgcn_make_buffer_rsrc((void*)O, 0, T_ALL * DFF * 2, 0x00020000);
;         const int row0 = row_off + u.pm * 256 + wr * 64 + fr, col0 = u.pn * 256 + wc * 32 + 8 * fq;
; #pragma unroll
;         for (int ai = 0; ai < 2; ++ai)
; #pragma unroll
;             for (int m = 0; m < 4; ++m) {
;                 const int row = row0 + ai * 128 + m * 16; const float rs = row_rstd(ssq, row);
; #pragma unroll
;                 for (int bj = 0; bj < 2; ++bj) { f32x4 v0 = acc[ai][bj][m][0] * rs, v1 = acc[ai][bj][m][1] * rs;
; #pragma unroll
;                     for (int j = 0; j < 4; ++j) { const float a = fmaxf(v0[j], 0.f), b = fmaxf(v1[j], 0.f); v0[j] = a * a; v1[j] = b * b; }
;                     __builtin_amdgcn_raw_buffer_store_b128(pack8(v0, v1), rsrc, (unsigned)(((size_t)row * DFF + col0 + bj * 128) * 2), 0, 16  ); }
	v_pk_add_f32 v[152:153], v[178:179], v[180:181]
	v_pk_add_f32 v[154:155], v[182:183], v[184:185]
	v_pk_add_f32 v[156:157], v[186:187], v[188:189]
	v_pk_add_f32 v[158:159], v[190:191], v[192:193]
	v_pk_add_f32 v[152:153], v[152:153], v[154:155]
	v_pk_add_f32 v[156:157], v[156:157], v[158:159]
	v_pk_add_f32 v[152:153], v[152:153], v[156:157]
	v_add_f32_e32 v152, v152, v153
	s_nop 0
	s_nop 0
	v_fmamk_f32 v152, v152, 0x3a800000, v148
	s_nop 0
	s_nop 0
	s_nop 1
	s_nop 0
	v_rsq_f32_e32 v154, v152
	s_nop 0
	s_nop 0
	s_nop 0
	s_nop 0
	v_pk_mul_f32 v[126:127], v[126:127], v[154:155] op_sel_hi:[1,0]
	v_pk_mul_f32 v[124:125], v[124:125], v[154:155] op_sel_hi:[1,0]
	v_pk_mul_f32 v[122:123], v[122:123], v[154:155] op_sel_hi:[1,0]
	v_pk_mul_f32 v[120:121], v[120:121], v[154:155] op_sel_hi:[1,0]
	v_pk_mul_f32 v[114:115], v[114:115], v[154:155] op_sel_hi:[1,0]
	v_pk_mul_f32 v[112:113], v[112:113], v[154:155] op_sel_hi:[1,0]
	v_pk_mul_f32 v[118:119], v[118:119], v[154:155] op_sel_hi:[1,0]
	v_pk_mul_f32 v[116:117], v[116:117], v[154:155] op_sel_hi:[1,0]
	v_max_f32_e32 v124, 0, v124
	v_max_f32_e32 v120, 0, v120
	v_max_f32_e32 v125, 0, v125
	v_max_f32_e32 v121, 0, v121
	v_max_f32_e32 v126, 0, v126
	v_max_f32_e32 v122, 0, v122
	v_max_f32_e32 v127, 0, v127
	v_max_f32_e32 v123, 0, v123
	v_max_f32_e32 v112, 0, v112
	v_max_f32_e32 v113, 0, v113
	v_max_f32_e32 v114, 0, v114
	v_max_f32_e32 v115, 0, v115
	v_max_f32_e32 v116, 0, v116
	v_max_f32_e32 v117, 0, v117
	v_max_f32_e32 v118, 0, v118
	v_max_f32_e32 v119, 0, v119
	v_pk_mul_f32 v[124:125], v[124:125], v[124:125]
	v_pk_mul_f32 v[120:121], v[120:121], v[120:121]
	v_pk_mul_f32 v[126:127], v[126:127], v[126:127]
	v_pk_mul_f32 v[122:123], v[122:123], v[122:123]
	v_pk_mul_f32 v[154:155], v[112:113], v[112:113]
	v_pk_mul_f32 v[156:157], v[114:115], v[114:115]
	v_cvt_pk_bf16_f32 v112, v124, v125
	v_cvt_pk_bf16_f32 v113, v126, v127
	v_cvt_pk_bf16_f32 v114, v120, v121
	v_cvt_pk_bf16_f32 v115, v122, v123
	v_pk_mul_f32 v[116:117], v[116:117], v[116:117]
	v_pk_mul_f32 v[118:119], v[118:119], v[118:119]
	buffer_store_dwordx4 v[112:115], v151, s[8:11], 0 offen sc1
	s_nop 1
	v_cvt_pk_bf16_f32 v112, v116, v117
	v_cvt_pk_bf16_f32 v113, v118, v119
	v_cvt_pk_bf16_f32 v114, v154, v155
	v_cvt_pk_bf16_f32 v115, v156, v157
	buffer_store_dwordx4 v[112:115], v151, s[8:11], 0 offen offset:256 sc1
	s_nop 0
	v_add_u32_e32 v152, 0x4020, v150
	v_ashrrev_i32_e32 v153, 31, v152
	v_lshl_add_u32 v151, v174, 13, v149
	v_add_u32_e32 v177, 0x2000, v176
	global_load_dwordx4 v[178:181], v177, s[14:15]
	v_add_u32_e32 v177, 0x2010, v176
	global_load_dwordx4 v[182:185], v177, s[14:15]
	v_add_u32_e32 v177, 0x2020, v176
	global_load_dwordx4 v[186:189], v177, s[14:15]
	v_add_u32_e32 v177, 0x2030, v176
	global_load_dwordx4 v[190:193], v177, s[14:15]
	s_waitcnt vmcnt(14)
	v_pk_add_f32 v[112:113], v[194:195], v[196:197]
	v_pk_add_f32 v[114:115], v[198:199], v[200:201]
	v_pk_add_f32 v[116:117], v[202:203], v[204:205]
	v_pk_add_f32 v[118:119], v[206:207], v[208:209]
	v_pk_add_f32 v[112:113], v[112:113], v[114:115]
	v_pk_add_f32 v[116:117], v[116:117], v[118:119]
	v_pk_add_f32 v[112:113], v[112:113], v[116:117]
	v_add_f32_e32 v112, v112, v113
	s_nop 0
	s_nop 0
	v_fmamk_f32 v112, v112, 0x3a800000, v148
	s_nop 0
	s_nop 0
	s_nop 1
	s_nop 0
	v_rsq_f32_e32 v114, v112
	s_nop 0
	s_nop 0
	s_nop 0
	s_nop 0
	v_pk_mul_f32 v[110:111], v[110:111], v[114:115] op_sel_hi:[1,0]
	v_pk_mul_f32 v[108:109], v[108:109], v[114:115] op_sel_hi:[1,0]
	v_pk_mul_f32 v[106:107], v[106:107], v[114:115] op_sel_hi:[1,0]
	v_pk_mul_f32 v[104:105], v[104:105], v[114:115] op_sel_hi:[1,0]
	v_pk_mul_f32 v[98:99], v[98:99], v[114:115] op_sel_hi:[1,0]
	v_pk_mul_f32 v[96:97], v[96:97], v[114:115] op_sel_hi:[1,0]
	v_pk_mul_f32 v[102:103], v[102:103], v[114:115] op_sel_hi:[1,0]
	v_pk_mul_f32 v[100:101], v[100:101], v[114:115] op_sel_hi:[1,0]
	v_max_f32_e32 v108, 0, v108
	v_max_f32_e32 v104, 0, v104
	v_max_f32_e32 v109, 0, v109
	v_max_f32_e32 v105, 0, v105
	v_max_f32_e32 v110, 0, v110
	v_max_f32_e32 v106, 0, v106
	v_max_f32_e32 v111, 0, v111
	v_max_f32_e32 v107, 0, v107
	v_max_f32_e32 v96, 0, v96
	v_max_f32_e32 v97, 0, v97
	v_max_f32_e32 v98, 0, v98
	v_max_f32_e32 v99, 0, v99
	v_max_f32_e32 v100, 0, v100
	v_max_f32_e32 v101, 0, v101
	v_max_f32_e32 v102, 0, v102
	v_max_f32_e32 v103, 0, v103
	v_pk_mul_f32 v[108:109], v[108:109], v[108:109]
	v_pk_mul_f32 v[104:105], v[104:105], v[104:105]
	v_pk_mul_f32 v[110:111], v[110:111], v[110:111]
	v_pk_mul_f32 v[106:107], v[106:107], v[106:107]
	v_pk_mul_f32 v[114:115], v[96:97], v[96:97]
	v_pk_mul_f32 v[116:117], v[98:99], v[98:99]
	v_cvt_pk_bf16_f32 v96, v108, v109
	v_cvt_pk_bf16_f32 v97, v110, v111
	v_cvt_pk_bf16_f32 v98, v104, v105
	v_cvt_pk_bf16_f32 v99, v106, v107
	v_pk_mul_f32 v[100:101], v[100:101], v[100:101]
	v_pk_mul_f32 v[102:103], v[102:103], v[102:103]
	buffer_store_dwordx4 v[96:99], v151, s[8:11], 0 offen sc1
	s_nop 1
	v_cvt_pk_bf16_f32 v96, v100, v101
	v_cvt_pk_bf16_f32 v97, v102, v103
	v_cvt_pk_bf16_f32 v98, v114, v115
	v_cvt_pk_bf16_f32 v99, v116, v117
	buffer_store_dwordx4 v[96:99], v151, s[8:11], 0 offen offset:256 sc1
	s_nop 0
	v_add_u32_e32 v112, 0x4030, v150
	v_ashrrev_i32_e32 v113, 31, v112
	v_lshl_add_u32 v116, v152, 13, v149
	v_add_u32_e32 v177, 0x2400, v176
	global_load_dwordx4 v[194:197], v177, s[14:15]
	v_add_u32_e32 v177, 0x2410, v176
	global_load_dwordx4 v[198:201], v177, s[14:15]
	v_add_u32_e32 v177, 0x2420, v176
	global_load_dwordx4 v[202:205], v177, s[14:15]
	v_add_u32_e32 v177, 0x2430, v176
	global_load_dwordx4 v[206:209], v177, s[14:15]
	s_waitcnt vmcnt(16)
; __device__ __forceinline__ u32x4 pack8(const f32x4 v0, const f32x4 v1) { u32x4 w; w.x = pk2(v0[0], v0[1]); w.y = pk2(v0[2], v0[3]); w.z = pk2(v1[0], v1[1]); w.w = pk2(v1[2], v1[3]); return w; }
; __device__ __forceinline__ float row_rstd(const float* ssq, int row) {
;     const f32x4* p = (const f32x4*)(ssq + (size_t)row * 16);
;     const f32x4 a = p[0], b = p[1], c = p[2], d = p[3];
;     const float s = ((a[0] + a[1]) + (a[2] + a[3])) + ((b[0] + b[1]) + (b[2] + b[3])) + ((c[0] + c[1]) + (c[2] + c[3])) + ((d[0] + d[1]) + (d[2] + d[3]));
;     return rsqrtf(s * (1.0f / 1024.0f) + 1e-6f);
;     __device__ __forceinline__ void operator()(const f32x4 (&acc)[2][2][4][2], const Unit& u, int wr, int wc, int fr, int fq) const {
;         const __amdgpu_buffer_rsrc_t rsrc = __builtin_amdgcn_make_buffer_rsrc((void*)O, 0, T_ALL * DFF * 2, 0x00020000);
;         const int row0 = row_off + u.pm * 256 + wr * 64 + fr, col0 = u.pn * 256 + wc * 32 + 8 * fq;
; #pragma unroll
;         for (int ai = 0; ai < 2; ++ai)
; #pragma unroll
;             for (int m = 0; m < 4; ++m) {
;                 const int row = row0 + ai * 128 + m * 16; const float rs = row_rstd(ssq, row);
; #pragma unroll
;                 for (int bj = 0; bj < 2; ++bj) { f32x4 v0 = acc[ai][bj][m][0] * rs, v1 = acc[ai][bj][m][1] * rs;
; #pragma unroll
;                     for (int j = 0; j < 4; ++j) { const float a = fmaxf(v0[j], 0.f), b = fmaxf(v1[j], 0.f); v0[j] = a * a; v1[j] = b * b; }
;                     __builtin_amdgcn_raw_buffer_store_b128(pack8(v0, v1), rsrc, (unsigned)(((size_t)row * DFF + col0 + bj * 128) * 2), 0, 16  ); }
	v_pk_add_f32 v[96:97], v[210:211], v[212:213]
	v_pk_add_f32 v[98:99], v[214:215], v[216:217]
	v_pk_add_f32 v[100:101], v[232:233], v[234:235]
	v_pk_add_f32 v[102:103], v[236:237], v[238:239]
	v_pk_add_f32 v[96:97], v[96:97], v[98:99]
	v_pk_add_f32 v[100:101], v[100:101], v[102:103]
	v_pk_add_f32 v[96:97], v[96:97], v[100:101]
	v_add_f32_e32 v96, v96, v97
	s_nop 0
	s_nop 0
	v_fmamk_f32 v96, v96, 0x3a800000, v148
	s_nop 0
	s_nop 0
	s_nop 1
	s_nop 0
	v_rsq_f32_e32 v98, v96
	s_nop 0
	s_nop 0
	s_nop 0
	s_nop 0
	v_pk_mul_f32 v[94:95], v[94:95], v[98:99] op_sel_hi:[1,0]
	v_pk_mul_f32 v[92:93], v[92:93], v[98:99] op_sel_hi:[1,0]
	v_pk_mul_f32 v[90:91], v[90:91], v[98:99] op_sel_hi:[1,0]
	v_pk_mul_f32 v[88:89], v[88:89], v[98:99] op_sel_hi:[1,0]
	v_pk_mul_f32 v[82:83], v[82:83], v[98:99] op_sel_hi:[1,0]
	v_pk_mul_f32 v[80:81], v[80:81], v[98:99] op_sel_hi:[1,0]
	v_pk_mul_f32 v[86:87], v[86:87], v[98:99] op_sel_hi:[1,0]
	v_pk_mul_f32 v[84:85], v[84:85], v[98:99] op_sel_hi:[1,0]
	v_max_f32_e32 v92, 0, v92
	v_max_f32_e32 v88, 0, v88
	v_max_f32_e32 v93, 0, v93
	v_max_f32_e32 v89, 0, v89
	v_max_f32_e32 v94, 0, v94
	v_max_f32_e32 v90, 0, v90
	v_max_f32_e32 v95, 0, v95
	v_max_f32_e32 v91, 0, v91
	v_max_f32_e32 v80, 0, v80
	v_max_f32_e32 v81, 0, v81
	v_max_f32_e32 v82, 0, v82
	v_max_f32_e32 v83, 0, v83
	v_max_f32_e32 v84, 0, v84
	v_max_f32_e32 v85, 0, v85
	v_max_f32_e32 v86, 0, v86
	v_max_f32_e32 v87, 0, v87
	v_pk_mul_f32 v[92:93], v[92:93], v[92:93]
	v_pk_mul_f32 v[88:89], v[88:89], v[88:89]
	v_pk_mul_f32 v[94:95], v[94:95], v[94:95]
	v_pk_mul_f32 v[90:91], v[90:91], v[90:91]
	v_pk_mul_f32 v[98:99], v[80:81], v[80:81]
	v_pk_mul_f32 v[100:101], v[82:83], v[82:83]
	v_cvt_pk_bf16_f32 v80, v92, v93
	v_cvt_pk_bf16_f32 v81, v94, v95
	v_cvt_pk_bf16_f32 v82, v88, v89
	v_cvt_pk_bf16_f32 v83, v90, v91
	v_pk_mul_f32 v[84:85], v[84:85], v[84:85]
	v_pk_mul_f32 v[86:87], v[86:87], v[86:87]
	buffer_store_dwordx4 v[80:83], v116, s[8:11], 0 offen sc1
	s_nop 1
	v_cvt_pk_bf16_f32 v80, v84, v85
	v_cvt_pk_bf16_f32 v81, v86, v87
	v_cvt_pk_bf16_f32 v82, v98, v99
	v_cvt_pk_bf16_f32 v83, v100, v101
	buffer_store_dwordx4 v[80:83], v116, s[8:11], 0 offen offset:256 sc1
	s_nop 0
	v_add_u32_e32 v96, 0x4080, v150
	v_ashrrev_i32_e32 v97, 31, v96
	v_lshl_add_u32 v100, v112, 13, v149
	v_add_u32_e32 v177, 0x2800, v176
	global_load_dwordx4 v[210:213], v177, s[14:15]
	v_add_u32_e32 v177, 0x2810, v176
	global_load_dwordx4 v[214:217], v177, s[14:15]
	v_add_u32_e32 v177, 0x2820, v176
	global_load_dwordx4 v[232:235], v177, s[14:15]
	v_add_u32_e32 v177, 0x2830, v176
	global_load_dwordx4 v[236:239], v177, s[14:15]
	s_waitcnt vmcnt(18)
	v_pk_add_f32 v[80:81], v[240:241], v[242:243]
	v_pk_add_f32 v[82:83], v[244:245], v[246:247]
	v_pk_add_f32 v[84:85], v[248:249], v[250:251]
	v_pk_add_f32 v[86:87], v[252:253], v[254:255]
	v_pk_add_f32 v[80:81], v[80:81], v[82:83]
	v_pk_add_f32 v[84:85], v[84:85], v[86:87]
	v_pk_add_f32 v[80:81], v[80:81], v[84:85]
	v_add_f32_e32 v80, v80, v81
	s_nop 0
	s_nop 0
	v_fmamk_f32 v80, v80, 0x3a800000, v148
	s_nop 0
	s_nop 0
	s_nop 1
	s_nop 0
	v_rsq_f32_e32 v82, v80
	s_nop 0
	s_nop 0
	s_nop 0
	s_nop 0
	v_pk_mul_f32 v[78:79], v[78:79], v[82:83] op_sel_hi:[1,0]
	v_pk_mul_f32 v[76:77], v[76:77], v[82:83] op_sel_hi:[1,0]
	v_pk_mul_f32 v[74:75], v[74:75], v[82:83] op_sel_hi:[1,0]
	v_pk_mul_f32 v[72:73], v[72:73], v[82:83] op_sel_hi:[1,0]
	v_pk_mul_f32 v[66:67], v[66:67], v[82:83] op_sel_hi:[1,0]
	v_pk_mul_f32 v[64:65], v[64:65], v[82:83] op_sel_hi:[1,0]
	v_pk_mul_f32 v[70:71], v[70:71], v[82:83] op_sel_hi:[1,0]
	v_pk_mul_f32 v[68:69], v[68:69], v[82:83] op_sel_hi:[1,0]
	v_max_f32_e32 v76, 0, v76
	v_max_f32_e32 v72, 0, v72
	v_max_f32_e32 v77, 0, v77
	v_max_f32_e32 v73, 0, v73
	v_max_f32_e32 v78, 0, v78
	v_max_f32_e32 v74, 0, v74
	v_max_f32_e32 v79, 0, v79
	v_max_f32_e32 v75, 0, v75
	v_max_f32_e32 v64, 0, v64
	v_max_f32_e32 v65, 0, v65
	v_max_f32_e32 v66, 0, v66
	v_max_f32_e32 v67, 0, v67
	v_max_f32_e32 v68, 0, v68
	v_max_f32_e32 v69, 0, v69
	v_max_f32_e32 v70, 0, v70
	v_max_f32_e32 v71, 0, v71
	v_pk_mul_f32 v[76:77], v[76:77], v[76:77]
	v_pk_mul_f32 v[72:73], v[72:73], v[72:73]
	v_pk_mul_f32 v[78:79], v[78:79], v[78:79]
	v_pk_mul_f32 v[74:75], v[74:75], v[74:75]
	v_pk_mul_f32 v[82:83], v[64:65], v[64:65]
	v_pk_mul_f32 v[84:85], v[66:67], v[66:67]
	v_cvt_pk_bf16_f32 v64, v76, v77
	v_cvt_pk_bf16_f32 v65, v78, v79
	v_cvt_pk_bf16_f32 v66, v72, v73
	v_cvt_pk_bf16_f32 v67, v74, v75
	v_pk_mul_f32 v[68:69], v[68:69], v[68:69]
	v_pk_mul_f32 v[70:71], v[70:71], v[70:71]
	buffer_store_dwordx4 v[64:67], v100, s[8:11], 0 offen sc1
	s_nop 1
	v_cvt_pk_bf16_f32 v64, v68, v69
	v_cvt_pk_bf16_f32 v65, v70, v71
	v_cvt_pk_bf16_f32 v66, v82, v83
	v_cvt_pk_bf16_f32 v67, v84, v85
	buffer_store_dwordx4 v[64:67], v100, s[8:11], 0 offen offset:256 sc1
	s_nop 0
	v_add_u32_e32 v80, 0x4090, v150
	v_ashrrev_i32_e32 v81, 31, v80
	v_lshl_add_u32 v84, v96, 13, v149
	v_add_u32_e32 v177, 0x2c00, v176
	global_load_dwordx4 v[240:243], v177, s[14:15]
	v_add_u32_e32 v177, 0x2c10, v176
	global_load_dwordx4 v[244:247], v177, s[14:15]
	v_add_u32_e32 v177, 0x2c20, v176
	global_load_dwordx4 v[248:251], v177, s[14:15]
	v_add_u32_e32 v177, 0x2c30, v176
	global_load_dwordx4 v[252:255], v177, s[14:15]
	s_waitcnt vmcnt(18)
; __device__ __forceinline__ u32x4 pack8(const f32x4 v0, const f32x4 v1) { u32x4 w; w.x = pk2(v0[0], v0[1]); w.y = pk2(v0[2], v0[3]); w.z = pk2(v1[0], v1[1]); w.w = pk2(v1[2], v1[3]); return w; }
; __device__ __forceinline__ float row_rstd(const float* ssq, int row) {
;     const f32x4* p = (const f32x4*)(ssq + (size_t)row * 16);
;     const f32x4 a = p[0], b = p[1], c = p[2], d = p[3];
;     const float s = ((a[0] + a[1]) + (a[2] + a[3])) + ((b[0] + b[1]) + (b[2] + b[3])) + ((c[0] + c[1]) + (c[2] + c[3])) + ((d[0] + d[1]) + (d[2] + d[3]));
;     return rsqrtf(s * (1.0f / 1024.0f) + 1e-6f);
;     __device__ __forceinline__ void operator()(const f32x4 (&acc)[2][2][4][2], const Unit& u, int wr, int wc, int fr, int fq) const {
;         const __amdgpu_buffer_rsrc_t rsrc = __builtin_amdgcn_make_buffer_rsrc((void*)O, 0, T_ALL * DFF * 2, 0x00020000);
;         const int row0 = row_off + u.pm * 256 + wr * 64 + fr, col0 = u.pn * 256 + wc * 32 + 8 * fq;
; #pragma unroll
;         for (int ai = 0; ai < 2; ++ai)
; #pragma unroll
;             for (int m = 0; m < 4; ++m) {
;                 const int row = row0 + ai * 128 + m * 16; const float rs = row_rstd(ssq, row);
; #pragma unroll
;                 for (int bj = 0; bj < 2; ++bj) { f32x4 v0 = acc[ai][bj][m][0] * rs, v1 = acc[ai][bj][m][1] * rs;
; #pragma unroll
;                     for (int j = 0; j < 4; ++j) { const float a = fmaxf(v0[j], 0.f), b = fmaxf(v1[j], 0.f); v0[j] = a * a; v1[j] = b * b; }
;                     __builtin_amdgcn_raw_buffer_store_b128(pack8(v0, v1), rsrc, (unsigned)(((size_t)row * DFF + col0 + bj * 128) * 2), 0, 16  ); }
	v_pk_add_f32 v[64:65], v[178:179], v[180:181]
	v_pk_add_f32 v[66:67], v[182:183], v[184:185]
	v_pk_add_f32 v[68:69], v[186:187], v[188:189]
	v_pk_add_f32 v[70:71], v[190:191], v[192:193]
	v_pk_add_f32 v[64:65], v[64:65], v[66:67]
	v_pk_add_f32 v[68:69], v[68:69], v[70:71]
	v_pk_add_f32 v[64:65], v[64:65], v[68:69]
	v_add_f32_e32 v64, v64, v65
	s_nop 0
	s_nop 0
	v_fmamk_f32 v64, v64, 0x3a800000, v148
	s_nop 0
	s_nop 0
	s_nop 1
	s_nop 0
	v_rsq_f32_e32 v66, v64
	s_nop 0
	s_nop 0
	s_nop 0
	s_nop 0
	v_pk_mul_f32 v[62:63], v[62:63], v[66:67] op_sel_hi:[1,0]
	v_pk_mul_f32 v[60:61], v[60:61], v[66:67] op_sel_hi:[1,0]
	v_pk_mul_f32 v[58:59], v[58:59], v[66:67] op_sel_hi:[1,0]
	v_pk_mul_f32 v[56:57], v[56:57], v[66:67] op_sel_hi:[1,0]
	v_pk_mul_f32 v[50:51], v[50:51], v[66:67] op_sel_hi:[1,0]
	v_pk_mul_f32 v[48:49], v[48:49], v[66:67] op_sel_hi:[1,0]
	v_pk_mul_f32 v[54:55], v[54:55], v[66:67] op_sel_hi:[1,0]
	v_pk_mul_f32 v[52:53], v[52:53], v[66:67] op_sel_hi:[1,0]
	v_max_f32_e32 v60, 0, v60
	v_max_f32_e32 v56, 0, v56
	v_max_f32_e32 v61, 0, v61
	v_max_f32_e32 v57, 0, v57
	v_max_f32_e32 v62, 0, v62
	v_max_f32_e32 v58, 0, v58
	v_max_f32_e32 v63, 0, v63
	v_max_f32_e32 v59, 0, v59
	v_max_f32_e32 v48, 0, v48
	v_max_f32_e32 v49, 0, v49
	v_max_f32_e32 v50, 0, v50
	v_max_f32_e32 v51, 0, v51
	v_max_f32_e32 v52, 0, v52
	v_max_f32_e32 v53, 0, v53
	v_max_f32_e32 v54, 0, v54
	v_max_f32_e32 v55, 0, v55
	v_pk_mul_f32 v[60:61], v[60:61], v[60:61]
	v_pk_mul_f32 v[56:57], v[56:57], v[56:57]
	v_pk_mul_f32 v[62:63], v[62:63], v[62:63]
	v_pk_mul_f32 v[58:59], v[58:59], v[58:59]
	v_pk_mul_f32 v[66:67], v[48:49], v[48:49]
	v_pk_mul_f32 v[68:69], v[50:51], v[50:51]
	v_cvt_pk_bf16_f32 v48, v60, v61
	v_cvt_pk_bf16_f32 v49, v62, v63
	v_cvt_pk_bf16_f32 v50, v56, v57
	v_cvt_pk_bf16_f32 v51, v58, v59
	v_pk_mul_f32 v[52:53], v[52:53], v[52:53]
	v_pk_mul_f32 v[54:55], v[54:55], v[54:55]
	buffer_store_dwordx4 v[48:51], v84, s[8:11], 0 offen sc1
	s_nop 1
	v_cvt_pk_bf16_f32 v48, v52, v53
	v_cvt_pk_bf16_f32 v49, v54, v55
	v_cvt_pk_bf16_f32 v50, v66, v67
	v_cvt_pk_bf16_f32 v51, v68, v69
	buffer_store_dwordx4 v[48:51], v84, s[8:11], 0 offen offset:256 sc1
	s_nop 0
	v_add_u32_e32 v64, 0x40a0, v150
	v_ashrrev_i32_e32 v65, 31, v64
	v_lshl_add_u32 v68, v80, 13, v149
	s_waitcnt vmcnt(14)
	v_pk_add_f32 v[48:49], v[194:195], v[196:197]
	v_pk_add_f32 v[50:51], v[198:199], v[200:201]
	v_pk_add_f32 v[52:53], v[202:203], v[204:205]
	v_pk_add_f32 v[54:55], v[206:207], v[208:209]
	v_pk_add_f32 v[48:49], v[48:49], v[50:51]
	v_pk_add_f32 v[52:53], v[52:53], v[54:55]
	v_pk_add_f32 v[48:49], v[48:49], v[52:53]
	v_add_f32_e32 v48, v48, v49
	s_nop 0
	s_nop 0
	v_fmamk_f32 v48, v48, 0x3a800000, v148
	s_nop 0
	s_nop 0
	s_nop 1
	s_nop 0
	v_rsq_f32_e32 v50, v48
	s_nop 0
	s_nop 0
	s_nop 0
	s_nop 0
	v_pk_mul_f32 v[46:47], v[46:47], v[50:51] op_sel_hi:[1,0]
	v_pk_mul_f32 v[44:45], v[44:45], v[50:51] op_sel_hi:[1,0]
	v_pk_mul_f32 v[42:43], v[42:43], v[50:51] op_sel_hi:[1,0]
	v_pk_mul_f32 v[40:41], v[40:41], v[50:51] op_sel_hi:[1,0]
	v_pk_mul_f32 v[34:35], v[34:35], v[50:51] op_sel_hi:[1,0]
	v_pk_mul_f32 v[32:33], v[32:33], v[50:51] op_sel_hi:[1,0]
	v_pk_mul_f32 v[38:39], v[38:39], v[50:51] op_sel_hi:[1,0]
	v_pk_mul_f32 v[36:37], v[36:37], v[50:51] op_sel_hi:[1,0]
	v_max_f32_e32 v44, 0, v44
	v_max_f32_e32 v40, 0, v40
	v_max_f32_e32 v45, 0, v45
	v_max_f32_e32 v41, 0, v41
	v_max_f32_e32 v46, 0, v46
	v_max_f32_e32 v42, 0, v42
	v_max_f32_e32 v47, 0, v47
	v_max_f32_e32 v43, 0, v43
	v_max_f32_e32 v32, 0, v32
	v_max_f32_e32 v33, 0, v33
	v_max_f32_e32 v34, 0, v34
	v_max_f32_e32 v35, 0, v35
	v_max_f32_e32 v36, 0, v36
	v_max_f32_e32 v37, 0, v37
	v_max_f32_e32 v38, 0, v38
	v_max_f32_e32 v39, 0, v39
	v_pk_mul_f32 v[44:45], v[44:45], v[44:45]
	v_pk_mul_f32 v[40:41], v[40:41], v[40:41]
	v_pk_mul_f32 v[46:47], v[46:47], v[46:47]
	v_pk_mul_f32 v[42:43], v[42:43], v[42:43]
	v_pk_mul_f32 v[50:51], v[32:33], v[32:33]
	v_pk_mul_f32 v[52:53], v[34:35], v[34:35]
	v_cvt_pk_bf16_f32 v32, v44, v45
	v_cvt_pk_bf16_f32 v33, v46, v47
	v_cvt_pk_bf16_f32 v34, v40, v41
	v_cvt_pk_bf16_f32 v35, v42, v43
	v_pk_mul_f32 v[36:37], v[36:37], v[36:37]
	v_pk_mul_f32 v[38:39], v[38:39], v[38:39]
	buffer_store_dwordx4 v[32:35], v68, s[8:11], 0 offen sc1
	s_nop 1
	v_cvt_pk_bf16_f32 v32, v36, v37
	v_cvt_pk_bf16_f32 v33, v38, v39
	v_cvt_pk_bf16_f32 v34, v50, v51
	v_cvt_pk_bf16_f32 v35, v52, v53
	buffer_store_dwordx4 v[32:35], v68, s[8:11], 0 offen offset:256 sc1
	s_nop 0
	v_add_u32_e32 v48, 0x40b0, v150
	v_ashrrev_i32_e32 v49, 31, v48
	v_lshl_add_u32 v52, v64, 13, v149
	s_waitcnt vmcnt(10)
; __device__ __forceinline__ u32x4 pack8(const f32x4 v0, const f32x4 v1) { u32x4 w; w.x = pk2(v0[0], v0[1]); w.y = pk2(v0[2], v0[3]); w.z = pk2(v1[0], v1[1]); w.w = pk2(v1[2], v1[3]); return w; }
; __device__ __forceinline__ float row_rstd(const float* ssq, int row) {
;     const f32x4* p = (const f32x4*)(ssq + (size_t)row * 16);
;     const f32x4 a = p[0], b = p[1], c = p[2], d = p[3];
;     const float s = ((a[0] + a[1]) + (a[2] + a[3])) + ((b[0] + b[1]) + (b[2] + b[3])) + ((c[0] + c[1]) + (c[2] + c[3])) + ((d[0] + d[1]) + (d[2] + d[3]));
;     return rsqrtf(s * (1.0f / 1024.0f) + 1e-6f);
;     __device__ __forceinline__ void operator()(const f32x4 (&acc)[2][2][4][2], const Unit& u, int wr, int wc, int fr, int fq) const {
;         const __amdgpu_buffer_rsrc_t rsrc = __builtin_amdgcn_make_buffer_rsrc((void*)O, 0, T_ALL * DFF * 2, 0x00020000);
;         const int row0 = row_off + u.pm * 256 + wr * 64 + fr, col0 = u.pn * 256 + wc * 32 + 8 * fq;
; #pragma unroll
;         for (int ai = 0; ai < 2; ++ai)
; #pragma unroll
;             for (int m = 0; m < 4; ++m) {
;                 const int row = row0 + ai * 128 + m * 16; const float rs = row_rstd(ssq, row);
; #pragma unroll
;                 for (int bj = 0; bj < 2; ++bj) { f32x4 v0 = acc[ai][bj][m][0] * rs, v1 = acc[ai][bj][m][1] * rs;
; #pragma unroll
;                     for (int j = 0; j < 4; ++j) { const float a = fmaxf(v0[j], 0.f), b = fmaxf(v1[j], 0.f); v0[j] = a * a; v1[j] = b * b; }
;                     __builtin_amdgcn_raw_buffer_store_b128(pack8(v0, v1), rsrc, (unsigned)(((size_t)row * DFF + col0 + bj * 128) * 2), 0, 16  ); }
;             }
;         asm volatile("s_waitcnt vmcnt(0)" ::: "memory");
;         if (fr == 0 && fq == 0) (void)__hip_atomic_fetch_add(ready + 64 * (pm_off + u.pm), 1u, __ATOMIC_RELAXED, __HIP_MEMORY_SCOPE_AGENT);
	v_pk_add_f32 v[32:33], v[210:211], v[212:213]
	v_pk_add_f32 v[34:35], v[214:215], v[216:217]
	v_pk_add_f32 v[36:37], v[232:233], v[234:235]
	v_pk_add_f32 v[38:39], v[236:237], v[238:239]
	v_pk_add_f32 v[32:33], v[32:33], v[34:35]
	v_pk_add_f32 v[36:37], v[36:37], v[38:39]
	v_pk_add_f32 v[32:33], v[32:33], v[36:37]
	v_add_f32_e32 v32, v32, v33
	s_nop 0
	s_nop 0
	v_fmamk_f32 v32, v32, 0x3a800000, v148
	s_nop 0
	s_nop 0
	s_nop 1
	s_nop 0
	v_rsq_f32_e32 v34, v32
	v_lshlrev_b64 v[32:33], 6, v[48:49]
	v_lshl_add_u64 v[32:33], s[14:15], 0, v[32:33]
	s_nop 0
	s_nop 0
	v_pk_mul_f32 v[30:31], v[30:31], v[34:35] op_sel_hi:[1,0]
	v_pk_mul_f32 v[28:29], v[28:29], v[34:35] op_sel_hi:[1,0]
	v_pk_mul_f32 v[26:27], v[26:27], v[34:35] op_sel_hi:[1,0]
	v_pk_mul_f32 v[24:25], v[24:25], v[34:35] op_sel_hi:[1,0]
	v_pk_mul_f32 v[18:19], v[18:19], v[34:35] op_sel_hi:[1,0]
	v_pk_mul_f32 v[16:17], v[16:17], v[34:35] op_sel_hi:[1,0]
	v_pk_mul_f32 v[22:23], v[22:23], v[34:35] op_sel_hi:[1,0]
	v_pk_mul_f32 v[20:21], v[20:21], v[34:35] op_sel_hi:[1,0]
	v_max_f32_e32 v28, 0, v28
	v_max_f32_e32 v24, 0, v24
	v_max_f32_e32 v29, 0, v29
	v_max_f32_e32 v25, 0, v25
	v_max_f32_e32 v30, 0, v30
	v_max_f32_e32 v26, 0, v26
	v_max_f32_e32 v31, 0, v31
	v_max_f32_e32 v27, 0, v27
	v_max_f32_e32 v16, 0, v16
	v_max_f32_e32 v17, 0, v17
	v_max_f32_e32 v18, 0, v18
	v_max_f32_e32 v19, 0, v19
	v_max_f32_e32 v20, 0, v20
	v_max_f32_e32 v21, 0, v21
	v_max_f32_e32 v22, 0, v22
	v_max_f32_e32 v23, 0, v23
	v_pk_mul_f32 v[28:29], v[28:29], v[28:29]
	v_pk_mul_f32 v[24:25], v[24:25], v[24:25]
	v_pk_mul_f32 v[30:31], v[30:31], v[30:31]
	v_pk_mul_f32 v[26:27], v[26:27], v[26:27]
	v_pk_mul_f32 v[34:35], v[16:17], v[16:17]
	v_pk_mul_f32 v[36:37], v[18:19], v[18:19]
	v_cvt_pk_bf16_f32 v16, v28, v29
	v_cvt_pk_bf16_f32 v17, v30, v31
	v_cvt_pk_bf16_f32 v18, v24, v25
	v_cvt_pk_bf16_f32 v19, v26, v27
	v_pk_mul_f32 v[20:21], v[20:21], v[20:21]
	v_pk_mul_f32 v[22:23], v[22:23], v[22:23]
	buffer_store_dwordx4 v[16:19], v52, s[8:11], 0 offen sc1
	s_nop 1
	v_cvt_pk_bf16_f32 v16, v20, v21
	v_cvt_pk_bf16_f32 v17, v22, v23
	v_cvt_pk_bf16_f32 v18, v34, v35
	v_cvt_pk_bf16_f32 v19, v36, v37
	buffer_store_dwordx4 v[16:19], v52, s[8:11], 0 offen offset:256 sc1
	s_nop 0
	s_waitcnt vmcnt(6)
	v_pk_add_f32 v[16:17], v[240:241], v[242:243]
	v_pk_add_f32 v[18:19], v[244:245], v[246:247]
	v_pk_add_f32 v[20:21], v[248:249], v[250:251]
	v_pk_add_f32 v[22:23], v[252:253], v[254:255]
	v_pk_add_f32 v[16:17], v[16:17], v[18:19]
	v_pk_add_f32 v[20:21], v[20:21], v[22:23]
	v_pk_add_f32 v[16:17], v[16:17], v[20:21]
	v_add_f32_e32 v16, v16, v17
	s_nop 0
	s_nop 0
	v_fmamk_f32 v16, v16, 0x3a800000, v148
	s_nop 0
	s_nop 0
	s_nop 1
	s_nop 0
	v_rsq_f32_e32 v16, v16
	v_lshl_add_u32 v17, v48, 13, v149
	s_nop 0
	s_nop 0
	v_pk_mul_f32 v[14:15], v[14:15], v[16:17] op_sel_hi:[1,0]
	v_pk_mul_f32 v[12:13], v[12:13], v[16:17] op_sel_hi:[1,0]
	v_pk_mul_f32 v[10:11], v[10:11], v[16:17] op_sel_hi:[1,0]
	v_pk_mul_f32 v[8:9], v[8:9], v[16:17] op_sel_hi:[1,0]
	v_pk_mul_f32 v[2:3], v[2:3], v[16:17] op_sel_hi:[1,0]
	v_pk_mul_f32 v[0:1], v[0:1], v[16:17] op_sel_hi:[1,0]
	v_pk_mul_f32 v[6:7], v[6:7], v[16:17] op_sel_hi:[1,0]
	v_pk_mul_f32 v[4:5], v[4:5], v[16:17] op_sel_hi:[1,0]
	v_max_f32_e32 v12, 0, v12
	v_max_f32_e32 v8, 0, v8
	v_max_f32_e32 v13, 0, v13
	v_max_f32_e32 v9, 0, v9
	v_max_f32_e32 v14, 0, v14
	v_max_f32_e32 v10, 0, v10
	v_max_f32_e32 v15, 0, v15
	v_max_f32_e32 v11, 0, v11
	v_max_f32_e32 v0, 0, v0
	v_max_f32_e32 v1, 0, v1
	v_max_f32_e32 v2, 0, v2
	v_max_f32_e32 v3, 0, v3
	v_max_f32_e32 v4, 0, v4
	v_max_f32_e32 v5, 0, v5
	v_max_f32_e32 v6, 0, v6
	v_max_f32_e32 v7, 0, v7
	v_pk_mul_f32 v[12:13], v[12:13], v[12:13]
	v_pk_mul_f32 v[8:9], v[8:9], v[8:9]
	v_pk_mul_f32 v[14:15], v[14:15], v[14:15]
	v_pk_mul_f32 v[10:11], v[10:11], v[10:11]
	v_mul_f32_e32 v16, v0, v0
	v_mul_f32_e32 v18, v1, v1
	v_mul_f32_e32 v19, v2, v2
	v_mul_f32_e32 v20, v3, v3
	v_cvt_pk_bf16_f32 v0, v12, v13
	v_cvt_pk_bf16_f32 v1, v14, v15
	v_cvt_pk_bf16_f32 v2, v8, v9
	v_cvt_pk_bf16_f32 v3, v10, v11
	v_pk_mul_f32 v[4:5], v[4:5], v[4:5]
	v_pk_mul_f32 v[6:7], v[6:7], v[6:7]
	buffer_store_dwordx4 v[0:3], v17, s[8:11], 0 offen sc1
	s_nop 1
	v_cvt_pk_bf16_f32 v0, v4, v5
	v_cvt_pk_bf16_f32 v1, v6, v7
	v_cvt_pk_bf16_f32 v2, v16, v18
	v_cvt_pk_bf16_f32 v3, v19, v20
	buffer_store_dwordx4 v[0:3], v17, s[8:11], 0 offen offset:256 sc1
	s_waitcnt vmcnt(0)
	s_and_saveexec_b64 s[34:35], s[6:7]
	s_cbranch_execz .LBB0_2114
	s_mov_b64 s[36:37], exec
	v_mbcnt_lo_u32_b32 v0, s36, 0
	v_mbcnt_hi_u32_b32 v0, s37, v0
	v_cmp_eq_u32_e32 vcc, 0, v0
	s_and_b64 s[38:39], exec, vcc
	s_mov_b64 exec, s[38:39]
	s_cbranch_execz .LBB0_2114
	s_lshl_b32 s21, s68, 6
	s_add_i32 s38, s21, 0x1000
	s_ashr_i32 s39, s38, 31
	s_lshl_b64 s[38:39], s[38:39], 2
	s_add_u32 s38, s66, s38
	s_addc_u32 s39, s67, s39
	s_bcnt1_i32_b64 s21, s[36:37]
	v_mov_b32_e32 v0, s21
	global_atomic_add v131, v0, s[38:39]
	s_branch .LBB0_2114

; #define KP(f) ((decltype(Params::f))karg_ptr<(int)offsetof(Params, f)>())
; __device__ __forceinline__ float row_rstd(const float* ssq, int row) {
;     const f32x4* p = (const f32x4*)(ssq + (size_t)row * 16);
;     const f32x4 a = p[0], b = p[1], c = p[2], d = p[3];
;     const float s = ((a[0] + a[1]) + (a[2] + a[3])) + ((b[0] + b[1]) + (b[2] + b[3])) + ((c[0] + c[1]) + (c[2] + c[3])) + ((d[0] + d[1]) + (d[2] + d[3]));
;     return rsqrtf(s * (1.0f / 1024.0f) + 1e-6f);
; __device__ void phase_final() {
;     float* out = KP(out); const float* ssq = KP(ssq); const float* fg = KP(final_g);
;     const int lane = threadIdx.x & 63, gw = blockIdx.x * 8 + (threadIdx.x >> 6), nw = gridDim.x * 8;
;     for (int row = gw; row < T_ALL; row += nw) {
;         const float rs = row_rstd(ssq, row);
;         float* xr = out + (size_t)row * DM;
; #pragma unroll
;         for (int i = 0; i < 4; ++i) { const int c = i * 256 + lane * 4; const f32x4 v = *(const f32x4*)(xr + c); const f32x4 g = *(const f32x4*)(fg + c);
;             *(f32x4*)(xr + c) = v * rs * g; }
;     }
.LBB0_2319:
	s_or_b64 exec, exec, s[6:7]
	s_waitcnt lgkmcnt(0)
	s_barrier
	v_readlane_b32 s8, v230, 4
	s_load_dwordx2 s[2:3], s[0:1], 0xd8
	s_waitcnt lgkmcnt(0)
	s_load_dwordx2 s[4:5], s[0:1], 0x128
	s_waitcnt lgkmcnt(0)
	s_load_dwordx2 s[0:1], s[0:1], 0xd0
	s_waitcnt lgkmcnt(0)
	v_readlane_b32 s9, v230, 5
	s_and_saveexec_b64 s[6:7], s[8:9]
	s_cbranch_execz .LBB0_2322
	v_lshlrev_b32_e32 v0, 4, v166
	v_lshlrev_b64 v[2:3], 6, v[144:145]
	v_lshlrev_b64 v[4:5], 12, v[144:145]
	v_and_b32_e32 v0, 0x3f0, v0
	v_mov_b32_e32 v1, 0
	v_lshl_add_u64 v[2:3], s[4:5], 0, v[2:3]
	s_ashr_i32 s51, s50, 31
	v_lshl_or_b32 v4, v167, 4, v4
	v_lshl_add_u64 v[0:1], s[0:1], 0, v[0:1]
	v_lshl_add_u64 v[2:3], v[2:3], 0, 32
	s_lshl_b64 s[0:1], s[50:51], 6
	v_lshl_add_u64 v[4:5], s[2:3], 0, v[4:5]
	s_lshl_b64 s[2:3], s[50:51], 12
	s_mov_b64 s[4:5], 0
	v_mov_b32_e32 v6, 0x358637bd
	s_mov_b32 s6, 0x800000
	s_movk_i32 s7, 0x43ff
	global_load_dwordx4 v[40:43], v[0:1], off
	global_load_dwordx4 v[44:47], v[0:1], off offset:1024
	global_load_dwordx4 v[48:51], v[0:1], off offset:2048
	global_load_dwordx4 v[52:55], v[0:1], off offset:3072
	v_mov_b64_e32 v[92:93], v[4:5]
	global_load_dwordx4 v[8:11], v[2:3], off offset:-32
	global_load_dwordx4 v[12:15], v[2:3], off offset:-16
	global_load_dwordx4 v[16:19], v[2:3], off
	global_load_dwordx4 v[20:23], v[2:3], off offset:16
	global_load_dwordx4 v[24:27], v[4:5], off
	global_load_dwordx4 v[28:31], v[4:5], off offset:1024
	global_load_dwordx4 v[32:35], v[4:5], off offset:2048
	global_load_dwordx4 v[36:39], v[4:5], off offset:3072
	v_add_u32_e32 v144, s50, v144
	v_lshl_add_u64 v[2:3], v[2:3], 0, s[0:1]
	v_lshl_add_u64 v[4:5], v[4:5], 0, s[2:3]
	v_cmp_ge_i32_e32 vcc, s7, v144
	s_cbranch_vccz .Lfin_lastA
	v_mov_b64_e32 v[94:95], v[4:5]
	global_load_dwordx4 v[56:59], v[2:3], off offset:-32
	global_load_dwordx4 v[60:63], v[2:3], off offset:-16
	global_load_dwordx4 v[64:67], v[2:3], off
	global_load_dwordx4 v[68:71], v[2:3], off offset:16
	global_load_dwordx4 v[72:75], v[4:5], off
	global_load_dwordx4 v[76:79], v[4:5], off offset:1024
	global_load_dwordx4 v[80:83], v[4:5], off offset:2048
	global_load_dwordx4 v[84:87], v[4:5], off offset:3072
	s_waitcnt vmcnt(8)
	v_add_f32_e32 v96, v8, v9
	v_add_f32_e32 v97, v10, v11
	v_add_f32_e32 v98, v12, v13
	v_add_f32_e32 v99, v14, v15
	v_add_f32_e32 v100, v16, v17
	v_add_f32_e32 v101, v18, v19
	v_add_f32_e32 v102, v20, v21
	v_add_f32_e32 v103, v22, v23
	v_add_f32_e32 v96, v96, v97
	v_add_f32_e32 v98, v98, v99
	v_add_f32_e32 v100, v100, v101
	v_add_f32_e32 v102, v102, v103
	v_add_f32_e32 v96, v96, v98
	v_add_f32_e32 v96, v96, v100
	v_add_f32_e32 v96, v96, v102
	v_fmamk_f32 v96, v96, 0x3a800000, v6
	s_nop 0
	s_nop 0
	s_nop 1
	s_nop 0
	v_rsq_f32_e32 v96, v96
	s_nop 0
	s_nop 0
	v_mov_b32_e32 v90, v96
	v_pk_mul_f32 v[24:25], v[24:25], v[90:91] op_sel_hi:[1,0]
	v_pk_mul_f32 v[26:27], v[26:27], v[90:91] op_sel_hi:[1,0]
	v_pk_mul_f32 v[24:25], v[40:41], v[24:25]
	v_pk_mul_f32 v[26:27], v[42:43], v[26:27]
	global_store_dwordx4 v[92:93], v[24:27], off
	v_pk_mul_f32 v[28:29], v[28:29], v[90:91] op_sel_hi:[1,0]
	v_pk_mul_f32 v[30:31], v[30:31], v[90:91] op_sel_hi:[1,0]
	v_pk_mul_f32 v[28:29], v[44:45], v[28:29]
	v_pk_mul_f32 v[30:31], v[46:47], v[30:31]
	global_store_dwordx4 v[92:93], v[28:31], off offset:1024
	v_pk_mul_f32 v[32:33], v[32:33], v[90:91] op_sel_hi:[1,0]
	v_pk_mul_f32 v[34:35], v[34:35], v[90:91] op_sel_hi:[1,0]
	v_pk_mul_f32 v[32:33], v[48:49], v[32:33]
	v_pk_mul_f32 v[34:35], v[50:51], v[34:35]
	global_store_dwordx4 v[92:93], v[32:35], off offset:2048
	v_pk_mul_f32 v[36:37], v[36:37], v[90:91] op_sel_hi:[1,0]
	v_pk_mul_f32 v[38:39], v[38:39], v[90:91] op_sel_hi:[1,0]
	v_pk_mul_f32 v[36:37], v[52:53], v[36:37]
	v_pk_mul_f32 v[38:39], v[54:55], v[38:39]
	global_store_dwordx4 v[92:93], v[36:39], off offset:3072
; #define KP(f) ((decltype(Params::f))karg_ptr<(int)offsetof(Params, f)>())
; __device__ __forceinline__ float row_rstd(const float* ssq, int row) {
;     const f32x4* p = (const f32x4*)(ssq + (size_t)row * 16);
;     const f32x4 a = p[0], b = p[1], c = p[2], d = p[3];
;     const float s = ((a[0] + a[1]) + (a[2] + a[3])) + ((b[0] + b[1]) + (b[2] + b[3])) + ((c[0] + c[1]) + (c[2] + c[3])) + ((d[0] + d[1]) + (d[2] + d[3]));
;     return rsqrtf(s * (1.0f / 1024.0f) + 1e-6f);
; __device__ void phase_final() {
;     float* out = KP(out); const float* ssq = KP(ssq); const float* fg = KP(final_g);
;     const int lane = threadIdx.x & 63, gw = blockIdx.x * 8 + (threadIdx.x >> 6), nw = gridDim.x * 8;
;     for (int row = gw; row < T_ALL; row += nw) {
;         const float rs = row_rstd(ssq, row);
;         float* xr = out + (size_t)row * DM;
; #pragma unroll
;         for (int i = 0; i < 4; ++i) { const int c = i * 256 + lane * 4; const f32x4 v = *(const f32x4*)(xr + c); const f32x4 g = *(const f32x4*)(fg + c);
;             *(f32x4*)(xr + c) = v * rs * g; }
;     }
.Lfin_loop:
	v_add_u32_e32 v144, s50, v144
	v_lshl_add_u64 v[2:3], v[2:3], 0, s[0:1]
	v_lshl_add_u64 v[4:5], v[4:5], 0, s[2:3]
	v_cmp_ge_i32_e32 vcc, s7, v144
	s_cbranch_vccz .Lfin_lastB
	v_mov_b64_e32 v[92:93], v[4:5]
	global_load_dwordx4 v[8:11], v[2:3], off offset:-32
	global_load_dwordx4 v[12:15], v[2:3], off offset:-16
	global_load_dwordx4 v[16:19], v[2:3], off
	global_load_dwordx4 v[20:23], v[2:3], off offset:16
	global_load_dwordx4 v[24:27], v[4:5], off
	global_load_dwordx4 v[28:31], v[4:5], off offset:1024
	global_load_dwordx4 v[32:35], v[4:5], off offset:2048
	global_load_dwordx4 v[36:39], v[4:5], off offset:3072
	s_waitcnt vmcnt(12)
	v_add_f32_e32 v96, v56, v57
	v_add_f32_e32 v97, v58, v59
	v_add_f32_e32 v98, v60, v61
	v_add_f32_e32 v99, v62, v63
	v_add_f32_e32 v100, v64, v65
	v_add_f32_e32 v101, v66, v67
	v_add_f32_e32 v102, v68, v69
	v_add_f32_e32 v103, v70, v71
	v_add_f32_e32 v96, v96, v97
	v_add_f32_e32 v98, v98, v99
	v_add_f32_e32 v100, v100, v101
	v_add_f32_e32 v102, v102, v103
	v_add_f32_e32 v96, v96, v98
	v_add_f32_e32 v96, v96, v100
	v_add_f32_e32 v96, v96, v102
	v_fmamk_f32 v96, v96, 0x3a800000, v6
	s_nop 0
	s_nop 0
	s_nop 1
	s_nop 0
	v_rsq_f32_e32 v96, v96
	s_nop 0
	s_nop 0
	v_mov_b32_e32 v90, v96
	v_pk_mul_f32 v[72:73], v[72:73], v[90:91] op_sel_hi:[1,0]
	v_pk_mul_f32 v[74:75], v[74:75], v[90:91] op_sel_hi:[1,0]
	v_pk_mul_f32 v[72:73], v[40:41], v[72:73]
	v_pk_mul_f32 v[74:75], v[42:43], v[74:75]
	global_store_dwordx4 v[94:95], v[72:75], off
	v_pk_mul_f32 v[76:77], v[76:77], v[90:91] op_sel_hi:[1,0]
	v_pk_mul_f32 v[78:79], v[78:79], v[90:91] op_sel_hi:[1,0]
	v_pk_mul_f32 v[76:77], v[44:45], v[76:77]
	v_pk_mul_f32 v[78:79], v[46:47], v[78:79]
	global_store_dwordx4 v[94:95], v[76:79], off offset:1024
	v_pk_mul_f32 v[80:81], v[80:81], v[90:91] op_sel_hi:[1,0]
	v_pk_mul_f32 v[82:83], v[82:83], v[90:91] op_sel_hi:[1,0]
	v_pk_mul_f32 v[80:81], v[48:49], v[80:81]
	v_pk_mul_f32 v[82:83], v[50:51], v[82:83]
	global_store_dwordx4 v[94:95], v[80:83], off offset:2048
	v_pk_mul_f32 v[84:85], v[84:85], v[90:91] op_sel_hi:[1,0]
	v_pk_mul_f32 v[86:87], v[86:87], v[90:91] op_sel_hi:[1,0]
	v_pk_mul_f32 v[84:85], v[52:53], v[84:85]
	v_pk_mul_f32 v[86:87], v[54:55], v[86:87]
	global_store_dwordx4 v[94:95], v[84:87], off offset:3072
	v_add_u32_e32 v144, s50, v144
	v_lshl_add_u64 v[2:3], v[2:3], 0, s[0:1]
	v_lshl_add_u64 v[4:5], v[4:5], 0, s[2:3]
	v_cmp_ge_i32_e32 vcc, s7, v144
	s_cbranch_vccz .Lfin_lastA
	v_mov_b64_e32 v[94:95], v[4:5]
	global_load_dwordx4 v[56:59], v[2:3], off offset:-32
	global_load_dwordx4 v[60:63], v[2:3], off offset:-16
	global_load_dwordx4 v[64:67], v[2:3], off
	global_load_dwordx4 v[68:71], v[2:3], off offset:16
	global_load_dwordx4 v[72:75], v[4:5], off
	global_load_dwordx4 v[76:79], v[4:5], off offset:1024
	global_load_dwordx4 v[80:83], v[4:5], off offset:2048
	global_load_dwordx4 v[84:87], v[4:5], off offset:3072
	s_waitcnt vmcnt(12)
	v_add_f32_e32 v96, v8, v9
	v_add_f32_e32 v97, v10, v11
	v_add_f32_e32 v98, v12, v13
	v_add_f32_e32 v99, v14, v15
	v_add_f32_e32 v100, v16, v17
	v_add_f32_e32 v101, v18, v19
	v_add_f32_e32 v102, v20, v21
	v_add_f32_e32 v103, v22, v23
	v_add_f32_e32 v96, v96, v97
	v_add_f32_e32 v98, v98, v99
	v_add_f32_e32 v100, v100, v101
	v_add_f32_e32 v102, v102, v103
	v_add_f32_e32 v96, v96, v98
	v_add_f32_e32 v96, v96, v100
	v_add_f32_e32 v96, v96, v102
	v_fmamk_f32 v96, v96, 0x3a800000, v6
	s_nop 0
	s_nop 0
	s_nop 1
	s_nop 0
	v_rsq_f32_e32 v96, v96
	s_nop 0
	s_nop 0
	v_mov_b32_e32 v90, v96
	v_pk_mul_f32 v[24:25], v[24:25], v[90:91] op_sel_hi:[1,0]
	v_pk_mul_f32 v[26:27], v[26:27], v[90:91] op_sel_hi:[1,0]
	v_pk_mul_f32 v[24:25], v[40:41], v[24:25]
	v_pk_mul_f32 v[26:27], v[42:43], v[26:27]
	global_store_dwordx4 v[92:93], v[24:27], off
	v_pk_mul_f32 v[28:29], v[28:29], v[90:91] op_sel_hi:[1,0]
	v_pk_mul_f32 v[30:31], v[30:31], v[90:91] op_sel_hi:[1,0]
	v_pk_mul_f32 v[28:29], v[44:45], v[28:29]
	v_pk_mul_f32 v[30:31], v[46:47], v[30:31]
	global_store_dwordx4 v[92:93], v[28:31], off offset:1024
	v_pk_mul_f32 v[32:33], v[32:33], v[90:91] op_sel_hi:[1,0]
	v_pk_mul_f32 v[34:35], v[34:35], v[90:91] op_sel_hi:[1,0]
	v_pk_mul_f32 v[32:33], v[48:49], v[32:33]
	v_pk_mul_f32 v[34:35], v[50:51], v[34:35]
	global_store_dwordx4 v[92:93], v[32:35], off offset:2048
	v_pk_mul_f32 v[36:37], v[36:37], v[90:91] op_sel_hi:[1,0]
	v_pk_mul_f32 v[38:39], v[38:39], v[90:91] op_sel_hi:[1,0]
	v_pk_mul_f32 v[36:37], v[52:53], v[36:37]
	v_pk_mul_f32 v[38:39], v[54:55], v[38:39]
	global_store_dwordx4 v[92:93], v[36:39], off offset:3072
	s_branch .Lfin_loop
.Lfin_lastA:
	s_waitcnt vmcnt(0)
	v_add_f32_e32 v96, v8, v9
	v_add_f32_e32 v97, v10, v11
	v_add_f32_e32 v98, v12, v13
	v_add_f32_e32 v99, v14, v15
	v_add_f32_e32 v100, v16, v17
	v_add_f32_e32 v101, v18, v19
	v_add_f32_e32 v102, v20, v21
	v_add_f32_e32 v103, v22, v23
	v_add_f32_e32 v96, v96, v97
	v_add_f32_e32 v98, v98, v99
	v_add_f32_e32 v100, v100, v101
	v_add_f32_e32 v102, v102, v103
	v_add_f32_e32 v96, v96, v98
	v_add_f32_e32 v96, v96, v100
	v_add_f32_e32 v96, v96, v102
	v_fmamk_f32 v96, v96, 0x3a800000, v6
	s_nop 0
	s_nop 0
	s_nop 1
	s_nop 0
	v_rsq_f32_e32 v96, v96
	s_nop 0
	s_nop 0
	v_mov_b32_e32 v90, v96
	v_pk_mul_f32 v[24:25], v[24:25], v[90:91] op_sel_hi:[1,0]
	v_pk_mul_f32 v[26:27], v[26:27], v[90:91] op_sel_hi:[1,0]
	v_pk_mul_f32 v[24:25], v[40:41], v[24:25]
	v_pk_mul_f32 v[26:27], v[42:43], v[26:27]
	global_store_dwordx4 v[92:93], v[24:27], off
	v_pk_mul_f32 v[28:29], v[28:29], v[90:91] op_sel_hi:[1,0]
	v_pk_mul_f32 v[30:31], v[30:31], v[90:91] op_sel_hi:[1,0]
	v_pk_mul_f32 v[28:29], v[44:45], v[28:29]
	v_pk_mul_f32 v[30:31], v[46:47], v[30:31]
	global_store_dwordx4 v[92:93], v[28:31], off offset:1024
	v_pk_mul_f32 v[32:33], v[32:33], v[90:91] op_sel_hi:[1,0]
	v_pk_mul_f32 v[34:35], v[34:35], v[90:91] op_sel_hi:[1,0]
	v_pk_mul_f32 v[32:33], v[48:49], v[32:33]
	v_pk_mul_f32 v[34:35], v[50:51], v[34:35]
	global_store_dwordx4 v[92:93], v[32:35], off offset:2048
	v_pk_mul_f32 v[36:37], v[36:37], v[90:91] op_sel_hi:[1,0]
	v_pk_mul_f32 v[38:39], v[38:39], v[90:91] op_sel_hi:[1,0]
	v_pk_mul_f32 v[36:37], v[52:53], v[36:37]
	v_pk_mul_f32 v[38:39], v[54:55], v[38:39]
	global_store_dwordx4 v[92:93], v[36:39], off offset:3072
	s_branch .LBB0_2322
